# loop-edge: peeled the last double-k-tile iteration of all 20 GStream k-loops; the peeled copy drops the clamped dead prefetch loads and the dead LDS stores, with recounted waits
# speedup vs baseline: 1.0404x; 1.0133x over previous
.LBB0_84:
	s_add_i32 s3, s24, 2
	v_add_u32_e32 v181, v144, v145
	ds_read_b128 v[80:83], v181 offset:16384
	ds_read_b128 v[84:87], v181 offset:18432
	ds_read_b128 v[88:91], v181 offset:20480
	ds_read_b128 v[92:95], v181 offset:22528
	v_add_u32_e32 v180, v143, v145
	ds_read_b128 v[64:67], v180
	s_add_i32 s24, s24, 4
	ds_read_b128 v[68:71], v180 offset:2048
	s_min_u32 s24, s24, 15
	s_lshl_b32 s92, s24, 7
	ds_read_b128 v[72:75], v180 offset:4096
	ds_read_b128 v[76:79], v180 offset:6144
	v_add_u32_e32 v182, v143, v146
	v_add_u32_e32 v186, v144, v146
	v_lshl_add_u64 v[224:225], v[138:139], 0, s[92:93]
	ds_read_b128 v[192:195], v182
	ds_read_b128 v[196:199], v182 offset:2048
	ds_read_b128 v[200:203], v182 offset:4096
	ds_read_b128 v[204:207], v182 offset:6144
	ds_read_b128 v[208:211], v186 offset:16384
	ds_read_b128 v[212:215], v186 offset:18432
	ds_read_b128 v[216:219], v186 offset:20480
	ds_read_b128 v[220:223], v186 offset:22528
	s_waitcnt lgkmcnt(11)
	v_mfma_f32_16x16x32_bf16 v[60:63], v[80:83], v[64:67], v[60:63]
	v_mfma_f32_16x16x32_bf16 v[56:59], v[84:87], v[64:67], v[56:59]
	v_mfma_f32_16x16x32_bf16 v[52:55], v[88:91], v[64:67], v[52:55]
	v_mfma_f32_16x16x32_bf16 v[48:51], v[92:95], v[64:67], v[48:51]
	global_load_dwordx4 v[64:67], v[224:225], off
	s_waitcnt vmcnt(6)
	ds_write_b128 v156, v[96:99] offset:32768
	v_add_co_u32_e32 v96, vcc, s11, v224
	s_waitcnt lgkmcnt(11)
	v_mfma_f32_16x16x32_bf16 v[44:47], v[80:83], v[68:71], v[44:47]
	v_addc_co_u32_e32 v97, vcc, 0, v225, vcc
	v_mfma_f32_16x16x32_bf16 v[40:43], v[84:87], v[68:71], v[40:43]
	v_mfma_f32_16x16x32_bf16 v[36:39], v[88:91], v[68:71], v[36:39]
	v_mfma_f32_16x16x32_bf16 v[32:35], v[92:95], v[68:71], v[32:35]
	global_load_dwordx4 v[68:71], v[96:97], off
	v_add_co_u32_e32 v96, vcc, s33, v224
	ds_write_b128 v156, v[100:103] offset:36864
	s_nop 0
	v_addc_co_u32_e32 v97, vcc, 0, v225, vcc
	s_waitcnt lgkmcnt(11)
	v_mfma_f32_16x16x32_bf16 v[28:31], v[80:83], v[72:75], v[28:31]
	v_mfma_f32_16x16x32_bf16 v[24:27], v[84:87], v[72:75], v[24:27]
	v_mfma_f32_16x16x32_bf16 v[20:23], v[88:91], v[72:75], v[20:23]
	v_mfma_f32_16x16x32_bf16 v[16:19], v[92:95], v[72:75], v[16:19]
	global_load_dwordx4 v[72:75], v[96:97], off
	ds_write_b128 v156, v[104:107] offset:40960
	s_waitcnt lgkmcnt(11)
	v_mfma_f32_16x16x32_bf16 v[12:15], v[80:83], v[76:79], v[12:15]
	v_add_co_u32_e32 v80, vcc, s59, v224
	v_mfma_f32_16x16x32_bf16 v[0:3], v[92:95], v[76:79], v[0:3]
	s_nop 0
	v_addc_co_u32_e32 v81, vcc, 0, v225, vcc
	v_lshl_add_u64 v[92:93], v[140:141], 0, s[92:93]
	v_mfma_f32_16x16x32_bf16 v[8:11], v[84:87], v[76:79], v[8:11]
	v_add_co_u32_e32 v84, vcc, s11, v92
	s_nop 1
	v_addc_co_u32_e32 v85, vcc, 0, v93, vcc
	v_mfma_f32_16x16x32_bf16 v[4:7], v[88:91], v[76:79], v[4:7]
	v_add_co_u32_e32 v88, vcc, s33, v92
	global_load_dwordx4 v[76:79], v[80:81], off
	s_nop 0
	v_addc_co_u32_e32 v89, vcc, 0, v93, vcc
	s_waitcnt vmcnt(7)
	ds_write_b128 v156, v[112:115] offset:45056
	s_waitcnt lgkmcnt(7)
	v_mfma_f32_16x16x32_bf16 v[60:63], v[208:211], v[192:195], v[60:63]
	s_waitcnt lgkmcnt(6)
	v_mfma_f32_16x16x32_bf16 v[56:59], v[212:215], v[192:195], v[56:59]
	s_waitcnt lgkmcnt(5)
	v_mfma_f32_16x16x32_bf16 v[52:55], v[216:219], v[192:195], v[52:55]
	s_waitcnt lgkmcnt(4)
	v_mfma_f32_16x16x32_bf16 v[48:51], v[220:223], v[192:195], v[48:51]
	global_load_dwordx4 v[80:83], v[92:93], off
	v_add_co_u32_e32 v92, vcc, s59, v92
	ds_write_b128 v156, v[108:111] offset:49152
	s_nop 0
	v_addc_co_u32_e32 v93, vcc, 0, v93, vcc
	v_mfma_f32_16x16x32_bf16 v[44:47], v[208:211], v[196:199], v[44:47]
	v_mfma_f32_16x16x32_bf16 v[40:43], v[212:215], v[196:199], v[40:43]
	v_mfma_f32_16x16x32_bf16 v[36:39], v[216:219], v[196:199], v[36:39]
	v_mfma_f32_16x16x32_bf16 v[32:35], v[220:223], v[196:199], v[32:35]
	global_load_dwordx4 v[84:87], v[84:85], off
	s_waitcnt vmcnt(8)
	ds_write_b128 v156, v[116:119] offset:53248
	v_mfma_f32_16x16x32_bf16 v[28:31], v[208:211], v[200:203], v[28:31]
	v_mfma_f32_16x16x32_bf16 v[24:27], v[212:215], v[200:203], v[24:27]
	v_mfma_f32_16x16x32_bf16 v[20:23], v[216:219], v[200:203], v[20:23]
	v_mfma_f32_16x16x32_bf16 v[16:19], v[220:223], v[200:203], v[16:19]
	global_load_dwordx4 v[88:91], v[88:89], off
	s_waitcnt vmcnt(8)
	ds_write_b128 v156, v[120:123] offset:57344
	v_mfma_f32_16x16x32_bf16 v[12:15], v[208:211], v[204:207], v[12:15]
	v_mfma_f32_16x16x32_bf16 v[8:11], v[212:215], v[204:207], v[8:11]
	v_mfma_f32_16x16x32_bf16 v[4:7], v[216:219], v[204:207], v[4:7]
	v_mfma_f32_16x16x32_bf16 v[0:3], v[220:223], v[204:207], v[0:3]
	global_load_dwordx4 v[92:95], v[92:93], off
	s_waitcnt vmcnt(8)
	ds_write_b128 v156, v[124:127] offset:61440
	s_waitcnt lgkmcnt(0)
	s_barrier
	ds_read_b128 v[112:115], v181 offset:49152
	ds_read_b128 v[116:119], v181 offset:51200
	ds_read_b128 v[120:123], v181 offset:53248
	ds_read_b128 v[124:127], v181 offset:55296
	ds_read_b128 v[96:99], v180 offset:32768
	ds_read_b128 v[100:103], v180 offset:34816
	s_min_u32 s24, s3, 12
	s_lshl_b32 s92, s24, 7
	ds_read_b128 v[104:107], v180 offset:36864
	v_lshl_add_u64 v[224:225], v[138:139], 0, s[92:93]
	ds_read_b128 v[108:111], v180 offset:38912
	ds_read_b128 v[192:195], v182 offset:32768
	ds_read_b128 v[196:199], v182 offset:34816
	ds_read_b128 v[200:203], v182 offset:36864
	ds_read_b128 v[204:207], v182 offset:38912
	ds_read_b128 v[208:211], v186 offset:49152
	ds_read_b128 v[212:215], v186 offset:51200
	ds_read_b128 v[216:219], v186 offset:53248
	ds_read_b128 v[220:223], v186 offset:55296
	s_waitcnt lgkmcnt(11)
	v_mfma_f32_16x16x32_bf16 v[60:63], v[112:115], v[96:99], v[60:63]
	v_mfma_f32_16x16x32_bf16 v[56:59], v[116:119], v[96:99], v[56:59]
	v_mfma_f32_16x16x32_bf16 v[52:55], v[120:123], v[96:99], v[52:55]
	v_mfma_f32_16x16x32_bf16 v[48:51], v[124:127], v[96:99], v[48:51]
	global_load_dwordx4 v[96:99], v[224:225], off offset:384
	s_waitcnt vmcnt(8)
	ds_write_b128 v156, v[64:67]
	v_add_co_u32_e32 v64, vcc, s11, v224
	s_waitcnt lgkmcnt(11)
	v_mfma_f32_16x16x32_bf16 v[44:47], v[112:115], v[100:103], v[44:47]
	v_addc_co_u32_e32 v65, vcc, 0, v225, vcc
	v_mfma_f32_16x16x32_bf16 v[40:43], v[116:119], v[100:103], v[40:43]
	v_mfma_f32_16x16x32_bf16 v[36:39], v[120:123], v[100:103], v[36:39]
	v_mfma_f32_16x16x32_bf16 v[32:35], v[124:127], v[100:103], v[32:35]
	global_load_dwordx4 v[100:103], v[64:65], off offset:384
	v_add_co_u32_e32 v64, vcc, s33, v224
	s_waitcnt vmcnt(8)
	ds_write_b128 v156, v[68:71] offset:4096
	v_addc_co_u32_e32 v65, vcc, 0, v225, vcc
	s_waitcnt lgkmcnt(11)
	v_mfma_f32_16x16x32_bf16 v[28:31], v[112:115], v[104:107], v[28:31]
	v_mfma_f32_16x16x32_bf16 v[24:27], v[116:119], v[104:107], v[24:27]
	v_mfma_f32_16x16x32_bf16 v[20:23], v[120:123], v[104:107], v[20:23]
	v_mfma_f32_16x16x32_bf16 v[16:19], v[124:127], v[104:107], v[16:19]
	global_load_dwordx4 v[104:107], v[64:65], off offset:384
	v_add_co_u32_e32 v64, vcc, s59, v224
	s_waitcnt vmcnt(8)
	ds_write_b128 v156, v[72:75] offset:8192
	v_addc_co_u32_e32 v65, vcc, 0, v225, vcc
	s_waitcnt lgkmcnt(11)
	v_mfma_f32_16x16x32_bf16 v[12:15], v[112:115], v[108:111], v[12:15]
	v_mfma_f32_16x16x32_bf16 v[8:11], v[116:119], v[108:111], v[8:11]
	v_mfma_f32_16x16x32_bf16 v[4:7], v[120:123], v[108:111], v[4:7]
	v_mfma_f32_16x16x32_bf16 v[0:3], v[124:127], v[108:111], v[0:3]
	global_load_dwordx4 v[112:115], v[64:65], off offset:384
	v_lshl_add_u64 v[64:65], v[140:141], 0, s[92:93]
	v_add_co_u32_e32 v66, vcc, s11, v64
	s_waitcnt vmcnt(8)
	ds_write_b128 v156, v[76:79] offset:12288
	v_addc_co_u32_e32 v67, vcc, 0, v65, vcc
	s_waitcnt lgkmcnt(7)
	v_mfma_f32_16x16x32_bf16 v[60:63], v[208:211], v[192:195], v[60:63]
	s_waitcnt lgkmcnt(6)
	v_mfma_f32_16x16x32_bf16 v[56:59], v[212:215], v[192:195], v[56:59]
	s_waitcnt lgkmcnt(5)
	v_mfma_f32_16x16x32_bf16 v[52:55], v[216:219], v[192:195], v[52:55]
	s_waitcnt lgkmcnt(4)
	v_mfma_f32_16x16x32_bf16 v[48:51], v[220:223], v[192:195], v[48:51]
	global_load_dwordx4 v[108:111], v[64:65], off offset:384
	s_waitcnt vmcnt(8)
	ds_write_b128 v156, v[80:83] offset:16384
	v_mfma_f32_16x16x32_bf16 v[44:47], v[208:211], v[196:199], v[44:47]
	v_mfma_f32_16x16x32_bf16 v[40:43], v[212:215], v[196:199], v[40:43]
	v_mfma_f32_16x16x32_bf16 v[36:39], v[216:219], v[196:199], v[36:39]
	v_mfma_f32_16x16x32_bf16 v[32:35], v[220:223], v[196:199], v[32:35]
	global_load_dwordx4 v[116:119], v[66:67], off offset:384
	v_add_co_u32_e32 v66, vcc, s33, v64
	s_waitcnt vmcnt(8)
	ds_write_b128 v156, v[84:87] offset:20480
	v_addc_co_u32_e32 v67, vcc, 0, v65, vcc
	v_add_co_u32_e32 v64, vcc, s59, v64
	v_mfma_f32_16x16x32_bf16 v[28:31], v[208:211], v[200:203], v[28:31]
	s_nop 0
	v_addc_co_u32_e32 v65, vcc, 0, v65, vcc
	v_mfma_f32_16x16x32_bf16 v[24:27], v[212:215], v[200:203], v[24:27]
	v_mfma_f32_16x16x32_bf16 v[20:23], v[216:219], v[200:203], v[20:23]
	v_mfma_f32_16x16x32_bf16 v[16:19], v[220:223], v[200:203], v[16:19]
	global_load_dwordx4 v[120:123], v[66:67], off offset:384
	s_waitcnt vmcnt(8)
	ds_write_b128 v156, v[88:91] offset:24576
	v_mfma_f32_16x16x32_bf16 v[12:15], v[208:211], v[204:207], v[12:15]
	v_mfma_f32_16x16x32_bf16 v[8:11], v[212:215], v[204:207], v[8:11]
	v_mfma_f32_16x16x32_bf16 v[4:7], v[216:219], v[204:207], v[4:7]
	v_mfma_f32_16x16x32_bf16 v[0:3], v[220:223], v[204:207], v[0:3]
	global_load_dwordx4 v[124:127], v[64:65], off offset:384
	s_waitcnt vmcnt(8)
	ds_write_b128 v156, v[92:95] offset:28672
	s_cmp_lt_u32 s3, 12
	s_mov_b32 s24, s3
	s_waitcnt lgkmcnt(0)
	s_barrier
	s_cbranch_scc1 .LBB0_84
.Ltail84:
	s_add_i32 s3, s24, 2
	v_add_u32_e32 v181, v144, v145
	ds_read_b128 v[80:83], v181 offset:16384
	ds_read_b128 v[84:87], v181 offset:18432
	ds_read_b128 v[88:91], v181 offset:20480
	ds_read_b128 v[92:95], v181 offset:22528
	v_add_u32_e32 v180, v143, v145
	ds_read_b128 v[64:67], v180
	s_add_i32 s24, s24, 4
	ds_read_b128 v[68:71], v180 offset:2048
	s_min_u32 s24, s24, 15
	s_lshl_b32 s92, s24, 7
	ds_read_b128 v[72:75], v180 offset:4096
	ds_read_b128 v[76:79], v180 offset:6144
	v_add_u32_e32 v182, v143, v146
	v_add_u32_e32 v186, v144, v146
	v_lshl_add_u64 v[224:225], v[138:139], 0, s[92:93]
	ds_read_b128 v[192:195], v182
	ds_read_b128 v[196:199], v182 offset:2048
	ds_read_b128 v[200:203], v182 offset:4096
	ds_read_b128 v[204:207], v182 offset:6144
	ds_read_b128 v[208:211], v186 offset:16384
	ds_read_b128 v[212:215], v186 offset:18432
	ds_read_b128 v[216:219], v186 offset:20480
	ds_read_b128 v[220:223], v186 offset:22528
	s_waitcnt lgkmcnt(11)
	v_mfma_f32_16x16x32_bf16 v[60:63], v[80:83], v[64:67], v[60:63]
	v_mfma_f32_16x16x32_bf16 v[56:59], v[84:87], v[64:67], v[56:59]
	v_mfma_f32_16x16x32_bf16 v[52:55], v[88:91], v[64:67], v[52:55]
	v_mfma_f32_16x16x32_bf16 v[48:51], v[92:95], v[64:67], v[48:51]
	s_waitcnt vmcnt(7)
	ds_write_b128 v156, v[96:99] offset:32768
	v_add_co_u32_e32 v96, vcc, s11, v224
	s_waitcnt lgkmcnt(11)
	v_mfma_f32_16x16x32_bf16 v[44:47], v[80:83], v[68:71], v[44:47]
	v_addc_co_u32_e32 v97, vcc, 0, v225, vcc
	v_mfma_f32_16x16x32_bf16 v[40:43], v[84:87], v[68:71], v[40:43]
	v_mfma_f32_16x16x32_bf16 v[36:39], v[88:91], v[68:71], v[36:39]
	v_mfma_f32_16x16x32_bf16 v[32:35], v[92:95], v[68:71], v[32:35]
	v_add_co_u32_e32 v96, vcc, s33, v224
	s_waitcnt vmcnt(6)
	ds_write_b128 v156, v[100:103] offset:36864
	s_nop 0
	v_addc_co_u32_e32 v97, vcc, 0, v225, vcc
	s_waitcnt lgkmcnt(11)
	v_mfma_f32_16x16x32_bf16 v[28:31], v[80:83], v[72:75], v[28:31]
	v_mfma_f32_16x16x32_bf16 v[24:27], v[84:87], v[72:75], v[24:27]
	v_mfma_f32_16x16x32_bf16 v[20:23], v[88:91], v[72:75], v[20:23]
	v_mfma_f32_16x16x32_bf16 v[16:19], v[92:95], v[72:75], v[16:19]
	s_waitcnt vmcnt(5)
	ds_write_b128 v156, v[104:107] offset:40960
	s_waitcnt lgkmcnt(11)
	v_mfma_f32_16x16x32_bf16 v[12:15], v[80:83], v[76:79], v[12:15]
	v_add_co_u32_e32 v80, vcc, s59, v224
	v_mfma_f32_16x16x32_bf16 v[0:3], v[92:95], v[76:79], v[0:3]
	s_nop 0
	v_addc_co_u32_e32 v81, vcc, 0, v225, vcc
	v_lshl_add_u64 v[92:93], v[140:141], 0, s[92:93]
	v_mfma_f32_16x16x32_bf16 v[8:11], v[84:87], v[76:79], v[8:11]
	v_add_co_u32_e32 v84, vcc, s11, v92
	s_nop 1
	v_addc_co_u32_e32 v85, vcc, 0, v93, vcc
	v_mfma_f32_16x16x32_bf16 v[4:7], v[88:91], v[76:79], v[4:7]
	v_add_co_u32_e32 v88, vcc, s33, v92
	s_nop 0
	v_addc_co_u32_e32 v89, vcc, 0, v93, vcc
	s_waitcnt vmcnt(4)
	ds_write_b128 v156, v[112:115] offset:45056
	s_waitcnt lgkmcnt(7)
	v_mfma_f32_16x16x32_bf16 v[60:63], v[208:211], v[192:195], v[60:63]
	s_waitcnt lgkmcnt(6)
	v_mfma_f32_16x16x32_bf16 v[56:59], v[212:215], v[192:195], v[56:59]
	s_waitcnt lgkmcnt(5)
	v_mfma_f32_16x16x32_bf16 v[52:55], v[216:219], v[192:195], v[52:55]
	s_waitcnt lgkmcnt(4)
	v_mfma_f32_16x16x32_bf16 v[48:51], v[220:223], v[192:195], v[48:51]
	v_add_co_u32_e32 v92, vcc, s59, v92
	s_waitcnt vmcnt(3)
	ds_write_b128 v156, v[108:111] offset:49152
	s_nop 0
	v_addc_co_u32_e32 v93, vcc, 0, v93, vcc
	v_mfma_f32_16x16x32_bf16 v[44:47], v[208:211], v[196:199], v[44:47]
	v_mfma_f32_16x16x32_bf16 v[40:43], v[212:215], v[196:199], v[40:43]
	v_mfma_f32_16x16x32_bf16 v[36:39], v[216:219], v[196:199], v[36:39]
	v_mfma_f32_16x16x32_bf16 v[32:35], v[220:223], v[196:199], v[32:35]
	s_waitcnt vmcnt(2)
	ds_write_b128 v156, v[116:119] offset:53248
	v_mfma_f32_16x16x32_bf16 v[28:31], v[208:211], v[200:203], v[28:31]
	v_mfma_f32_16x16x32_bf16 v[24:27], v[212:215], v[200:203], v[24:27]
	v_mfma_f32_16x16x32_bf16 v[20:23], v[216:219], v[200:203], v[20:23]
	v_mfma_f32_16x16x32_bf16 v[16:19], v[220:223], v[200:203], v[16:19]
	s_waitcnt vmcnt(1)
	ds_write_b128 v156, v[120:123] offset:57344
	v_mfma_f32_16x16x32_bf16 v[12:15], v[208:211], v[204:207], v[12:15]
	v_mfma_f32_16x16x32_bf16 v[8:11], v[212:215], v[204:207], v[8:11]
	v_mfma_f32_16x16x32_bf16 v[4:7], v[216:219], v[204:207], v[4:7]
	v_mfma_f32_16x16x32_bf16 v[0:3], v[220:223], v[204:207], v[0:3]
	s_waitcnt vmcnt(0)
	ds_write_b128 v156, v[124:127] offset:61440
	s_waitcnt lgkmcnt(0)
	s_barrier
	ds_read_b128 v[112:115], v181 offset:49152
	ds_read_b128 v[116:119], v181 offset:51200
	ds_read_b128 v[120:123], v181 offset:53248
	ds_read_b128 v[124:127], v181 offset:55296
	ds_read_b128 v[96:99], v180 offset:32768
	ds_read_b128 v[100:103], v180 offset:34816
	s_min_u32 s24, s3, 12
	s_lshl_b32 s92, s24, 7
	ds_read_b128 v[104:107], v180 offset:36864
	v_lshl_add_u64 v[224:225], v[138:139], 0, s[92:93]
	ds_read_b128 v[108:111], v180 offset:38912
	ds_read_b128 v[192:195], v182 offset:32768
	ds_read_b128 v[196:199], v182 offset:34816
	ds_read_b128 v[200:203], v182 offset:36864
	ds_read_b128 v[204:207], v182 offset:38912
	ds_read_b128 v[208:211], v186 offset:49152
	ds_read_b128 v[212:215], v186 offset:51200
	ds_read_b128 v[216:219], v186 offset:53248
	ds_read_b128 v[220:223], v186 offset:55296
	s_waitcnt lgkmcnt(11)
	v_mfma_f32_16x16x32_bf16 v[60:63], v[112:115], v[96:99], v[60:63]
	v_mfma_f32_16x16x32_bf16 v[56:59], v[116:119], v[96:99], v[56:59]
	v_mfma_f32_16x16x32_bf16 v[52:55], v[120:123], v[96:99], v[52:55]
	v_mfma_f32_16x16x32_bf16 v[48:51], v[124:127], v[96:99], v[48:51]
	v_add_co_u32_e32 v64, vcc, s11, v224
	s_waitcnt lgkmcnt(10)
	v_mfma_f32_16x16x32_bf16 v[44:47], v[112:115], v[100:103], v[44:47]
	v_addc_co_u32_e32 v65, vcc, 0, v225, vcc
	v_mfma_f32_16x16x32_bf16 v[40:43], v[116:119], v[100:103], v[40:43]
	v_mfma_f32_16x16x32_bf16 v[36:39], v[120:123], v[100:103], v[36:39]
	v_mfma_f32_16x16x32_bf16 v[32:35], v[124:127], v[100:103], v[32:35]
	v_add_co_u32_e32 v64, vcc, s33, v224
	v_addc_co_u32_e32 v65, vcc, 0, v225, vcc
	s_waitcnt lgkmcnt(9)
	v_mfma_f32_16x16x32_bf16 v[28:31], v[112:115], v[104:107], v[28:31]
	v_mfma_f32_16x16x32_bf16 v[24:27], v[116:119], v[104:107], v[24:27]
	v_mfma_f32_16x16x32_bf16 v[20:23], v[120:123], v[104:107], v[20:23]
	v_mfma_f32_16x16x32_bf16 v[16:19], v[124:127], v[104:107], v[16:19]
	v_add_co_u32_e32 v64, vcc, s59, v224
	v_addc_co_u32_e32 v65, vcc, 0, v225, vcc
	s_waitcnt lgkmcnt(8)
	v_mfma_f32_16x16x32_bf16 v[12:15], v[112:115], v[108:111], v[12:15]
	v_mfma_f32_16x16x32_bf16 v[8:11], v[116:119], v[108:111], v[8:11]
	v_mfma_f32_16x16x32_bf16 v[4:7], v[120:123], v[108:111], v[4:7]
	v_mfma_f32_16x16x32_bf16 v[0:3], v[124:127], v[108:111], v[0:3]
	v_lshl_add_u64 v[64:65], v[140:141], 0, s[92:93]
	v_add_co_u32_e32 v66, vcc, s11, v64
	v_addc_co_u32_e32 v67, vcc, 0, v65, vcc
	s_waitcnt lgkmcnt(3)
	v_mfma_f32_16x16x32_bf16 v[60:63], v[208:211], v[192:195], v[60:63]
	s_waitcnt lgkmcnt(2)
	v_mfma_f32_16x16x32_bf16 v[56:59], v[212:215], v[192:195], v[56:59]
	s_waitcnt lgkmcnt(1)
	v_mfma_f32_16x16x32_bf16 v[52:55], v[216:219], v[192:195], v[52:55]
	s_waitcnt lgkmcnt(0)
	v_mfma_f32_16x16x32_bf16 v[48:51], v[220:223], v[192:195], v[48:51]
	v_mfma_f32_16x16x32_bf16 v[44:47], v[208:211], v[196:199], v[44:47]
	v_mfma_f32_16x16x32_bf16 v[40:43], v[212:215], v[196:199], v[40:43]
	v_mfma_f32_16x16x32_bf16 v[36:39], v[216:219], v[196:199], v[36:39]
	v_mfma_f32_16x16x32_bf16 v[32:35], v[220:223], v[196:199], v[32:35]
	v_add_co_u32_e32 v66, vcc, s33, v64
	v_addc_co_u32_e32 v67, vcc, 0, v65, vcc
	v_add_co_u32_e32 v64, vcc, s59, v64
	v_mfma_f32_16x16x32_bf16 v[28:31], v[208:211], v[200:203], v[28:31]
	s_nop 0
	v_addc_co_u32_e32 v65, vcc, 0, v65, vcc
	v_mfma_f32_16x16x32_bf16 v[24:27], v[212:215], v[200:203], v[24:27]
	v_mfma_f32_16x16x32_bf16 v[20:23], v[216:219], v[200:203], v[20:23]
	v_mfma_f32_16x16x32_bf16 v[16:19], v[220:223], v[200:203], v[16:19]
	v_mfma_f32_16x16x32_bf16 v[12:15], v[208:211], v[204:207], v[12:15]
	v_mfma_f32_16x16x32_bf16 v[8:11], v[212:215], v[204:207], v[8:11]
	v_mfma_f32_16x16x32_bf16 v[4:7], v[216:219], v[204:207], v[4:7]
	v_mfma_f32_16x16x32_bf16 v[0:3], v[220:223], v[204:207], v[0:3]
	s_mov_b32 s24, s3
	s_waitcnt lgkmcnt(0)
	s_barrier
	s_and_saveexec_b64 s[24:25], s[36:37]
	s_cbranch_execz .LBB0_82
	v_add_f32_e32 v64, 0, v128
	v_add_f32_e32 v64, v64, v157
	v_add_f32_e32 v64, v64, v158
	v_add_f32_e32 v64, v64, v159
	v_add_f32_e32 v64, v64, v160
	v_add_f32_e32 v64, v64, v161
	v_add_f32_e32 v64, v64, v162
	v_add_f32_e32 v64, v64, v163
	v_add_f32_e32 v64, v64, v164
	v_add_f32_e32 v64, v64, v165
	v_add_f32_e32 v64, v64, v168
	v_add_f32_e32 v64, v64, v175
	v_add_f32_e32 v64, v64, v179
	v_add_f32_e32 v64, v64, v183
	v_add_f32_e32 v64, v64, v190
	v_add_f32_e32 v64, v64, v191
	v_fmamk_f32 v64, v64, 0x3a800000, v167
	s_mov_b32 s3, 0x800000
	v_mul_f32_e32 v65, 0x4b800000, v64
	v_cmp_gt_f32_e32 vcc, s3, v64
	s_nop 1
	v_cndmask_b32_e32 v64, v64, v65, vcc
	v_rsq_f32_e32 v64, v64
	s_nop 0
	v_mul_f32_e32 v65, 0x45800000, v64
	v_cndmask_b32_e32 v64, v64, v65, vcc
	ds_write_b32 v155, v64
	s_branch .LBB0_82

.LBB0_92:
	s_add_i32 s0, s1, 2
	v_add_u32_e32 v111, v104, v105
	ds_read_b128 v[136:139], v111 offset:16384
	ds_read_b128 v[140:143], v111 offset:18432
	ds_read_b128 v[144:147], v111 offset:20480
	ds_read_b128 v[148:151], v111 offset:22528
	v_add_u32_e32 v110, v103, v105
	ds_read_b128 v[116:119], v110
	s_add_i32 s1, s1, 4
	ds_read_b128 v[120:123], v110 offset:2048
	s_min_u32 s1, s1, 15
	v_add_u32_e32 v113, v104, v114
	s_lshl_b32 s92, s1, 7
	ds_read_b128 v[124:127], v110 offset:4096
	v_add_u32_e32 v112, v103, v114
	ds_read_b128 v[194:197], v113 offset:16384
	ds_read_b128 v[198:201], v113 offset:18432
	ds_read_b128 v[202:205], v113 offset:20480
	ds_read_b128 v[206:209], v113 offset:22528
	v_lshl_add_u64 v[164:165], v[98:99], 0, s[92:93]
	ds_read_b128 v[132:135], v110 offset:6144
	ds_read_b128 v[152:155], v112
	ds_read_b128 v[156:159], v112 offset:2048
	ds_read_b128 v[160:163], v112 offset:4096
	ds_read_b128 v[190:193], v112 offset:6144
	s_waitcnt lgkmcnt(11)
	v_mfma_f32_16x16x32_bf16 v[92:95], v[136:139], v[116:119], v[92:95]
	v_mfma_f32_16x16x32_bf16 v[88:91], v[140:143], v[116:119], v[88:91]
	v_mfma_f32_16x16x32_bf16 v[52:55], v[144:147], v[116:119], v[52:55]
	v_mfma_f32_16x16x32_bf16 v[48:51], v[148:151], v[116:119], v[48:51]
	global_load_dwordx4 v[116:119], v[164:165], off
	s_waitcnt vmcnt(6)
	ds_write_b128 v109, v[56:59] offset:32768
	v_add_co_u32_e32 v56, vcc, s11, v164
	s_waitcnt lgkmcnt(11)
	v_mfma_f32_16x16x32_bf16 v[44:47], v[136:139], v[120:123], v[44:47]
	v_addc_co_u32_e32 v57, vcc, 0, v165, vcc
	v_mfma_f32_16x16x32_bf16 v[40:43], v[140:143], v[120:123], v[40:43]
	v_mfma_f32_16x16x32_bf16 v[36:39], v[144:147], v[120:123], v[36:39]
	v_mfma_f32_16x16x32_bf16 v[32:35], v[148:151], v[120:123], v[32:35]
	global_load_dwordx4 v[120:123], v[56:57], off
	v_add_co_u32_e32 v56, vcc, s33, v164
	ds_write_b128 v109, v[60:63] offset:36864
	s_nop 0
	v_addc_co_u32_e32 v57, vcc, 0, v165, vcc
	s_waitcnt lgkmcnt(11)
	v_mfma_f32_16x16x32_bf16 v[28:31], v[136:139], v[124:127], v[28:31]
	v_mfma_f32_16x16x32_bf16 v[24:27], v[140:143], v[124:127], v[24:27]
	v_mfma_f32_16x16x32_bf16 v[20:23], v[144:147], v[124:127], v[20:23]
	v_mfma_f32_16x16x32_bf16 v[16:19], v[148:151], v[124:127], v[16:19]
	global_load_dwordx4 v[124:127], v[56:57], off
	v_add_co_u32_e32 v56, vcc, s59, v164
	ds_write_b128 v109, v[64:67] offset:40960
	s_nop 0
	v_addc_co_u32_e32 v57, vcc, 0, v165, vcc
	v_lshl_add_u64 v[64:65], v[100:101], 0, s[92:93]
	v_add_co_u32_e32 v66, vcc, s11, v64
	s_waitcnt lgkmcnt(7)
	v_mfma_f32_16x16x32_bf16 v[12:15], v[136:139], v[132:135], v[12:15]
	v_addc_co_u32_e32 v67, vcc, 0, v65, vcc
	v_mfma_f32_16x16x32_bf16 v[8:11], v[140:143], v[132:135], v[8:11]
	v_mfma_f32_16x16x32_bf16 v[4:7], v[144:147], v[132:135], v[4:7]
	v_mfma_f32_16x16x32_bf16 v[0:3], v[148:151], v[132:135], v[0:3]
	global_load_dwordx4 v[132:135], v[56:57], off
	s_waitcnt vmcnt(7)
	ds_write_b128 v109, v[72:75] offset:45056
	s_waitcnt lgkmcnt(7)
	v_mfma_f32_16x16x32_bf16 v[56:59], v[194:197], v[152:155], v[92:95]
	v_mfma_f32_16x16x32_bf16 v[60:63], v[198:201], v[152:155], v[88:91]
	v_mfma_f32_16x16x32_bf16 v[52:55], v[202:205], v[152:155], v[52:55]
	v_mfma_f32_16x16x32_bf16 v[48:51], v[206:209], v[152:155], v[48:51]
	global_load_dwordx4 v[136:139], v[64:65], off
	ds_write_b128 v109, v[68:71] offset:49152
	s_waitcnt lgkmcnt(7)
	v_mfma_f32_16x16x32_bf16 v[44:47], v[194:197], v[156:159], v[44:47]
	v_mfma_f32_16x16x32_bf16 v[40:43], v[198:201], v[156:159], v[40:43]
	v_mfma_f32_16x16x32_bf16 v[36:39], v[202:205], v[156:159], v[36:39]
	v_mfma_f32_16x16x32_bf16 v[32:35], v[206:209], v[156:159], v[32:35]
	global_load_dwordx4 v[140:143], v[66:67], off
	v_add_co_u32_e32 v66, vcc, s33, v64
	s_waitcnt vmcnt(8)
	ds_write_b128 v109, v[76:79] offset:53248
	v_addc_co_u32_e32 v67, vcc, 0, v65, vcc
	v_add_co_u32_e32 v64, vcc, s59, v64
	s_waitcnt lgkmcnt(7)
	v_mfma_f32_16x16x32_bf16 v[28:31], v[194:197], v[160:163], v[28:31]
	v_addc_co_u32_e32 v65, vcc, 0, v65, vcc
	v_mfma_f32_16x16x32_bf16 v[24:27], v[198:201], v[160:163], v[24:27]
	v_mfma_f32_16x16x32_bf16 v[20:23], v[202:205], v[160:163], v[20:23]
	v_mfma_f32_16x16x32_bf16 v[16:19], v[206:209], v[160:163], v[16:19]
	global_load_dwordx4 v[144:147], v[66:67], off
	s_waitcnt vmcnt(8)
	ds_write_b128 v109, v[80:83] offset:57344
	s_waitcnt lgkmcnt(7)
	v_mfma_f32_16x16x32_bf16 v[12:15], v[194:197], v[190:193], v[12:15]
	v_mfma_f32_16x16x32_bf16 v[8:11], v[198:201], v[190:193], v[8:11]
	v_mfma_f32_16x16x32_bf16 v[4:7], v[202:205], v[190:193], v[4:7]
	v_mfma_f32_16x16x32_bf16 v[0:3], v[206:209], v[190:193], v[0:3]
	global_load_dwordx4 v[148:151], v[64:65], off
	s_waitcnt vmcnt(8)
	ds_write_b128 v109, v[84:87] offset:61440
	s_waitcnt lgkmcnt(0)
	s_barrier
	ds_read_b128 v[84:87], v111 offset:51200
	ds_read_b128 v[80:83], v111 offset:49152
	ds_read_b128 v[88:91], v111 offset:53248
	ds_read_b128 v[92:95], v111 offset:55296
	ds_read_b128 v[64:67], v110 offset:32768
	s_min_u32 s1, s0, 12
	s_lshl_b32 s92, s1, 7
	ds_read_b128 v[68:71], v110 offset:34816
	v_lshl_add_u64 v[164:165], v[98:99], 0, s[92:93]
	ds_read_b128 v[72:75], v110 offset:36864
	ds_read_b128 v[76:79], v110 offset:38912
	ds_read_b128 v[152:155], v112 offset:32768
	ds_read_b128 v[156:159], v112 offset:34816
	ds_read_b128 v[160:163], v112 offset:36864
	ds_read_b128 v[190:193], v112 offset:38912
	ds_read_b128 v[194:197], v113 offset:49152
	ds_read_b128 v[198:201], v113 offset:51200
	ds_read_b128 v[202:205], v113 offset:53248
	ds_read_b128 v[206:209], v113 offset:55296
	s_waitcnt lgkmcnt(11)
	v_mfma_f32_16x16x32_bf16 v[214:217], v[84:87], v[64:67], v[60:63]
	v_mfma_f32_16x16x32_bf16 v[210:213], v[80:83], v[64:67], v[56:59]
	s_nop 1
	v_add_co_u32_e32 v60, vcc, s11, v164
	s_nop 1
	v_addc_co_u32_e32 v61, vcc, 0, v165, vcc
	v_mfma_f32_16x16x32_bf16 v[52:55], v[88:91], v[64:67], v[52:55]
	v_mfma_f32_16x16x32_bf16 v[48:51], v[92:95], v[64:67], v[48:51]
	v_add_co_u32_e32 v64, vcc, s33, v164
	global_load_dwordx4 v[56:59], v[164:165], off offset:384
	s_nop 0
	v_addc_co_u32_e32 v65, vcc, 0, v165, vcc
	s_waitcnt vmcnt(8)
	ds_write_b128 v109, v[116:119]
	s_waitcnt lgkmcnt(11)
	v_mfma_f32_16x16x32_bf16 v[44:47], v[80:83], v[68:71], v[44:47]
	v_mfma_f32_16x16x32_bf16 v[40:43], v[84:87], v[68:71], v[40:43]
	v_mfma_f32_16x16x32_bf16 v[36:39], v[88:91], v[68:71], v[36:39]
	v_mfma_f32_16x16x32_bf16 v[32:35], v[92:95], v[68:71], v[32:35]
	v_add_co_u32_e32 v68, vcc, s59, v164
	global_load_dwordx4 v[60:63], v[60:61], off offset:384
	s_waitcnt vmcnt(8)
	ds_write_b128 v109, v[120:123] offset:4096
	s_waitcnt lgkmcnt(11)
	v_mfma_f32_16x16x32_bf16 v[28:31], v[80:83], v[72:75], v[28:31]
	v_addc_co_u32_e32 v69, vcc, 0, v165, vcc
	v_mfma_f32_16x16x32_bf16 v[24:27], v[84:87], v[72:75], v[24:27]
	v_mfma_f32_16x16x32_bf16 v[20:23], v[88:91], v[72:75], v[20:23]
	v_mfma_f32_16x16x32_bf16 v[16:19], v[92:95], v[72:75], v[16:19]
	global_load_dwordx4 v[64:67], v[64:65], off offset:384
	s_waitcnt vmcnt(8)
	ds_write_b128 v109, v[124:127] offset:8192
	s_waitcnt lgkmcnt(11)
	v_mfma_f32_16x16x32_bf16 v[8:11], v[84:87], v[76:79], v[8:11]
	v_lshl_add_u64 v[84:85], v[100:101], 0, s[92:93]
	v_mfma_f32_16x16x32_bf16 v[12:15], v[80:83], v[76:79], v[12:15]
	v_mfma_f32_16x16x32_bf16 v[4:7], v[88:91], v[76:79], v[4:7]
	v_mfma_f32_16x16x32_bf16 v[0:3], v[92:95], v[76:79], v[0:3]
	v_add_co_u32_e32 v76, vcc, s11, v84
	global_load_dwordx4 v[72:75], v[68:69], off offset:384
	s_nop 0
	v_addc_co_u32_e32 v77, vcc, 0, v85, vcc
	v_add_co_u32_e32 v80, vcc, s33, v84
	s_waitcnt vmcnt(8)
	ds_write_b128 v109, v[132:135] offset:12288
	v_addc_co_u32_e32 v81, vcc, 0, v85, vcc
	s_waitcnt lgkmcnt(7)
	v_mfma_f32_16x16x32_bf16 v[92:95], v[194:197], v[152:155], v[210:213]
	s_waitcnt lgkmcnt(6)
	v_mfma_f32_16x16x32_bf16 v[88:91], v[198:201], v[152:155], v[214:217]
	s_waitcnt lgkmcnt(5)
	v_mfma_f32_16x16x32_bf16 v[52:55], v[202:205], v[152:155], v[52:55]
	s_waitcnt lgkmcnt(4)
	v_mfma_f32_16x16x32_bf16 v[48:51], v[206:209], v[152:155], v[48:51]
	global_load_dwordx4 v[68:71], v[84:85], off offset:384
	v_add_co_u32_e32 v84, vcc, s59, v84
	s_waitcnt vmcnt(8)
	ds_write_b128 v109, v[136:139] offset:16384
	v_addc_co_u32_e32 v85, vcc, 0, v85, vcc
	v_mfma_f32_16x16x32_bf16 v[44:47], v[194:197], v[156:159], v[44:47]
	v_mfma_f32_16x16x32_bf16 v[40:43], v[198:201], v[156:159], v[40:43]
	v_mfma_f32_16x16x32_bf16 v[36:39], v[202:205], v[156:159], v[36:39]
	v_mfma_f32_16x16x32_bf16 v[32:35], v[206:209], v[156:159], v[32:35]
	global_load_dwordx4 v[76:79], v[76:77], off offset:384
	s_waitcnt vmcnt(8)
	ds_write_b128 v109, v[140:143] offset:20480
	v_mfma_f32_16x16x32_bf16 v[28:31], v[194:197], v[160:163], v[28:31]
	v_mfma_f32_16x16x32_bf16 v[24:27], v[198:201], v[160:163], v[24:27]
	v_mfma_f32_16x16x32_bf16 v[20:23], v[202:205], v[160:163], v[20:23]
	v_mfma_f32_16x16x32_bf16 v[16:19], v[206:209], v[160:163], v[16:19]
	global_load_dwordx4 v[80:83], v[80:81], off offset:384
	s_waitcnt vmcnt(8)
	ds_write_b128 v109, v[144:147] offset:24576
	v_mfma_f32_16x16x32_bf16 v[12:15], v[194:197], v[190:193], v[12:15]
	v_mfma_f32_16x16x32_bf16 v[8:11], v[198:201], v[190:193], v[8:11]
	v_mfma_f32_16x16x32_bf16 v[4:7], v[202:205], v[190:193], v[4:7]
	v_mfma_f32_16x16x32_bf16 v[0:3], v[206:209], v[190:193], v[0:3]
	global_load_dwordx4 v[84:87], v[84:85], off offset:384
	s_waitcnt vmcnt(8)
	ds_write_b128 v109, v[148:151] offset:28672
	s_cmp_lt_u32 s0, 12
	s_mov_b32 s1, s0
	s_waitcnt lgkmcnt(0)
	s_barrier
	s_cbranch_scc1 .LBB0_92
.Ltail92:
	s_add_i32 s0, s1, 2
	v_add_u32_e32 v111, v104, v105
	ds_read_b128 v[136:139], v111 offset:16384
	ds_read_b128 v[140:143], v111 offset:18432
	ds_read_b128 v[144:147], v111 offset:20480
	ds_read_b128 v[148:151], v111 offset:22528
	v_add_u32_e32 v110, v103, v105
	ds_read_b128 v[116:119], v110
	s_add_i32 s1, s1, 4
	ds_read_b128 v[120:123], v110 offset:2048
	s_min_u32 s1, s1, 15
	v_add_u32_e32 v113, v104, v114
	s_lshl_b32 s92, s1, 7
	ds_read_b128 v[124:127], v110 offset:4096
	v_add_u32_e32 v112, v103, v114
	ds_read_b128 v[194:197], v113 offset:16384
	ds_read_b128 v[198:201], v113 offset:18432
	ds_read_b128 v[202:205], v113 offset:20480
	ds_read_b128 v[206:209], v113 offset:22528
	v_lshl_add_u64 v[164:165], v[98:99], 0, s[92:93]
	ds_read_b128 v[132:135], v110 offset:6144
	ds_read_b128 v[152:155], v112
	ds_read_b128 v[156:159], v112 offset:2048
	ds_read_b128 v[160:163], v112 offset:4096
	ds_read_b128 v[190:193], v112 offset:6144
	s_waitcnt lgkmcnt(11)
	v_mfma_f32_16x16x32_bf16 v[92:95], v[136:139], v[116:119], v[92:95]
	v_mfma_f32_16x16x32_bf16 v[88:91], v[140:143], v[116:119], v[88:91]
	v_mfma_f32_16x16x32_bf16 v[52:55], v[144:147], v[116:119], v[52:55]
	v_mfma_f32_16x16x32_bf16 v[48:51], v[148:151], v[116:119], v[48:51]
	s_waitcnt vmcnt(7)
	ds_write_b128 v109, v[56:59] offset:32768
	v_add_co_u32_e32 v56, vcc, s11, v164
	s_waitcnt lgkmcnt(11)
	v_mfma_f32_16x16x32_bf16 v[44:47], v[136:139], v[120:123], v[44:47]
	v_addc_co_u32_e32 v57, vcc, 0, v165, vcc
	v_mfma_f32_16x16x32_bf16 v[40:43], v[140:143], v[120:123], v[40:43]
	v_mfma_f32_16x16x32_bf16 v[36:39], v[144:147], v[120:123], v[36:39]
	v_mfma_f32_16x16x32_bf16 v[32:35], v[148:151], v[120:123], v[32:35]
	v_add_co_u32_e32 v56, vcc, s33, v164
	s_waitcnt vmcnt(6)
	ds_write_b128 v109, v[60:63] offset:36864
	s_nop 0
	v_addc_co_u32_e32 v57, vcc, 0, v165, vcc
	s_waitcnt lgkmcnt(11)
	v_mfma_f32_16x16x32_bf16 v[28:31], v[136:139], v[124:127], v[28:31]
	v_mfma_f32_16x16x32_bf16 v[24:27], v[140:143], v[124:127], v[24:27]
	v_mfma_f32_16x16x32_bf16 v[20:23], v[144:147], v[124:127], v[20:23]
	v_mfma_f32_16x16x32_bf16 v[16:19], v[148:151], v[124:127], v[16:19]
	v_add_co_u32_e32 v56, vcc, s59, v164
	s_waitcnt vmcnt(5)
	ds_write_b128 v109, v[64:67] offset:40960
	s_nop 0
	v_addc_co_u32_e32 v57, vcc, 0, v165, vcc
	v_lshl_add_u64 v[64:65], v[100:101], 0, s[92:93]
	v_add_co_u32_e32 v66, vcc, s11, v64
	s_waitcnt lgkmcnt(7)
	v_mfma_f32_16x16x32_bf16 v[12:15], v[136:139], v[132:135], v[12:15]
	v_addc_co_u32_e32 v67, vcc, 0, v65, vcc
	v_mfma_f32_16x16x32_bf16 v[8:11], v[140:143], v[132:135], v[8:11]
	v_mfma_f32_16x16x32_bf16 v[4:7], v[144:147], v[132:135], v[4:7]
	v_mfma_f32_16x16x32_bf16 v[0:3], v[148:151], v[132:135], v[0:3]
	s_waitcnt vmcnt(4)
	ds_write_b128 v109, v[72:75] offset:45056
	s_waitcnt lgkmcnt(7)
	v_mfma_f32_16x16x32_bf16 v[56:59], v[194:197], v[152:155], v[92:95]
	v_mfma_f32_16x16x32_bf16 v[60:63], v[198:201], v[152:155], v[88:91]
	v_mfma_f32_16x16x32_bf16 v[52:55], v[202:205], v[152:155], v[52:55]
	v_mfma_f32_16x16x32_bf16 v[48:51], v[206:209], v[152:155], v[48:51]
	s_waitcnt vmcnt(3)
	ds_write_b128 v109, v[68:71] offset:49152
	s_waitcnt lgkmcnt(7)
	v_mfma_f32_16x16x32_bf16 v[44:47], v[194:197], v[156:159], v[44:47]
	v_mfma_f32_16x16x32_bf16 v[40:43], v[198:201], v[156:159], v[40:43]
	v_mfma_f32_16x16x32_bf16 v[36:39], v[202:205], v[156:159], v[36:39]
	v_mfma_f32_16x16x32_bf16 v[32:35], v[206:209], v[156:159], v[32:35]
	v_add_co_u32_e32 v66, vcc, s33, v64
	s_waitcnt vmcnt(2)
	ds_write_b128 v109, v[76:79] offset:53248
	v_addc_co_u32_e32 v67, vcc, 0, v65, vcc
	v_add_co_u32_e32 v64, vcc, s59, v64
	s_waitcnt lgkmcnt(7)
	v_mfma_f32_16x16x32_bf16 v[28:31], v[194:197], v[160:163], v[28:31]
	v_addc_co_u32_e32 v65, vcc, 0, v65, vcc
	v_mfma_f32_16x16x32_bf16 v[24:27], v[198:201], v[160:163], v[24:27]
	v_mfma_f32_16x16x32_bf16 v[20:23], v[202:205], v[160:163], v[20:23]
	v_mfma_f32_16x16x32_bf16 v[16:19], v[206:209], v[160:163], v[16:19]
	s_waitcnt vmcnt(1)
	ds_write_b128 v109, v[80:83] offset:57344
	s_waitcnt lgkmcnt(7)
	v_mfma_f32_16x16x32_bf16 v[12:15], v[194:197], v[190:193], v[12:15]
	v_mfma_f32_16x16x32_bf16 v[8:11], v[198:201], v[190:193], v[8:11]
	v_mfma_f32_16x16x32_bf16 v[4:7], v[202:205], v[190:193], v[4:7]
	v_mfma_f32_16x16x32_bf16 v[0:3], v[206:209], v[190:193], v[0:3]
	s_waitcnt vmcnt(0)
	ds_write_b128 v109, v[84:87] offset:61440
	s_waitcnt lgkmcnt(0)
	s_barrier
	ds_read_b128 v[84:87], v111 offset:51200
	ds_read_b128 v[80:83], v111 offset:49152
	ds_read_b128 v[88:91], v111 offset:53248
	ds_read_b128 v[92:95], v111 offset:55296
	ds_read_b128 v[64:67], v110 offset:32768
	s_min_u32 s1, s0, 12
	s_lshl_b32 s92, s1, 7
	ds_read_b128 v[68:71], v110 offset:34816
	v_lshl_add_u64 v[164:165], v[98:99], 0, s[92:93]
	ds_read_b128 v[72:75], v110 offset:36864
	ds_read_b128 v[76:79], v110 offset:38912
	ds_read_b128 v[152:155], v112 offset:32768
	ds_read_b128 v[156:159], v112 offset:34816
	ds_read_b128 v[160:163], v112 offset:36864
	ds_read_b128 v[190:193], v112 offset:38912
	ds_read_b128 v[194:197], v113 offset:49152
	ds_read_b128 v[198:201], v113 offset:51200
	ds_read_b128 v[202:205], v113 offset:53248
	ds_read_b128 v[206:209], v113 offset:55296
	s_waitcnt lgkmcnt(11)
	v_mfma_f32_16x16x32_bf16 v[214:217], v[84:87], v[64:67], v[60:63]
	v_mfma_f32_16x16x32_bf16 v[210:213], v[80:83], v[64:67], v[56:59]
	s_nop 1
	v_add_co_u32_e32 v60, vcc, s11, v164
	s_nop 1
	v_addc_co_u32_e32 v61, vcc, 0, v165, vcc
	v_mfma_f32_16x16x32_bf16 v[52:55], v[88:91], v[64:67], v[52:55]
	v_mfma_f32_16x16x32_bf16 v[48:51], v[92:95], v[64:67], v[48:51]
	v_add_co_u32_e32 v64, vcc, s33, v164
	s_nop 0
	v_addc_co_u32_e32 v65, vcc, 0, v165, vcc
	s_waitcnt lgkmcnt(10)
	v_mfma_f32_16x16x32_bf16 v[44:47], v[80:83], v[68:71], v[44:47]
	v_mfma_f32_16x16x32_bf16 v[40:43], v[84:87], v[68:71], v[40:43]
	v_mfma_f32_16x16x32_bf16 v[36:39], v[88:91], v[68:71], v[36:39]
	v_mfma_f32_16x16x32_bf16 v[32:35], v[92:95], v[68:71], v[32:35]
	v_add_co_u32_e32 v68, vcc, s59, v164
	s_waitcnt lgkmcnt(9)
	v_mfma_f32_16x16x32_bf16 v[28:31], v[80:83], v[72:75], v[28:31]
	v_addc_co_u32_e32 v69, vcc, 0, v165, vcc
	v_mfma_f32_16x16x32_bf16 v[24:27], v[84:87], v[72:75], v[24:27]
	v_mfma_f32_16x16x32_bf16 v[20:23], v[88:91], v[72:75], v[20:23]
	v_mfma_f32_16x16x32_bf16 v[16:19], v[92:95], v[72:75], v[16:19]
	s_waitcnt lgkmcnt(8)
	v_mfma_f32_16x16x32_bf16 v[8:11], v[84:87], v[76:79], v[8:11]
	v_lshl_add_u64 v[84:85], v[100:101], 0, s[92:93]
	v_mfma_f32_16x16x32_bf16 v[12:15], v[80:83], v[76:79], v[12:15]
	v_mfma_f32_16x16x32_bf16 v[4:7], v[88:91], v[76:79], v[4:7]
	v_mfma_f32_16x16x32_bf16 v[0:3], v[92:95], v[76:79], v[0:3]
	v_add_co_u32_e32 v76, vcc, s11, v84
	s_nop 0
	v_addc_co_u32_e32 v77, vcc, 0, v85, vcc
	v_add_co_u32_e32 v80, vcc, s33, v84
	v_addc_co_u32_e32 v81, vcc, 0, v85, vcc
	s_waitcnt lgkmcnt(3)
	v_mfma_f32_16x16x32_bf16 v[92:95], v[194:197], v[152:155], v[210:213]
	s_waitcnt lgkmcnt(2)
	v_mfma_f32_16x16x32_bf16 v[88:91], v[198:201], v[152:155], v[214:217]
	s_waitcnt lgkmcnt(1)
	v_mfma_f32_16x16x32_bf16 v[52:55], v[202:205], v[152:155], v[52:55]
	s_waitcnt lgkmcnt(0)
	v_mfma_f32_16x16x32_bf16 v[48:51], v[206:209], v[152:155], v[48:51]
	v_add_co_u32_e32 v84, vcc, s59, v84
	v_addc_co_u32_e32 v85, vcc, 0, v85, vcc
	v_mfma_f32_16x16x32_bf16 v[44:47], v[194:197], v[156:159], v[44:47]
	v_mfma_f32_16x16x32_bf16 v[40:43], v[198:201], v[156:159], v[40:43]
	v_mfma_f32_16x16x32_bf16 v[36:39], v[202:205], v[156:159], v[36:39]
	v_mfma_f32_16x16x32_bf16 v[32:35], v[206:209], v[156:159], v[32:35]
	v_mfma_f32_16x16x32_bf16 v[28:31], v[194:197], v[160:163], v[28:31]
	v_mfma_f32_16x16x32_bf16 v[24:27], v[198:201], v[160:163], v[24:27]
	v_mfma_f32_16x16x32_bf16 v[20:23], v[202:205], v[160:163], v[20:23]
	v_mfma_f32_16x16x32_bf16 v[16:19], v[206:209], v[160:163], v[16:19]
	v_mfma_f32_16x16x32_bf16 v[12:15], v[194:197], v[190:193], v[12:15]
	v_mfma_f32_16x16x32_bf16 v[8:11], v[198:201], v[190:193], v[8:11]
	v_mfma_f32_16x16x32_bf16 v[4:7], v[202:205], v[190:193], v[4:7]
	v_mfma_f32_16x16x32_bf16 v[0:3], v[206:209], v[190:193], v[0:3]
	s_mov_b32 s1, s0
	s_waitcnt lgkmcnt(0)
	s_barrier
	s_mul_i32 s0, s69, 0x12000
	v_readlane_b32 s16, v250, 25
	s_add_u32 s24, s16, s0
	v_readlane_b32 s0, v251, 5
	v_lshlrev_b32_e32 v114, 6, v102
	v_readlane_b32 s17, v250, 26
	s_waitcnt vmcnt(5)
	v_add_u32_e32 v64, s0, v108
	v_readlane_b32 s0, v251, 6
	v_add_u32_e32 v56, 0xffffe000, v64
	v_or_b32_e32 v62, v64, v107
	v_or_b32_e32 v65, s0, v114
	v_lshrrev_b32_e32 v56, 10, v56
	s_movk_i32 s0, 0x1800
	v_mad_u32_u24 v56, v56, s0, s0
	v_cmp_lt_i32_e32 vcc, s13, v62
	s_addc_u32 s25, s17, 0
	v_lshlrev_b32_e32 v115, 2, v97
	v_cndmask_b32_e32 v56, 0, v56, vcc
	s_add_u32 s40, s24, 0x2000
	v_or_b32_e32 v58, v65, v115
	v_ashrrev_i32_e32 v57, 31, v56
	s_addc_u32 s41, s25, 0
	s_waitcnt vmcnt(4)
	v_lshlrev_b64 v[74:75], 2, v[56:57]
	v_ashrrev_i32_e32 v59, 31, v58
	v_ashrrev_i32_e32 v63, 31, v62
	v_lshl_add_u64 v[56:57], s[40:41], 0, v[74:75]
	v_lshlrev_b64 v[60:61], 2, v[58:59]
	v_readlane_b32 s0, v250, 15
	s_waitcnt vmcnt(1)
	v_lshl_add_u64 v[82:83], v[56:57], 0, v[60:61]
	v_lshlrev_b64 v[56:57], 12, v[62:63]
	v_readlane_b32 s1, v250, 16
	v_readlane_b32 s16, v250, 21
	v_lshlrev_b64 v[78:79], 11, v[62:63]
	v_lshl_add_u64 v[56:57], s[0:1], 0, v[56:57]
	s_waitcnt vmcnt(0)
	v_lshl_add_u64 v[84:85], v[56:57], 0, v[60:61]
	global_load_dwordx4 v[116:119], v[82:83], off
	global_load_dwordx4 v[120:123], v[82:83], off offset:64
	global_load_dwordx4 v[124:127], v[82:83], off offset:128
	global_load_dwordx4 v[132:135], v[82:83], off offset:192
	global_load_dwordx4 v[190:193], v[84:85], off
	global_load_dwordx4 v[194:197], v[84:85], off offset:64
	global_load_dwordx4 v[198:201], v[84:85], off offset:128
	global_load_dwordx4 v[202:205], v[84:85], off offset:192
	v_add_co_u32_e32 v164, vcc, 0x10000, v84
	s_nop 1
	v_addc_co_u32_e32 v165, vcc, 0, v85, vcc
	v_add_co_u32_e32 v222, vcc, 0x20000, v84
	s_nop 1
	v_addc_co_u32_e32 v223, vcc, 0, v85, vcc
	v_add_co_u32_e32 v224, vcc, 0x30000, v84
	s_nop 1
	v_addc_co_u32_e32 v225, vcc, 0, v85, vcc
	global_load_dwordx4 v[206:209], v[164:165], off
	global_load_dwordx4 v[210:213], v[164:165], off offset:64
	global_load_dwordx4 v[214:217], v[164:165], off offset:128
	global_load_dwordx4 v[218:221], v[164:165], off offset:192
	s_lshl_b32 s0, s69, 12
	v_readlane_b32 s68, v250, 41
	v_readlane_b32 s72, v250, 45
	v_readlane_b32 s73, v250, 46
	s_add_u32 s0, s72, s0
	s_addc_u32 s1, s73, 0
	s_add_u32 s42, s24, 0x4000
	s_addc_u32 s43, s25, 0
	v_lshl_add_u64 v[74:75], s[42:43], 0, v[74:75]
	v_lshl_add_u64 v[56:57], s[0:1], 0, v[60:61]
	v_lshl_add_u64 v[86:87], v[74:75], 0, v[60:61]
	v_readlane_b32 s17, v250, 22
	v_readlane_b32 s69, v250, 42
	v_readlane_b32 s69, v254, 49
	v_lshl_add_u64 v[78:79], s[16:17], 0, v[78:79]
	s_mul_i32 s24, s69, 0x140000
	s_add_u32 s24, s86, s24
	v_lshrrev_b32_e32 v65, 6, v65
	s_mov_b32 s16, 0xa000
	s_addc_u32 s25, s87, 0
	s_add_u32 s26, s24, 0xaf1a000
	s_addc_u32 s27, s25, 0
	v_cmp_eq_u32_e64 s[36:37], 0, v97
	v_readlane_b32 s70, v250, 43
	v_readlane_b32 s71, v250, 44
	v_readlane_b32 s74, v250, 47
	v_readlane_b32 s75, v250, 48
	v_readlane_b32 s76, v250, 49
	v_readlane_b32 s77, v250, 50
	v_readlane_b32 s78, v250, 51
	v_readlane_b32 s79, v250, 52
	v_readlane_b32 s80, v250, 53
	v_readlane_b32 s81, v250, 54
	v_readlane_b32 s82, v250, 55
	v_readlane_b32 s83, v250, 56
	s_waitcnt vmcnt(4)
	v_pk_fma_f32 v[68:69], v[94:95], v[118:119], v[192:193]
	v_pk_fma_f32 v[66:67], v[92:93], v[116:117], v[190:191]
	global_store_dwordx4 v[84:85], v[66:69], off
	global_load_dwordx4 v[136:139], v[56:57], off
	global_load_dwordx4 v[140:143], v[56:57], off offset:64
	global_load_dwordx4 v[144:147], v[56:57], off offset:128
	global_load_dwordx4 v[148:151], v[56:57], off offset:192
	global_load_dwordx4 v[152:155], v[86:87], off
	global_load_dwordx4 v[156:159], v[86:87], off offset:64
	global_load_dwordx4 v[160:163], v[86:87], off offset:128
	global_load_dwordx4 v[180:183], v[86:87], off offset:192
	v_lshl_add_u64 v[92:93], v[58:59], 1, v[78:79]
	s_waitcnt vmcnt(0)
	v_pk_mul_f32 v[72:73], v[68:69], v[138:139]
	v_pk_mul_f32 v[70:71], v[66:67], v[136:137]
	s_waitcnt vmcnt(0)
	v_pk_add_f32 v[76:77], v[154:155], 1.0 op_sel_hi:[1,0]
	v_pk_add_f32 v[74:75], v[152:153], 1.0 op_sel_hi:[1,0]
	v_pk_mul_f32 v[72:73], v[72:73], v[76:77]
	v_pk_mul_f32 v[70:71], v[70:71], v[74:75]
	v_and_b32_sdwa v76, v73, v170 dst_sel:DWORD dst_unused:UNUSED_PAD src0_sel:WORD_1 src1_sel:DWORD
	v_and_b32_sdwa v77, v71, v170 dst_sel:DWORD dst_unused:UNUSED_PAD src0_sel:WORD_1 src1_sel:DWORD
	v_and_b32_sdwa v74, v72, v170 dst_sel:DWORD dst_unused:UNUSED_PAD src0_sel:WORD_1 src1_sel:DWORD
	v_and_b32_sdwa v75, v70, v170 dst_sel:DWORD dst_unused:UNUSED_PAD src0_sel:WORD_1 src1_sel:DWORD
	v_add3_u32 v73, v73, v76, s56
	v_add3_u32 v71, v71, v77, s56
	v_add3_u32 v70, v70, v75, s56
	v_add3_u32 v72, v72, v74, s56
	v_and_b32_e32 v73, 0xffff0000, v73
	v_and_b32_e32 v74, 0xffff0000, v71
	v_or_b32_sdwa v71, v73, v72 dst_sel:DWORD dst_unused:UNUSED_PAD src0_sel:DWORD src1_sel:WORD_1
	v_or_b32_sdwa v70, v74, v70 dst_sel:DWORD dst_unused:UNUSED_PAD src0_sel:DWORD src1_sel:WORD_1
	global_store_dwordx2 v[92:93], v[70:71], off
	s_nop 0
	s_waitcnt vmcnt(0)
	v_pk_fma_f32 v[72:73], v[90:91], v[122:123], v[196:197]
	v_pk_fma_f32 v[70:71], v[88:89], v[120:121], v[194:195]
	global_store_dwordx4 v[84:85], v[70:73], off offset:64
	v_pk_mul_f32 v[76:77], v[72:73], v[142:143]
	v_pk_mul_f32 v[74:75], v[70:71], v[140:141]
	v_pk_add_f32 v[80:81], v[158:159], 1.0 op_sel_hi:[1,0]
	v_pk_add_f32 v[78:79], v[156:157], 1.0 op_sel_hi:[1,0]
	v_pk_mul_f32 v[76:77], v[76:77], v[80:81]
	v_pk_mul_f32 v[74:75], v[74:75], v[78:79]
	v_and_b32_sdwa v80, v77, v170 dst_sel:DWORD dst_unused:UNUSED_PAD src0_sel:WORD_1 src1_sel:DWORD
	v_and_b32_sdwa v81, v75, v170 dst_sel:DWORD dst_unused:UNUSED_PAD src0_sel:WORD_1 src1_sel:DWORD
	v_and_b32_sdwa v78, v76, v170 dst_sel:DWORD dst_unused:UNUSED_PAD src0_sel:WORD_1 src1_sel:DWORD
	v_and_b32_sdwa v79, v74, v170 dst_sel:DWORD dst_unused:UNUSED_PAD src0_sel:WORD_1 src1_sel:DWORD
	v_add3_u32 v77, v77, v80, s56
	v_add3_u32 v75, v75, v81, s56
	v_add3_u32 v74, v74, v79, s56
	v_add3_u32 v76, v76, v78, s56
	v_and_b32_e32 v77, 0xffff0000, v77
	v_and_b32_e32 v78, 0xffff0000, v75
	v_or_b32_sdwa v75, v77, v76 dst_sel:DWORD dst_unused:UNUSED_PAD src0_sel:DWORD src1_sel:WORD_1
	v_or_b32_sdwa v74, v78, v74 dst_sel:DWORD dst_unused:UNUSED_PAD src0_sel:DWORD src1_sel:WORD_1
	global_store_dwordx2 v[92:93], v[74:75], off offset:32
	s_nop 0
	v_pk_fma_f32 v[54:55], v[54:55], v[126:127], v[200:201]
	v_pk_fma_f32 v[52:53], v[52:53], v[124:125], v[198:199]
	global_store_dwordx4 v[84:85], v[52:55], off offset:128
	v_pk_mul_f32 v[76:77], v[54:55], v[146:147]
	v_pk_mul_f32 v[74:75], v[52:53], v[144:145]
	v_pk_add_f32 v[80:81], v[162:163], 1.0 op_sel_hi:[1,0]
	v_pk_add_f32 v[78:79], v[160:161], 1.0 op_sel_hi:[1,0]
	v_pk_mul_f32 v[76:77], v[76:77], v[80:81]
	v_pk_mul_f32 v[74:75], v[74:75], v[78:79]
	v_and_b32_sdwa v80, v77, v170 dst_sel:DWORD dst_unused:UNUSED_PAD src0_sel:WORD_1 src1_sel:DWORD
	v_and_b32_sdwa v81, v75, v170 dst_sel:DWORD dst_unused:UNUSED_PAD src0_sel:WORD_1 src1_sel:DWORD
	v_and_b32_sdwa v78, v76, v170 dst_sel:DWORD dst_unused:UNUSED_PAD src0_sel:WORD_1 src1_sel:DWORD
	v_and_b32_sdwa v79, v74, v170 dst_sel:DWORD dst_unused:UNUSED_PAD src0_sel:WORD_1 src1_sel:DWORD
	v_add3_u32 v77, v77, v80, s56
	v_add3_u32 v75, v75, v81, s56
	v_add3_u32 v74, v74, v79, s56
	v_add3_u32 v76, v76, v78, s56
	v_and_b32_e32 v77, 0xffff0000, v77
	v_and_b32_e32 v78, 0xffff0000, v75
	v_or_b32_sdwa v75, v77, v76 dst_sel:DWORD dst_unused:UNUSED_PAD src0_sel:DWORD src1_sel:WORD_1
	v_or_b32_sdwa v74, v78, v74 dst_sel:DWORD dst_unused:UNUSED_PAD src0_sel:DWORD src1_sel:WORD_1
	global_store_dwordx2 v[92:93], v[74:75], off offset:64
	s_nop 0
	v_pk_fma_f32 v[76:77], v[50:51], v[134:135], v[204:205]
	v_pk_fma_f32 v[74:75], v[48:49], v[132:133], v[202:203]
	global_store_dwordx4 v[84:85], v[74:77], off offset:192
	s_nop 0
	v_mbcnt_lo_u32_b32 v48, -1, 0
	v_mbcnt_hi_u32_b32 v48, -1, v48
	v_and_b32_e32 v50, 64, v48
	v_xor_b32_e32 v49, 16, v48
	v_add_u32_e32 v50, 64, v50
	v_xor_b32_e32 v51, 32, v48
	v_cmp_lt_i32_e32 vcc, v49, v50
	s_nop 1
	v_cndmask_b32_e32 v49, v48, v49, vcc
	v_cmp_lt_i32_e32 vcc, v51, v50
	v_lshlrev_b32_e32 v105, 2, v49
	s_nop 0
	v_cndmask_b32_e32 v50, v48, v51, vcc
	v_lshlrev_b32_e32 v104, 2, v50
	v_mul_f32_e32 v50, v67, v67
	v_mul_f32_e32 v51, v71, v71
	v_fmac_f32_e32 v50, v66, v66
	v_fmac_f32_e32 v51, v70, v70
	v_fmac_f32_e32 v50, v68, v68
	v_fmac_f32_e32 v51, v72, v72
	v_fmac_f32_e32 v50, v69, v69
	v_fmac_f32_e32 v51, v73, v73
	v_add_f32_e32 v50, v50, v51
	v_mul_f32_e32 v51, v53, v53
	v_fmac_f32_e32 v51, v52, v52
	v_fmac_f32_e32 v51, v54, v54
	v_fmac_f32_e32 v51, v55, v55
	v_add_f32_e32 v50, v50, v51
	v_mul_f32_e32 v51, v75, v75
	v_fmac_f32_e32 v51, v74, v74
	v_fmac_f32_e32 v51, v76, v76
	v_fmac_f32_e32 v51, v77, v77
	v_add_f32_e32 v50, v50, v51
	ds_bpermute_b32 v51, v105, v50
	v_mul_lo_u32 v48, v65, s16
	v_ashrrev_i32_e32 v49, 31, v48
	v_lshl_add_u64 v[48:49], s[26:27], 0, v[48:49]
	v_lshl_add_u64 v[48:49], v[62:63], 2, v[48:49]
	s_waitcnt lgkmcnt(0)
	v_add_f32_e32 v50, v50, v51
	ds_bpermute_b32 v51, v104, v50
	v_pk_mul_f32 v[52:53], v[76:77], v[150:151]
	v_pk_mul_f32 v[54:55], v[74:75], v[148:149]
	v_pk_add_f32 v[66:67], v[182:183], 1.0 op_sel_hi:[1,0]
	v_pk_add_f32 v[68:69], v[180:181], 1.0 op_sel_hi:[1,0]
	v_pk_mul_f32 v[52:53], v[52:53], v[66:67]
	v_pk_mul_f32 v[54:55], v[54:55], v[68:69]
	v_and_b32_sdwa v67, v53, v170 dst_sel:DWORD dst_unused:UNUSED_PAD src0_sel:WORD_1 src1_sel:DWORD
	v_and_b32_sdwa v68, v55, v170 dst_sel:DWORD dst_unused:UNUSED_PAD src0_sel:WORD_1 src1_sel:DWORD
	v_and_b32_sdwa v65, v52, v170 dst_sel:DWORD dst_unused:UNUSED_PAD src0_sel:WORD_1 src1_sel:DWORD
	v_and_b32_sdwa v66, v54, v170 dst_sel:DWORD dst_unused:UNUSED_PAD src0_sel:WORD_1 src1_sel:DWORD
	v_add3_u32 v53, v53, v67, s56
	v_add3_u32 v55, v55, v68, s56
	v_add3_u32 v54, v54, v66, s56
	v_add3_u32 v52, v52, v65, s56
	v_and_b32_e32 v53, 0xffff0000, v53
	v_and_b32_e32 v55, 0xffff0000, v55
	v_or_b32_sdwa v53, v53, v52 dst_sel:DWORD dst_unused:UNUSED_PAD src0_sel:DWORD src1_sel:WORD_1
	v_or_b32_sdwa v52, v55, v54 dst_sel:DWORD dst_unused:UNUSED_PAD src0_sel:DWORD src1_sel:WORD_1
	global_store_dwordx2 v[92:93], v[52:53], off offset:96
	s_and_saveexec_b64 s[24:25], s[36:37]
	s_cbranch_execz .LBB0_95
	s_waitcnt lgkmcnt(0)
	v_add_f32_e32 v50, v50, v51
	global_store_dword v[48:49], v50, off

.LBB0_106:
	s_add_i32 s29, s44, 2
	ds_read_b128 v[136:139], v111 offset:16384
	ds_read_b128 v[140:143], v111 offset:18432
	ds_read_b128 v[144:147], v111 offset:20480
	ds_read_b128 v[148:151], v111 offset:22528
	ds_read_b128 v[116:119], v110
	s_add_i32 s44, s44, 4
	ds_read_b128 v[120:123], v110 offset:2048
	s_min_u32 s44, s44, 15
	s_lshl_b32 s92, s44, 7
	ds_read_b128 v[124:127], v110 offset:4096
	ds_read_b128 v[194:197], v113 offset:16384
	ds_read_b128 v[198:201], v113 offset:18432
	ds_read_b128 v[202:205], v113 offset:20480
	ds_read_b128 v[206:209], v113 offset:22528
	v_lshl_add_u64 v[164:165], v[100:101], 0, s[92:93]
	ds_read_b128 v[132:135], v110 offset:6144
	ds_read_b128 v[152:155], v112
	ds_read_b128 v[156:159], v112 offset:2048
	ds_read_b128 v[160:163], v112 offset:4096
	ds_read_b128 v[190:193], v112 offset:6144
	s_waitcnt lgkmcnt(11)
	v_mfma_f32_16x16x32_bf16 v[92:95], v[136:139], v[116:119], v[92:95]
	v_mfma_f32_16x16x32_bf16 v[88:91], v[140:143], v[116:119], v[88:91]
	v_mfma_f32_16x16x32_bf16 v[56:59], v[144:147], v[116:119], v[56:59]
	v_mfma_f32_16x16x32_bf16 v[48:51], v[148:151], v[116:119], v[48:51]
	global_load_dwordx4 v[116:119], v[164:165], off
	s_waitcnt vmcnt(6)
	ds_write_b128 v109, v[52:55] offset:32768
	v_add_co_u32_e32 v52, vcc, s11, v164
	s_waitcnt lgkmcnt(11)
	v_mfma_f32_16x16x32_bf16 v[44:47], v[136:139], v[120:123], v[44:47]
	v_addc_co_u32_e32 v53, vcc, 0, v165, vcc
	v_mfma_f32_16x16x32_bf16 v[40:43], v[140:143], v[120:123], v[40:43]
	v_mfma_f32_16x16x32_bf16 v[36:39], v[144:147], v[120:123], v[36:39]
	v_mfma_f32_16x16x32_bf16 v[32:35], v[148:151], v[120:123], v[32:35]
	global_load_dwordx4 v[120:123], v[52:53], off
	v_add_co_u32_e32 v52, vcc, s33, v164
	ds_write_b128 v109, v[60:63] offset:36864
	s_nop 0
	v_addc_co_u32_e32 v53, vcc, 0, v165, vcc
	s_waitcnt lgkmcnt(11)
	v_mfma_f32_16x16x32_bf16 v[28:31], v[136:139], v[124:127], v[28:31]
	v_mfma_f32_16x16x32_bf16 v[24:27], v[140:143], v[124:127], v[24:27]
	v_mfma_f32_16x16x32_bf16 v[20:23], v[144:147], v[124:127], v[20:23]
	v_mfma_f32_16x16x32_bf16 v[16:19], v[148:151], v[124:127], v[16:19]
	global_load_dwordx4 v[124:127], v[52:53], off
	v_add_co_u32_e32 v52, vcc, s59, v164
	ds_write_b128 v109, v[64:67] offset:40960
	s_nop 0
	v_addc_co_u32_e32 v53, vcc, 0, v165, vcc
	v_lshl_add_u64 v[64:65], v[102:103], 0, s[92:93]
	v_add_co_u32_e32 v66, vcc, s11, v64
	s_waitcnt lgkmcnt(7)
	v_mfma_f32_16x16x32_bf16 v[12:15], v[136:139], v[132:135], v[12:15]
	v_addc_co_u32_e32 v67, vcc, 0, v65, vcc
	v_mfma_f32_16x16x32_bf16 v[8:11], v[140:143], v[132:135], v[8:11]
	v_mfma_f32_16x16x32_bf16 v[4:7], v[144:147], v[132:135], v[4:7]
	v_mfma_f32_16x16x32_bf16 v[0:3], v[148:151], v[132:135], v[0:3]
	global_load_dwordx4 v[132:135], v[52:53], off
	s_waitcnt vmcnt(7)
	ds_write_b128 v109, v[72:75] offset:45056
	s_waitcnt lgkmcnt(7)
	v_mfma_f32_16x16x32_bf16 v[52:55], v[194:197], v[152:155], v[92:95]
	v_mfma_f32_16x16x32_bf16 v[60:63], v[198:201], v[152:155], v[88:91]
	v_mfma_f32_16x16x32_bf16 v[56:59], v[202:205], v[152:155], v[56:59]
	v_mfma_f32_16x16x32_bf16 v[48:51], v[206:209], v[152:155], v[48:51]
	global_load_dwordx4 v[136:139], v[64:65], off
	ds_write_b128 v109, v[68:71] offset:49152
	s_waitcnt lgkmcnt(7)
	v_mfma_f32_16x16x32_bf16 v[44:47], v[194:197], v[156:159], v[44:47]
	v_mfma_f32_16x16x32_bf16 v[40:43], v[198:201], v[156:159], v[40:43]
	v_mfma_f32_16x16x32_bf16 v[36:39], v[202:205], v[156:159], v[36:39]
	v_mfma_f32_16x16x32_bf16 v[32:35], v[206:209], v[156:159], v[32:35]
	global_load_dwordx4 v[140:143], v[66:67], off
	v_add_co_u32_e32 v66, vcc, s33, v64
	s_waitcnt vmcnt(8)
	ds_write_b128 v109, v[76:79] offset:53248
	v_addc_co_u32_e32 v67, vcc, 0, v65, vcc
	v_add_co_u32_e32 v64, vcc, s59, v64
	s_waitcnt lgkmcnt(7)
	v_mfma_f32_16x16x32_bf16 v[28:31], v[194:197], v[160:163], v[28:31]
	v_addc_co_u32_e32 v65, vcc, 0, v65, vcc
	v_mfma_f32_16x16x32_bf16 v[24:27], v[198:201], v[160:163], v[24:27]
	v_mfma_f32_16x16x32_bf16 v[20:23], v[202:205], v[160:163], v[20:23]
	v_mfma_f32_16x16x32_bf16 v[16:19], v[206:209], v[160:163], v[16:19]
	global_load_dwordx4 v[144:147], v[66:67], off
	s_waitcnt vmcnt(8)
	ds_write_b128 v109, v[80:83] offset:57344
	s_waitcnt lgkmcnt(7)
	v_mfma_f32_16x16x32_bf16 v[12:15], v[194:197], v[190:193], v[12:15]
	v_mfma_f32_16x16x32_bf16 v[8:11], v[198:201], v[190:193], v[8:11]
	v_mfma_f32_16x16x32_bf16 v[4:7], v[202:205], v[190:193], v[4:7]
	v_mfma_f32_16x16x32_bf16 v[0:3], v[206:209], v[190:193], v[0:3]
	global_load_dwordx4 v[148:151], v[64:65], off
	s_waitcnt vmcnt(8)
	ds_write_b128 v109, v[84:87] offset:61440
	s_waitcnt lgkmcnt(0)
	s_barrier
	ds_read_b128 v[84:87], v111 offset:51200
	ds_read_b128 v[80:83], v111 offset:49152
	ds_read_b128 v[88:91], v111 offset:53248
	ds_read_b128 v[92:95], v111 offset:55296
	ds_read_b128 v[64:67], v110 offset:32768
	s_min_u32 s44, s29, 12
	s_lshl_b32 s92, s44, 7
	ds_read_b128 v[68:71], v110 offset:34816
	v_lshl_add_u64 v[164:165], v[100:101], 0, s[92:93]
	ds_read_b128 v[72:75], v110 offset:36864
	ds_read_b128 v[76:79], v110 offset:38912
	ds_read_b128 v[152:155], v112 offset:32768
	ds_read_b128 v[156:159], v112 offset:34816
	ds_read_b128 v[160:163], v112 offset:36864
	ds_read_b128 v[190:193], v112 offset:38912
	ds_read_b128 v[194:197], v113 offset:49152
	ds_read_b128 v[198:201], v113 offset:51200
	ds_read_b128 v[202:205], v113 offset:53248
	ds_read_b128 v[206:209], v113 offset:55296
	s_waitcnt lgkmcnt(11)
	v_mfma_f32_16x16x32_bf16 v[214:217], v[84:87], v[64:67], v[60:63]
	v_mfma_f32_16x16x32_bf16 v[210:213], v[80:83], v[64:67], v[52:55]
	s_nop 1
	v_add_co_u32_e32 v60, vcc, s11, v164
	s_nop 1
	v_addc_co_u32_e32 v61, vcc, 0, v165, vcc
	v_mfma_f32_16x16x32_bf16 v[56:59], v[88:91], v[64:67], v[56:59]
	v_mfma_f32_16x16x32_bf16 v[48:51], v[92:95], v[64:67], v[48:51]
	v_add_co_u32_e32 v64, vcc, s33, v164
	global_load_dwordx4 v[52:55], v[164:165], off offset:384
	s_nop 0
	v_addc_co_u32_e32 v65, vcc, 0, v165, vcc
	s_waitcnt vmcnt(8)
	ds_write_b128 v109, v[116:119]
	s_waitcnt lgkmcnt(11)
	v_mfma_f32_16x16x32_bf16 v[44:47], v[80:83], v[68:71], v[44:47]
	v_mfma_f32_16x16x32_bf16 v[40:43], v[84:87], v[68:71], v[40:43]
	v_mfma_f32_16x16x32_bf16 v[36:39], v[88:91], v[68:71], v[36:39]
	v_mfma_f32_16x16x32_bf16 v[32:35], v[92:95], v[68:71], v[32:35]
	v_add_co_u32_e32 v68, vcc, s59, v164
	global_load_dwordx4 v[60:63], v[60:61], off offset:384
	s_waitcnt vmcnt(8)
	ds_write_b128 v109, v[120:123] offset:4096
	s_waitcnt lgkmcnt(11)
	v_mfma_f32_16x16x32_bf16 v[28:31], v[80:83], v[72:75], v[28:31]
	v_addc_co_u32_e32 v69, vcc, 0, v165, vcc
	v_mfma_f32_16x16x32_bf16 v[24:27], v[84:87], v[72:75], v[24:27]
	v_mfma_f32_16x16x32_bf16 v[20:23], v[88:91], v[72:75], v[20:23]
	v_mfma_f32_16x16x32_bf16 v[16:19], v[92:95], v[72:75], v[16:19]
	global_load_dwordx4 v[64:67], v[64:65], off offset:384
	s_waitcnt vmcnt(8)
	ds_write_b128 v109, v[124:127] offset:8192
	s_waitcnt lgkmcnt(11)
	v_mfma_f32_16x16x32_bf16 v[8:11], v[84:87], v[76:79], v[8:11]
	v_lshl_add_u64 v[84:85], v[102:103], 0, s[92:93]
	v_mfma_f32_16x16x32_bf16 v[12:15], v[80:83], v[76:79], v[12:15]
	v_mfma_f32_16x16x32_bf16 v[4:7], v[88:91], v[76:79], v[4:7]
	v_mfma_f32_16x16x32_bf16 v[0:3], v[92:95], v[76:79], v[0:3]
	v_add_co_u32_e32 v76, vcc, s11, v84
	global_load_dwordx4 v[72:75], v[68:69], off offset:384
	s_nop 0
	v_addc_co_u32_e32 v77, vcc, 0, v85, vcc
	v_add_co_u32_e32 v80, vcc, s33, v84
	s_waitcnt vmcnt(8)
	ds_write_b128 v109, v[132:135] offset:12288
	v_addc_co_u32_e32 v81, vcc, 0, v85, vcc
	s_waitcnt lgkmcnt(7)
	v_mfma_f32_16x16x32_bf16 v[92:95], v[194:197], v[152:155], v[210:213]
	s_waitcnt lgkmcnt(6)
	v_mfma_f32_16x16x32_bf16 v[88:91], v[198:201], v[152:155], v[214:217]
	s_waitcnt lgkmcnt(5)
	v_mfma_f32_16x16x32_bf16 v[56:59], v[202:205], v[152:155], v[56:59]
	s_waitcnt lgkmcnt(4)
	v_mfma_f32_16x16x32_bf16 v[48:51], v[206:209], v[152:155], v[48:51]
	global_load_dwordx4 v[68:71], v[84:85], off offset:384
	v_add_co_u32_e32 v84, vcc, s59, v84
	s_waitcnt vmcnt(8)
	ds_write_b128 v109, v[136:139] offset:16384
	v_addc_co_u32_e32 v85, vcc, 0, v85, vcc
	v_mfma_f32_16x16x32_bf16 v[44:47], v[194:197], v[156:159], v[44:47]
	v_mfma_f32_16x16x32_bf16 v[40:43], v[198:201], v[156:159], v[40:43]
	v_mfma_f32_16x16x32_bf16 v[36:39], v[202:205], v[156:159], v[36:39]
	v_mfma_f32_16x16x32_bf16 v[32:35], v[206:209], v[156:159], v[32:35]
	global_load_dwordx4 v[76:79], v[76:77], off offset:384
	s_waitcnt vmcnt(8)
	ds_write_b128 v109, v[140:143] offset:20480
	v_mfma_f32_16x16x32_bf16 v[28:31], v[194:197], v[160:163], v[28:31]
	v_mfma_f32_16x16x32_bf16 v[24:27], v[198:201], v[160:163], v[24:27]
	v_mfma_f32_16x16x32_bf16 v[20:23], v[202:205], v[160:163], v[20:23]
	v_mfma_f32_16x16x32_bf16 v[16:19], v[206:209], v[160:163], v[16:19]
	global_load_dwordx4 v[80:83], v[80:81], off offset:384
	s_waitcnt vmcnt(8)
	ds_write_b128 v109, v[144:147] offset:24576
	v_mfma_f32_16x16x32_bf16 v[12:15], v[194:197], v[190:193], v[12:15]
	v_mfma_f32_16x16x32_bf16 v[8:11], v[198:201], v[190:193], v[8:11]
	v_mfma_f32_16x16x32_bf16 v[4:7], v[202:205], v[190:193], v[4:7]
	v_mfma_f32_16x16x32_bf16 v[0:3], v[206:209], v[190:193], v[0:3]
	global_load_dwordx4 v[84:87], v[84:85], off offset:384
	s_waitcnt vmcnt(8)
	ds_write_b128 v109, v[148:151] offset:28672
	s_cmp_lt_u32 s29, 12
	s_mov_b32 s44, s29
	s_waitcnt lgkmcnt(0)
	s_barrier
	s_cbranch_scc1 .LBB0_106
.Ltail106:
	s_add_i32 s29, s44, 2
	ds_read_b128 v[136:139], v111 offset:16384
	ds_read_b128 v[140:143], v111 offset:18432
	ds_read_b128 v[144:147], v111 offset:20480
	ds_read_b128 v[148:151], v111 offset:22528
	ds_read_b128 v[116:119], v110
	s_add_i32 s44, s44, 4
	ds_read_b128 v[120:123], v110 offset:2048
	s_min_u32 s44, s44, 15
	s_lshl_b32 s92, s44, 7
	ds_read_b128 v[124:127], v110 offset:4096
	ds_read_b128 v[194:197], v113 offset:16384
	ds_read_b128 v[198:201], v113 offset:18432
	ds_read_b128 v[202:205], v113 offset:20480
	ds_read_b128 v[206:209], v113 offset:22528
	v_lshl_add_u64 v[164:165], v[100:101], 0, s[92:93]
	ds_read_b128 v[132:135], v110 offset:6144
	ds_read_b128 v[152:155], v112
	ds_read_b128 v[156:159], v112 offset:2048
	ds_read_b128 v[160:163], v112 offset:4096
	ds_read_b128 v[190:193], v112 offset:6144
	s_waitcnt lgkmcnt(11)
	v_mfma_f32_16x16x32_bf16 v[92:95], v[136:139], v[116:119], v[92:95]
	v_mfma_f32_16x16x32_bf16 v[88:91], v[140:143], v[116:119], v[88:91]
	v_mfma_f32_16x16x32_bf16 v[56:59], v[144:147], v[116:119], v[56:59]
	v_mfma_f32_16x16x32_bf16 v[48:51], v[148:151], v[116:119], v[48:51]
	s_waitcnt vmcnt(7)
	ds_write_b128 v109, v[52:55] offset:32768
	v_add_co_u32_e32 v52, vcc, s11, v164
	s_waitcnt lgkmcnt(11)
	v_mfma_f32_16x16x32_bf16 v[44:47], v[136:139], v[120:123], v[44:47]
	v_addc_co_u32_e32 v53, vcc, 0, v165, vcc
	v_mfma_f32_16x16x32_bf16 v[40:43], v[140:143], v[120:123], v[40:43]
	v_mfma_f32_16x16x32_bf16 v[36:39], v[144:147], v[120:123], v[36:39]
	v_mfma_f32_16x16x32_bf16 v[32:35], v[148:151], v[120:123], v[32:35]
	v_add_co_u32_e32 v52, vcc, s33, v164
	s_waitcnt vmcnt(6)
	ds_write_b128 v109, v[60:63] offset:36864
	s_nop 0
	v_addc_co_u32_e32 v53, vcc, 0, v165, vcc
	s_waitcnt lgkmcnt(11)
	v_mfma_f32_16x16x32_bf16 v[28:31], v[136:139], v[124:127], v[28:31]
	v_mfma_f32_16x16x32_bf16 v[24:27], v[140:143], v[124:127], v[24:27]
	v_mfma_f32_16x16x32_bf16 v[20:23], v[144:147], v[124:127], v[20:23]
	v_mfma_f32_16x16x32_bf16 v[16:19], v[148:151], v[124:127], v[16:19]
	v_add_co_u32_e32 v52, vcc, s59, v164
	s_waitcnt vmcnt(5)
	ds_write_b128 v109, v[64:67] offset:40960
	s_nop 0
	v_addc_co_u32_e32 v53, vcc, 0, v165, vcc
	v_lshl_add_u64 v[64:65], v[102:103], 0, s[92:93]
	v_add_co_u32_e32 v66, vcc, s11, v64
	s_waitcnt lgkmcnt(7)
	v_mfma_f32_16x16x32_bf16 v[12:15], v[136:139], v[132:135], v[12:15]
	v_addc_co_u32_e32 v67, vcc, 0, v65, vcc
	v_mfma_f32_16x16x32_bf16 v[8:11], v[140:143], v[132:135], v[8:11]
	v_mfma_f32_16x16x32_bf16 v[4:7], v[144:147], v[132:135], v[4:7]
	v_mfma_f32_16x16x32_bf16 v[0:3], v[148:151], v[132:135], v[0:3]
	s_waitcnt vmcnt(4)
	ds_write_b128 v109, v[72:75] offset:45056
	s_waitcnt lgkmcnt(7)
	v_mfma_f32_16x16x32_bf16 v[52:55], v[194:197], v[152:155], v[92:95]
	v_mfma_f32_16x16x32_bf16 v[60:63], v[198:201], v[152:155], v[88:91]
	v_mfma_f32_16x16x32_bf16 v[56:59], v[202:205], v[152:155], v[56:59]
	v_mfma_f32_16x16x32_bf16 v[48:51], v[206:209], v[152:155], v[48:51]
	s_waitcnt vmcnt(3)
	ds_write_b128 v109, v[68:71] offset:49152
	s_waitcnt lgkmcnt(7)
	v_mfma_f32_16x16x32_bf16 v[44:47], v[194:197], v[156:159], v[44:47]
	v_mfma_f32_16x16x32_bf16 v[40:43], v[198:201], v[156:159], v[40:43]
	v_mfma_f32_16x16x32_bf16 v[36:39], v[202:205], v[156:159], v[36:39]
	v_mfma_f32_16x16x32_bf16 v[32:35], v[206:209], v[156:159], v[32:35]
	v_add_co_u32_e32 v66, vcc, s33, v64
	s_waitcnt vmcnt(2)
	ds_write_b128 v109, v[76:79] offset:53248
	v_addc_co_u32_e32 v67, vcc, 0, v65, vcc
	v_add_co_u32_e32 v64, vcc, s59, v64
	s_waitcnt lgkmcnt(7)
	v_mfma_f32_16x16x32_bf16 v[28:31], v[194:197], v[160:163], v[28:31]
	v_addc_co_u32_e32 v65, vcc, 0, v65, vcc
	v_mfma_f32_16x16x32_bf16 v[24:27], v[198:201], v[160:163], v[24:27]
	v_mfma_f32_16x16x32_bf16 v[20:23], v[202:205], v[160:163], v[20:23]
	v_mfma_f32_16x16x32_bf16 v[16:19], v[206:209], v[160:163], v[16:19]
	s_waitcnt vmcnt(1)
	ds_write_b128 v109, v[80:83] offset:57344
	s_waitcnt lgkmcnt(7)
	v_mfma_f32_16x16x32_bf16 v[12:15], v[194:197], v[190:193], v[12:15]
	v_mfma_f32_16x16x32_bf16 v[8:11], v[198:201], v[190:193], v[8:11]
	v_mfma_f32_16x16x32_bf16 v[4:7], v[202:205], v[190:193], v[4:7]
	v_mfma_f32_16x16x32_bf16 v[0:3], v[206:209], v[190:193], v[0:3]
	s_waitcnt vmcnt(0)
	ds_write_b128 v109, v[84:87] offset:61440
	s_waitcnt lgkmcnt(0)
	s_barrier
	ds_read_b128 v[84:87], v111 offset:51200
	ds_read_b128 v[80:83], v111 offset:49152
	ds_read_b128 v[88:91], v111 offset:53248
	ds_read_b128 v[92:95], v111 offset:55296
	ds_read_b128 v[64:67], v110 offset:32768
	s_min_u32 s44, s29, 12
	s_lshl_b32 s92, s44, 7
	ds_read_b128 v[68:71], v110 offset:34816
	v_lshl_add_u64 v[164:165], v[100:101], 0, s[92:93]
	ds_read_b128 v[72:75], v110 offset:36864
	ds_read_b128 v[76:79], v110 offset:38912
	ds_read_b128 v[152:155], v112 offset:32768
	ds_read_b128 v[156:159], v112 offset:34816
	ds_read_b128 v[160:163], v112 offset:36864
	ds_read_b128 v[190:193], v112 offset:38912
	ds_read_b128 v[194:197], v113 offset:49152
	ds_read_b128 v[198:201], v113 offset:51200
	ds_read_b128 v[202:205], v113 offset:53248
	ds_read_b128 v[206:209], v113 offset:55296
	s_waitcnt lgkmcnt(11)
	v_mfma_f32_16x16x32_bf16 v[214:217], v[84:87], v[64:67], v[60:63]
	v_mfma_f32_16x16x32_bf16 v[210:213], v[80:83], v[64:67], v[52:55]
	s_nop 1
	v_add_co_u32_e32 v60, vcc, s11, v164
	s_nop 1
	v_addc_co_u32_e32 v61, vcc, 0, v165, vcc
	v_mfma_f32_16x16x32_bf16 v[56:59], v[88:91], v[64:67], v[56:59]
	v_mfma_f32_16x16x32_bf16 v[48:51], v[92:95], v[64:67], v[48:51]
	v_add_co_u32_e32 v64, vcc, s33, v164
	s_nop 0
	v_addc_co_u32_e32 v65, vcc, 0, v165, vcc
	s_waitcnt lgkmcnt(10)
	v_mfma_f32_16x16x32_bf16 v[44:47], v[80:83], v[68:71], v[44:47]
	v_mfma_f32_16x16x32_bf16 v[40:43], v[84:87], v[68:71], v[40:43]
	v_mfma_f32_16x16x32_bf16 v[36:39], v[88:91], v[68:71], v[36:39]
	v_mfma_f32_16x16x32_bf16 v[32:35], v[92:95], v[68:71], v[32:35]
	v_add_co_u32_e32 v68, vcc, s59, v164
	s_waitcnt lgkmcnt(9)
	v_mfma_f32_16x16x32_bf16 v[28:31], v[80:83], v[72:75], v[28:31]
	v_addc_co_u32_e32 v69, vcc, 0, v165, vcc
	v_mfma_f32_16x16x32_bf16 v[24:27], v[84:87], v[72:75], v[24:27]
	v_mfma_f32_16x16x32_bf16 v[20:23], v[88:91], v[72:75], v[20:23]
	v_mfma_f32_16x16x32_bf16 v[16:19], v[92:95], v[72:75], v[16:19]
	s_waitcnt lgkmcnt(8)
	v_mfma_f32_16x16x32_bf16 v[8:11], v[84:87], v[76:79], v[8:11]
	v_lshl_add_u64 v[84:85], v[102:103], 0, s[92:93]
	v_mfma_f32_16x16x32_bf16 v[12:15], v[80:83], v[76:79], v[12:15]
	v_mfma_f32_16x16x32_bf16 v[4:7], v[88:91], v[76:79], v[4:7]
	v_mfma_f32_16x16x32_bf16 v[0:3], v[92:95], v[76:79], v[0:3]
	v_add_co_u32_e32 v76, vcc, s11, v84
	s_nop 0
	v_addc_co_u32_e32 v77, vcc, 0, v85, vcc
	v_add_co_u32_e32 v80, vcc, s33, v84
	v_addc_co_u32_e32 v81, vcc, 0, v85, vcc
	s_waitcnt lgkmcnt(3)
	v_mfma_f32_16x16x32_bf16 v[92:95], v[194:197], v[152:155], v[210:213]
	s_waitcnt lgkmcnt(2)
	v_mfma_f32_16x16x32_bf16 v[88:91], v[198:201], v[152:155], v[214:217]
	s_waitcnt lgkmcnt(1)
	v_mfma_f32_16x16x32_bf16 v[56:59], v[202:205], v[152:155], v[56:59]
	s_waitcnt lgkmcnt(0)
	v_mfma_f32_16x16x32_bf16 v[48:51], v[206:209], v[152:155], v[48:51]
	v_add_co_u32_e32 v84, vcc, s59, v84
	v_addc_co_u32_e32 v85, vcc, 0, v85, vcc
	v_mfma_f32_16x16x32_bf16 v[44:47], v[194:197], v[156:159], v[44:47]
	v_mfma_f32_16x16x32_bf16 v[40:43], v[198:201], v[156:159], v[40:43]
	v_mfma_f32_16x16x32_bf16 v[36:39], v[202:205], v[156:159], v[36:39]
	v_mfma_f32_16x16x32_bf16 v[32:35], v[206:209], v[156:159], v[32:35]
	v_mfma_f32_16x16x32_bf16 v[28:31], v[194:197], v[160:163], v[28:31]
	v_mfma_f32_16x16x32_bf16 v[24:27], v[198:201], v[160:163], v[24:27]
	v_mfma_f32_16x16x32_bf16 v[20:23], v[202:205], v[160:163], v[20:23]
	v_mfma_f32_16x16x32_bf16 v[16:19], v[206:209], v[160:163], v[16:19]
	v_mfma_f32_16x16x32_bf16 v[12:15], v[194:197], v[190:193], v[12:15]
	v_mfma_f32_16x16x32_bf16 v[8:11], v[198:201], v[190:193], v[8:11]
	v_mfma_f32_16x16x32_bf16 v[4:7], v[202:205], v[190:193], v[4:7]
	v_mfma_f32_16x16x32_bf16 v[0:3], v[206:209], v[190:193], v[0:3]
	s_mov_b32 s44, s29
	s_waitcnt lgkmcnt(0)
	s_barrier
	s_waitcnt vmcnt(5)
	v_add_u32_e32 v64, s24, v108
	v_add_u32_e32 v52, 0xffffe000, v64
	v_or_b32_e32 v62, v64, v107
	v_lshrrev_b32_e32 v52, 10, v52
	s_movk_i32 s16, 0x1800
	v_mad_u32_u24 v52, v52, s16, s16
	v_cmp_lt_i32_e32 vcc, s13, v62
	v_or_b32_e32 v65, s25, v114
	v_or_b32_e32 v54, v65, v115
	v_cndmask_b32_e32 v52, 0, v52, vcc
	v_ashrrev_i32_e32 v53, 31, v52
	s_waitcnt vmcnt(4)
	v_lshlrev_b64 v[74:75], 2, v[52:53]
	v_ashrrev_i32_e32 v55, 31, v54
	v_ashrrev_i32_e32 v63, 31, v62
	v_lshl_add_u64 v[52:53], s[40:41], 0, v[74:75]
	v_lshlrev_b64 v[60:61], 2, v[54:55]
	v_readlane_b32 s16, v250, 15
	s_waitcnt vmcnt(1)
	v_lshl_add_u64 v[82:83], v[52:53], 0, v[60:61]
	v_lshlrev_b64 v[52:53], 12, v[62:63]
	v_readlane_b32 s17, v250, 16
	v_lshl_add_u64 v[74:75], s[42:43], 0, v[74:75]
	s_waitcnt vmcnt(0)
	v_lshl_add_u64 v[86:87], v[74:75], 0, v[60:61]
	v_lshl_add_u64 v[52:53], s[16:17], 0, v[52:53]
	v_lshl_add_u64 v[84:85], v[52:53], 0, v[60:61]
	global_load_dwordx4 v[66:69], v[82:83], off
	global_load_dwordx4 v[70:73], v[84:85], off
	v_lshl_add_u64 v[52:53], s[0:1], 0, v[60:61]
	v_readlane_b32 s16, v250, 21
	v_lshlrev_b64 v[78:79], 11, v[62:63]
	v_readlane_b32 s17, v250, 22
	s_waitcnt vmcnt(0)
	v_pk_fma_f32 v[68:69], v[94:95], v[68:69], v[72:73]
	v_pk_fma_f32 v[66:67], v[92:93], v[66:67], v[70:71]
	global_store_dwordx4 v[84:85], v[66:69], off
	global_load_dwordx4 v[70:73], v[52:53], off
	global_load_dwordx4 v[74:77], v[86:87], off
	v_lshl_add_u64 v[78:79], s[16:17], 0, v[78:79]
	v_lshl_add_u64 v[92:93], v[54:55], 1, v[78:79]
	s_mov_b32 s16, 0xa000
	s_waitcnt vmcnt(1)
	v_pk_mul_f32 v[72:73], v[68:69], v[72:73]
	v_pk_mul_f32 v[70:71], v[66:67], v[70:71]
	s_waitcnt vmcnt(0)
	v_pk_add_f32 v[76:77], v[76:77], 1.0 op_sel_hi:[1,0]
	v_pk_add_f32 v[74:75], v[74:75], 1.0 op_sel_hi:[1,0]
	v_pk_mul_f32 v[72:73], v[72:73], v[76:77]
	v_pk_mul_f32 v[70:71], v[70:71], v[74:75]
	v_and_b32_sdwa v76, v73, v170 dst_sel:DWORD dst_unused:UNUSED_PAD src0_sel:WORD_1 src1_sel:DWORD
	v_and_b32_sdwa v77, v71, v170 dst_sel:DWORD dst_unused:UNUSED_PAD src0_sel:WORD_1 src1_sel:DWORD
	v_and_b32_sdwa v74, v72, v170 dst_sel:DWORD dst_unused:UNUSED_PAD src0_sel:WORD_1 src1_sel:DWORD
	v_and_b32_sdwa v75, v70, v170 dst_sel:DWORD dst_unused:UNUSED_PAD src0_sel:WORD_1 src1_sel:DWORD
	v_add3_u32 v73, v73, v76, s56
	v_add3_u32 v71, v71, v77, s56
	v_add3_u32 v70, v70, v75, s56
	v_add3_u32 v72, v72, v74, s56
	v_and_b32_e32 v73, 0xffff0000, v73
	v_and_b32_e32 v74, 0xffff0000, v71
	v_or_b32_sdwa v71, v73, v72 dst_sel:DWORD dst_unused:UNUSED_PAD src0_sel:DWORD src1_sel:WORD_1
	v_or_b32_sdwa v70, v74, v70 dst_sel:DWORD dst_unused:UNUSED_PAD src0_sel:DWORD src1_sel:WORD_1
	global_store_dwordx2 v[92:93], v[70:71], off
	global_load_dwordx4 v[70:73], v[82:83], off offset:64
	s_nop 0
	global_load_dwordx4 v[74:77], v[84:85], off offset:64
	s_waitcnt vmcnt(0)
	v_pk_fma_f32 v[72:73], v[90:91], v[72:73], v[76:77]
	v_pk_fma_f32 v[70:71], v[88:89], v[70:71], v[74:75]
	global_store_dwordx4 v[84:85], v[70:73], off offset:64
	global_load_dwordx4 v[74:77], v[52:53], off offset:64
	global_load_dwordx4 v[78:81], v[86:87], off offset:64
	s_waitcnt vmcnt(1)
	v_pk_mul_f32 v[76:77], v[72:73], v[76:77]
	v_pk_mul_f32 v[74:75], v[70:71], v[74:75]
	s_waitcnt vmcnt(0)
	v_pk_add_f32 v[80:81], v[80:81], 1.0 op_sel_hi:[1,0]
	v_pk_add_f32 v[78:79], v[78:79], 1.0 op_sel_hi:[1,0]
	v_pk_mul_f32 v[76:77], v[76:77], v[80:81]
	v_pk_mul_f32 v[74:75], v[74:75], v[78:79]
	v_and_b32_sdwa v80, v77, v170 dst_sel:DWORD dst_unused:UNUSED_PAD src0_sel:WORD_1 src1_sel:DWORD
	v_and_b32_sdwa v81, v75, v170 dst_sel:DWORD dst_unused:UNUSED_PAD src0_sel:WORD_1 src1_sel:DWORD
	v_and_b32_sdwa v78, v76, v170 dst_sel:DWORD dst_unused:UNUSED_PAD src0_sel:WORD_1 src1_sel:DWORD
	v_and_b32_sdwa v79, v74, v170 dst_sel:DWORD dst_unused:UNUSED_PAD src0_sel:WORD_1 src1_sel:DWORD
	v_add3_u32 v77, v77, v80, s56
	v_add3_u32 v75, v75, v81, s56
	v_add3_u32 v74, v74, v79, s56
	v_add3_u32 v76, v76, v78, s56
	v_and_b32_e32 v77, 0xffff0000, v77
	v_and_b32_e32 v78, 0xffff0000, v75
	v_or_b32_sdwa v75, v77, v76 dst_sel:DWORD dst_unused:UNUSED_PAD src0_sel:DWORD src1_sel:WORD_1
	v_or_b32_sdwa v74, v78, v74 dst_sel:DWORD dst_unused:UNUSED_PAD src0_sel:DWORD src1_sel:WORD_1
	global_store_dwordx2 v[92:93], v[74:75], off offset:32
	global_load_dwordx4 v[74:77], v[82:83], off offset:128
	s_nop 0
	global_load_dwordx4 v[78:81], v[84:85], off offset:128
	s_waitcnt vmcnt(0)
	v_pk_fma_f32 v[58:59], v[58:59], v[76:77], v[80:81]
	v_pk_fma_f32 v[56:57], v[56:57], v[74:75], v[78:79]
	global_store_dwordx4 v[84:85], v[56:59], off offset:128
	global_load_dwordx4 v[74:77], v[52:53], off offset:128
	global_load_dwordx4 v[78:81], v[86:87], off offset:128
	s_waitcnt vmcnt(1)
	v_pk_mul_f32 v[76:77], v[58:59], v[76:77]
	v_pk_mul_f32 v[74:75], v[56:57], v[74:75]
	s_waitcnt vmcnt(0)
	v_pk_add_f32 v[80:81], v[80:81], 1.0 op_sel_hi:[1,0]
	v_pk_add_f32 v[78:79], v[78:79], 1.0 op_sel_hi:[1,0]
	v_pk_mul_f32 v[76:77], v[76:77], v[80:81]
	v_pk_mul_f32 v[74:75], v[74:75], v[78:79]
	v_and_b32_sdwa v80, v77, v170 dst_sel:DWORD dst_unused:UNUSED_PAD src0_sel:WORD_1 src1_sel:DWORD
	v_and_b32_sdwa v81, v75, v170 dst_sel:DWORD dst_unused:UNUSED_PAD src0_sel:WORD_1 src1_sel:DWORD
	v_and_b32_sdwa v78, v76, v170 dst_sel:DWORD dst_unused:UNUSED_PAD src0_sel:WORD_1 src1_sel:DWORD
	v_and_b32_sdwa v79, v74, v170 dst_sel:DWORD dst_unused:UNUSED_PAD src0_sel:WORD_1 src1_sel:DWORD
	v_add3_u32 v77, v77, v80, s56
	v_add3_u32 v75, v75, v81, s56
	v_add3_u32 v74, v74, v79, s56
	v_add3_u32 v76, v76, v78, s56
	v_and_b32_e32 v77, 0xffff0000, v77
	v_and_b32_e32 v78, 0xffff0000, v75
	v_or_b32_sdwa v75, v77, v76 dst_sel:DWORD dst_unused:UNUSED_PAD src0_sel:DWORD src1_sel:WORD_1
	v_or_b32_sdwa v74, v78, v74 dst_sel:DWORD dst_unused:UNUSED_PAD src0_sel:DWORD src1_sel:WORD_1
	global_store_dwordx2 v[92:93], v[74:75], off offset:64
	global_load_dwordx4 v[74:77], v[82:83], off offset:192
	s_nop 0
	global_load_dwordx4 v[78:81], v[84:85], off offset:192
	s_waitcnt vmcnt(0)
	v_pk_fma_f32 v[76:77], v[50:51], v[76:77], v[80:81]
	v_pk_fma_f32 v[74:75], v[48:49], v[74:75], v[78:79]
	global_store_dwordx4 v[84:85], v[74:77], off offset:192
	global_load_dwordx4 v[78:81], v[52:53], off offset:192
	s_nop 0
	global_load_dwordx4 v[82:85], v[86:87], off offset:192
	v_mul_f32_e32 v48, v67, v67
	v_mul_f32_e32 v49, v71, v71
	v_fmac_f32_e32 v48, v66, v66
	v_fmac_f32_e32 v49, v70, v70
	v_fmac_f32_e32 v48, v68, v68
	v_fmac_f32_e32 v49, v72, v72
	v_fmac_f32_e32 v48, v69, v69
	v_fmac_f32_e32 v49, v73, v73
	v_add_f32_e32 v48, v48, v49
	v_mul_f32_e32 v49, v57, v57
	v_fmac_f32_e32 v49, v56, v56
	v_fmac_f32_e32 v49, v58, v58
	v_fmac_f32_e32 v49, v59, v59
	v_add_f32_e32 v48, v48, v49
	v_mul_f32_e32 v49, v75, v75
	v_fmac_f32_e32 v49, v74, v74
	v_fmac_f32_e32 v49, v76, v76
	v_fmac_f32_e32 v49, v77, v77
	v_add_f32_e32 v50, v48, v49
	ds_bpermute_b32 v51, v105, v50
	v_lshrrev_b32_e32 v48, 6, v65
	v_mul_lo_u32 v48, v48, s16
	v_ashrrev_i32_e32 v49, 31, v48
	v_lshl_add_u64 v[48:49], s[26:27], 0, v[48:49]
	s_waitcnt lgkmcnt(0)
	v_add_f32_e32 v50, v50, v51
	ds_bpermute_b32 v51, v104, v50
	v_lshl_add_u64 v[48:49], v[62:63], 2, v[48:49]
	s_waitcnt vmcnt(1)
	v_pk_mul_f32 v[56:57], v[76:77], v[80:81]
	v_pk_mul_f32 v[58:59], v[74:75], v[78:79]
	s_waitcnt vmcnt(0)
	v_pk_add_f32 v[66:67], v[84:85], 1.0 op_sel_hi:[1,0]
	v_pk_add_f32 v[68:69], v[82:83], 1.0 op_sel_hi:[1,0]
	v_pk_mul_f32 v[56:57], v[56:57], v[66:67]
	v_pk_mul_f32 v[58:59], v[58:59], v[68:69]
	v_and_b32_sdwa v67, v57, v170 dst_sel:DWORD dst_unused:UNUSED_PAD src0_sel:WORD_1 src1_sel:DWORD
	v_and_b32_sdwa v68, v59, v170 dst_sel:DWORD dst_unused:UNUSED_PAD src0_sel:WORD_1 src1_sel:DWORD
	v_and_b32_sdwa v65, v56, v170 dst_sel:DWORD dst_unused:UNUSED_PAD src0_sel:WORD_1 src1_sel:DWORD
	v_and_b32_sdwa v66, v58, v170 dst_sel:DWORD dst_unused:UNUSED_PAD src0_sel:WORD_1 src1_sel:DWORD
	v_add3_u32 v57, v57, v67, s56
	v_add3_u32 v59, v59, v68, s56
	v_add3_u32 v58, v58, v66, s56
	v_add3_u32 v56, v56, v65, s56
	v_and_b32_e32 v57, 0xffff0000, v57
	v_and_b32_e32 v59, 0xffff0000, v59
	v_or_b32_sdwa v57, v57, v56 dst_sel:DWORD dst_unused:UNUSED_PAD src0_sel:DWORD src1_sel:WORD_1
	v_or_b32_sdwa v56, v59, v58 dst_sel:DWORD dst_unused:UNUSED_PAD src0_sel:DWORD src1_sel:WORD_1
	global_store_dwordx2 v[92:93], v[56:57], off offset:96
	s_and_saveexec_b64 s[24:25], s[36:37]
	s_cbranch_execz .LBB0_109
	s_waitcnt lgkmcnt(0)
	v_add_f32_e32 v50, v50, v51
	global_store_dword v[48:49], v50, off

.LBB0_119:
	s_add_i32 s2, s3, 2
	v_add_u32_e32 v127, v89, v90
	ds_read_b128 v[100:103], v127 offset:16384
	ds_read_b128 v[106:109], v127 offset:18432
	ds_read_b128 v[110:113], v127 offset:20480
	ds_read_b128 v[114:117], v127 offset:22528
	v_add_u32_e32 v126, v88, v90
	ds_read_b128 v[92:95], v126
	ds_read_b128 v[96:99], v126 offset:2048
	s_add_i32 s3, s3, 4
	s_min_u32 s3, s3, 15
	v_add_u32_e32 v128, v88, v91
	v_add_u32_e32 v130, v89, v91
	s_lshl_b32 s92, s3, 7
	ds_read_b128 v[118:121], v130 offset:18432
	ds_read_b128 v[122:125], v130 offset:20480
	ds_read_b128 v[132:135], v130 offset:22528
	s_waitcnt lgkmcnt(4)
	v_mfma_f32_16x16x32_bf16 v[76:79], v[100:103], v[92:95], v[76:79]
	v_lshl_add_u64 v[44:45], v[80:81], 0, s[92:93]
	v_add_co_u32_e32 v46, vcc, s11, v44
	v_mfma_f32_16x16x32_bf16 v[68:71], v[106:109], v[92:95], v[68:71]
	s_nop 0
	v_addc_co_u32_e32 v47, vcc, 0, v45, vcc
	v_mfma_f32_16x16x32_bf16 v[52:55], v[110:113], v[92:95], v[52:55]
	v_mfma_f32_16x16x32_bf16 v[40:43], v[114:117], v[92:95], v[40:43]
	s_waitcnt lgkmcnt(3)
	v_mfma_f32_16x16x32_bf16 v[92:95], v[100:103], v[96:99], v[36:39]
	s_nop 2
	ds_read_b128 v[36:39], v128
	v_mfma_f32_16x16x32_bf16 v[100:103], v[106:109], v[96:99], v[8:11]
	v_mfma_f32_16x16x32_bf16 v[106:109], v[110:113], v[96:99], v[4:7]
	ds_read_b128 v[110:113], v128 offset:2048
	v_mfma_f32_16x16x32_bf16 v[96:99], v[114:117], v[96:99], v[0:3]
	ds_read_b128 v[114:117], v130 offset:16384
	global_load_dwordx4 v[72:75], v[44:45], off
	s_waitcnt vmcnt(1)
	ds_write_b128 v87, v[12:15] offset:53248
	global_load_dwordx4 v[64:67], v[46:47], off
	v_add_co_u32_e32 v46, vcc, s33, v44
	ds_write_b128 v87, v[16:19] offset:49152
	s_nop 0
	v_addc_co_u32_e32 v47, vcc, 0, v45, vcc
	v_add_co_u32_e32 v44, vcc, s59, v44
	global_load_dwordx4 v[60:63], v[46:47], off
	s_nop 0
	v_addc_co_u32_e32 v45, vcc, 0, v45, vcc
	ds_write_b128 v87, v[20:23] offset:45056
	global_load_dwordx4 v[56:59], v[44:45], off
	v_lshl_add_u64 v[44:45], v[82:83], 0, s[92:93]
	ds_write_b128 v87, v[28:31] offset:32768
	s_waitcnt lgkmcnt(4)
	v_mfma_f32_16x16x32_bf16 v[0:3], v[114:117], v[36:39], v[76:79]
	v_mfma_f32_16x16x32_bf16 v[4:7], v[118:121], v[36:39], v[68:71]
	global_load_dwordx4 v[48:51], v[44:45], off
	v_add_co_u32_e32 v44, vcc, s11, v44
	ds_write_b128 v87, v[32:35] offset:36864
	s_nop 0
	v_addc_co_u32_e32 v45, vcc, 0, v45, vcc
	v_mfma_f32_16x16x32_bf16 v[8:11], v[122:125], v[36:39], v[52:55]
	v_mfma_f32_16x16x32_bf16 v[36:39], v[132:135], v[36:39], v[40:43]
	global_load_dwordx4 v[44:47], v[44:45], off
	ds_write_b128 v87, v[24:27] offset:40960
	v_mfma_f32_16x16x32_bf16 v[40:43], v[114:117], v[110:113], v[92:95]
	v_mfma_f32_16x16x32_bf16 v[52:55], v[118:121], v[110:113], v[100:103]
	v_mfma_f32_16x16x32_bf16 v[68:71], v[122:125], v[110:113], v[106:109]
	v_mfma_f32_16x16x32_bf16 v[76:79], v[132:135], v[110:113], v[96:99]
	s_waitcnt lgkmcnt(0)
	s_barrier
	ds_read_b128 v[100:103], v127 offset:49152
	ds_read_b128 v[106:109], v127 offset:51200
	ds_read_b128 v[110:113], v127 offset:53248
	ds_read_b128 v[114:117], v127 offset:55296
	ds_read_b128 v[92:95], v126 offset:32768
	ds_read_b128 v[96:99], v126 offset:34816
	s_min_u32 s3, s2, 12
	s_lshl_b32 s92, s3, 7
	ds_read_b128 v[118:121], v130 offset:51200
	ds_read_b128 v[122:125], v130 offset:53248
	ds_read_b128 v[132:135], v130 offset:55296
	s_waitcnt lgkmcnt(4)
	v_mfma_f32_16x16x32_bf16 v[0:3], v[100:103], v[92:95], v[0:3]
	v_lshl_add_u64 v[12:13], v[80:81], 0, s[92:93]
	v_add_co_u32_e32 v14, vcc, s11, v12
	v_mfma_f32_16x16x32_bf16 v[4:7], v[106:109], v[92:95], v[4:7]
	s_nop 0
	v_addc_co_u32_e32 v15, vcc, 0, v13, vcc
	v_mfma_f32_16x16x32_bf16 v[8:11], v[110:113], v[92:95], v[8:11]
	v_mfma_f32_16x16x32_bf16 v[36:39], v[114:117], v[92:95], v[36:39]
	s_waitcnt lgkmcnt(3)
	v_mfma_f32_16x16x32_bf16 v[92:95], v[100:103], v[96:99], v[40:43]
	s_nop 2
	ds_read_b128 v[40:43], v128 offset:32768
	v_mfma_f32_16x16x32_bf16 v[100:103], v[106:109], v[96:99], v[52:55]
	v_mfma_f32_16x16x32_bf16 v[106:109], v[110:113], v[96:99], v[68:71]
	ds_read_b128 v[110:113], v128 offset:34816
	v_mfma_f32_16x16x32_bf16 v[96:99], v[114:117], v[96:99], v[76:79]
	ds_read_b128 v[114:117], v130 offset:49152
	global_load_dwordx4 v[28:31], v[12:13], off offset:384
	s_waitcnt vmcnt(1)
	ds_write_b128 v87, v[44:47] offset:20480
	global_load_dwordx4 v[32:35], v[14:15], off offset:384
	v_add_co_u32_e32 v14, vcc, s33, v12
	ds_write_b128 v87, v[48:51] offset:16384
	s_nop 0
	v_addc_co_u32_e32 v15, vcc, 0, v13, vcc
	v_add_co_u32_e32 v12, vcc, s59, v12
	global_load_dwordx4 v[24:27], v[14:15], off offset:384
	s_nop 0
	v_addc_co_u32_e32 v13, vcc, 0, v13, vcc
	ds_write_b128 v87, v[56:59] offset:12288
	global_load_dwordx4 v[20:23], v[12:13], off offset:384
	v_lshl_add_u64 v[12:13], v[82:83], 0, s[92:93]
	ds_write_b128 v87, v[72:75]
	s_waitcnt lgkmcnt(4)
	v_mfma_f32_16x16x32_bf16 v[76:79], v[114:117], v[40:43], v[0:3]
	v_mfma_f32_16x16x32_bf16 v[68:71], v[118:121], v[40:43], v[4:7]
	global_load_dwordx4 v[16:19], v[12:13], off offset:384
	v_add_co_u32_e32 v12, vcc, s11, v12
	ds_write_b128 v87, v[64:67] offset:4096
	s_nop 0
	v_addc_co_u32_e32 v13, vcc, 0, v13, vcc
	v_mfma_f32_16x16x32_bf16 v[52:55], v[122:125], v[40:43], v[8:11]
	v_mfma_f32_16x16x32_bf16 v[40:43], v[132:135], v[40:43], v[36:39]
	global_load_dwordx4 v[12:15], v[12:13], off offset:384
	ds_write_b128 v87, v[60:63] offset:8192
	v_mfma_f32_16x16x32_bf16 v[36:39], v[114:117], v[110:113], v[92:95]
	v_mfma_f32_16x16x32_bf16 v[8:11], v[118:121], v[110:113], v[100:103]
	v_mfma_f32_16x16x32_bf16 v[4:7], v[122:125], v[110:113], v[106:109]
	v_mfma_f32_16x16x32_bf16 v[0:3], v[132:135], v[110:113], v[96:99]
	s_cmp_lt_u32 s2, 12
	s_mov_b32 s3, s2
	s_waitcnt lgkmcnt(0)
	s_barrier
	s_cbranch_scc1 .LBB0_119
.Ltail119:
	s_add_i32 s2, s3, 2
	v_add_u32_e32 v127, v89, v90
	ds_read_b128 v[100:103], v127 offset:16384
	ds_read_b128 v[106:109], v127 offset:18432
	ds_read_b128 v[110:113], v127 offset:20480
	ds_read_b128 v[114:117], v127 offset:22528
	v_add_u32_e32 v126, v88, v90
	ds_read_b128 v[92:95], v126
	ds_read_b128 v[96:99], v126 offset:2048
	s_add_i32 s3, s3, 4
	s_min_u32 s3, s3, 15
	v_add_u32_e32 v128, v88, v91
	v_add_u32_e32 v130, v89, v91
	s_lshl_b32 s92, s3, 7
	ds_read_b128 v[118:121], v130 offset:18432
	ds_read_b128 v[122:125], v130 offset:20480
	ds_read_b128 v[132:135], v130 offset:22528
	s_waitcnt lgkmcnt(4)
	v_mfma_f32_16x16x32_bf16 v[76:79], v[100:103], v[92:95], v[76:79]
	v_lshl_add_u64 v[44:45], v[80:81], 0, s[92:93]
	v_add_co_u32_e32 v46, vcc, s11, v44
	v_mfma_f32_16x16x32_bf16 v[68:71], v[106:109], v[92:95], v[68:71]
	s_nop 0
	v_addc_co_u32_e32 v47, vcc, 0, v45, vcc
	v_mfma_f32_16x16x32_bf16 v[52:55], v[110:113], v[92:95], v[52:55]
	v_mfma_f32_16x16x32_bf16 v[40:43], v[114:117], v[92:95], v[40:43]
	s_waitcnt lgkmcnt(3)
	v_mfma_f32_16x16x32_bf16 v[92:95], v[100:103], v[96:99], v[36:39]
	s_nop 2
	ds_read_b128 v[36:39], v128
	v_mfma_f32_16x16x32_bf16 v[100:103], v[106:109], v[96:99], v[8:11]
	v_mfma_f32_16x16x32_bf16 v[106:109], v[110:113], v[96:99], v[4:7]
	ds_read_b128 v[110:113], v128 offset:2048
	v_mfma_f32_16x16x32_bf16 v[96:99], v[114:117], v[96:99], v[0:3]
	ds_read_b128 v[114:117], v130 offset:16384
	s_waitcnt vmcnt(0)
	ds_write_b128 v87, v[12:15] offset:53248
	v_add_co_u32_e32 v46, vcc, s33, v44
	s_waitcnt vmcnt(1)
	ds_write_b128 v87, v[16:19] offset:49152
	s_nop 0
	v_addc_co_u32_e32 v47, vcc, 0, v45, vcc
	v_add_co_u32_e32 v44, vcc, s59, v44
	s_nop 0
	v_addc_co_u32_e32 v45, vcc, 0, v45, vcc
	s_waitcnt vmcnt(2)
	ds_write_b128 v87, v[20:23] offset:45056
	v_lshl_add_u64 v[44:45], v[82:83], 0, s[92:93]
	s_waitcnt vmcnt(5)
	ds_write_b128 v87, v[28:31] offset:32768
	s_waitcnt lgkmcnt(4)
	v_mfma_f32_16x16x32_bf16 v[0:3], v[114:117], v[36:39], v[76:79]
	v_mfma_f32_16x16x32_bf16 v[4:7], v[118:121], v[36:39], v[68:71]
	v_add_co_u32_e32 v44, vcc, s11, v44
	s_waitcnt vmcnt(4)
	ds_write_b128 v87, v[32:35] offset:36864
	s_nop 0
	v_addc_co_u32_e32 v45, vcc, 0, v45, vcc
	v_mfma_f32_16x16x32_bf16 v[8:11], v[122:125], v[36:39], v[52:55]
	v_mfma_f32_16x16x32_bf16 v[36:39], v[132:135], v[36:39], v[40:43]
	s_waitcnt vmcnt(3)
	ds_write_b128 v87, v[24:27] offset:40960
	v_mfma_f32_16x16x32_bf16 v[40:43], v[114:117], v[110:113], v[92:95]
	v_mfma_f32_16x16x32_bf16 v[52:55], v[118:121], v[110:113], v[100:103]
	v_mfma_f32_16x16x32_bf16 v[68:71], v[122:125], v[110:113], v[106:109]
	v_mfma_f32_16x16x32_bf16 v[76:79], v[132:135], v[110:113], v[96:99]
	s_waitcnt lgkmcnt(0)
	s_barrier
	ds_read_b128 v[100:103], v127 offset:49152
	ds_read_b128 v[106:109], v127 offset:51200
	ds_read_b128 v[110:113], v127 offset:53248
	ds_read_b128 v[114:117], v127 offset:55296
	ds_read_b128 v[92:95], v126 offset:32768
	ds_read_b128 v[96:99], v126 offset:34816
	s_min_u32 s3, s2, 12
	s_lshl_b32 s92, s3, 7
	ds_read_b128 v[118:121], v130 offset:51200
	ds_read_b128 v[122:125], v130 offset:53248
	ds_read_b128 v[132:135], v130 offset:55296
	s_waitcnt lgkmcnt(4)
	v_mfma_f32_16x16x32_bf16 v[0:3], v[100:103], v[92:95], v[0:3]
	v_lshl_add_u64 v[12:13], v[80:81], 0, s[92:93]
	v_add_co_u32_e32 v14, vcc, s11, v12
	v_mfma_f32_16x16x32_bf16 v[4:7], v[106:109], v[92:95], v[4:7]
	s_nop 0
	v_addc_co_u32_e32 v15, vcc, 0, v13, vcc
	v_mfma_f32_16x16x32_bf16 v[8:11], v[110:113], v[92:95], v[8:11]
	v_mfma_f32_16x16x32_bf16 v[36:39], v[114:117], v[92:95], v[36:39]
	s_waitcnt lgkmcnt(3)
	v_mfma_f32_16x16x32_bf16 v[92:95], v[100:103], v[96:99], v[40:43]
	s_nop 2
	ds_read_b128 v[40:43], v128 offset:32768
	v_mfma_f32_16x16x32_bf16 v[100:103], v[106:109], v[96:99], v[52:55]
	v_mfma_f32_16x16x32_bf16 v[106:109], v[110:113], v[96:99], v[68:71]
	ds_read_b128 v[110:113], v128 offset:34816
	v_mfma_f32_16x16x32_bf16 v[96:99], v[114:117], v[96:99], v[76:79]
	ds_read_b128 v[114:117], v130 offset:49152
	v_add_co_u32_e32 v14, vcc, s33, v12
	s_nop 0
	v_addc_co_u32_e32 v15, vcc, 0, v13, vcc
	v_add_co_u32_e32 v12, vcc, s59, v12
	s_nop 0
	v_addc_co_u32_e32 v13, vcc, 0, v13, vcc
	v_lshl_add_u64 v[12:13], v[82:83], 0, s[92:93]
	s_waitcnt lgkmcnt(0)
	v_mfma_f32_16x16x32_bf16 v[76:79], v[114:117], v[40:43], v[0:3]
	v_mfma_f32_16x16x32_bf16 v[68:71], v[118:121], v[40:43], v[4:7]
	v_add_co_u32_e32 v12, vcc, s11, v12
	s_nop 0
	v_addc_co_u32_e32 v13, vcc, 0, v13, vcc
	v_mfma_f32_16x16x32_bf16 v[52:55], v[122:125], v[40:43], v[8:11]
	v_mfma_f32_16x16x32_bf16 v[40:43], v[132:135], v[40:43], v[36:39]
	v_mfma_f32_16x16x32_bf16 v[36:39], v[114:117], v[110:113], v[92:95]
	v_mfma_f32_16x16x32_bf16 v[8:11], v[118:121], v[110:113], v[100:103]
	v_mfma_f32_16x16x32_bf16 v[4:7], v[122:125], v[110:113], v[106:109]
	v_mfma_f32_16x16x32_bf16 v[0:3], v[132:135], v[110:113], v[96:99]
	s_mov_b32 s3, s2
	s_waitcnt lgkmcnt(0)
	s_barrier
	v_readlane_b32 s2, v251, 18
	s_waitcnt vmcnt(1)
	s_nop 0
	v_add_u32_e32 v18, s2, v86
	v_readlane_b32 s2, v251, 19
	s_waitcnt vmcnt(0)
	v_add_u32_e32 v13, 0xffffe000, v18
	v_or_b32_e32 v12, v18, v85
	v_lshl_or_b32 v19, v84, 2, s2
	v_lshrrev_b32_e32 v13, 10, v13
	s_movk_i32 s2, 0x1800
	v_mad_u32_u24 v13, v13, s2, s2
	v_cmp_lt_i32_e32 vcc, s13, v12
	v_lshlrev_b32_e32 v128, 2, v19
	v_readlane_b32 s2, v250, 15
	v_cndmask_b32_e32 v14, 0, v13, vcc
	v_ashrrev_i32_e32 v15, 31, v14
	v_lshlrev_b64 v[24:25], 2, v[14:15]
	v_ashrrev_i32_e32 v13, 31, v12
	v_lshl_add_u64 v[14:15], s[40:41], 0, v[24:25]
	v_lshl_add_u64 v[48:49], v[14:15], 0, v[128:129]
	v_lshlrev_b64 v[14:15], 12, v[12:13]
	v_readlane_b32 s3, v250, 16
	v_lshl_add_u64 v[28:29], s[42:43], 0, v[24:25]
	v_lshlrev_b64 v[32:33], 11, v[12:13]
	v_lshl_add_u64 v[14:15], s[2:3], 0, v[14:15]
	v_lshl_add_u64 v[50:51], v[14:15], 0, v[128:129]
	global_load_dwordx4 v[72:75], v[48:49], off
	global_load_dwordx4 v[80:83], v[48:49], off offset:64
	global_load_dwordx4 v[88:91], v[48:49], off offset:128
	global_load_dwordx4 v[136:139], v[48:49], off offset:192
	global_load_dwordx4 v[194:197], v[50:51], off
	global_load_dwordx4 v[198:201], v[50:51], off offset:64
	global_load_dwordx4 v[202:205], v[50:51], off offset:128
	global_load_dwordx4 v[206:209], v[50:51], off offset:192
	v_add_co_u32_e32 v58, vcc, 0x10000, v50
	s_nop 1
	v_addc_co_u32_e32 v59, vcc, 0, v51, vcc
	global_load_dwordx4 v[210:213], v[58:59], off
	global_load_dwordx4 v[214:217], v[58:59], off offset:64
	global_load_dwordx4 v[218:221], v[58:59], off offset:128
	global_load_dwordx4 v[222:225], v[58:59], off offset:192
	v_readlane_b32 s2, v250, 21
	v_readlane_b32 s3, v250, 22
	v_cmp_eq_u32_e32 vcc, 0, v84
	s_waitcnt vmcnt(4)
	v_pk_fma_f32 v[22:23], v[78:79], v[74:75], v[196:197]
	v_pk_fma_f32 v[20:21], v[76:77], v[72:73], v[194:195]
	global_store_dwordx4 v[50:51], v[20:23], off
	v_lshl_add_u64 v[14:15], v[28:29], 0, v[128:129]
	global_load_dwordx4 v[140:143], v128, s[0:1]
	global_load_dwordx4 v[144:147], v128, s[0:1] offset:64
	global_load_dwordx4 v[148:151], v128, s[0:1] offset:128
	global_load_dwordx4 v[152:155], v128, s[0:1] offset:192
	global_load_dwordx4 v[156:159], v[14:15], off
	global_load_dwordx4 v[160:163], v[14:15], off offset:64
	global_load_dwordx4 v[180:183], v[14:15], off offset:128
	global_load_dwordx4 v[190:193], v[14:15], off offset:192
	v_lshlrev_b32_e32 v16, 1, v19
	v_mov_b32_e32 v17, v129
	v_lshl_add_u64 v[32:33], s[2:3], 0, v[32:33]
	v_lshl_add_u64 v[56:57], v[32:33], 0, v[16:17]
	s_waitcnt vmcnt(0)
	v_pk_mul_f32 v[26:27], v[22:23], v[142:143]
	v_pk_mul_f32 v[24:25], v[20:21], v[140:141]
	s_waitcnt vmcnt(0)
	v_pk_add_f32 v[30:31], v[158:159], 1.0 op_sel_hi:[1,0]
	v_pk_add_f32 v[28:29], v[156:157], 1.0 op_sel_hi:[1,0]
	v_pk_mul_f32 v[26:27], v[26:27], v[30:31]
	v_pk_mul_f32 v[24:25], v[24:25], v[28:29]
	v_and_b32_sdwa v19, v26, v170 dst_sel:DWORD dst_unused:UNUSED_PAD src0_sel:WORD_1 src1_sel:DWORD
	v_and_b32_sdwa v29, v27, v170 dst_sel:DWORD dst_unused:UNUSED_PAD src0_sel:WORD_1 src1_sel:DWORD
	v_and_b32_sdwa v30, v25, v170 dst_sel:DWORD dst_unused:UNUSED_PAD src0_sel:WORD_1 src1_sel:DWORD
	v_and_b32_sdwa v28, v24, v170 dst_sel:DWORD dst_unused:UNUSED_PAD src0_sel:WORD_1 src1_sel:DWORD
	v_add3_u32 v19, v26, v19, s56
	v_add3_u32 v26, v27, v29, s56
	v_add3_u32 v25, v25, v30, s56
	v_add3_u32 v24, v24, v28, s56
	v_and_b32_e32 v26, 0xffff0000, v26
	v_and_b32_e32 v27, 0xffff0000, v25
	v_or_b32_sdwa v25, v26, v19 dst_sel:DWORD dst_unused:UNUSED_PAD src0_sel:DWORD src1_sel:WORD_1
	v_or_b32_sdwa v24, v27, v24 dst_sel:DWORD dst_unused:UNUSED_PAD src0_sel:DWORD src1_sel:WORD_1
	global_store_dwordx2 v[56:57], v[24:25], off
	s_nop 0
	s_waitcnt vmcnt(0)
	v_pk_fma_f32 v[26:27], v[70:71], v[82:83], v[200:201]
	v_pk_fma_f32 v[24:25], v[68:69], v[80:81], v[198:199]
	global_store_dwordx4 v[50:51], v[24:27], off offset:64
	v_pk_mul_f32 v[30:31], v[26:27], v[146:147]
	v_pk_mul_f32 v[28:29], v[24:25], v[144:145]
	v_pk_add_f32 v[34:35], v[162:163], 1.0 op_sel_hi:[1,0]
	v_pk_add_f32 v[32:33], v[160:161], 1.0 op_sel_hi:[1,0]
	v_pk_mul_f32 v[30:31], v[30:31], v[34:35]
	v_pk_mul_f32 v[28:29], v[28:29], v[32:33]
	v_and_b32_sdwa v19, v30, v170 dst_sel:DWORD dst_unused:UNUSED_PAD src0_sel:WORD_1 src1_sel:DWORD
	v_and_b32_sdwa v33, v31, v170 dst_sel:DWORD dst_unused:UNUSED_PAD src0_sel:WORD_1 src1_sel:DWORD
	v_and_b32_sdwa v34, v29, v170 dst_sel:DWORD dst_unused:UNUSED_PAD src0_sel:WORD_1 src1_sel:DWORD
	v_and_b32_sdwa v32, v28, v170 dst_sel:DWORD dst_unused:UNUSED_PAD src0_sel:WORD_1 src1_sel:DWORD
	v_add3_u32 v19, v30, v19, s56
	v_add3_u32 v30, v31, v33, s56
	v_add3_u32 v29, v29, v34, s56
	v_add3_u32 v28, v28, v32, s56
	v_and_b32_e32 v30, 0xffff0000, v30
	v_and_b32_e32 v31, 0xffff0000, v29
	v_or_b32_sdwa v29, v30, v19 dst_sel:DWORD dst_unused:UNUSED_PAD src0_sel:DWORD src1_sel:WORD_1
	v_or_b32_sdwa v28, v31, v28 dst_sel:DWORD dst_unused:UNUSED_PAD src0_sel:DWORD src1_sel:WORD_1
	global_store_dwordx2 v[56:57], v[28:29], off offset:32
	s_nop 0
	v_pk_fma_f32 v[30:31], v[54:55], v[90:91], v[204:205]
	v_pk_fma_f32 v[28:29], v[52:53], v[88:89], v[202:203]
	global_store_dwordx4 v[50:51], v[28:31], off offset:128
	v_pk_mul_f32 v[34:35], v[30:31], v[150:151]
	v_pk_mul_f32 v[32:33], v[28:29], v[148:149]
	v_pk_add_f32 v[46:47], v[182:183], 1.0 op_sel_hi:[1,0]
	v_pk_add_f32 v[44:45], v[180:181], 1.0 op_sel_hi:[1,0]
	v_pk_mul_f32 v[34:35], v[34:35], v[46:47]
	v_pk_mul_f32 v[32:33], v[32:33], v[44:45]
	v_and_b32_sdwa v19, v34, v170 dst_sel:DWORD dst_unused:UNUSED_PAD src0_sel:WORD_1 src1_sel:DWORD
	v_and_b32_sdwa v45, v35, v170 dst_sel:DWORD dst_unused:UNUSED_PAD src0_sel:WORD_1 src1_sel:DWORD
	v_and_b32_sdwa v46, v33, v170 dst_sel:DWORD dst_unused:UNUSED_PAD src0_sel:WORD_1 src1_sel:DWORD
	v_and_b32_sdwa v44, v32, v170 dst_sel:DWORD dst_unused:UNUSED_PAD src0_sel:WORD_1 src1_sel:DWORD
	v_add3_u32 v19, v34, v19, s56
	v_add3_u32 v34, v35, v45, s56
	v_add3_u32 v33, v33, v46, s56
	v_add3_u32 v32, v32, v44, s56
	v_and_b32_e32 v34, 0xffff0000, v34
	v_and_b32_e32 v35, 0xffff0000, v33
	v_or_b32_sdwa v33, v34, v19 dst_sel:DWORD dst_unused:UNUSED_PAD src0_sel:DWORD src1_sel:WORD_1
	v_or_b32_sdwa v32, v35, v32 dst_sel:DWORD dst_unused:UNUSED_PAD src0_sel:DWORD src1_sel:WORD_1
	global_store_dwordx2 v[56:57], v[32:33], off offset:64
	s_nop 0
	v_pk_fma_f32 v[34:35], v[42:43], v[138:139], v[208:209]
	v_pk_fma_f32 v[32:33], v[40:41], v[136:137], v[206:207]
	global_store_dwordx4 v[50:51], v[32:35], off offset:192
	v_mul_f32_e32 v14, v21, v21
	v_mul_f32_e32 v15, v25, v25
	v_fmac_f32_e32 v14, v20, v20
	v_fmac_f32_e32 v15, v24, v24
	v_fmac_f32_e32 v14, v22, v22
	v_fmac_f32_e32 v15, v26, v26
	v_fmac_f32_e32 v14, v23, v23
	v_fmac_f32_e32 v15, v27, v27
	v_add_f32_e32 v14, v14, v15
	v_mul_f32_e32 v15, v29, v29
	v_fmac_f32_e32 v15, v28, v28
	v_fmac_f32_e32 v15, v30, v30
	v_fmac_f32_e32 v15, v31, v31
	v_add_f32_e32 v14, v14, v15
	v_mul_f32_e32 v15, v33, v33
	v_fmac_f32_e32 v15, v32, v32
	v_fmac_f32_e32 v15, v34, v34
	v_fmac_f32_e32 v15, v35, v35
	v_add_f32_e32 v14, v14, v15
	ds_bpermute_b32 v15, v105, v14
	s_waitcnt lgkmcnt(0)
	v_add_f32_e32 v14, v14, v15
	ds_bpermute_b32 v15, v104, v14
	v_pk_mul_f32 v[20:21], v[34:35], v[154:155]
	v_pk_mul_f32 v[22:23], v[32:33], v[152:153]
	v_pk_add_f32 v[24:25], v[192:193], 1.0 op_sel_hi:[1,0]
	v_pk_add_f32 v[26:27], v[190:191], 1.0 op_sel_hi:[1,0]
	v_pk_mul_f32 v[20:21], v[20:21], v[24:25]
	v_pk_mul_f32 v[22:23], v[22:23], v[26:27]
	v_and_b32_sdwa v19, v20, v170 dst_sel:DWORD dst_unused:UNUSED_PAD src0_sel:WORD_1 src1_sel:DWORD
	v_and_b32_sdwa v25, v21, v170 dst_sel:DWORD dst_unused:UNUSED_PAD src0_sel:WORD_1 src1_sel:DWORD
	v_and_b32_sdwa v26, v23, v170 dst_sel:DWORD dst_unused:UNUSED_PAD src0_sel:WORD_1 src1_sel:DWORD
	v_and_b32_sdwa v24, v22, v170 dst_sel:DWORD dst_unused:UNUSED_PAD src0_sel:WORD_1 src1_sel:DWORD
	v_add3_u32 v19, v20, v19, s56
	v_add3_u32 v20, v21, v25, s56
	v_add3_u32 v21, v23, v26, s56
	v_add3_u32 v22, v22, v24, s56
	v_and_b32_e32 v20, 0xffff0000, v20
	v_and_b32_e32 v23, 0xffff0000, v21
	v_or_b32_sdwa v21, v20, v19 dst_sel:DWORD dst_unused:UNUSED_PAD src0_sel:DWORD src1_sel:WORD_1
	v_or_b32_sdwa v20, v23, v22 dst_sel:DWORD dst_unused:UNUSED_PAD src0_sel:DWORD src1_sel:WORD_1
	global_store_dwordx2 v[56:57], v[20:21], off offset:96
	s_and_saveexec_b64 s[2:3], vcc
	s_cbranch_execz .LBB0_122
	v_readlane_b32 s16, v253, 20
	s_add_u32 s24, s26, s16
	s_addc_u32 s25, s27, 0
	v_lshl_add_u64 v[20:21], v[12:13], 2, s[24:25]
	s_waitcnt lgkmcnt(0)
	v_add_f32_e32 v13, v14, v15
	global_store_dword v[20:21], v13, off

.LBB0_236:
	s_add_i32 s24, s25, 2
	v_add_u32_e32 v111, v104, v105
	ds_read_b128 v[136:139], v111 offset:16384
	ds_read_b128 v[140:143], v111 offset:18432
	ds_read_b128 v[144:147], v111 offset:20480
	ds_read_b128 v[148:151], v111 offset:22528
	v_add_u32_e32 v110, v103, v105
	ds_read_b128 v[116:119], v110
	s_add_i32 s25, s25, 4
	ds_read_b128 v[120:123], v110 offset:2048
	s_min_u32 s25, s25, 63
	v_add_u32_e32 v113, v104, v114
	s_lshl_b32 s92, s25, 7
	ds_read_b128 v[124:127], v110 offset:4096
	v_add_u32_e32 v112, v103, v114
	ds_read_b128 v[194:197], v113 offset:16384
	ds_read_b128 v[198:201], v113 offset:18432
	ds_read_b128 v[202:205], v113 offset:20480
	ds_read_b128 v[206:209], v113 offset:22528
	v_lshl_add_u64 v[164:165], v[98:99], 0, s[92:93]
	ds_read_b128 v[132:135], v110 offset:6144
	ds_read_b128 v[152:155], v112
	ds_read_b128 v[156:159], v112 offset:2048
	ds_read_b128 v[160:163], v112 offset:4096
	ds_read_b128 v[190:193], v112 offset:6144
	s_waitcnt lgkmcnt(11)
	v_mfma_f32_16x16x32_bf16 v[92:95], v[136:139], v[116:119], v[92:95]
	v_mfma_f32_16x16x32_bf16 v[56:59], v[140:143], v[116:119], v[56:59]
	v_mfma_f32_16x16x32_bf16 v[52:55], v[144:147], v[116:119], v[52:55]
	v_mfma_f32_16x16x32_bf16 v[48:51], v[148:151], v[116:119], v[48:51]
	global_load_dwordx4 v[116:119], v[164:165], off
	s_waitcnt vmcnt(6)
	ds_write_b128 v109, v[60:63] offset:32768
	v_add_co_u32_e32 v60, vcc, s7, v164
	s_waitcnt lgkmcnt(11)
	v_mfma_f32_16x16x32_bf16 v[44:47], v[136:139], v[120:123], v[44:47]
	v_addc_co_u32_e32 v61, vcc, 0, v165, vcc
	v_mfma_f32_16x16x32_bf16 v[40:43], v[140:143], v[120:123], v[40:43]
	v_mfma_f32_16x16x32_bf16 v[36:39], v[144:147], v[120:123], v[36:39]
	v_mfma_f32_16x16x32_bf16 v[32:35], v[148:151], v[120:123], v[32:35]
	global_load_dwordx4 v[120:123], v[60:61], off
	v_add_co_u32_e32 v60, vcc, s52, v164
	ds_write_b128 v109, v[64:67] offset:36864
	s_nop 0
	v_addc_co_u32_e32 v61, vcc, 0, v165, vcc
	s_waitcnt lgkmcnt(11)
	v_mfma_f32_16x16x32_bf16 v[28:31], v[136:139], v[124:127], v[28:31]
	v_lshl_add_u64 v[64:65], v[100:101], 0, s[92:93]
	v_mfma_f32_16x16x32_bf16 v[24:27], v[140:143], v[124:127], v[24:27]
	v_mfma_f32_16x16x32_bf16 v[20:23], v[144:147], v[124:127], v[20:23]
	v_mfma_f32_16x16x32_bf16 v[16:19], v[148:151], v[124:127], v[16:19]
	global_load_dwordx4 v[124:127], v[60:61], off
	v_add_co_u32_e32 v60, vcc, s34, v164
	ds_write_b128 v109, v[68:71] offset:40960
	s_nop 0
	v_addc_co_u32_e32 v61, vcc, 0, v165, vcc
	v_add_co_u32_e32 v66, vcc, s7, v64
	s_waitcnt lgkmcnt(7)
	v_mfma_f32_16x16x32_bf16 v[12:15], v[136:139], v[132:135], v[12:15]
	v_addc_co_u32_e32 v67, vcc, 0, v65, vcc
	v_mfma_f32_16x16x32_bf16 v[8:11], v[140:143], v[132:135], v[8:11]
	v_mfma_f32_16x16x32_bf16 v[4:7], v[144:147], v[132:135], v[4:7]
	v_mfma_f32_16x16x32_bf16 v[0:3], v[148:151], v[132:135], v[0:3]
	global_load_dwordx4 v[132:135], v[60:61], off
	s_waitcnt vmcnt(7)
	ds_write_b128 v109, v[76:79] offset:45056
	s_waitcnt lgkmcnt(7)
	v_mfma_f32_16x16x32_bf16 v[60:63], v[194:197], v[152:155], v[92:95]
	v_mfma_f32_16x16x32_bf16 v[56:59], v[198:201], v[152:155], v[56:59]
	v_mfma_f32_16x16x32_bf16 v[52:55], v[202:205], v[152:155], v[52:55]
	v_mfma_f32_16x16x32_bf16 v[48:51], v[206:209], v[152:155], v[48:51]
	global_load_dwordx4 v[136:139], v[64:65], off
	ds_write_b128 v109, v[72:75] offset:49152
	s_waitcnt lgkmcnt(7)
	v_mfma_f32_16x16x32_bf16 v[44:47], v[194:197], v[156:159], v[44:47]
	v_mfma_f32_16x16x32_bf16 v[40:43], v[198:201], v[156:159], v[40:43]
	v_mfma_f32_16x16x32_bf16 v[36:39], v[202:205], v[156:159], v[36:39]
	v_mfma_f32_16x16x32_bf16 v[32:35], v[206:209], v[156:159], v[32:35]
	global_load_dwordx4 v[140:143], v[66:67], off
	v_add_co_u32_e32 v66, vcc, s52, v64
	s_waitcnt vmcnt(8)
	ds_write_b128 v109, v[80:83] offset:53248
	v_addc_co_u32_e32 v67, vcc, 0, v65, vcc
	v_add_co_u32_e32 v64, vcc, s34, v64
	s_waitcnt lgkmcnt(7)
	v_mfma_f32_16x16x32_bf16 v[28:31], v[194:197], v[160:163], v[28:31]
	v_addc_co_u32_e32 v65, vcc, 0, v65, vcc
	v_mfma_f32_16x16x32_bf16 v[24:27], v[198:201], v[160:163], v[24:27]
	v_mfma_f32_16x16x32_bf16 v[20:23], v[202:205], v[160:163], v[20:23]
	v_mfma_f32_16x16x32_bf16 v[16:19], v[206:209], v[160:163], v[16:19]
	global_load_dwordx4 v[144:147], v[66:67], off
	s_waitcnt vmcnt(8)
	ds_write_b128 v109, v[84:87] offset:57344
	s_waitcnt lgkmcnt(7)
	v_mfma_f32_16x16x32_bf16 v[12:15], v[194:197], v[190:193], v[12:15]
	v_mfma_f32_16x16x32_bf16 v[8:11], v[198:201], v[190:193], v[8:11]
	v_mfma_f32_16x16x32_bf16 v[4:7], v[202:205], v[190:193], v[4:7]
	v_mfma_f32_16x16x32_bf16 v[0:3], v[206:209], v[190:193], v[0:3]
	global_load_dwordx4 v[148:151], v[64:65], off
	s_waitcnt vmcnt(8)
	ds_write_b128 v109, v[88:91] offset:61440
	s_waitcnt lgkmcnt(0)
	s_barrier
	ds_read_b128 v[80:83], v111 offset:49152
	ds_read_b128 v[84:87], v111 offset:51200
	ds_read_b128 v[88:91], v111 offset:53248
	ds_read_b128 v[92:95], v111 offset:55296
	ds_read_b128 v[64:67], v110 offset:32768
	ds_read_b128 v[68:71], v110 offset:34816
	s_min_u32 s25, s24, 60
	s_lshl_b32 s92, s25, 7
	ds_read_b128 v[72:75], v110 offset:36864
	v_lshl_add_u64 v[164:165], v[98:99], 0, s[92:93]
	ds_read_b128 v[76:79], v110 offset:38912
	ds_read_b128 v[152:155], v112 offset:32768
	ds_read_b128 v[156:159], v112 offset:34816
	ds_read_b128 v[160:163], v112 offset:36864
	ds_read_b128 v[190:193], v112 offset:38912
	ds_read_b128 v[194:197], v113 offset:49152
	ds_read_b128 v[198:201], v113 offset:51200
	ds_read_b128 v[202:205], v113 offset:53248
	ds_read_b128 v[206:209], v113 offset:55296
	s_waitcnt lgkmcnt(11)
	v_mfma_f32_16x16x32_bf16 v[210:213], v[80:83], v[64:67], v[60:63]
	v_mfma_f32_16x16x32_bf16 v[56:59], v[84:87], v[64:67], v[56:59]
	v_mfma_f32_16x16x32_bf16 v[52:55], v[88:91], v[64:67], v[52:55]
	v_mfma_f32_16x16x32_bf16 v[48:51], v[92:95], v[64:67], v[48:51]
	v_add_co_u32_e32 v64, vcc, s7, v164
	global_load_dwordx4 v[60:63], v[164:165], off offset:384
	s_nop 0
	v_addc_co_u32_e32 v65, vcc, 0, v165, vcc
	s_waitcnt vmcnt(8)
	ds_write_b128 v109, v[116:119]
	s_waitcnt lgkmcnt(11)
	v_mfma_f32_16x16x32_bf16 v[44:47], v[80:83], v[68:71], v[44:47]
	v_mfma_f32_16x16x32_bf16 v[40:43], v[84:87], v[68:71], v[40:43]
	v_mfma_f32_16x16x32_bf16 v[36:39], v[88:91], v[68:71], v[36:39]
	v_mfma_f32_16x16x32_bf16 v[32:35], v[92:95], v[68:71], v[32:35]
	v_add_co_u32_e32 v68, vcc, s52, v164
	global_load_dwordx4 v[64:67], v[64:65], off offset:384
	s_nop 0
	v_addc_co_u32_e32 v69, vcc, 0, v165, vcc
	s_waitcnt vmcnt(8)
	ds_write_b128 v109, v[120:123] offset:4096
	s_waitcnt lgkmcnt(11)
	v_mfma_f32_16x16x32_bf16 v[28:31], v[80:83], v[72:75], v[28:31]
	v_mfma_f32_16x16x32_bf16 v[24:27], v[84:87], v[72:75], v[24:27]
	v_mfma_f32_16x16x32_bf16 v[20:23], v[88:91], v[72:75], v[20:23]
	v_mfma_f32_16x16x32_bf16 v[16:19], v[92:95], v[72:75], v[16:19]
	v_add_co_u32_e32 v72, vcc, s34, v164
	global_load_dwordx4 v[68:71], v[68:69], off offset:384
	s_waitcnt vmcnt(8)
	ds_write_b128 v109, v[124:127] offset:8192
	s_waitcnt lgkmcnt(11)
	v_mfma_f32_16x16x32_bf16 v[4:7], v[88:91], v[76:79], v[4:7]
	v_addc_co_u32_e32 v73, vcc, 0, v165, vcc
	v_lshl_add_u64 v[88:89], v[100:101], 0, s[92:93]
	v_mfma_f32_16x16x32_bf16 v[12:15], v[80:83], v[76:79], v[12:15]
	v_add_co_u32_e32 v80, vcc, s7, v88
	v_mfma_f32_16x16x32_bf16 v[8:11], v[84:87], v[76:79], v[8:11]
	s_nop 0
	v_addc_co_u32_e32 v81, vcc, 0, v89, vcc
	v_add_co_u32_e32 v84, vcc, s52, v88
	v_mfma_f32_16x16x32_bf16 v[0:3], v[92:95], v[76:79], v[0:3]
	s_nop 0
	v_addc_co_u32_e32 v85, vcc, 0, v89, vcc
	global_load_dwordx4 v[76:79], v[72:73], off offset:384
	s_waitcnt vmcnt(8)
	ds_write_b128 v109, v[132:135] offset:12288
	s_waitcnt lgkmcnt(7)
	v_mfma_f32_16x16x32_bf16 v[92:95], v[194:197], v[152:155], v[210:213]
	s_waitcnt lgkmcnt(6)
	v_mfma_f32_16x16x32_bf16 v[56:59], v[198:201], v[152:155], v[56:59]
	s_waitcnt lgkmcnt(5)
	v_mfma_f32_16x16x32_bf16 v[52:55], v[202:205], v[152:155], v[52:55]
	s_waitcnt lgkmcnt(4)
	v_mfma_f32_16x16x32_bf16 v[48:51], v[206:209], v[152:155], v[48:51]
	global_load_dwordx4 v[72:75], v[88:89], off offset:384
	v_add_co_u32_e32 v88, vcc, s34, v88
	s_waitcnt vmcnt(8)
	ds_write_b128 v109, v[136:139] offset:16384
	v_addc_co_u32_e32 v89, vcc, 0, v89, vcc
	v_mfma_f32_16x16x32_bf16 v[44:47], v[194:197], v[156:159], v[44:47]
	v_mfma_f32_16x16x32_bf16 v[40:43], v[198:201], v[156:159], v[40:43]
	v_mfma_f32_16x16x32_bf16 v[36:39], v[202:205], v[156:159], v[36:39]
	v_mfma_f32_16x16x32_bf16 v[32:35], v[206:209], v[156:159], v[32:35]
	global_load_dwordx4 v[80:83], v[80:81], off offset:384
	s_waitcnt vmcnt(8)
	ds_write_b128 v109, v[140:143] offset:20480
	v_mfma_f32_16x16x32_bf16 v[28:31], v[194:197], v[160:163], v[28:31]
	v_mfma_f32_16x16x32_bf16 v[24:27], v[198:201], v[160:163], v[24:27]
	v_mfma_f32_16x16x32_bf16 v[20:23], v[202:205], v[160:163], v[20:23]
	v_mfma_f32_16x16x32_bf16 v[16:19], v[206:209], v[160:163], v[16:19]
	global_load_dwordx4 v[84:87], v[84:85], off offset:384
	s_waitcnt vmcnt(8)
	ds_write_b128 v109, v[144:147] offset:24576
	v_mfma_f32_16x16x32_bf16 v[12:15], v[194:197], v[190:193], v[12:15]
	v_mfma_f32_16x16x32_bf16 v[8:11], v[198:201], v[190:193], v[8:11]
	v_mfma_f32_16x16x32_bf16 v[4:7], v[202:205], v[190:193], v[4:7]
	v_mfma_f32_16x16x32_bf16 v[0:3], v[206:209], v[190:193], v[0:3]
	global_load_dwordx4 v[88:91], v[88:89], off offset:384
	s_waitcnt vmcnt(8)
	ds_write_b128 v109, v[148:151] offset:28672
	s_cmp_lt_u32 s24, 60
	s_mov_b32 s25, s24
	s_waitcnt lgkmcnt(0)
	s_barrier
	s_cbranch_scc1 .LBB0_236
.Ltail236:
	s_add_i32 s24, s25, 2
	v_add_u32_e32 v111, v104, v105
	ds_read_b128 v[136:139], v111 offset:16384
	ds_read_b128 v[140:143], v111 offset:18432
	ds_read_b128 v[144:147], v111 offset:20480
	ds_read_b128 v[148:151], v111 offset:22528
	v_add_u32_e32 v110, v103, v105
	ds_read_b128 v[116:119], v110
	s_add_i32 s25, s25, 4
	ds_read_b128 v[120:123], v110 offset:2048
	s_min_u32 s25, s25, 63
	v_add_u32_e32 v113, v104, v114
	s_lshl_b32 s92, s25, 7
	ds_read_b128 v[124:127], v110 offset:4096
	v_add_u32_e32 v112, v103, v114
	ds_read_b128 v[194:197], v113 offset:16384
	ds_read_b128 v[198:201], v113 offset:18432
	ds_read_b128 v[202:205], v113 offset:20480
	ds_read_b128 v[206:209], v113 offset:22528
	v_lshl_add_u64 v[164:165], v[98:99], 0, s[92:93]
	ds_read_b128 v[132:135], v110 offset:6144
	ds_read_b128 v[152:155], v112
	ds_read_b128 v[156:159], v112 offset:2048
	ds_read_b128 v[160:163], v112 offset:4096
	ds_read_b128 v[190:193], v112 offset:6144
	s_waitcnt lgkmcnt(11)
	v_mfma_f32_16x16x32_bf16 v[92:95], v[136:139], v[116:119], v[92:95]
	v_mfma_f32_16x16x32_bf16 v[56:59], v[140:143], v[116:119], v[56:59]
	v_mfma_f32_16x16x32_bf16 v[52:55], v[144:147], v[116:119], v[52:55]
	v_mfma_f32_16x16x32_bf16 v[48:51], v[148:151], v[116:119], v[48:51]
	s_waitcnt vmcnt(7)
	ds_write_b128 v109, v[60:63] offset:32768
	v_add_co_u32_e32 v60, vcc, s7, v164
	s_waitcnt lgkmcnt(11)
	v_mfma_f32_16x16x32_bf16 v[44:47], v[136:139], v[120:123], v[44:47]
	v_addc_co_u32_e32 v61, vcc, 0, v165, vcc
	v_mfma_f32_16x16x32_bf16 v[40:43], v[140:143], v[120:123], v[40:43]
	v_mfma_f32_16x16x32_bf16 v[36:39], v[144:147], v[120:123], v[36:39]
	v_mfma_f32_16x16x32_bf16 v[32:35], v[148:151], v[120:123], v[32:35]
	v_add_co_u32_e32 v60, vcc, s52, v164
	s_waitcnt vmcnt(6)
	ds_write_b128 v109, v[64:67] offset:36864
	s_nop 0
	v_addc_co_u32_e32 v61, vcc, 0, v165, vcc
	s_waitcnt lgkmcnt(11)
	v_mfma_f32_16x16x32_bf16 v[28:31], v[136:139], v[124:127], v[28:31]
	v_lshl_add_u64 v[64:65], v[100:101], 0, s[92:93]
	v_mfma_f32_16x16x32_bf16 v[24:27], v[140:143], v[124:127], v[24:27]
	v_mfma_f32_16x16x32_bf16 v[20:23], v[144:147], v[124:127], v[20:23]
	v_mfma_f32_16x16x32_bf16 v[16:19], v[148:151], v[124:127], v[16:19]
	v_add_co_u32_e32 v60, vcc, s34, v164
	s_waitcnt vmcnt(5)
	ds_write_b128 v109, v[68:71] offset:40960
	s_nop 0
	v_addc_co_u32_e32 v61, vcc, 0, v165, vcc
	v_add_co_u32_e32 v66, vcc, s7, v64
	s_waitcnt lgkmcnt(7)
	v_mfma_f32_16x16x32_bf16 v[12:15], v[136:139], v[132:135], v[12:15]
	v_addc_co_u32_e32 v67, vcc, 0, v65, vcc
	v_mfma_f32_16x16x32_bf16 v[8:11], v[140:143], v[132:135], v[8:11]
	v_mfma_f32_16x16x32_bf16 v[4:7], v[144:147], v[132:135], v[4:7]
	v_mfma_f32_16x16x32_bf16 v[0:3], v[148:151], v[132:135], v[0:3]
	s_waitcnt vmcnt(4)
	ds_write_b128 v109, v[76:79] offset:45056
	s_waitcnt lgkmcnt(7)
	v_mfma_f32_16x16x32_bf16 v[60:63], v[194:197], v[152:155], v[92:95]
	v_mfma_f32_16x16x32_bf16 v[56:59], v[198:201], v[152:155], v[56:59]
	v_mfma_f32_16x16x32_bf16 v[52:55], v[202:205], v[152:155], v[52:55]
	v_mfma_f32_16x16x32_bf16 v[48:51], v[206:209], v[152:155], v[48:51]
	s_waitcnt vmcnt(3)
	ds_write_b128 v109, v[72:75] offset:49152
	s_waitcnt lgkmcnt(7)
	v_mfma_f32_16x16x32_bf16 v[44:47], v[194:197], v[156:159], v[44:47]
	v_mfma_f32_16x16x32_bf16 v[40:43], v[198:201], v[156:159], v[40:43]
	v_mfma_f32_16x16x32_bf16 v[36:39], v[202:205], v[156:159], v[36:39]
	v_mfma_f32_16x16x32_bf16 v[32:35], v[206:209], v[156:159], v[32:35]
	v_add_co_u32_e32 v66, vcc, s52, v64
	s_waitcnt vmcnt(2)
	ds_write_b128 v109, v[80:83] offset:53248
	v_addc_co_u32_e32 v67, vcc, 0, v65, vcc
	v_add_co_u32_e32 v64, vcc, s34, v64
	s_waitcnt lgkmcnt(7)
	v_mfma_f32_16x16x32_bf16 v[28:31], v[194:197], v[160:163], v[28:31]
	v_addc_co_u32_e32 v65, vcc, 0, v65, vcc
	v_mfma_f32_16x16x32_bf16 v[24:27], v[198:201], v[160:163], v[24:27]
	v_mfma_f32_16x16x32_bf16 v[20:23], v[202:205], v[160:163], v[20:23]
	v_mfma_f32_16x16x32_bf16 v[16:19], v[206:209], v[160:163], v[16:19]
	s_waitcnt vmcnt(1)
	ds_write_b128 v109, v[84:87] offset:57344
	s_waitcnt lgkmcnt(7)
	v_mfma_f32_16x16x32_bf16 v[12:15], v[194:197], v[190:193], v[12:15]
	v_mfma_f32_16x16x32_bf16 v[8:11], v[198:201], v[190:193], v[8:11]
	v_mfma_f32_16x16x32_bf16 v[4:7], v[202:205], v[190:193], v[4:7]
	v_mfma_f32_16x16x32_bf16 v[0:3], v[206:209], v[190:193], v[0:3]
	s_waitcnt vmcnt(0)
	ds_write_b128 v109, v[88:91] offset:61440
	s_waitcnt lgkmcnt(0)
	s_barrier
	ds_read_b128 v[80:83], v111 offset:49152
	ds_read_b128 v[84:87], v111 offset:51200
	ds_read_b128 v[88:91], v111 offset:53248
	ds_read_b128 v[92:95], v111 offset:55296
	ds_read_b128 v[64:67], v110 offset:32768
	ds_read_b128 v[68:71], v110 offset:34816
	s_min_u32 s25, s24, 60
	s_lshl_b32 s92, s25, 7
	ds_read_b128 v[72:75], v110 offset:36864
	v_lshl_add_u64 v[164:165], v[98:99], 0, s[92:93]
	ds_read_b128 v[76:79], v110 offset:38912
	ds_read_b128 v[152:155], v112 offset:32768
	ds_read_b128 v[156:159], v112 offset:34816
	ds_read_b128 v[160:163], v112 offset:36864
	ds_read_b128 v[190:193], v112 offset:38912
	ds_read_b128 v[194:197], v113 offset:49152
	ds_read_b128 v[198:201], v113 offset:51200
	ds_read_b128 v[202:205], v113 offset:53248
	ds_read_b128 v[206:209], v113 offset:55296
	s_waitcnt lgkmcnt(11)
	v_mfma_f32_16x16x32_bf16 v[210:213], v[80:83], v[64:67], v[60:63]
	v_mfma_f32_16x16x32_bf16 v[56:59], v[84:87], v[64:67], v[56:59]
	v_mfma_f32_16x16x32_bf16 v[52:55], v[88:91], v[64:67], v[52:55]
	v_mfma_f32_16x16x32_bf16 v[48:51], v[92:95], v[64:67], v[48:51]
	v_add_co_u32_e32 v64, vcc, s7, v164
	s_nop 0
	v_addc_co_u32_e32 v65, vcc, 0, v165, vcc
	s_waitcnt lgkmcnt(10)
	v_mfma_f32_16x16x32_bf16 v[44:47], v[80:83], v[68:71], v[44:47]
	v_mfma_f32_16x16x32_bf16 v[40:43], v[84:87], v[68:71], v[40:43]
	v_mfma_f32_16x16x32_bf16 v[36:39], v[88:91], v[68:71], v[36:39]
	v_mfma_f32_16x16x32_bf16 v[32:35], v[92:95], v[68:71], v[32:35]
	v_add_co_u32_e32 v68, vcc, s52, v164
	s_nop 0
	v_addc_co_u32_e32 v69, vcc, 0, v165, vcc
	s_waitcnt lgkmcnt(9)
	v_mfma_f32_16x16x32_bf16 v[28:31], v[80:83], v[72:75], v[28:31]
	v_mfma_f32_16x16x32_bf16 v[24:27], v[84:87], v[72:75], v[24:27]
	v_mfma_f32_16x16x32_bf16 v[20:23], v[88:91], v[72:75], v[20:23]
	v_mfma_f32_16x16x32_bf16 v[16:19], v[92:95], v[72:75], v[16:19]
	v_add_co_u32_e32 v72, vcc, s34, v164
	s_waitcnt lgkmcnt(8)
	v_mfma_f32_16x16x32_bf16 v[4:7], v[88:91], v[76:79], v[4:7]
	v_addc_co_u32_e32 v73, vcc, 0, v165, vcc
	v_lshl_add_u64 v[88:89], v[100:101], 0, s[92:93]
	v_mfma_f32_16x16x32_bf16 v[12:15], v[80:83], v[76:79], v[12:15]
	v_add_co_u32_e32 v80, vcc, s7, v88
	v_mfma_f32_16x16x32_bf16 v[8:11], v[84:87], v[76:79], v[8:11]
	s_nop 0
	v_addc_co_u32_e32 v81, vcc, 0, v89, vcc
	v_add_co_u32_e32 v84, vcc, s52, v88
	v_mfma_f32_16x16x32_bf16 v[0:3], v[92:95], v[76:79], v[0:3]
	s_nop 0
	v_addc_co_u32_e32 v85, vcc, 0, v89, vcc
	s_waitcnt lgkmcnt(3)
	v_mfma_f32_16x16x32_bf16 v[92:95], v[194:197], v[152:155], v[210:213]
	s_waitcnt lgkmcnt(2)
	v_mfma_f32_16x16x32_bf16 v[56:59], v[198:201], v[152:155], v[56:59]
	s_waitcnt lgkmcnt(1)
	v_mfma_f32_16x16x32_bf16 v[52:55], v[202:205], v[152:155], v[52:55]
	s_waitcnt lgkmcnt(0)
	v_mfma_f32_16x16x32_bf16 v[48:51], v[206:209], v[152:155], v[48:51]
	v_add_co_u32_e32 v88, vcc, s34, v88
	v_addc_co_u32_e32 v89, vcc, 0, v89, vcc
	v_mfma_f32_16x16x32_bf16 v[44:47], v[194:197], v[156:159], v[44:47]
	v_mfma_f32_16x16x32_bf16 v[40:43], v[198:201], v[156:159], v[40:43]
	v_mfma_f32_16x16x32_bf16 v[36:39], v[202:205], v[156:159], v[36:39]
	v_mfma_f32_16x16x32_bf16 v[32:35], v[206:209], v[156:159], v[32:35]
	v_mfma_f32_16x16x32_bf16 v[28:31], v[194:197], v[160:163], v[28:31]
	v_mfma_f32_16x16x32_bf16 v[24:27], v[198:201], v[160:163], v[24:27]
	v_mfma_f32_16x16x32_bf16 v[20:23], v[202:205], v[160:163], v[20:23]
	v_mfma_f32_16x16x32_bf16 v[16:19], v[206:209], v[160:163], v[16:19]
	v_mfma_f32_16x16x32_bf16 v[12:15], v[194:197], v[190:193], v[12:15]
	v_mfma_f32_16x16x32_bf16 v[8:11], v[198:201], v[190:193], v[8:11]
	v_mfma_f32_16x16x32_bf16 v[4:7], v[202:205], v[190:193], v[4:7]
	v_mfma_f32_16x16x32_bf16 v[0:3], v[206:209], v[190:193], v[0:3]
	s_mov_b32 s25, s24
	s_waitcnt lgkmcnt(0)
	s_barrier
	s_add_i32 s26, s69, 1
	v_readlane_b32 s16, v251, 5
	s_and_b64 s[24:25], s[8:9], exec
	s_mul_i32 s25, s69, 0x12000
	s_waitcnt vmcnt(2)
	v_add_u32_e32 v80, s16, v108
	v_readlane_b32 s28, v250, 25
	v_add_u32_e32 v60, 0xffffe000, v80
	s_cselect_b32 s24, 3, s26
	v_readlane_b32 s29, v250, 26
	s_add_u32 s25, s28, s25
	v_or_b32_e32 v70, v80, v107
	v_lshlrev_b32_e32 v114, 6, v102
	v_readlane_b32 s16, v251, 6
	v_lshrrev_b32_e32 v60, 10, v60
	s_movk_i32 s5, 0x1800
	s_addc_u32 s26, s29, 0
	v_or_b32_e32 v81, s16, v114
	v_lshlrev_b32_e32 v115, 2, v97
	v_mad_u32_u24 v60, v60, s5, s5
	v_cmp_lt_i32_e32 vcc, s13, v70
	s_add_u32 s40, s25, 0x5000
	v_or_b32_e32 v64, v81, v115
	v_cndmask_b32_e32 v76, 0, v60, vcc
	s_addc_u32 s41, s26, 0
	v_ashrrev_i32_e32 v77, 31, v76
	v_ashrrev_i32_e32 v65, 31, v64
	v_ashrrev_i32_e32 v71, 31, v70
	v_lshl_add_u64 v[60:61], v[76:77], 2, s[40:41]
	v_lshlrev_b64 v[66:67], 2, v[64:65]
	v_readlane_b32 s16, v250, 15
	v_lshl_add_u64 v[74:75], v[60:61], 0, v[66:67]
	v_lshlrev_b64 v[60:61], 12, v[70:71]
	v_readlane_b32 s17, v250, 16
	v_readlane_b32 s68, v250, 41
	s_mul_i32 s25, s24, 0x12000
	v_lshl_add_u64 v[60:61], s[16:17], 0, v[60:61]
	v_lshl_add_u64 v[72:73], v[60:61], 0, v[66:67]
	global_load_dwordx4 v[116:119], v[74:75], off
	global_load_dwordx4 v[120:123], v[74:75], off offset:64
	global_load_dwordx4 v[124:127], v[74:75], off offset:128
	global_load_dwordx4 v[132:135], v[74:75], off offset:192
	global_load_dwordx4 v[190:193], v[72:73], off
	global_load_dwordx4 v[194:197], v[72:73], off offset:64
	global_load_dwordx4 v[198:201], v[72:73], off offset:128
	global_load_dwordx4 v[202:205], v[72:73], off offset:192
	v_add_co_u32_e32 v164, vcc, 0x10000, v72
	s_nop 1
	v_addc_co_u32_e32 v165, vcc, 0, v73, vcc
	v_add_co_u32_e32 v222, vcc, 0x20000, v72
	s_nop 1
	v_addc_co_u32_e32 v223, vcc, 0, v73, vcc
	v_add_co_u32_e32 v224, vcc, 0x30000, v72
	s_nop 1
	v_addc_co_u32_e32 v225, vcc, 0, v73, vcc
	global_load_dwordx4 v[206:209], v[164:165], off
	global_load_dwordx4 v[210:213], v[164:165], off offset:64
	global_load_dwordx4 v[214:217], v[164:165], off offset:128
	global_load_dwordx4 v[218:221], v[164:165], off offset:192
	s_lshl_b32 s24, s24, 12
	v_readlane_b32 s70, v250, 43
	v_readlane_b32 s71, v250, 44
	s_add_u32 s26, s70, s24
	s_addc_u32 s27, s71, 0
	s_add_u32 s24, s28, s25
	s_addc_u32 s25, s29, 0
	s_add_u32 s42, s24, 0x1000
	v_cndmask_b32_e64 v68, 0, 1, s[2:3]
	s_addc_u32 s43, s25, 0
	s_andn2_b64 vcc, exec, s[2:3]
	v_readlane_b32 s2, v250, 21
	s_waitcnt vmcnt(3)
	v_lshlrev_b64 v[86:87], 10, v[70:71]
	v_readlane_b32 s3, v250, 22
	v_cmp_ne_u32_e64 s[36:37], 1, v68
	v_lshl_add_u64 v[68:69], s[26:27], 0, v[66:67]
	v_lshl_add_u64 v[78:79], v[76:77], 2, s[42:43]
	v_lshl_add_u64 v[76:77], v[86:87], 1, s[2:3]
	v_readlane_b32 s69, v250, 42
	v_readlane_b32 s72, v250, 45
	v_readlane_b32 s73, v250, 46
	v_readlane_b32 s74, v250, 47
	v_readlane_b32 s75, v250, 48
	v_readlane_b32 s76, v250, 49
	v_readlane_b32 s77, v250, 50
	v_readlane_b32 s78, v250, 51
	v_readlane_b32 s79, v250, 52
	v_readlane_b32 s80, v250, 53
	v_readlane_b32 s81, v250, 54
	v_readlane_b32 s82, v250, 55
	v_readlane_b32 s83, v250, 56
	s_waitcnt vmcnt(4)
	v_pk_fma_f32 v[62:63], v[94:95], v[118:119], v[192:193]
	v_pk_fma_f32 v[60:61], v[92:93], v[116:117], v[190:191]
	global_store_dwordx4 v[72:73], v[60:63], off
	s_cbranch_vccnz .LBB0_239
	v_lshl_add_u64 v[86:87], v[78:79], 0, v[66:67]
	global_load_dwordx4 v[136:139], v[68:69], off
	global_load_dwordx4 v[140:143], v[68:69], off offset:64
	global_load_dwordx4 v[144:147], v[68:69], off offset:128
	global_load_dwordx4 v[148:151], v[68:69], off offset:192
	s_waitcnt vmcnt(0)
	v_pk_mul_f32 v[84:85], v[62:63], v[138:139]
	global_load_dwordx4 v[152:155], v[86:87], off
	global_load_dwordx4 v[156:159], v[86:87], off offset:64
	global_load_dwordx4 v[160:163], v[86:87], off offset:128
	global_load_dwordx4 v[180:183], v[86:87], off offset:192
	v_pk_mul_f32 v[82:83], v[60:61], v[136:137]
	s_waitcnt vmcnt(0)
	v_pk_add_f32 v[88:89], v[154:155], 1.0 op_sel_hi:[1,0]
	v_pk_add_f32 v[86:87], v[152:153], 1.0 op_sel_hi:[1,0]
	v_pk_mul_f32 v[84:85], v[84:85], v[88:89]
	v_pk_mul_f32 v[82:83], v[82:83], v[86:87]
	v_and_b32_sdwa v88, v84, v170 dst_sel:DWORD dst_unused:UNUSED_PAD src0_sel:WORD_1 src1_sel:DWORD
	v_and_b32_sdwa v89, v82, v170 dst_sel:DWORD dst_unused:UNUSED_PAD src0_sel:WORD_1 src1_sel:DWORD
	v_add3_u32 v82, v82, v89, s56
	v_add3_u32 v84, v84, v88, s56
	v_and_b32_sdwa v88, v85, v170 dst_sel:DWORD dst_unused:UNUSED_PAD src0_sel:WORD_1 src1_sel:DWORD
	v_and_b32_sdwa v89, v83, v170 dst_sel:DWORD dst_unused:UNUSED_PAD src0_sel:WORD_1 src1_sel:DWORD
	v_add3_u32 v85, v85, v88, s56
	v_add3_u32 v83, v83, v89, s56
	v_and_b32_e32 v85, 0xffff0000, v85
	v_and_b32_e32 v88, 0xffff0000, v83
	v_lshl_add_u64 v[86:87], v[64:65], 1, v[76:77]
	v_or_b32_sdwa v83, v85, v84 dst_sel:DWORD dst_unused:UNUSED_PAD src0_sel:DWORD src1_sel:WORD_1
	v_or_b32_sdwa v82, v88, v82 dst_sel:DWORD dst_unused:UNUSED_PAD src0_sel:DWORD src1_sel:WORD_1
	global_store_dwordx2 v[86:87], v[82:83], off

.LBB0_282:
	s_add_i32 s25, s28, 2
	ds_read_b128 v[136:139], v111 offset:16384
	ds_read_b128 v[140:143], v111 offset:18432
	ds_read_b128 v[144:147], v111 offset:20480
	ds_read_b128 v[148:151], v111 offset:22528
	ds_read_b128 v[116:119], v110
	s_add_i32 s28, s28, 4
	ds_read_b128 v[120:123], v110 offset:2048
	s_min_u32 s28, s28, 63
	s_lshl_b32 s92, s28, 7
	ds_read_b128 v[124:127], v110 offset:4096
	ds_read_b128 v[194:197], v113 offset:16384
	ds_read_b128 v[198:201], v113 offset:18432
	ds_read_b128 v[202:205], v113 offset:20480
	ds_read_b128 v[206:209], v113 offset:22528
	v_lshl_add_u64 v[164:165], v[100:101], 0, s[92:93]
	ds_read_b128 v[132:135], v110 offset:6144
	ds_read_b128 v[152:155], v112
	ds_read_b128 v[156:159], v112 offset:2048
	ds_read_b128 v[160:163], v112 offset:4096
	ds_read_b128 v[190:193], v112 offset:6144
	s_waitcnt lgkmcnt(11)
	v_mfma_f32_16x16x32_bf16 v[92:95], v[136:139], v[116:119], v[92:95]
	v_mfma_f32_16x16x32_bf16 v[56:59], v[140:143], v[116:119], v[56:59]
	v_mfma_f32_16x16x32_bf16 v[52:55], v[144:147], v[116:119], v[52:55]
	v_mfma_f32_16x16x32_bf16 v[48:51], v[148:151], v[116:119], v[48:51]
	global_load_dwordx4 v[116:119], v[164:165], off
	s_waitcnt vmcnt(6)
	ds_write_b128 v109, v[60:63] offset:32768
	v_add_co_u32_e32 v60, vcc, s7, v164
	s_waitcnt lgkmcnt(11)
	v_mfma_f32_16x16x32_bf16 v[44:47], v[136:139], v[120:123], v[44:47]
	v_addc_co_u32_e32 v61, vcc, 0, v165, vcc
	v_mfma_f32_16x16x32_bf16 v[40:43], v[140:143], v[120:123], v[40:43]
	v_mfma_f32_16x16x32_bf16 v[36:39], v[144:147], v[120:123], v[36:39]
	v_mfma_f32_16x16x32_bf16 v[32:35], v[148:151], v[120:123], v[32:35]
	global_load_dwordx4 v[120:123], v[60:61], off
	v_add_co_u32_e32 v60, vcc, s52, v164
	ds_write_b128 v109, v[64:67] offset:36864
	s_nop 0
	v_addc_co_u32_e32 v61, vcc, 0, v165, vcc
	s_waitcnt lgkmcnt(11)
	v_mfma_f32_16x16x32_bf16 v[28:31], v[136:139], v[124:127], v[28:31]
	v_lshl_add_u64 v[64:65], v[102:103], 0, s[92:93]
	v_mfma_f32_16x16x32_bf16 v[24:27], v[140:143], v[124:127], v[24:27]
	v_mfma_f32_16x16x32_bf16 v[20:23], v[144:147], v[124:127], v[20:23]
	v_mfma_f32_16x16x32_bf16 v[16:19], v[148:151], v[124:127], v[16:19]
	global_load_dwordx4 v[124:127], v[60:61], off
	v_add_co_u32_e32 v60, vcc, s34, v164
	ds_write_b128 v109, v[68:71] offset:40960
	s_nop 0
	v_addc_co_u32_e32 v61, vcc, 0, v165, vcc
	v_add_co_u32_e32 v66, vcc, s7, v64
	s_waitcnt lgkmcnt(7)
	v_mfma_f32_16x16x32_bf16 v[12:15], v[136:139], v[132:135], v[12:15]
	v_addc_co_u32_e32 v67, vcc, 0, v65, vcc
	v_mfma_f32_16x16x32_bf16 v[8:11], v[140:143], v[132:135], v[8:11]
	v_mfma_f32_16x16x32_bf16 v[4:7], v[144:147], v[132:135], v[4:7]
	v_mfma_f32_16x16x32_bf16 v[0:3], v[148:151], v[132:135], v[0:3]
	global_load_dwordx4 v[132:135], v[60:61], off
	s_waitcnt vmcnt(7)
	ds_write_b128 v109, v[76:79] offset:45056
	s_waitcnt lgkmcnt(7)
	v_mfma_f32_16x16x32_bf16 v[60:63], v[194:197], v[152:155], v[92:95]
	v_mfma_f32_16x16x32_bf16 v[56:59], v[198:201], v[152:155], v[56:59]
	v_mfma_f32_16x16x32_bf16 v[52:55], v[202:205], v[152:155], v[52:55]
	v_mfma_f32_16x16x32_bf16 v[48:51], v[206:209], v[152:155], v[48:51]
	global_load_dwordx4 v[136:139], v[64:65], off
	ds_write_b128 v109, v[72:75] offset:49152
	s_waitcnt lgkmcnt(7)
	v_mfma_f32_16x16x32_bf16 v[44:47], v[194:197], v[156:159], v[44:47]
	v_mfma_f32_16x16x32_bf16 v[40:43], v[198:201], v[156:159], v[40:43]
	v_mfma_f32_16x16x32_bf16 v[36:39], v[202:205], v[156:159], v[36:39]
	v_mfma_f32_16x16x32_bf16 v[32:35], v[206:209], v[156:159], v[32:35]
	global_load_dwordx4 v[140:143], v[66:67], off
	v_add_co_u32_e32 v66, vcc, s52, v64
	s_waitcnt vmcnt(8)
	ds_write_b128 v109, v[80:83] offset:53248
	v_addc_co_u32_e32 v67, vcc, 0, v65, vcc
	v_add_co_u32_e32 v64, vcc, s34, v64
	s_waitcnt lgkmcnt(7)
	v_mfma_f32_16x16x32_bf16 v[28:31], v[194:197], v[160:163], v[28:31]
	v_addc_co_u32_e32 v65, vcc, 0, v65, vcc
	v_mfma_f32_16x16x32_bf16 v[24:27], v[198:201], v[160:163], v[24:27]
	v_mfma_f32_16x16x32_bf16 v[20:23], v[202:205], v[160:163], v[20:23]
	v_mfma_f32_16x16x32_bf16 v[16:19], v[206:209], v[160:163], v[16:19]
	global_load_dwordx4 v[144:147], v[66:67], off
	s_waitcnt vmcnt(8)
	ds_write_b128 v109, v[84:87] offset:57344
	s_waitcnt lgkmcnt(7)
	v_mfma_f32_16x16x32_bf16 v[12:15], v[194:197], v[190:193], v[12:15]
	v_mfma_f32_16x16x32_bf16 v[8:11], v[198:201], v[190:193], v[8:11]
	v_mfma_f32_16x16x32_bf16 v[4:7], v[202:205], v[190:193], v[4:7]
	v_mfma_f32_16x16x32_bf16 v[0:3], v[206:209], v[190:193], v[0:3]
	global_load_dwordx4 v[148:151], v[64:65], off
	s_waitcnt vmcnt(8)
	ds_write_b128 v109, v[88:91] offset:61440
	s_waitcnt lgkmcnt(0)
	s_barrier
	ds_read_b128 v[80:83], v111 offset:49152
	ds_read_b128 v[84:87], v111 offset:51200
	ds_read_b128 v[88:91], v111 offset:53248
	ds_read_b128 v[92:95], v111 offset:55296
	ds_read_b128 v[64:67], v110 offset:32768
	ds_read_b128 v[68:71], v110 offset:34816
	s_min_u32 s28, s25, 60
	s_lshl_b32 s92, s28, 7
	ds_read_b128 v[72:75], v110 offset:36864
	v_lshl_add_u64 v[164:165], v[100:101], 0, s[92:93]
	ds_read_b128 v[76:79], v110 offset:38912
	ds_read_b128 v[152:155], v112 offset:32768
	ds_read_b128 v[156:159], v112 offset:34816
	ds_read_b128 v[160:163], v112 offset:36864
	ds_read_b128 v[190:193], v112 offset:38912
	ds_read_b128 v[194:197], v113 offset:49152
	ds_read_b128 v[198:201], v113 offset:51200
	ds_read_b128 v[202:205], v113 offset:53248
	ds_read_b128 v[206:209], v113 offset:55296
	s_waitcnt lgkmcnt(11)
	v_mfma_f32_16x16x32_bf16 v[210:213], v[80:83], v[64:67], v[60:63]
	v_mfma_f32_16x16x32_bf16 v[56:59], v[84:87], v[64:67], v[56:59]
	v_mfma_f32_16x16x32_bf16 v[52:55], v[88:91], v[64:67], v[52:55]
	v_mfma_f32_16x16x32_bf16 v[48:51], v[92:95], v[64:67], v[48:51]
	v_add_co_u32_e32 v64, vcc, s7, v164
	global_load_dwordx4 v[60:63], v[164:165], off offset:384
	s_nop 0
	v_addc_co_u32_e32 v65, vcc, 0, v165, vcc
	s_waitcnt vmcnt(8)
	ds_write_b128 v109, v[116:119]
	s_waitcnt lgkmcnt(11)
	v_mfma_f32_16x16x32_bf16 v[44:47], v[80:83], v[68:71], v[44:47]
	v_mfma_f32_16x16x32_bf16 v[40:43], v[84:87], v[68:71], v[40:43]
	v_mfma_f32_16x16x32_bf16 v[36:39], v[88:91], v[68:71], v[36:39]
	v_mfma_f32_16x16x32_bf16 v[32:35], v[92:95], v[68:71], v[32:35]
	v_add_co_u32_e32 v68, vcc, s52, v164
	global_load_dwordx4 v[64:67], v[64:65], off offset:384
	s_nop 0
	v_addc_co_u32_e32 v69, vcc, 0, v165, vcc
	s_waitcnt vmcnt(8)
	ds_write_b128 v109, v[120:123] offset:4096
	s_waitcnt lgkmcnt(11)
	v_mfma_f32_16x16x32_bf16 v[28:31], v[80:83], v[72:75], v[28:31]
	v_mfma_f32_16x16x32_bf16 v[24:27], v[84:87], v[72:75], v[24:27]
	v_mfma_f32_16x16x32_bf16 v[20:23], v[88:91], v[72:75], v[20:23]
	v_mfma_f32_16x16x32_bf16 v[16:19], v[92:95], v[72:75], v[16:19]
	v_add_co_u32_e32 v72, vcc, s34, v164
	global_load_dwordx4 v[68:71], v[68:69], off offset:384
	s_waitcnt vmcnt(8)
	ds_write_b128 v109, v[124:127] offset:8192
	s_waitcnt lgkmcnt(11)
	v_mfma_f32_16x16x32_bf16 v[4:7], v[88:91], v[76:79], v[4:7]
	v_addc_co_u32_e32 v73, vcc, 0, v165, vcc
	v_lshl_add_u64 v[88:89], v[102:103], 0, s[92:93]
	v_mfma_f32_16x16x32_bf16 v[12:15], v[80:83], v[76:79], v[12:15]
	v_add_co_u32_e32 v80, vcc, s7, v88
	v_mfma_f32_16x16x32_bf16 v[8:11], v[84:87], v[76:79], v[8:11]
	s_nop 0
	v_addc_co_u32_e32 v81, vcc, 0, v89, vcc
	v_add_co_u32_e32 v84, vcc, s52, v88
	v_mfma_f32_16x16x32_bf16 v[0:3], v[92:95], v[76:79], v[0:3]
	s_nop 0
	v_addc_co_u32_e32 v85, vcc, 0, v89, vcc
	global_load_dwordx4 v[76:79], v[72:73], off offset:384
	s_waitcnt vmcnt(8)
	ds_write_b128 v109, v[132:135] offset:12288
	s_waitcnt lgkmcnt(7)
	v_mfma_f32_16x16x32_bf16 v[92:95], v[194:197], v[152:155], v[210:213]
	s_waitcnt lgkmcnt(6)
	v_mfma_f32_16x16x32_bf16 v[56:59], v[198:201], v[152:155], v[56:59]
	s_waitcnt lgkmcnt(5)
	v_mfma_f32_16x16x32_bf16 v[52:55], v[202:205], v[152:155], v[52:55]
	s_waitcnt lgkmcnt(4)
	v_mfma_f32_16x16x32_bf16 v[48:51], v[206:209], v[152:155], v[48:51]
	global_load_dwordx4 v[72:75], v[88:89], off offset:384
	v_add_co_u32_e32 v88, vcc, s34, v88
	s_waitcnt vmcnt(8)
	ds_write_b128 v109, v[136:139] offset:16384
	v_addc_co_u32_e32 v89, vcc, 0, v89, vcc
	v_mfma_f32_16x16x32_bf16 v[44:47], v[194:197], v[156:159], v[44:47]
	v_mfma_f32_16x16x32_bf16 v[40:43], v[198:201], v[156:159], v[40:43]
	v_mfma_f32_16x16x32_bf16 v[36:39], v[202:205], v[156:159], v[36:39]
	v_mfma_f32_16x16x32_bf16 v[32:35], v[206:209], v[156:159], v[32:35]
	global_load_dwordx4 v[80:83], v[80:81], off offset:384
	s_waitcnt vmcnt(8)
	ds_write_b128 v109, v[140:143] offset:20480
	v_mfma_f32_16x16x32_bf16 v[28:31], v[194:197], v[160:163], v[28:31]
	v_mfma_f32_16x16x32_bf16 v[24:27], v[198:201], v[160:163], v[24:27]
	v_mfma_f32_16x16x32_bf16 v[20:23], v[202:205], v[160:163], v[20:23]
	v_mfma_f32_16x16x32_bf16 v[16:19], v[206:209], v[160:163], v[16:19]
	global_load_dwordx4 v[84:87], v[84:85], off offset:384
	s_waitcnt vmcnt(8)
	ds_write_b128 v109, v[144:147] offset:24576
	v_mfma_f32_16x16x32_bf16 v[12:15], v[194:197], v[190:193], v[12:15]
	v_mfma_f32_16x16x32_bf16 v[8:11], v[198:201], v[190:193], v[8:11]
	v_mfma_f32_16x16x32_bf16 v[4:7], v[202:205], v[190:193], v[4:7]
	v_mfma_f32_16x16x32_bf16 v[0:3], v[206:209], v[190:193], v[0:3]
	global_load_dwordx4 v[88:91], v[88:89], off offset:384
	s_waitcnt vmcnt(8)
	ds_write_b128 v109, v[148:151] offset:28672
	s_cmp_lt_u32 s25, 60
	s_mov_b32 s28, s25
	s_waitcnt lgkmcnt(0)
	s_barrier
	s_cbranch_scc1 .LBB0_282
.Ltail282:
	s_add_i32 s25, s28, 2
	ds_read_b128 v[136:139], v111 offset:16384
	ds_read_b128 v[140:143], v111 offset:18432
	ds_read_b128 v[144:147], v111 offset:20480
	ds_read_b128 v[148:151], v111 offset:22528
	ds_read_b128 v[116:119], v110
	s_add_i32 s28, s28, 4
	ds_read_b128 v[120:123], v110 offset:2048
	s_min_u32 s28, s28, 63
	s_lshl_b32 s92, s28, 7
	ds_read_b128 v[124:127], v110 offset:4096
	ds_read_b128 v[194:197], v113 offset:16384
	ds_read_b128 v[198:201], v113 offset:18432
	ds_read_b128 v[202:205], v113 offset:20480
	ds_read_b128 v[206:209], v113 offset:22528
	v_lshl_add_u64 v[164:165], v[100:101], 0, s[92:93]
	ds_read_b128 v[132:135], v110 offset:6144
	ds_read_b128 v[152:155], v112
	ds_read_b128 v[156:159], v112 offset:2048
	ds_read_b128 v[160:163], v112 offset:4096
	ds_read_b128 v[190:193], v112 offset:6144
	s_waitcnt lgkmcnt(11)
	v_mfma_f32_16x16x32_bf16 v[92:95], v[136:139], v[116:119], v[92:95]
	v_mfma_f32_16x16x32_bf16 v[56:59], v[140:143], v[116:119], v[56:59]
	v_mfma_f32_16x16x32_bf16 v[52:55], v[144:147], v[116:119], v[52:55]
	v_mfma_f32_16x16x32_bf16 v[48:51], v[148:151], v[116:119], v[48:51]
	s_waitcnt vmcnt(7)
	ds_write_b128 v109, v[60:63] offset:32768
	v_add_co_u32_e32 v60, vcc, s7, v164
	s_waitcnt lgkmcnt(11)
	v_mfma_f32_16x16x32_bf16 v[44:47], v[136:139], v[120:123], v[44:47]
	v_addc_co_u32_e32 v61, vcc, 0, v165, vcc
	v_mfma_f32_16x16x32_bf16 v[40:43], v[140:143], v[120:123], v[40:43]
	v_mfma_f32_16x16x32_bf16 v[36:39], v[144:147], v[120:123], v[36:39]
	v_mfma_f32_16x16x32_bf16 v[32:35], v[148:151], v[120:123], v[32:35]
	v_add_co_u32_e32 v60, vcc, s52, v164
	s_waitcnt vmcnt(6)
	ds_write_b128 v109, v[64:67] offset:36864
	s_nop 0
	v_addc_co_u32_e32 v61, vcc, 0, v165, vcc
	s_waitcnt lgkmcnt(11)
	v_mfma_f32_16x16x32_bf16 v[28:31], v[136:139], v[124:127], v[28:31]
	v_lshl_add_u64 v[64:65], v[102:103], 0, s[92:93]
	v_mfma_f32_16x16x32_bf16 v[24:27], v[140:143], v[124:127], v[24:27]
	v_mfma_f32_16x16x32_bf16 v[20:23], v[144:147], v[124:127], v[20:23]
	v_mfma_f32_16x16x32_bf16 v[16:19], v[148:151], v[124:127], v[16:19]
	v_add_co_u32_e32 v60, vcc, s34, v164
	s_waitcnt vmcnt(5)
	ds_write_b128 v109, v[68:71] offset:40960
	s_nop 0
	v_addc_co_u32_e32 v61, vcc, 0, v165, vcc
	v_add_co_u32_e32 v66, vcc, s7, v64
	s_waitcnt lgkmcnt(7)
	v_mfma_f32_16x16x32_bf16 v[12:15], v[136:139], v[132:135], v[12:15]
	v_addc_co_u32_e32 v67, vcc, 0, v65, vcc
	v_mfma_f32_16x16x32_bf16 v[8:11], v[140:143], v[132:135], v[8:11]
	v_mfma_f32_16x16x32_bf16 v[4:7], v[144:147], v[132:135], v[4:7]
	v_mfma_f32_16x16x32_bf16 v[0:3], v[148:151], v[132:135], v[0:3]
	s_waitcnt vmcnt(4)
	ds_write_b128 v109, v[76:79] offset:45056
	s_waitcnt lgkmcnt(7)
	v_mfma_f32_16x16x32_bf16 v[60:63], v[194:197], v[152:155], v[92:95]
	v_mfma_f32_16x16x32_bf16 v[56:59], v[198:201], v[152:155], v[56:59]
	v_mfma_f32_16x16x32_bf16 v[52:55], v[202:205], v[152:155], v[52:55]
	v_mfma_f32_16x16x32_bf16 v[48:51], v[206:209], v[152:155], v[48:51]
	s_waitcnt vmcnt(3)
	ds_write_b128 v109, v[72:75] offset:49152
	s_waitcnt lgkmcnt(7)
	v_mfma_f32_16x16x32_bf16 v[44:47], v[194:197], v[156:159], v[44:47]
	v_mfma_f32_16x16x32_bf16 v[40:43], v[198:201], v[156:159], v[40:43]
	v_mfma_f32_16x16x32_bf16 v[36:39], v[202:205], v[156:159], v[36:39]
	v_mfma_f32_16x16x32_bf16 v[32:35], v[206:209], v[156:159], v[32:35]
	v_add_co_u32_e32 v66, vcc, s52, v64
	s_waitcnt vmcnt(2)
	ds_write_b128 v109, v[80:83] offset:53248
	v_addc_co_u32_e32 v67, vcc, 0, v65, vcc
	v_add_co_u32_e32 v64, vcc, s34, v64
	s_waitcnt lgkmcnt(7)
	v_mfma_f32_16x16x32_bf16 v[28:31], v[194:197], v[160:163], v[28:31]
	v_addc_co_u32_e32 v65, vcc, 0, v65, vcc
	v_mfma_f32_16x16x32_bf16 v[24:27], v[198:201], v[160:163], v[24:27]
	v_mfma_f32_16x16x32_bf16 v[20:23], v[202:205], v[160:163], v[20:23]
	v_mfma_f32_16x16x32_bf16 v[16:19], v[206:209], v[160:163], v[16:19]
	s_waitcnt vmcnt(1)
	ds_write_b128 v109, v[84:87] offset:57344
	s_waitcnt lgkmcnt(7)
	v_mfma_f32_16x16x32_bf16 v[12:15], v[194:197], v[190:193], v[12:15]
	v_mfma_f32_16x16x32_bf16 v[8:11], v[198:201], v[190:193], v[8:11]
	v_mfma_f32_16x16x32_bf16 v[4:7], v[202:205], v[190:193], v[4:7]
	v_mfma_f32_16x16x32_bf16 v[0:3], v[206:209], v[190:193], v[0:3]
	s_waitcnt vmcnt(0)
	ds_write_b128 v109, v[88:91] offset:61440
	s_waitcnt lgkmcnt(0)
	s_barrier
	ds_read_b128 v[80:83], v111 offset:49152
	ds_read_b128 v[84:87], v111 offset:51200
	ds_read_b128 v[88:91], v111 offset:53248
	ds_read_b128 v[92:95], v111 offset:55296
	ds_read_b128 v[64:67], v110 offset:32768
	ds_read_b128 v[68:71], v110 offset:34816
	s_min_u32 s28, s25, 60
	s_lshl_b32 s92, s28, 7
	ds_read_b128 v[72:75], v110 offset:36864
	v_lshl_add_u64 v[164:165], v[100:101], 0, s[92:93]
	ds_read_b128 v[76:79], v110 offset:38912
	ds_read_b128 v[152:155], v112 offset:32768
	ds_read_b128 v[156:159], v112 offset:34816
	ds_read_b128 v[160:163], v112 offset:36864
	ds_read_b128 v[190:193], v112 offset:38912
	ds_read_b128 v[194:197], v113 offset:49152
	ds_read_b128 v[198:201], v113 offset:51200
	ds_read_b128 v[202:205], v113 offset:53248
	ds_read_b128 v[206:209], v113 offset:55296
	s_waitcnt lgkmcnt(11)
	v_mfma_f32_16x16x32_bf16 v[210:213], v[80:83], v[64:67], v[60:63]
	v_mfma_f32_16x16x32_bf16 v[56:59], v[84:87], v[64:67], v[56:59]
	v_mfma_f32_16x16x32_bf16 v[52:55], v[88:91], v[64:67], v[52:55]
	v_mfma_f32_16x16x32_bf16 v[48:51], v[92:95], v[64:67], v[48:51]
	v_add_co_u32_e32 v64, vcc, s7, v164
	s_nop 0
	v_addc_co_u32_e32 v65, vcc, 0, v165, vcc
	s_waitcnt lgkmcnt(10)
	v_mfma_f32_16x16x32_bf16 v[44:47], v[80:83], v[68:71], v[44:47]
	v_mfma_f32_16x16x32_bf16 v[40:43], v[84:87], v[68:71], v[40:43]
	v_mfma_f32_16x16x32_bf16 v[36:39], v[88:91], v[68:71], v[36:39]
	v_mfma_f32_16x16x32_bf16 v[32:35], v[92:95], v[68:71], v[32:35]
	v_add_co_u32_e32 v68, vcc, s52, v164
	s_nop 0
	v_addc_co_u32_e32 v69, vcc, 0, v165, vcc
	s_waitcnt lgkmcnt(9)
	v_mfma_f32_16x16x32_bf16 v[28:31], v[80:83], v[72:75], v[28:31]
	v_mfma_f32_16x16x32_bf16 v[24:27], v[84:87], v[72:75], v[24:27]
	v_mfma_f32_16x16x32_bf16 v[20:23], v[88:91], v[72:75], v[20:23]
	v_mfma_f32_16x16x32_bf16 v[16:19], v[92:95], v[72:75], v[16:19]
	v_add_co_u32_e32 v72, vcc, s34, v164
	s_waitcnt lgkmcnt(8)
	v_mfma_f32_16x16x32_bf16 v[4:7], v[88:91], v[76:79], v[4:7]
	v_addc_co_u32_e32 v73, vcc, 0, v165, vcc
	v_lshl_add_u64 v[88:89], v[102:103], 0, s[92:93]
	v_mfma_f32_16x16x32_bf16 v[12:15], v[80:83], v[76:79], v[12:15]
	v_add_co_u32_e32 v80, vcc, s7, v88
	v_mfma_f32_16x16x32_bf16 v[8:11], v[84:87], v[76:79], v[8:11]
	s_nop 0
	v_addc_co_u32_e32 v81, vcc, 0, v89, vcc
	v_add_co_u32_e32 v84, vcc, s52, v88
	v_mfma_f32_16x16x32_bf16 v[0:3], v[92:95], v[76:79], v[0:3]
	s_nop 0
	v_addc_co_u32_e32 v85, vcc, 0, v89, vcc
	s_waitcnt lgkmcnt(3)
	v_mfma_f32_16x16x32_bf16 v[92:95], v[194:197], v[152:155], v[210:213]
	s_waitcnt lgkmcnt(2)
	v_mfma_f32_16x16x32_bf16 v[56:59], v[198:201], v[152:155], v[56:59]
	s_waitcnt lgkmcnt(1)
	v_mfma_f32_16x16x32_bf16 v[52:55], v[202:205], v[152:155], v[52:55]
	s_waitcnt lgkmcnt(0)
	v_mfma_f32_16x16x32_bf16 v[48:51], v[206:209], v[152:155], v[48:51]
	v_add_co_u32_e32 v88, vcc, s34, v88
	v_addc_co_u32_e32 v89, vcc, 0, v89, vcc
	v_mfma_f32_16x16x32_bf16 v[44:47], v[194:197], v[156:159], v[44:47]
	v_mfma_f32_16x16x32_bf16 v[40:43], v[198:201], v[156:159], v[40:43]
	v_mfma_f32_16x16x32_bf16 v[36:39], v[202:205], v[156:159], v[36:39]
	v_mfma_f32_16x16x32_bf16 v[32:35], v[206:209], v[156:159], v[32:35]
	v_mfma_f32_16x16x32_bf16 v[28:31], v[194:197], v[160:163], v[28:31]
	v_mfma_f32_16x16x32_bf16 v[24:27], v[198:201], v[160:163], v[24:27]
	v_mfma_f32_16x16x32_bf16 v[20:23], v[202:205], v[160:163], v[20:23]
	v_mfma_f32_16x16x32_bf16 v[16:19], v[206:209], v[160:163], v[16:19]
	v_mfma_f32_16x16x32_bf16 v[12:15], v[194:197], v[190:193], v[12:15]
	v_mfma_f32_16x16x32_bf16 v[8:11], v[198:201], v[190:193], v[8:11]
	v_mfma_f32_16x16x32_bf16 v[4:7], v[202:205], v[190:193], v[4:7]
	v_mfma_f32_16x16x32_bf16 v[0:3], v[206:209], v[190:193], v[0:3]
	s_mov_b32 s28, s25
	s_waitcnt lgkmcnt(0)
	s_barrier
	s_waitcnt vmcnt(2)
	v_add_u32_e32 v80, s2, v108
	v_add_u32_e32 v60, 0xffffe000, v80
	v_or_b32_e32 v70, v80, v107
	v_lshrrev_b32_e32 v60, 10, v60
	s_movk_i32 s2, 0x1800
	v_or_b32_e32 v81, s3, v114
	v_mad_u32_u24 v60, v60, s2, s2
	v_cmp_lt_i32_e32 vcc, s13, v70
	v_or_b32_e32 v64, v81, v115
	v_ashrrev_i32_e32 v71, 31, v70
	v_cndmask_b32_e32 v82, 0, v60, vcc
	v_readlane_b32 s2, v250, 15
	v_ashrrev_i32_e32 v83, 31, v82
	v_ashrrev_i32_e32 v65, 31, v64
	v_lshlrev_b64 v[68:69], 12, v[70:71]
	v_readlane_b32 s3, v250, 16
	v_lshl_add_u64 v[60:61], v[82:83], 2, s[40:41]
	v_lshlrev_b64 v[66:67], 2, v[64:65]
	v_lshl_add_u64 v[68:69], s[2:3], 0, v[68:69]
	v_lshl_add_u64 v[74:75], v[60:61], 0, v[66:67]
	v_lshl_add_u64 v[72:73], v[68:69], 0, v[66:67]
	global_load_dwordx4 v[60:63], v[74:75], off
	global_load_dwordx4 v[76:79], v[72:73], off
	v_readlane_b32 s2, v250, 21
	s_waitcnt vmcnt(3)
	v_lshlrev_b64 v[84:85], 10, v[70:71]
	v_readlane_b32 s3, v250, 22
	s_and_b64 vcc, exec, s[36:37]
	v_lshl_add_u64 v[68:69], s[26:27], 0, v[66:67]
	s_waitcnt vmcnt(0)
	v_pk_fma_f32 v[62:63], v[94:95], v[62:63], v[78:79]
	v_pk_fma_f32 v[60:61], v[92:93], v[60:61], v[76:77]
	v_lshl_add_u64 v[76:77], v[82:83], 2, s[42:43]
	v_lshl_add_u64 v[78:79], v[84:85], 1, s[2:3]
	global_store_dwordx4 v[72:73], v[60:63], off
	s_cbranch_vccnz .LBB0_285
	v_lshl_add_u64 v[86:87], v[76:77], 0, v[66:67]
	global_load_dwordx4 v[82:85], v[68:69], off
	s_waitcnt vmcnt(0)
	v_pk_mul_f32 v[84:85], v[62:63], v[84:85]
	global_load_dwordx4 v[86:89], v[86:87], off
	v_pk_mul_f32 v[82:83], v[60:61], v[82:83]
	s_waitcnt vmcnt(0)
	v_pk_add_f32 v[88:89], v[88:89], 1.0 op_sel_hi:[1,0]
	v_pk_add_f32 v[86:87], v[86:87], 1.0 op_sel_hi:[1,0]
	v_pk_mul_f32 v[84:85], v[84:85], v[88:89]
	v_pk_mul_f32 v[82:83], v[82:83], v[86:87]
	v_and_b32_sdwa v88, v84, v170 dst_sel:DWORD dst_unused:UNUSED_PAD src0_sel:WORD_1 src1_sel:DWORD
	v_and_b32_sdwa v89, v82, v170 dst_sel:DWORD dst_unused:UNUSED_PAD src0_sel:WORD_1 src1_sel:DWORD
	v_add3_u32 v82, v82, v89, s56
	v_add3_u32 v84, v84, v88, s56
	v_and_b32_sdwa v88, v85, v170 dst_sel:DWORD dst_unused:UNUSED_PAD src0_sel:WORD_1 src1_sel:DWORD
	v_and_b32_sdwa v89, v83, v170 dst_sel:DWORD dst_unused:UNUSED_PAD src0_sel:WORD_1 src1_sel:DWORD
	v_add3_u32 v85, v85, v88, s56
	v_add3_u32 v83, v83, v89, s56
	v_and_b32_e32 v85, 0xffff0000, v85
	v_and_b32_e32 v88, 0xffff0000, v83
	v_lshl_add_u64 v[86:87], v[64:65], 1, v[78:79]
	v_or_b32_sdwa v83, v85, v84 dst_sel:DWORD dst_unused:UNUSED_PAD src0_sel:DWORD src1_sel:WORD_1
	v_or_b32_sdwa v82, v88, v82 dst_sel:DWORD dst_unused:UNUSED_PAD src0_sel:DWORD src1_sel:WORD_1
	global_store_dwordx2 v[86:87], v[82:83], off

.LBB0_327:
	s_add_i32 s0, s1, 2
	v_add_u32_e32 v127, v89, v90
	ds_read_b128 v[100:103], v127 offset:16384
	ds_read_b128 v[106:109], v127 offset:18432
	ds_read_b128 v[110:113], v127 offset:20480
	ds_read_b128 v[114:117], v127 offset:22528
	v_add_u32_e32 v126, v88, v90
	ds_read_b128 v[92:95], v126
	ds_read_b128 v[96:99], v126 offset:2048
	s_add_i32 s1, s1, 4
	s_min_u32 s1, s1, 63
	v_add_u32_e32 v128, v88, v91
	v_add_u32_e32 v130, v89, v91
	s_lshl_b32 s92, s1, 7
	ds_read_b128 v[118:121], v130 offset:18432
	ds_read_b128 v[122:125], v130 offset:20480
	ds_read_b128 v[132:135], v130 offset:22528
	s_waitcnt lgkmcnt(4)
	v_mfma_f32_16x16x32_bf16 v[76:79], v[100:103], v[92:95], v[76:79]
	v_lshl_add_u64 v[48:49], v[80:81], 0, s[92:93]
	v_add_co_u32_e32 v50, vcc, s7, v48
	v_mfma_f32_16x16x32_bf16 v[56:59], v[106:109], v[92:95], v[56:59]
	s_nop 0
	v_addc_co_u32_e32 v51, vcc, 0, v49, vcc
	v_mfma_f32_16x16x32_bf16 v[44:47], v[110:113], v[92:95], v[44:47]
	v_mfma_f32_16x16x32_bf16 v[24:27], v[114:117], v[92:95], v[24:27]
	s_waitcnt lgkmcnt(3)
	v_mfma_f32_16x16x32_bf16 v[92:95], v[100:103], v[96:99], v[12:15]
	s_nop 2
	ds_read_b128 v[12:15], v128
	v_mfma_f32_16x16x32_bf16 v[100:103], v[106:109], v[96:99], v[8:11]
	v_mfma_f32_16x16x32_bf16 v[106:109], v[110:113], v[96:99], v[4:7]
	ds_read_b128 v[110:113], v128 offset:2048
	v_mfma_f32_16x16x32_bf16 v[96:99], v[114:117], v[96:99], v[0:3]
	ds_read_b128 v[114:117], v130 offset:16384
	global_load_dwordx4 v[72:75], v[48:49], off
	s_waitcnt vmcnt(1)
	ds_write_b128 v87, v[16:19] offset:53248
	global_load_dwordx4 v[68:71], v[50:51], off
	v_add_co_u32_e32 v50, vcc, s52, v48
	ds_write_b128 v87, v[20:23] offset:49152
	s_nop 0
	v_addc_co_u32_e32 v51, vcc, 0, v49, vcc
	v_add_co_u32_e32 v48, vcc, s34, v48
	global_load_dwordx4 v[64:67], v[50:51], off
	s_nop 0
	v_addc_co_u32_e32 v49, vcc, 0, v49, vcc
	ds_write_b128 v87, v[28:31] offset:45056
	global_load_dwordx4 v[60:63], v[48:49], off
	v_lshl_add_u64 v[48:49], v[82:83], 0, s[92:93]
	ds_write_b128 v87, v[36:39] offset:32768
	s_waitcnt lgkmcnt(4)
	v_mfma_f32_16x16x32_bf16 v[0:3], v[114:117], v[12:15], v[76:79]
	v_mfma_f32_16x16x32_bf16 v[4:7], v[118:121], v[12:15], v[56:59]
	global_load_dwordx4 v[52:55], v[48:49], off
	v_add_co_u32_e32 v48, vcc, s7, v48
	ds_write_b128 v87, v[40:43] offset:36864
	s_nop 0
	v_addc_co_u32_e32 v49, vcc, 0, v49, vcc
	v_mfma_f32_16x16x32_bf16 v[8:11], v[122:125], v[12:15], v[44:47]
	v_mfma_f32_16x16x32_bf16 v[12:15], v[132:135], v[12:15], v[24:27]
	global_load_dwordx4 v[48:51], v[48:49], off
	ds_write_b128 v87, v[32:35] offset:40960
	v_mfma_f32_16x16x32_bf16 v[24:27], v[114:117], v[110:113], v[92:95]
	v_mfma_f32_16x16x32_bf16 v[44:47], v[118:121], v[110:113], v[100:103]
	v_mfma_f32_16x16x32_bf16 v[56:59], v[122:125], v[110:113], v[106:109]
	v_mfma_f32_16x16x32_bf16 v[76:79], v[132:135], v[110:113], v[96:99]
	s_waitcnt lgkmcnt(0)
	s_barrier
	ds_read_b128 v[100:103], v127 offset:49152
	ds_read_b128 v[106:109], v127 offset:51200
	ds_read_b128 v[110:113], v127 offset:53248
	ds_read_b128 v[114:117], v127 offset:55296
	ds_read_b128 v[92:95], v126 offset:32768
	ds_read_b128 v[96:99], v126 offset:34816
	s_min_u32 s1, s0, 60
	s_lshl_b32 s92, s1, 7
	ds_read_b128 v[118:121], v130 offset:51200
	ds_read_b128 v[122:125], v130 offset:53248
	ds_read_b128 v[132:135], v130 offset:55296
	s_waitcnt lgkmcnt(4)
	v_mfma_f32_16x16x32_bf16 v[0:3], v[100:103], v[92:95], v[0:3]
	v_lshl_add_u64 v[16:17], v[80:81], 0, s[92:93]
	v_add_co_u32_e32 v18, vcc, s7, v16
	v_mfma_f32_16x16x32_bf16 v[4:7], v[106:109], v[92:95], v[4:7]
	s_nop 0
	v_addc_co_u32_e32 v19, vcc, 0, v17, vcc
	v_mfma_f32_16x16x32_bf16 v[8:11], v[110:113], v[92:95], v[8:11]
	v_mfma_f32_16x16x32_bf16 v[12:15], v[114:117], v[92:95], v[12:15]
	s_waitcnt lgkmcnt(3)
	v_mfma_f32_16x16x32_bf16 v[92:95], v[100:103], v[96:99], v[24:27]
	s_nop 2
	ds_read_b128 v[24:27], v128 offset:32768
	v_mfma_f32_16x16x32_bf16 v[100:103], v[106:109], v[96:99], v[44:47]
	v_mfma_f32_16x16x32_bf16 v[106:109], v[110:113], v[96:99], v[56:59]
	ds_read_b128 v[110:113], v128 offset:34816
	v_mfma_f32_16x16x32_bf16 v[96:99], v[114:117], v[96:99], v[76:79]
	ds_read_b128 v[114:117], v130 offset:49152
	global_load_dwordx4 v[36:39], v[16:17], off offset:384
	s_waitcnt vmcnt(1)
	ds_write_b128 v87, v[48:51] offset:20480
	global_load_dwordx4 v[40:43], v[18:19], off offset:384
	v_add_co_u32_e32 v18, vcc, s52, v16
	ds_write_b128 v87, v[52:55] offset:16384
	s_nop 0
	v_addc_co_u32_e32 v19, vcc, 0, v17, vcc
	v_add_co_u32_e32 v16, vcc, s34, v16
	global_load_dwordx4 v[32:35], v[18:19], off offset:384
	s_nop 0
	v_addc_co_u32_e32 v17, vcc, 0, v17, vcc
	ds_write_b128 v87, v[60:63] offset:12288
	global_load_dwordx4 v[28:31], v[16:17], off offset:384
	v_lshl_add_u64 v[16:17], v[82:83], 0, s[92:93]
	ds_write_b128 v87, v[72:75]
	s_waitcnt lgkmcnt(4)
	v_mfma_f32_16x16x32_bf16 v[76:79], v[114:117], v[24:27], v[0:3]
	v_mfma_f32_16x16x32_bf16 v[56:59], v[118:121], v[24:27], v[4:7]
	global_load_dwordx4 v[20:23], v[16:17], off offset:384
	v_add_co_u32_e32 v16, vcc, s7, v16
	ds_write_b128 v87, v[68:71] offset:4096
	s_nop 0
	v_addc_co_u32_e32 v17, vcc, 0, v17, vcc
	v_mfma_f32_16x16x32_bf16 v[44:47], v[122:125], v[24:27], v[8:11]
	v_mfma_f32_16x16x32_bf16 v[24:27], v[132:135], v[24:27], v[12:15]
	global_load_dwordx4 v[16:19], v[16:17], off offset:384
	ds_write_b128 v87, v[64:67] offset:8192
	v_mfma_f32_16x16x32_bf16 v[12:15], v[114:117], v[110:113], v[92:95]
	v_mfma_f32_16x16x32_bf16 v[8:11], v[118:121], v[110:113], v[100:103]
	v_mfma_f32_16x16x32_bf16 v[4:7], v[122:125], v[110:113], v[106:109]
	v_mfma_f32_16x16x32_bf16 v[0:3], v[132:135], v[110:113], v[96:99]
	s_cmp_lt_u32 s0, 60
	s_mov_b32 s1, s0
	s_waitcnt lgkmcnt(0)
	s_barrier
	s_cbranch_scc1 .LBB0_327
.Ltail327:
	s_add_i32 s0, s1, 2
	v_add_u32_e32 v127, v89, v90
	ds_read_b128 v[100:103], v127 offset:16384
	ds_read_b128 v[106:109], v127 offset:18432
	ds_read_b128 v[110:113], v127 offset:20480
	ds_read_b128 v[114:117], v127 offset:22528
	v_add_u32_e32 v126, v88, v90
	ds_read_b128 v[92:95], v126
	ds_read_b128 v[96:99], v126 offset:2048
	s_add_i32 s1, s1, 4
	s_min_u32 s1, s1, 63
	v_add_u32_e32 v128, v88, v91
	v_add_u32_e32 v130, v89, v91
	s_lshl_b32 s92, s1, 7
	ds_read_b128 v[118:121], v130 offset:18432
	ds_read_b128 v[122:125], v130 offset:20480
	ds_read_b128 v[132:135], v130 offset:22528
	s_waitcnt lgkmcnt(4)
	v_mfma_f32_16x16x32_bf16 v[76:79], v[100:103], v[92:95], v[76:79]
	v_lshl_add_u64 v[48:49], v[80:81], 0, s[92:93]
	v_add_co_u32_e32 v50, vcc, s7, v48
	v_mfma_f32_16x16x32_bf16 v[56:59], v[106:109], v[92:95], v[56:59]
	s_nop 0
	v_addc_co_u32_e32 v51, vcc, 0, v49, vcc
	v_mfma_f32_16x16x32_bf16 v[44:47], v[110:113], v[92:95], v[44:47]
	v_mfma_f32_16x16x32_bf16 v[24:27], v[114:117], v[92:95], v[24:27]
	s_waitcnt lgkmcnt(3)
	v_mfma_f32_16x16x32_bf16 v[92:95], v[100:103], v[96:99], v[12:15]
	s_nop 2
	ds_read_b128 v[12:15], v128
	v_mfma_f32_16x16x32_bf16 v[100:103], v[106:109], v[96:99], v[8:11]
	v_mfma_f32_16x16x32_bf16 v[106:109], v[110:113], v[96:99], v[4:7]
	ds_read_b128 v[110:113], v128 offset:2048
	v_mfma_f32_16x16x32_bf16 v[96:99], v[114:117], v[96:99], v[0:3]
	ds_read_b128 v[114:117], v130 offset:16384
	s_waitcnt vmcnt(0)
	ds_write_b128 v87, v[16:19] offset:53248
	v_add_co_u32_e32 v50, vcc, s52, v48
	s_waitcnt vmcnt(1)
	ds_write_b128 v87, v[20:23] offset:49152
	s_nop 0
	v_addc_co_u32_e32 v51, vcc, 0, v49, vcc
	v_add_co_u32_e32 v48, vcc, s34, v48
	s_nop 0
	v_addc_co_u32_e32 v49, vcc, 0, v49, vcc
	s_waitcnt vmcnt(2)
	ds_write_b128 v87, v[28:31] offset:45056
	v_lshl_add_u64 v[48:49], v[82:83], 0, s[92:93]
	s_waitcnt vmcnt(5)
	ds_write_b128 v87, v[36:39] offset:32768
	s_waitcnt lgkmcnt(4)
	v_mfma_f32_16x16x32_bf16 v[0:3], v[114:117], v[12:15], v[76:79]
	v_mfma_f32_16x16x32_bf16 v[4:7], v[118:121], v[12:15], v[56:59]
	v_add_co_u32_e32 v48, vcc, s7, v48
	s_waitcnt vmcnt(4)
	ds_write_b128 v87, v[40:43] offset:36864
	s_nop 0
	v_addc_co_u32_e32 v49, vcc, 0, v49, vcc
	v_mfma_f32_16x16x32_bf16 v[8:11], v[122:125], v[12:15], v[44:47]
	v_mfma_f32_16x16x32_bf16 v[12:15], v[132:135], v[12:15], v[24:27]
	s_waitcnt vmcnt(3)
	ds_write_b128 v87, v[32:35] offset:40960
	v_mfma_f32_16x16x32_bf16 v[24:27], v[114:117], v[110:113], v[92:95]
	v_mfma_f32_16x16x32_bf16 v[44:47], v[118:121], v[110:113], v[100:103]
	v_mfma_f32_16x16x32_bf16 v[56:59], v[122:125], v[110:113], v[106:109]
	v_mfma_f32_16x16x32_bf16 v[76:79], v[132:135], v[110:113], v[96:99]
	s_waitcnt lgkmcnt(0)
	s_barrier
	ds_read_b128 v[100:103], v127 offset:49152
	ds_read_b128 v[106:109], v127 offset:51200
	ds_read_b128 v[110:113], v127 offset:53248
	ds_read_b128 v[114:117], v127 offset:55296
	ds_read_b128 v[92:95], v126 offset:32768
	ds_read_b128 v[96:99], v126 offset:34816
	s_min_u32 s1, s0, 60
	s_lshl_b32 s92, s1, 7
	ds_read_b128 v[118:121], v130 offset:51200
	ds_read_b128 v[122:125], v130 offset:53248
	ds_read_b128 v[132:135], v130 offset:55296
	s_waitcnt lgkmcnt(4)
	v_mfma_f32_16x16x32_bf16 v[0:3], v[100:103], v[92:95], v[0:3]
	v_lshl_add_u64 v[16:17], v[80:81], 0, s[92:93]
	v_add_co_u32_e32 v18, vcc, s7, v16
	v_mfma_f32_16x16x32_bf16 v[4:7], v[106:109], v[92:95], v[4:7]
	s_nop 0
	v_addc_co_u32_e32 v19, vcc, 0, v17, vcc
	v_mfma_f32_16x16x32_bf16 v[8:11], v[110:113], v[92:95], v[8:11]
	v_mfma_f32_16x16x32_bf16 v[12:15], v[114:117], v[92:95], v[12:15]
	s_waitcnt lgkmcnt(3)
	v_mfma_f32_16x16x32_bf16 v[92:95], v[100:103], v[96:99], v[24:27]
	s_nop 2
	ds_read_b128 v[24:27], v128 offset:32768
	v_mfma_f32_16x16x32_bf16 v[100:103], v[106:109], v[96:99], v[44:47]
	v_mfma_f32_16x16x32_bf16 v[106:109], v[110:113], v[96:99], v[56:59]
	ds_read_b128 v[110:113], v128 offset:34816
	v_mfma_f32_16x16x32_bf16 v[96:99], v[114:117], v[96:99], v[76:79]
	ds_read_b128 v[114:117], v130 offset:49152
	v_add_co_u32_e32 v18, vcc, s52, v16
	s_nop 0
	v_addc_co_u32_e32 v19, vcc, 0, v17, vcc
	v_add_co_u32_e32 v16, vcc, s34, v16
	s_nop 0
	v_addc_co_u32_e32 v17, vcc, 0, v17, vcc
	v_lshl_add_u64 v[16:17], v[82:83], 0, s[92:93]
	s_waitcnt lgkmcnt(0)
	v_mfma_f32_16x16x32_bf16 v[76:79], v[114:117], v[24:27], v[0:3]
	v_mfma_f32_16x16x32_bf16 v[56:59], v[118:121], v[24:27], v[4:7]
	v_add_co_u32_e32 v16, vcc, s7, v16
	s_nop 0
	v_addc_co_u32_e32 v17, vcc, 0, v17, vcc
	v_mfma_f32_16x16x32_bf16 v[44:47], v[122:125], v[24:27], v[8:11]
	v_mfma_f32_16x16x32_bf16 v[24:27], v[132:135], v[24:27], v[12:15]
	v_mfma_f32_16x16x32_bf16 v[12:15], v[114:117], v[110:113], v[92:95]
	v_mfma_f32_16x16x32_bf16 v[8:11], v[118:121], v[110:113], v[100:103]
	v_mfma_f32_16x16x32_bf16 v[4:7], v[122:125], v[110:113], v[106:109]
	v_mfma_f32_16x16x32_bf16 v[0:3], v[132:135], v[110:113], v[96:99]
	s_mov_b32 s1, s0
	s_waitcnt lgkmcnt(0)
	s_barrier
	v_readlane_b32 s0, v251, 18
	s_nop 1
	v_add_u32_e32 v48, s0, v86
	v_readlane_b32 s0, v251, 19
	s_waitcnt vmcnt(0)
	v_add_u32_e32 v16, 0xffffe000, v48
	v_or_b32_e32 v34, v48, v85
	v_lshl_or_b32 v32, v84, 2, s0
	v_lshrrev_b32_e32 v16, 10, v16
	s_movk_i32 s0, 0x1800
	v_mad_u32_u24 v16, v16, s0, s0
	v_cmp_lt_i32_e32 vcc, s13, v34
	v_ashrrev_i32_e32 v35, 31, v34
	v_lshlrev_b32_e32 v128, 2, v32
	v_cndmask_b32_e32 v28, 0, v16, vcc
	v_ashrrev_i32_e32 v29, 31, v28
	v_lshl_add_u64 v[16:17], v[28:29], 2, s[40:41]
	v_readlane_b32 s0, v250, 15
	v_lshl_add_u64 v[40:41], v[16:17], 0, v[128:129]
	v_lshlrev_b64 v[16:17], 12, v[34:35]
	v_readlane_b32 s1, v250, 16
	v_lshlrev_b64 v[30:31], 10, v[34:35]
	s_and_b64 vcc, exec, s[36:37]
	v_lshl_add_u64 v[16:17], s[0:1], 0, v[16:17]
	v_lshl_add_u64 v[38:39], v[16:17], 0, v[128:129]
	global_load_dwordx4 v[60:63], v[40:41], off
	global_load_dwordx4 v[72:75], v[40:41], off offset:64
	global_load_dwordx4 v[80:83], v[40:41], off offset:128
	global_load_dwordx4 v[88:91], v[40:41], off offset:192
	global_load_dwordx4 v[190:193], v[38:39], off
	global_load_dwordx4 v[194:197], v[38:39], off offset:64
	global_load_dwordx4 v[198:201], v[38:39], off offset:128
	global_load_dwordx4 v[202:205], v[38:39], off offset:192
	v_add_co_u32_e32 v54, vcc, 0x10000, v38
	s_nop 1
	v_addc_co_u32_e32 v55, vcc, 0, v39, vcc
	global_load_dwordx4 v[206:209], v[54:55], off
	global_load_dwordx4 v[210:213], v[54:55], off offset:64
	global_load_dwordx4 v[214:217], v[54:55], off offset:128
	global_load_dwordx4 v[218:221], v[54:55], off offset:192
	v_readlane_b32 s0, v250, 21
	v_readlane_b32 s1, v250, 22
	v_lshl_add_u64 v[42:43], v[28:29], 2, s[42:43]
	v_lshlrev_b32_e32 v32, 1, v32
	v_lshl_add_u64 v[36:37], v[30:31], 1, s[0:1]
	s_waitcnt vmcnt(4)
	v_pk_fma_f32 v[18:19], v[78:79], v[62:63], v[192:193]
	v_pk_fma_f32 v[16:17], v[76:77], v[60:61], v[190:191]
	global_store_dwordx4 v[38:39], v[16:19], off
	s_cbranch_vccnz .LBB0_330
	v_lshl_add_u64 v[28:29], v[42:43], 0, v[128:129]
	global_load_dwordx4 v[136:139], v128, s[26:27]
	global_load_dwordx4 v[140:143], v128, s[26:27] offset:64
	global_load_dwordx4 v[144:147], v128, s[26:27] offset:128
	global_load_dwordx4 v[148:151], v128, s[26:27] offset:192
	v_mov_b32_e32 v33, v129
	global_load_dwordx4 v[152:155], v[28:29], off
	global_load_dwordx4 v[156:159], v[28:29], off offset:64
	global_load_dwordx4 v[160:163], v[28:29], off offset:128
	global_load_dwordx4 v[180:183], v[28:29], off offset:192
	s_waitcnt vmcnt(0)
	v_pk_mul_f32 v[22:23], v[18:19], v[138:139]
	v_pk_mul_f32 v[20:21], v[16:17], v[136:137]
	s_waitcnt vmcnt(0)
	v_pk_add_f32 v[30:31], v[154:155], 1.0 op_sel_hi:[1,0]
	v_pk_add_f32 v[28:29], v[152:153], 1.0 op_sel_hi:[1,0]
	v_pk_mul_f32 v[22:23], v[22:23], v[30:31]
	v_pk_mul_f32 v[20:21], v[20:21], v[28:29]
	v_and_b32_sdwa v30, v22, v170 dst_sel:DWORD dst_unused:UNUSED_PAD src0_sel:WORD_1 src1_sel:DWORD
	v_and_b32_sdwa v31, v20, v170 dst_sel:DWORD dst_unused:UNUSED_PAD src0_sel:WORD_1 src1_sel:DWORD
	v_add3_u32 v20, v20, v31, s56
	v_add3_u32 v22, v22, v30, s56
	v_and_b32_sdwa v30, v23, v170 dst_sel:DWORD dst_unused:UNUSED_PAD src0_sel:WORD_1 src1_sel:DWORD
	v_and_b32_sdwa v31, v21, v170 dst_sel:DWORD dst_unused:UNUSED_PAD src0_sel:WORD_1 src1_sel:DWORD
	v_add3_u32 v23, v23, v30, s56
	v_add3_u32 v21, v21, v31, s56
	v_and_b32_e32 v23, 0xffff0000, v23
	v_and_b32_e32 v30, 0xffff0000, v21
	v_lshl_add_u64 v[28:29], v[36:37], 0, v[32:33]
	v_or_b32_sdwa v21, v23, v22 dst_sel:DWORD dst_unused:UNUSED_PAD src0_sel:DWORD src1_sel:WORD_1
	v_or_b32_sdwa v20, v30, v20 dst_sel:DWORD dst_unused:UNUSED_PAD src0_sel:DWORD src1_sel:WORD_1
	global_store_dwordx2 v[28:29], v[20:21], off

.LBB0_359:
	s_add_i32 s27, s28, 2
	v_add_u32_e32 v181, v144, v145
	ds_read_b128 v[80:83], v181 offset:16384
	ds_read_b128 v[84:87], v181 offset:18432
	ds_read_b128 v[88:91], v181 offset:20480
	ds_read_b128 v[92:95], v181 offset:22528
	v_add_u32_e32 v180, v143, v145
	ds_read_b128 v[64:67], v180
	s_add_i32 s28, s28, 4
	ds_read_b128 v[68:71], v180 offset:2048
	s_min_u32 s28, s28, 15
	s_lshl_b32 s92, s28, 7
	ds_read_b128 v[72:75], v180 offset:4096
	ds_read_b128 v[76:79], v180 offset:6144
	v_add_u32_e32 v182, v143, v146
	v_add_u32_e32 v186, v144, v146
	v_lshl_add_u64 v[224:225], v[138:139], 0, s[92:93]
	ds_read_b128 v[192:195], v182
	ds_read_b128 v[196:199], v182 offset:2048
	ds_read_b128 v[200:203], v182 offset:4096
	ds_read_b128 v[204:207], v182 offset:6144
	ds_read_b128 v[208:211], v186 offset:16384
	ds_read_b128 v[212:215], v186 offset:18432
	ds_read_b128 v[216:219], v186 offset:20480
	ds_read_b128 v[220:223], v186 offset:22528
	s_waitcnt lgkmcnt(11)
	v_mfma_f32_16x16x32_bf16 v[60:63], v[80:83], v[64:67], v[60:63]
	v_mfma_f32_16x16x32_bf16 v[56:59], v[84:87], v[64:67], v[56:59]
	v_mfma_f32_16x16x32_bf16 v[52:55], v[88:91], v[64:67], v[52:55]
	v_mfma_f32_16x16x32_bf16 v[48:51], v[92:95], v[64:67], v[48:51]
	global_load_dwordx4 v[64:67], v[224:225], off
	s_waitcnt vmcnt(6)
	ds_write_b128 v156, v[96:99] offset:32768
	v_add_co_u32_e32 v96, vcc, s11, v224
	s_waitcnt lgkmcnt(11)
	v_mfma_f32_16x16x32_bf16 v[44:47], v[80:83], v[68:71], v[44:47]
	v_addc_co_u32_e32 v97, vcc, 0, v225, vcc
	v_mfma_f32_16x16x32_bf16 v[40:43], v[84:87], v[68:71], v[40:43]
	v_mfma_f32_16x16x32_bf16 v[36:39], v[88:91], v[68:71], v[36:39]
	v_mfma_f32_16x16x32_bf16 v[32:35], v[92:95], v[68:71], v[32:35]
	global_load_dwordx4 v[68:71], v[96:97], off
	v_add_co_u32_e32 v96, vcc, s33, v224
	ds_write_b128 v156, v[100:103] offset:36864
	s_nop 0
	v_addc_co_u32_e32 v97, vcc, 0, v225, vcc
	s_waitcnt lgkmcnt(11)
	v_mfma_f32_16x16x32_bf16 v[28:31], v[80:83], v[72:75], v[28:31]
	v_mfma_f32_16x16x32_bf16 v[24:27], v[84:87], v[72:75], v[24:27]
	v_mfma_f32_16x16x32_bf16 v[20:23], v[88:91], v[72:75], v[20:23]
	v_mfma_f32_16x16x32_bf16 v[16:19], v[92:95], v[72:75], v[16:19]
	global_load_dwordx4 v[72:75], v[96:97], off
	ds_write_b128 v156, v[104:107] offset:40960
	s_waitcnt lgkmcnt(11)
	v_mfma_f32_16x16x32_bf16 v[12:15], v[80:83], v[76:79], v[12:15]
	v_add_co_u32_e32 v80, vcc, s59, v224
	v_mfma_f32_16x16x32_bf16 v[0:3], v[92:95], v[76:79], v[0:3]
	s_nop 0
	v_addc_co_u32_e32 v81, vcc, 0, v225, vcc
	v_lshl_add_u64 v[92:93], v[140:141], 0, s[92:93]
	v_mfma_f32_16x16x32_bf16 v[8:11], v[84:87], v[76:79], v[8:11]
	v_add_co_u32_e32 v84, vcc, s11, v92
	s_nop 1
	v_addc_co_u32_e32 v85, vcc, 0, v93, vcc
	v_mfma_f32_16x16x32_bf16 v[4:7], v[88:91], v[76:79], v[4:7]
	v_add_co_u32_e32 v88, vcc, s33, v92
	global_load_dwordx4 v[76:79], v[80:81], off
	s_nop 0
	v_addc_co_u32_e32 v89, vcc, 0, v93, vcc
	s_waitcnt vmcnt(7)
	ds_write_b128 v156, v[112:115] offset:45056
	s_waitcnt lgkmcnt(7)
	v_mfma_f32_16x16x32_bf16 v[60:63], v[208:211], v[192:195], v[60:63]
	s_waitcnt lgkmcnt(6)
	v_mfma_f32_16x16x32_bf16 v[56:59], v[212:215], v[192:195], v[56:59]
	s_waitcnt lgkmcnt(5)
	v_mfma_f32_16x16x32_bf16 v[52:55], v[216:219], v[192:195], v[52:55]
	s_waitcnt lgkmcnt(4)
	v_mfma_f32_16x16x32_bf16 v[48:51], v[220:223], v[192:195], v[48:51]
	global_load_dwordx4 v[80:83], v[92:93], off
	v_add_co_u32_e32 v92, vcc, s59, v92
	ds_write_b128 v156, v[108:111] offset:49152
	s_nop 0
	v_addc_co_u32_e32 v93, vcc, 0, v93, vcc
	v_mfma_f32_16x16x32_bf16 v[44:47], v[208:211], v[196:199], v[44:47]
	v_mfma_f32_16x16x32_bf16 v[40:43], v[212:215], v[196:199], v[40:43]
	v_mfma_f32_16x16x32_bf16 v[36:39], v[216:219], v[196:199], v[36:39]
	v_mfma_f32_16x16x32_bf16 v[32:35], v[220:223], v[196:199], v[32:35]
	global_load_dwordx4 v[84:87], v[84:85], off
	s_waitcnt vmcnt(8)
	ds_write_b128 v156, v[116:119] offset:53248
	v_mfma_f32_16x16x32_bf16 v[28:31], v[208:211], v[200:203], v[28:31]
	v_mfma_f32_16x16x32_bf16 v[24:27], v[212:215], v[200:203], v[24:27]
	v_mfma_f32_16x16x32_bf16 v[20:23], v[216:219], v[200:203], v[20:23]
	v_mfma_f32_16x16x32_bf16 v[16:19], v[220:223], v[200:203], v[16:19]
	global_load_dwordx4 v[88:91], v[88:89], off
	s_waitcnt vmcnt(8)
	ds_write_b128 v156, v[120:123] offset:57344
	v_mfma_f32_16x16x32_bf16 v[12:15], v[208:211], v[204:207], v[12:15]
	v_mfma_f32_16x16x32_bf16 v[8:11], v[212:215], v[204:207], v[8:11]
	v_mfma_f32_16x16x32_bf16 v[4:7], v[216:219], v[204:207], v[4:7]
	v_mfma_f32_16x16x32_bf16 v[0:3], v[220:223], v[204:207], v[0:3]
	global_load_dwordx4 v[92:95], v[92:93], off
	s_waitcnt vmcnt(8)
	ds_write_b128 v156, v[124:127] offset:61440
	s_waitcnt lgkmcnt(0)
	s_barrier
	ds_read_b128 v[112:115], v181 offset:49152
	ds_read_b128 v[116:119], v181 offset:51200
	ds_read_b128 v[120:123], v181 offset:53248
	ds_read_b128 v[124:127], v181 offset:55296
	ds_read_b128 v[96:99], v180 offset:32768
	ds_read_b128 v[100:103], v180 offset:34816
	s_min_u32 s28, s27, 12
	s_lshl_b32 s92, s28, 7
	ds_read_b128 v[104:107], v180 offset:36864
	v_lshl_add_u64 v[224:225], v[138:139], 0, s[92:93]
	ds_read_b128 v[108:111], v180 offset:38912
	ds_read_b128 v[192:195], v182 offset:32768
	ds_read_b128 v[196:199], v182 offset:34816
	ds_read_b128 v[200:203], v182 offset:36864
	ds_read_b128 v[204:207], v182 offset:38912
	ds_read_b128 v[208:211], v186 offset:49152
	ds_read_b128 v[212:215], v186 offset:51200
	ds_read_b128 v[216:219], v186 offset:53248
	ds_read_b128 v[220:223], v186 offset:55296
	s_waitcnt lgkmcnt(11)
	v_mfma_f32_16x16x32_bf16 v[60:63], v[112:115], v[96:99], v[60:63]
	v_mfma_f32_16x16x32_bf16 v[56:59], v[116:119], v[96:99], v[56:59]
	v_mfma_f32_16x16x32_bf16 v[52:55], v[120:123], v[96:99], v[52:55]
	v_mfma_f32_16x16x32_bf16 v[48:51], v[124:127], v[96:99], v[48:51]
	global_load_dwordx4 v[96:99], v[224:225], off offset:384
	s_waitcnt vmcnt(8)
	ds_write_b128 v156, v[64:67]
	v_add_co_u32_e32 v64, vcc, s11, v224
	s_waitcnt lgkmcnt(11)
	v_mfma_f32_16x16x32_bf16 v[44:47], v[112:115], v[100:103], v[44:47]
	v_addc_co_u32_e32 v65, vcc, 0, v225, vcc
	v_mfma_f32_16x16x32_bf16 v[40:43], v[116:119], v[100:103], v[40:43]
	v_mfma_f32_16x16x32_bf16 v[36:39], v[120:123], v[100:103], v[36:39]
	v_mfma_f32_16x16x32_bf16 v[32:35], v[124:127], v[100:103], v[32:35]
	global_load_dwordx4 v[100:103], v[64:65], off offset:384
	v_add_co_u32_e32 v64, vcc, s33, v224
	s_waitcnt vmcnt(8)
	ds_write_b128 v156, v[68:71] offset:4096
	v_addc_co_u32_e32 v65, vcc, 0, v225, vcc
	s_waitcnt lgkmcnt(11)
	v_mfma_f32_16x16x32_bf16 v[28:31], v[112:115], v[104:107], v[28:31]
	v_mfma_f32_16x16x32_bf16 v[24:27], v[116:119], v[104:107], v[24:27]
	v_mfma_f32_16x16x32_bf16 v[20:23], v[120:123], v[104:107], v[20:23]
	v_mfma_f32_16x16x32_bf16 v[16:19], v[124:127], v[104:107], v[16:19]
	global_load_dwordx4 v[104:107], v[64:65], off offset:384
	v_add_co_u32_e32 v64, vcc, s59, v224
	s_waitcnt vmcnt(8)
	ds_write_b128 v156, v[72:75] offset:8192
	v_addc_co_u32_e32 v65, vcc, 0, v225, vcc
	s_waitcnt lgkmcnt(11)
	v_mfma_f32_16x16x32_bf16 v[12:15], v[112:115], v[108:111], v[12:15]
	v_mfma_f32_16x16x32_bf16 v[8:11], v[116:119], v[108:111], v[8:11]
	v_mfma_f32_16x16x32_bf16 v[4:7], v[120:123], v[108:111], v[4:7]
	v_mfma_f32_16x16x32_bf16 v[0:3], v[124:127], v[108:111], v[0:3]
	global_load_dwordx4 v[112:115], v[64:65], off offset:384
	v_lshl_add_u64 v[64:65], v[140:141], 0, s[92:93]
	v_add_co_u32_e32 v66, vcc, s11, v64
	s_waitcnt vmcnt(8)
	ds_write_b128 v156, v[76:79] offset:12288
	v_addc_co_u32_e32 v67, vcc, 0, v65, vcc
	s_waitcnt lgkmcnt(7)
	v_mfma_f32_16x16x32_bf16 v[60:63], v[208:211], v[192:195], v[60:63]
	s_waitcnt lgkmcnt(6)
	v_mfma_f32_16x16x32_bf16 v[56:59], v[212:215], v[192:195], v[56:59]
	s_waitcnt lgkmcnt(5)
	v_mfma_f32_16x16x32_bf16 v[52:55], v[216:219], v[192:195], v[52:55]
	s_waitcnt lgkmcnt(4)
	v_mfma_f32_16x16x32_bf16 v[48:51], v[220:223], v[192:195], v[48:51]
	global_load_dwordx4 v[108:111], v[64:65], off offset:384
	s_waitcnt vmcnt(8)
	ds_write_b128 v156, v[80:83] offset:16384
	v_mfma_f32_16x16x32_bf16 v[44:47], v[208:211], v[196:199], v[44:47]
	v_mfma_f32_16x16x32_bf16 v[40:43], v[212:215], v[196:199], v[40:43]
	v_mfma_f32_16x16x32_bf16 v[36:39], v[216:219], v[196:199], v[36:39]
	v_mfma_f32_16x16x32_bf16 v[32:35], v[220:223], v[196:199], v[32:35]
	global_load_dwordx4 v[116:119], v[66:67], off offset:384
	v_add_co_u32_e32 v66, vcc, s33, v64
	s_waitcnt vmcnt(8)
	ds_write_b128 v156, v[84:87] offset:20480
	v_addc_co_u32_e32 v67, vcc, 0, v65, vcc
	v_add_co_u32_e32 v64, vcc, s59, v64
	v_mfma_f32_16x16x32_bf16 v[28:31], v[208:211], v[200:203], v[28:31]
	s_nop 0
	v_addc_co_u32_e32 v65, vcc, 0, v65, vcc
	v_mfma_f32_16x16x32_bf16 v[24:27], v[212:215], v[200:203], v[24:27]
	v_mfma_f32_16x16x32_bf16 v[20:23], v[216:219], v[200:203], v[20:23]
	v_mfma_f32_16x16x32_bf16 v[16:19], v[220:223], v[200:203], v[16:19]
	global_load_dwordx4 v[120:123], v[66:67], off offset:384
	s_waitcnt vmcnt(8)
	ds_write_b128 v156, v[88:91] offset:24576
	v_mfma_f32_16x16x32_bf16 v[12:15], v[208:211], v[204:207], v[12:15]
	v_mfma_f32_16x16x32_bf16 v[8:11], v[212:215], v[204:207], v[8:11]
	v_mfma_f32_16x16x32_bf16 v[4:7], v[216:219], v[204:207], v[4:7]
	v_mfma_f32_16x16x32_bf16 v[0:3], v[220:223], v[204:207], v[0:3]
	global_load_dwordx4 v[124:127], v[64:65], off offset:384
	s_waitcnt vmcnt(8)
	ds_write_b128 v156, v[92:95] offset:28672
	s_cmp_gt_u32 s27, 11
	s_mov_b32 s28, s27
	s_waitcnt lgkmcnt(0)
	s_barrier
	s_cbranch_scc0 .LBB0_359
.Ltail359:
	s_add_i32 s27, s28, 2
	v_add_u32_e32 v181, v144, v145
	ds_read_b128 v[80:83], v181 offset:16384
	ds_read_b128 v[84:87], v181 offset:18432
	ds_read_b128 v[88:91], v181 offset:20480
	ds_read_b128 v[92:95], v181 offset:22528
	v_add_u32_e32 v180, v143, v145
	ds_read_b128 v[64:67], v180
	s_add_i32 s28, s28, 4
	ds_read_b128 v[68:71], v180 offset:2048
	s_min_u32 s28, s28, 15
	s_lshl_b32 s92, s28, 7
	ds_read_b128 v[72:75], v180 offset:4096
	ds_read_b128 v[76:79], v180 offset:6144
	v_add_u32_e32 v182, v143, v146
	v_add_u32_e32 v186, v144, v146
	v_lshl_add_u64 v[224:225], v[138:139], 0, s[92:93]
	ds_read_b128 v[192:195], v182
	ds_read_b128 v[196:199], v182 offset:2048
	ds_read_b128 v[200:203], v182 offset:4096
	ds_read_b128 v[204:207], v182 offset:6144
	ds_read_b128 v[208:211], v186 offset:16384
	ds_read_b128 v[212:215], v186 offset:18432
	ds_read_b128 v[216:219], v186 offset:20480
	ds_read_b128 v[220:223], v186 offset:22528
	s_waitcnt lgkmcnt(11)
	v_mfma_f32_16x16x32_bf16 v[60:63], v[80:83], v[64:67], v[60:63]
	v_mfma_f32_16x16x32_bf16 v[56:59], v[84:87], v[64:67], v[56:59]
	v_mfma_f32_16x16x32_bf16 v[52:55], v[88:91], v[64:67], v[52:55]
	v_mfma_f32_16x16x32_bf16 v[48:51], v[92:95], v[64:67], v[48:51]
	s_waitcnt vmcnt(7)
	ds_write_b128 v156, v[96:99] offset:32768
	v_add_co_u32_e32 v96, vcc, s11, v224
	s_waitcnt lgkmcnt(11)
	v_mfma_f32_16x16x32_bf16 v[44:47], v[80:83], v[68:71], v[44:47]
	v_addc_co_u32_e32 v97, vcc, 0, v225, vcc
	v_mfma_f32_16x16x32_bf16 v[40:43], v[84:87], v[68:71], v[40:43]
	v_mfma_f32_16x16x32_bf16 v[36:39], v[88:91], v[68:71], v[36:39]
	v_mfma_f32_16x16x32_bf16 v[32:35], v[92:95], v[68:71], v[32:35]
	v_add_co_u32_e32 v96, vcc, s33, v224
	s_waitcnt vmcnt(6)
	ds_write_b128 v156, v[100:103] offset:36864
	s_nop 0
	v_addc_co_u32_e32 v97, vcc, 0, v225, vcc
	s_waitcnt lgkmcnt(11)
	v_mfma_f32_16x16x32_bf16 v[28:31], v[80:83], v[72:75], v[28:31]
	v_mfma_f32_16x16x32_bf16 v[24:27], v[84:87], v[72:75], v[24:27]
	v_mfma_f32_16x16x32_bf16 v[20:23], v[88:91], v[72:75], v[20:23]
	v_mfma_f32_16x16x32_bf16 v[16:19], v[92:95], v[72:75], v[16:19]
	s_waitcnt vmcnt(5)
	ds_write_b128 v156, v[104:107] offset:40960
	s_waitcnt lgkmcnt(11)
	v_mfma_f32_16x16x32_bf16 v[12:15], v[80:83], v[76:79], v[12:15]
	v_add_co_u32_e32 v80, vcc, s59, v224
	v_mfma_f32_16x16x32_bf16 v[0:3], v[92:95], v[76:79], v[0:3]
	s_nop 0
	v_addc_co_u32_e32 v81, vcc, 0, v225, vcc
	v_lshl_add_u64 v[92:93], v[140:141], 0, s[92:93]
	v_mfma_f32_16x16x32_bf16 v[8:11], v[84:87], v[76:79], v[8:11]
	v_add_co_u32_e32 v84, vcc, s11, v92
	s_nop 1
	v_addc_co_u32_e32 v85, vcc, 0, v93, vcc
	v_mfma_f32_16x16x32_bf16 v[4:7], v[88:91], v[76:79], v[4:7]
	v_add_co_u32_e32 v88, vcc, s33, v92
	s_nop 0
	v_addc_co_u32_e32 v89, vcc, 0, v93, vcc
	s_waitcnt vmcnt(4)
	ds_write_b128 v156, v[112:115] offset:45056
	s_waitcnt lgkmcnt(7)
	v_mfma_f32_16x16x32_bf16 v[60:63], v[208:211], v[192:195], v[60:63]
	s_waitcnt lgkmcnt(6)
	v_mfma_f32_16x16x32_bf16 v[56:59], v[212:215], v[192:195], v[56:59]
	s_waitcnt lgkmcnt(5)
	v_mfma_f32_16x16x32_bf16 v[52:55], v[216:219], v[192:195], v[52:55]
	s_waitcnt lgkmcnt(4)
	v_mfma_f32_16x16x32_bf16 v[48:51], v[220:223], v[192:195], v[48:51]
	v_add_co_u32_e32 v92, vcc, s59, v92
	s_waitcnt vmcnt(3)
	ds_write_b128 v156, v[108:111] offset:49152
	s_nop 0
	v_addc_co_u32_e32 v93, vcc, 0, v93, vcc
	v_mfma_f32_16x16x32_bf16 v[44:47], v[208:211], v[196:199], v[44:47]
	v_mfma_f32_16x16x32_bf16 v[40:43], v[212:215], v[196:199], v[40:43]
	v_mfma_f32_16x16x32_bf16 v[36:39], v[216:219], v[196:199], v[36:39]
	v_mfma_f32_16x16x32_bf16 v[32:35], v[220:223], v[196:199], v[32:35]
	s_waitcnt vmcnt(2)
	ds_write_b128 v156, v[116:119] offset:53248
	v_mfma_f32_16x16x32_bf16 v[28:31], v[208:211], v[200:203], v[28:31]
	v_mfma_f32_16x16x32_bf16 v[24:27], v[212:215], v[200:203], v[24:27]
	v_mfma_f32_16x16x32_bf16 v[20:23], v[216:219], v[200:203], v[20:23]
	v_mfma_f32_16x16x32_bf16 v[16:19], v[220:223], v[200:203], v[16:19]
	s_waitcnt vmcnt(1)
	ds_write_b128 v156, v[120:123] offset:57344
	v_mfma_f32_16x16x32_bf16 v[12:15], v[208:211], v[204:207], v[12:15]
	v_mfma_f32_16x16x32_bf16 v[8:11], v[212:215], v[204:207], v[8:11]
	v_mfma_f32_16x16x32_bf16 v[4:7], v[216:219], v[204:207], v[4:7]
	v_mfma_f32_16x16x32_bf16 v[0:3], v[220:223], v[204:207], v[0:3]
	s_waitcnt vmcnt(0)
	ds_write_b128 v156, v[124:127] offset:61440
	s_waitcnt lgkmcnt(0)
	s_barrier
	ds_read_b128 v[112:115], v181 offset:49152
	ds_read_b128 v[116:119], v181 offset:51200
	ds_read_b128 v[120:123], v181 offset:53248
	ds_read_b128 v[124:127], v181 offset:55296
	ds_read_b128 v[96:99], v180 offset:32768
	ds_read_b128 v[100:103], v180 offset:34816
	s_min_u32 s28, s27, 12
	s_lshl_b32 s92, s28, 7
	ds_read_b128 v[104:107], v180 offset:36864
	v_lshl_add_u64 v[224:225], v[138:139], 0, s[92:93]
	ds_read_b128 v[108:111], v180 offset:38912
	ds_read_b128 v[192:195], v182 offset:32768
	ds_read_b128 v[196:199], v182 offset:34816
	ds_read_b128 v[200:203], v182 offset:36864
	ds_read_b128 v[204:207], v182 offset:38912
	ds_read_b128 v[208:211], v186 offset:49152
	ds_read_b128 v[212:215], v186 offset:51200
	ds_read_b128 v[216:219], v186 offset:53248
	ds_read_b128 v[220:223], v186 offset:55296
	s_waitcnt lgkmcnt(11)
	v_mfma_f32_16x16x32_bf16 v[60:63], v[112:115], v[96:99], v[60:63]
	v_mfma_f32_16x16x32_bf16 v[56:59], v[116:119], v[96:99], v[56:59]
	v_mfma_f32_16x16x32_bf16 v[52:55], v[120:123], v[96:99], v[52:55]
	v_mfma_f32_16x16x32_bf16 v[48:51], v[124:127], v[96:99], v[48:51]
	v_add_co_u32_e32 v64, vcc, s11, v224
	s_waitcnt lgkmcnt(10)
	v_mfma_f32_16x16x32_bf16 v[44:47], v[112:115], v[100:103], v[44:47]
	v_addc_co_u32_e32 v65, vcc, 0, v225, vcc
	v_mfma_f32_16x16x32_bf16 v[40:43], v[116:119], v[100:103], v[40:43]
	v_mfma_f32_16x16x32_bf16 v[36:39], v[120:123], v[100:103], v[36:39]
	v_mfma_f32_16x16x32_bf16 v[32:35], v[124:127], v[100:103], v[32:35]
	v_add_co_u32_e32 v64, vcc, s33, v224
	v_addc_co_u32_e32 v65, vcc, 0, v225, vcc
	s_waitcnt lgkmcnt(9)
	v_mfma_f32_16x16x32_bf16 v[28:31], v[112:115], v[104:107], v[28:31]
	v_mfma_f32_16x16x32_bf16 v[24:27], v[116:119], v[104:107], v[24:27]
	v_mfma_f32_16x16x32_bf16 v[20:23], v[120:123], v[104:107], v[20:23]
	v_mfma_f32_16x16x32_bf16 v[16:19], v[124:127], v[104:107], v[16:19]
	v_add_co_u32_e32 v64, vcc, s59, v224
	v_addc_co_u32_e32 v65, vcc, 0, v225, vcc
	s_waitcnt lgkmcnt(8)
	v_mfma_f32_16x16x32_bf16 v[12:15], v[112:115], v[108:111], v[12:15]
	v_mfma_f32_16x16x32_bf16 v[8:11], v[116:119], v[108:111], v[8:11]
	v_mfma_f32_16x16x32_bf16 v[4:7], v[120:123], v[108:111], v[4:7]
	v_mfma_f32_16x16x32_bf16 v[0:3], v[124:127], v[108:111], v[0:3]
	v_lshl_add_u64 v[64:65], v[140:141], 0, s[92:93]
	v_add_co_u32_e32 v66, vcc, s11, v64
	v_addc_co_u32_e32 v67, vcc, 0, v65, vcc
	s_waitcnt lgkmcnt(3)
	v_mfma_f32_16x16x32_bf16 v[60:63], v[208:211], v[192:195], v[60:63]
	s_waitcnt lgkmcnt(2)
	v_mfma_f32_16x16x32_bf16 v[56:59], v[212:215], v[192:195], v[56:59]
	s_waitcnt lgkmcnt(1)
	v_mfma_f32_16x16x32_bf16 v[52:55], v[216:219], v[192:195], v[52:55]
	s_waitcnt lgkmcnt(0)
	v_mfma_f32_16x16x32_bf16 v[48:51], v[220:223], v[192:195], v[48:51]
	v_mfma_f32_16x16x32_bf16 v[44:47], v[208:211], v[196:199], v[44:47]
	v_mfma_f32_16x16x32_bf16 v[40:43], v[212:215], v[196:199], v[40:43]
	v_mfma_f32_16x16x32_bf16 v[36:39], v[216:219], v[196:199], v[36:39]
	v_mfma_f32_16x16x32_bf16 v[32:35], v[220:223], v[196:199], v[32:35]
	v_add_co_u32_e32 v66, vcc, s33, v64
	v_addc_co_u32_e32 v67, vcc, 0, v65, vcc
	v_add_co_u32_e32 v64, vcc, s59, v64
	v_mfma_f32_16x16x32_bf16 v[28:31], v[208:211], v[200:203], v[28:31]
	s_nop 0
	v_addc_co_u32_e32 v65, vcc, 0, v65, vcc
	v_mfma_f32_16x16x32_bf16 v[24:27], v[212:215], v[200:203], v[24:27]
	v_mfma_f32_16x16x32_bf16 v[20:23], v[216:219], v[200:203], v[20:23]
	v_mfma_f32_16x16x32_bf16 v[16:19], v[220:223], v[200:203], v[16:19]
	v_mfma_f32_16x16x32_bf16 v[12:15], v[208:211], v[204:207], v[12:15]
	v_mfma_f32_16x16x32_bf16 v[8:11], v[212:215], v[204:207], v[8:11]
	v_mfma_f32_16x16x32_bf16 v[4:7], v[216:219], v[204:207], v[4:7]
	v_mfma_f32_16x16x32_bf16 v[0:3], v[220:223], v[204:207], v[0:3]
	s_mov_b32 s28, s27
	s_waitcnt lgkmcnt(0)
	s_barrier
	s_and_saveexec_b64 s[28:29], s[36:37]
	s_cbranch_execz .LBB0_353
	v_add_f32_e32 v64, 0, v128
	v_add_f32_e32 v64, v64, v157
	v_add_f32_e32 v64, v64, v158
	v_add_f32_e32 v64, v64, v159
	v_add_f32_e32 v64, v64, v160
	v_add_f32_e32 v64, v64, v161
	v_add_f32_e32 v64, v64, v162
	v_add_f32_e32 v64, v64, v163
	v_add_f32_e32 v64, v64, v164
	v_add_f32_e32 v64, v64, v165
	v_add_f32_e32 v64, v64, v168
	v_add_f32_e32 v64, v64, v175
	v_add_f32_e32 v64, v64, v179
	v_add_f32_e32 v64, v64, v183
	v_add_f32_e32 v64, v64, v190
	v_add_f32_e32 v64, v64, v191
	v_fmamk_f32 v64, v64, 0x3a800000, v167
	s_mov_b32 s16, 0x800000
	v_mul_f32_e32 v65, 0x4b800000, v64
	v_cmp_gt_f32_e32 vcc, s16, v64
	s_nop 1
	v_cndmask_b32_e32 v64, v64, v65, vcc
	v_rsq_f32_e32 v64, v64
	s_nop 0
	v_mul_f32_e32 v65, 0x45800000, v64
	v_cndmask_b32_e32 v64, v64, v65, vcc
	ds_write_b32 v155, v64
	s_branch .LBB0_353

.LBB0_372:
	s_add_i32 s3, s24, 2
	v_add_u32_e32 v180, v142, v144
	ds_read_b128 v[44:47], v180
	ds_read_b128 v[48:51], v180 offset:2048
	v_add_u32_e32 v181, v143, v144
	ds_read_b128 v[52:55], v180 offset:4096
	ds_read_b128 v[56:59], v180 offset:6144
	ds_read_b128 v[60:63], v181 offset:16384
	ds_read_b128 v[68:71], v181 offset:18432
	ds_read_b128 v[72:75], v181 offset:20480
	ds_read_b128 v[76:79], v181 offset:22528
	v_add_u32_e32 v182, v142, v145
	s_add_i32 s24, s24, 4
	ds_read_b128 v[192:195], v182
	s_min_u32 s24, s24, 15
	s_lshl_b32 s92, s24, 7
	v_add_u32_e32 v186, v143, v145
	v_lshl_add_u64 v[224:225], v[138:139], 0, s[92:93]
	ds_read_b128 v[196:199], v182 offset:2048
	ds_read_b128 v[200:203], v182 offset:4096
	ds_read_b128 v[204:207], v182 offset:6144
	ds_read_b128 v[208:211], v186 offset:16384
	ds_read_b128 v[212:215], v186 offset:18432
	ds_read_b128 v[216:219], v186 offset:20480
	ds_read_b128 v[220:223], v186 offset:22528
	s_waitcnt lgkmcnt(11)
	v_mfma_f32_16x16x32_bf16 v[92:95], v[44:47], v[60:63], v[92:95]
	s_waitcnt lgkmcnt(10)
	v_mfma_f32_16x16x32_bf16 v[88:91], v[44:47], v[68:71], v[88:91]
	s_waitcnt lgkmcnt(9)
	v_mfma_f32_16x16x32_bf16 v[84:87], v[44:47], v[72:75], v[84:87]
	s_waitcnt lgkmcnt(8)
	v_mfma_f32_16x16x32_bf16 v[44:47], v[44:47], v[76:79], v[80:83]
	s_nop 2
	global_load_dwordx4 v[80:83], v[224:225], off
	s_waitcnt vmcnt(6)
	ds_write_b128 v156, v[96:99] offset:32768
	v_add_co_u32_e32 v96, vcc, s11, v224
	v_mfma_f32_16x16x32_bf16 v[64:67], v[48:51], v[60:63], v[64:67]
	s_nop 0
	v_addc_co_u32_e32 v97, vcc, 0, v225, vcc
	v_mfma_f32_16x16x32_bf16 v[40:43], v[48:51], v[68:71], v[40:43]
	v_mfma_f32_16x16x32_bf16 v[36:39], v[48:51], v[72:75], v[36:39]
	v_mfma_f32_16x16x32_bf16 v[32:35], v[48:51], v[76:79], v[32:35]
	global_load_dwordx4 v[48:51], v[96:97], off
	v_add_co_u32_e32 v96, vcc, s33, v224
	ds_write_b128 v156, v[100:103] offset:36864
	s_nop 0
	v_addc_co_u32_e32 v97, vcc, 0, v225, vcc
	v_mfma_f32_16x16x32_bf16 v[28:31], v[52:55], v[60:63], v[28:31]
	v_mfma_f32_16x16x32_bf16 v[24:27], v[52:55], v[68:71], v[24:27]
	v_mfma_f32_16x16x32_bf16 v[20:23], v[52:55], v[72:75], v[20:23]
	v_mfma_f32_16x16x32_bf16 v[16:19], v[52:55], v[76:79], v[16:19]
	global_load_dwordx4 v[52:55], v[96:97], off
	ds_write_b128 v156, v[104:107] offset:40960
	v_mfma_f32_16x16x32_bf16 v[12:15], v[56:59], v[60:63], v[12:15]
	v_add_co_u32_e32 v60, vcc, s59, v224
	s_nop 1
	v_addc_co_u32_e32 v61, vcc, 0, v225, vcc
	v_mfma_f32_16x16x32_bf16 v[8:11], v[56:59], v[68:71], v[8:11]
	v_mfma_f32_16x16x32_bf16 v[4:7], v[56:59], v[72:75], v[4:7]
	v_mfma_f32_16x16x32_bf16 v[0:3], v[56:59], v[76:79], v[0:3]
	global_load_dwordx4 v[56:59], v[60:61], off
	s_waitcnt vmcnt(7)
	ds_write_b128 v156, v[112:115] offset:45056
	s_waitcnt lgkmcnt(5)
	v_mfma_f32_16x16x32_bf16 v[72:75], v[192:195], v[216:219], v[84:87]
	s_nop 2
	v_lshl_add_u64 v[84:85], v[140:141], 0, s[92:93]
	v_add_co_u32_e32 v86, vcc, s11, v84
	v_mfma_f32_16x16x32_bf16 v[60:63], v[192:195], v[208:211], v[92:95]
	s_nop 0
	v_addc_co_u32_e32 v87, vcc, 0, v85, vcc
	v_mfma_f32_16x16x32_bf16 v[68:71], v[192:195], v[212:215], v[88:91]
	s_waitcnt lgkmcnt(4)
	v_mfma_f32_16x16x32_bf16 v[44:47], v[192:195], v[220:223], v[44:47]
	global_load_dwordx4 v[76:79], v[84:85], off
	ds_write_b128 v156, v[108:111] offset:49152
	v_mfma_f32_16x16x32_bf16 v[64:67], v[196:199], v[208:211], v[64:67]
	v_mfma_f32_16x16x32_bf16 v[40:43], v[196:199], v[212:215], v[40:43]
	v_mfma_f32_16x16x32_bf16 v[36:39], v[196:199], v[216:219], v[36:39]
	v_mfma_f32_16x16x32_bf16 v[32:35], v[196:199], v[220:223], v[32:35]
	global_load_dwordx4 v[192:195], v[86:87], off
	v_add_co_u32_e32 v86, vcc, s33, v84
	s_waitcnt vmcnt(8)
	ds_write_b128 v156, v[116:119] offset:53248
	v_addc_co_u32_e32 v87, vcc, 0, v85, vcc
	v_add_co_u32_e32 v84, vcc, s59, v84
	v_mfma_f32_16x16x32_bf16 v[28:31], v[200:203], v[208:211], v[28:31]
	s_nop 0
	v_addc_co_u32_e32 v85, vcc, 0, v85, vcc
	v_mfma_f32_16x16x32_bf16 v[24:27], v[200:203], v[212:215], v[24:27]
	v_mfma_f32_16x16x32_bf16 v[20:23], v[200:203], v[216:219], v[20:23]
	v_mfma_f32_16x16x32_bf16 v[16:19], v[200:203], v[220:223], v[16:19]
	global_load_dwordx4 v[196:199], v[86:87], off
	s_waitcnt vmcnt(8)
	ds_write_b128 v156, v[120:123] offset:57344
	v_mfma_f32_16x16x32_bf16 v[12:15], v[204:207], v[208:211], v[12:15]
	v_mfma_f32_16x16x32_bf16 v[8:11], v[204:207], v[212:215], v[8:11]
	v_mfma_f32_16x16x32_bf16 v[4:7], v[204:207], v[216:219], v[4:7]
	v_mfma_f32_16x16x32_bf16 v[0:3], v[204:207], v[220:223], v[0:3]
	global_load_dwordx4 v[200:203], v[84:85], off
	s_waitcnt vmcnt(8)
	ds_write_b128 v156, v[124:127] offset:61440
	s_waitcnt lgkmcnt(0)
	s_barrier
	ds_read_b128 v[84:87], v180 offset:32768
	ds_read_b128 v[88:91], v180 offset:34816
	ds_read_b128 v[112:115], v181 offset:49152
	ds_read_b128 v[116:119], v181 offset:51200
	ds_read_b128 v[120:123], v181 offset:53248
	ds_read_b128 v[124:127], v181 offset:55296
	ds_read_b128 v[92:95], v180 offset:36864
	ds_read_b128 v[108:111], v180 offset:38912
	ds_read_b128 v[204:207], v182 offset:32768
	s_min_u32 s24, s3, 12
	s_lshl_b32 s92, s24, 7
	ds_read_b128 v[208:211], v182 offset:34816
	ds_read_b128 v[212:215], v182 offset:36864
	ds_read_b128 v[216:219], v182 offset:38912
	ds_read_b128 v[220:223], v186 offset:49152
	ds_read_b128 v[224:227], v186 offset:51200
	ds_read_b128 v[228:231], v186 offset:53248
	ds_read_b128 v[232:235], v186 offset:55296
	s_waitcnt lgkmcnt(13)
	v_mfma_f32_16x16x32_bf16 v[60:63], v[84:87], v[112:115], v[60:63]
	s_waitcnt lgkmcnt(12)
	v_mfma_f32_16x16x32_bf16 v[68:71], v[84:87], v[116:119], v[68:71]
	s_waitcnt lgkmcnt(11)
	v_mfma_f32_16x16x32_bf16 v[72:75], v[84:87], v[120:123], v[72:75]
	s_waitcnt lgkmcnt(10)
	v_mfma_f32_16x16x32_bf16 v[44:47], v[84:87], v[124:127], v[44:47]
	v_lshl_add_u64 v[84:85], v[138:139], 0, s[92:93]
	global_load_dwordx4 v[96:99], v[84:85], off offset:384
	s_waitcnt vmcnt(8)
	ds_write_b128 v156, v[80:83]
	v_add_co_u32_e32 v80, vcc, s11, v84
	v_mfma_f32_16x16x32_bf16 v[64:67], v[88:91], v[112:115], v[64:67]
	s_nop 0
	v_addc_co_u32_e32 v81, vcc, 0, v85, vcc
	v_mfma_f32_16x16x32_bf16 v[40:43], v[88:91], v[116:119], v[40:43]
	v_mfma_f32_16x16x32_bf16 v[36:39], v[88:91], v[120:123], v[36:39]
	v_mfma_f32_16x16x32_bf16 v[32:35], v[88:91], v[124:127], v[32:35]
	global_load_dwordx4 v[100:103], v[80:81], off offset:384
	s_waitcnt vmcnt(8)
	ds_write_b128 v156, v[48:51] offset:4096
	v_add_co_u32_e32 v48, vcc, s33, v84
	s_waitcnt lgkmcnt(11)
	v_mfma_f32_16x16x32_bf16 v[28:31], v[92:95], v[112:115], v[28:31]
	v_addc_co_u32_e32 v49, vcc, 0, v85, vcc
	v_mfma_f32_16x16x32_bf16 v[24:27], v[92:95], v[116:119], v[24:27]
	v_mfma_f32_16x16x32_bf16 v[20:23], v[92:95], v[120:123], v[20:23]
	v_mfma_f32_16x16x32_bf16 v[16:19], v[92:95], v[124:127], v[16:19]
	global_load_dwordx4 v[104:107], v[48:49], off offset:384
	v_add_co_u32_e32 v48, vcc, s59, v84
	s_waitcnt vmcnt(8)
	ds_write_b128 v156, v[52:55] offset:8192
	v_addc_co_u32_e32 v49, vcc, 0, v85, vcc
	s_waitcnt lgkmcnt(11)
	v_mfma_f32_16x16x32_bf16 v[12:15], v[108:111], v[112:115], v[12:15]
	v_mfma_f32_16x16x32_bf16 v[8:11], v[108:111], v[116:119], v[8:11]
	v_mfma_f32_16x16x32_bf16 v[4:7], v[108:111], v[120:123], v[4:7]
	v_mfma_f32_16x16x32_bf16 v[0:3], v[108:111], v[124:127], v[0:3]
	global_load_dwordx4 v[112:115], v[48:49], off offset:384
	s_waitcnt vmcnt(8)
	ds_write_b128 v156, v[56:59] offset:12288
	s_waitcnt lgkmcnt(4)
	v_mfma_f32_16x16x32_bf16 v[80:83], v[204:207], v[232:235], v[44:47]
	s_nop 2
	v_lshl_add_u64 v[44:45], v[140:141], 0, s[92:93]
	v_add_co_u32_e32 v46, vcc, s11, v44
	v_mfma_f32_16x16x32_bf16 v[92:95], v[204:207], v[220:223], v[60:63]
	s_nop 0
	v_addc_co_u32_e32 v47, vcc, 0, v45, vcc
	v_mfma_f32_16x16x32_bf16 v[88:91], v[204:207], v[224:227], v[68:71]
	v_mfma_f32_16x16x32_bf16 v[84:87], v[204:207], v[228:231], v[72:75]
	global_load_dwordx4 v[108:111], v[44:45], off offset:384
	s_waitcnt vmcnt(8)
	ds_write_b128 v156, v[76:79] offset:16384
	v_mfma_f32_16x16x32_bf16 v[64:67], v[208:211], v[220:223], v[64:67]
	v_mfma_f32_16x16x32_bf16 v[40:43], v[208:211], v[224:227], v[40:43]
	v_mfma_f32_16x16x32_bf16 v[36:39], v[208:211], v[228:231], v[36:39]
	v_mfma_f32_16x16x32_bf16 v[32:35], v[208:211], v[232:235], v[32:35]
	global_load_dwordx4 v[116:119], v[46:47], off offset:384
	v_add_co_u32_e32 v46, vcc, s33, v44
	s_waitcnt vmcnt(8)
	ds_write_b128 v156, v[192:195] offset:20480
	v_addc_co_u32_e32 v47, vcc, 0, v45, vcc
	v_add_co_u32_e32 v44, vcc, s59, v44
	v_mfma_f32_16x16x32_bf16 v[28:31], v[212:215], v[220:223], v[28:31]
	s_nop 0
	v_addc_co_u32_e32 v45, vcc, 0, v45, vcc
	v_mfma_f32_16x16x32_bf16 v[24:27], v[212:215], v[224:227], v[24:27]
	v_mfma_f32_16x16x32_bf16 v[20:23], v[212:215], v[228:231], v[20:23]
	v_mfma_f32_16x16x32_bf16 v[16:19], v[212:215], v[232:235], v[16:19]
	global_load_dwordx4 v[120:123], v[46:47], off offset:384
	s_waitcnt vmcnt(8)
	ds_write_b128 v156, v[196:199] offset:24576
	v_mfma_f32_16x16x32_bf16 v[12:15], v[216:219], v[220:223], v[12:15]
	v_mfma_f32_16x16x32_bf16 v[8:11], v[216:219], v[224:227], v[8:11]
	v_mfma_f32_16x16x32_bf16 v[4:7], v[216:219], v[228:231], v[4:7]
	v_mfma_f32_16x16x32_bf16 v[0:3], v[216:219], v[232:235], v[0:3]
	global_load_dwordx4 v[124:127], v[44:45], off offset:384
	s_waitcnt vmcnt(8)
	ds_write_b128 v156, v[200:203] offset:28672
	s_cmp_gt_u32 s3, 11
	s_mov_b32 s24, s3
	s_waitcnt lgkmcnt(0)
	s_barrier
	s_cbranch_scc0 .LBB0_372
.Ltail372:
	s_add_i32 s3, s24, 2
	v_add_u32_e32 v180, v142, v144
	ds_read_b128 v[44:47], v180
	ds_read_b128 v[48:51], v180 offset:2048
	v_add_u32_e32 v181, v143, v144
	ds_read_b128 v[52:55], v180 offset:4096
	ds_read_b128 v[56:59], v180 offset:6144
	ds_read_b128 v[60:63], v181 offset:16384
	ds_read_b128 v[68:71], v181 offset:18432
	ds_read_b128 v[72:75], v181 offset:20480
	ds_read_b128 v[76:79], v181 offset:22528
	v_add_u32_e32 v182, v142, v145
	s_add_i32 s24, s24, 4
	ds_read_b128 v[192:195], v182
	s_min_u32 s24, s24, 15
	s_lshl_b32 s92, s24, 7
	v_add_u32_e32 v186, v143, v145
	v_lshl_add_u64 v[224:225], v[138:139], 0, s[92:93]
	ds_read_b128 v[196:199], v182 offset:2048
	ds_read_b128 v[200:203], v182 offset:4096
	ds_read_b128 v[204:207], v182 offset:6144
	ds_read_b128 v[208:211], v186 offset:16384
	ds_read_b128 v[212:215], v186 offset:18432
	ds_read_b128 v[216:219], v186 offset:20480
	ds_read_b128 v[220:223], v186 offset:22528
	s_waitcnt lgkmcnt(11)
	v_mfma_f32_16x16x32_bf16 v[92:95], v[44:47], v[60:63], v[92:95]
	s_waitcnt lgkmcnt(10)
	v_mfma_f32_16x16x32_bf16 v[88:91], v[44:47], v[68:71], v[88:91]
	s_waitcnt lgkmcnt(9)
	v_mfma_f32_16x16x32_bf16 v[84:87], v[44:47], v[72:75], v[84:87]
	s_waitcnt lgkmcnt(8)
	v_mfma_f32_16x16x32_bf16 v[44:47], v[44:47], v[76:79], v[80:83]
	s_nop 2
	s_waitcnt vmcnt(7)
	ds_write_b128 v156, v[96:99] offset:32768
	v_add_co_u32_e32 v96, vcc, s11, v224
	v_mfma_f32_16x16x32_bf16 v[64:67], v[48:51], v[60:63], v[64:67]
	s_nop 0
	v_addc_co_u32_e32 v97, vcc, 0, v225, vcc
	v_mfma_f32_16x16x32_bf16 v[40:43], v[48:51], v[68:71], v[40:43]
	v_mfma_f32_16x16x32_bf16 v[36:39], v[48:51], v[72:75], v[36:39]
	v_mfma_f32_16x16x32_bf16 v[32:35], v[48:51], v[76:79], v[32:35]
	v_add_co_u32_e32 v96, vcc, s33, v224
	s_waitcnt vmcnt(6)
	ds_write_b128 v156, v[100:103] offset:36864
	s_nop 0
	v_addc_co_u32_e32 v97, vcc, 0, v225, vcc
	v_mfma_f32_16x16x32_bf16 v[28:31], v[52:55], v[60:63], v[28:31]
	v_mfma_f32_16x16x32_bf16 v[24:27], v[52:55], v[68:71], v[24:27]
	v_mfma_f32_16x16x32_bf16 v[20:23], v[52:55], v[72:75], v[20:23]
	v_mfma_f32_16x16x32_bf16 v[16:19], v[52:55], v[76:79], v[16:19]
	s_waitcnt vmcnt(5)
	ds_write_b128 v156, v[104:107] offset:40960
	v_mfma_f32_16x16x32_bf16 v[12:15], v[56:59], v[60:63], v[12:15]
	v_add_co_u32_e32 v60, vcc, s59, v224
	s_nop 1
	v_addc_co_u32_e32 v61, vcc, 0, v225, vcc
	v_mfma_f32_16x16x32_bf16 v[8:11], v[56:59], v[68:71], v[8:11]
	v_mfma_f32_16x16x32_bf16 v[4:7], v[56:59], v[72:75], v[4:7]
	v_mfma_f32_16x16x32_bf16 v[0:3], v[56:59], v[76:79], v[0:3]
	s_waitcnt vmcnt(4)
	ds_write_b128 v156, v[112:115] offset:45056
	s_waitcnt lgkmcnt(5)
	v_mfma_f32_16x16x32_bf16 v[72:75], v[192:195], v[216:219], v[84:87]
	s_nop 2
	v_lshl_add_u64 v[84:85], v[140:141], 0, s[92:93]
	v_add_co_u32_e32 v86, vcc, s11, v84
	v_mfma_f32_16x16x32_bf16 v[60:63], v[192:195], v[208:211], v[92:95]
	s_nop 0
	v_addc_co_u32_e32 v87, vcc, 0, v85, vcc
	v_mfma_f32_16x16x32_bf16 v[68:71], v[192:195], v[212:215], v[88:91]
	s_waitcnt lgkmcnt(4)
	v_mfma_f32_16x16x32_bf16 v[44:47], v[192:195], v[220:223], v[44:47]
	s_waitcnt vmcnt(3)
	ds_write_b128 v156, v[108:111] offset:49152
	v_mfma_f32_16x16x32_bf16 v[64:67], v[196:199], v[208:211], v[64:67]
	v_mfma_f32_16x16x32_bf16 v[40:43], v[196:199], v[212:215], v[40:43]
	v_mfma_f32_16x16x32_bf16 v[36:39], v[196:199], v[216:219], v[36:39]
	v_mfma_f32_16x16x32_bf16 v[32:35], v[196:199], v[220:223], v[32:35]
	v_add_co_u32_e32 v86, vcc, s33, v84
	s_waitcnt vmcnt(2)
	ds_write_b128 v156, v[116:119] offset:53248
	v_addc_co_u32_e32 v87, vcc, 0, v85, vcc
	v_add_co_u32_e32 v84, vcc, s59, v84
	v_mfma_f32_16x16x32_bf16 v[28:31], v[200:203], v[208:211], v[28:31]
	s_nop 0
	v_addc_co_u32_e32 v85, vcc, 0, v85, vcc
	v_mfma_f32_16x16x32_bf16 v[24:27], v[200:203], v[212:215], v[24:27]
	v_mfma_f32_16x16x32_bf16 v[20:23], v[200:203], v[216:219], v[20:23]
	v_mfma_f32_16x16x32_bf16 v[16:19], v[200:203], v[220:223], v[16:19]
	s_waitcnt vmcnt(1)
	ds_write_b128 v156, v[120:123] offset:57344
	v_mfma_f32_16x16x32_bf16 v[12:15], v[204:207], v[208:211], v[12:15]
	v_mfma_f32_16x16x32_bf16 v[8:11], v[204:207], v[212:215], v[8:11]
	v_mfma_f32_16x16x32_bf16 v[4:7], v[204:207], v[216:219], v[4:7]
	v_mfma_f32_16x16x32_bf16 v[0:3], v[204:207], v[220:223], v[0:3]
	s_waitcnt vmcnt(0)
	ds_write_b128 v156, v[124:127] offset:61440
	s_waitcnt lgkmcnt(0)
	s_barrier
	ds_read_b128 v[84:87], v180 offset:32768
	ds_read_b128 v[88:91], v180 offset:34816
	ds_read_b128 v[112:115], v181 offset:49152
	ds_read_b128 v[116:119], v181 offset:51200
	ds_read_b128 v[120:123], v181 offset:53248
	ds_read_b128 v[124:127], v181 offset:55296
	ds_read_b128 v[92:95], v180 offset:36864
	ds_read_b128 v[108:111], v180 offset:38912
	ds_read_b128 v[204:207], v182 offset:32768
	s_min_u32 s24, s3, 12
	s_lshl_b32 s92, s24, 7
	ds_read_b128 v[208:211], v182 offset:34816
	ds_read_b128 v[212:215], v182 offset:36864
	ds_read_b128 v[216:219], v182 offset:38912
	ds_read_b128 v[220:223], v186 offset:49152
	ds_read_b128 v[224:227], v186 offset:51200
	ds_read_b128 v[228:231], v186 offset:53248
	ds_read_b128 v[232:235], v186 offset:55296
	s_waitcnt lgkmcnt(13)
	v_mfma_f32_16x16x32_bf16 v[60:63], v[84:87], v[112:115], v[60:63]
	s_waitcnt lgkmcnt(12)
	v_mfma_f32_16x16x32_bf16 v[68:71], v[84:87], v[116:119], v[68:71]
	s_waitcnt lgkmcnt(11)
	v_mfma_f32_16x16x32_bf16 v[72:75], v[84:87], v[120:123], v[72:75]
	s_waitcnt lgkmcnt(10)
	v_mfma_f32_16x16x32_bf16 v[44:47], v[84:87], v[124:127], v[44:47]
	v_lshl_add_u64 v[84:85], v[138:139], 0, s[92:93]
	v_add_co_u32_e32 v80, vcc, s11, v84
	v_mfma_f32_16x16x32_bf16 v[64:67], v[88:91], v[112:115], v[64:67]
	s_nop 0
	v_addc_co_u32_e32 v81, vcc, 0, v85, vcc
	v_mfma_f32_16x16x32_bf16 v[40:43], v[88:91], v[116:119], v[40:43]
	v_mfma_f32_16x16x32_bf16 v[36:39], v[88:91], v[120:123], v[36:39]
	v_mfma_f32_16x16x32_bf16 v[32:35], v[88:91], v[124:127], v[32:35]
	v_add_co_u32_e32 v48, vcc, s33, v84
	s_waitcnt lgkmcnt(9)
	v_mfma_f32_16x16x32_bf16 v[28:31], v[92:95], v[112:115], v[28:31]
	v_addc_co_u32_e32 v49, vcc, 0, v85, vcc
	v_mfma_f32_16x16x32_bf16 v[24:27], v[92:95], v[116:119], v[24:27]
	v_mfma_f32_16x16x32_bf16 v[20:23], v[92:95], v[120:123], v[20:23]
	v_mfma_f32_16x16x32_bf16 v[16:19], v[92:95], v[124:127], v[16:19]
	v_add_co_u32_e32 v48, vcc, s59, v84
	v_addc_co_u32_e32 v49, vcc, 0, v85, vcc
	s_waitcnt lgkmcnt(8)
	v_mfma_f32_16x16x32_bf16 v[12:15], v[108:111], v[112:115], v[12:15]
	v_mfma_f32_16x16x32_bf16 v[8:11], v[108:111], v[116:119], v[8:11]
	v_mfma_f32_16x16x32_bf16 v[4:7], v[108:111], v[120:123], v[4:7]
	v_mfma_f32_16x16x32_bf16 v[0:3], v[108:111], v[124:127], v[0:3]
	s_waitcnt lgkmcnt(0)
	v_mfma_f32_16x16x32_bf16 v[80:83], v[204:207], v[232:235], v[44:47]
	s_nop 2
	v_lshl_add_u64 v[44:45], v[140:141], 0, s[92:93]
	v_add_co_u32_e32 v46, vcc, s11, v44
	v_mfma_f32_16x16x32_bf16 v[92:95], v[204:207], v[220:223], v[60:63]
	s_nop 0
	v_addc_co_u32_e32 v47, vcc, 0, v45, vcc
	v_mfma_f32_16x16x32_bf16 v[88:91], v[204:207], v[224:227], v[68:71]
	v_mfma_f32_16x16x32_bf16 v[84:87], v[204:207], v[228:231], v[72:75]
	v_mfma_f32_16x16x32_bf16 v[64:67], v[208:211], v[220:223], v[64:67]
	v_mfma_f32_16x16x32_bf16 v[40:43], v[208:211], v[224:227], v[40:43]
	v_mfma_f32_16x16x32_bf16 v[36:39], v[208:211], v[228:231], v[36:39]
	v_mfma_f32_16x16x32_bf16 v[32:35], v[208:211], v[232:235], v[32:35]
	v_add_co_u32_e32 v46, vcc, s33, v44
	v_addc_co_u32_e32 v47, vcc, 0, v45, vcc
	v_add_co_u32_e32 v44, vcc, s59, v44
	v_mfma_f32_16x16x32_bf16 v[28:31], v[212:215], v[220:223], v[28:31]
	s_nop 0
	v_addc_co_u32_e32 v45, vcc, 0, v45, vcc
	v_mfma_f32_16x16x32_bf16 v[24:27], v[212:215], v[224:227], v[24:27]
	v_mfma_f32_16x16x32_bf16 v[20:23], v[212:215], v[228:231], v[20:23]
	v_mfma_f32_16x16x32_bf16 v[16:19], v[212:215], v[232:235], v[16:19]
	v_mfma_f32_16x16x32_bf16 v[12:15], v[216:219], v[220:223], v[12:15]
	v_mfma_f32_16x16x32_bf16 v[8:11], v[216:219], v[224:227], v[8:11]
	v_mfma_f32_16x16x32_bf16 v[4:7], v[216:219], v[228:231], v[4:7]
	v_mfma_f32_16x16x32_bf16 v[0:3], v[216:219], v[232:235], v[0:3]
	s_mov_b32 s24, s3
	s_waitcnt lgkmcnt(0)
	s_barrier
	s_and_saveexec_b64 s[24:25], s[36:37]
	s_cbranch_execz .LBB0_366
	v_add_f32_e32 v44, 0, v128
	v_add_f32_e32 v44, v44, v157
	v_add_f32_e32 v44, v44, v158
	v_add_f32_e32 v44, v44, v159
	v_add_f32_e32 v44, v44, v160
	v_add_f32_e32 v44, v44, v161
	v_add_f32_e32 v44, v44, v162
	v_add_f32_e32 v44, v44, v163
	v_add_f32_e32 v44, v44, v164
	v_add_f32_e32 v44, v44, v165
	v_add_f32_e32 v44, v44, v168
	v_add_f32_e32 v44, v44, v175
	v_add_f32_e32 v44, v44, v179
	v_add_f32_e32 v44, v44, v183
	v_add_f32_e32 v44, v44, v190
	v_add_f32_e32 v44, v44, v191
	v_fmamk_f32 v44, v44, 0x3a800000, v167
	s_mov_b32 s3, 0x800000
	v_mul_f32_e32 v45, 0x4b800000, v44
	v_cmp_gt_f32_e32 vcc, s3, v44
	s_nop 1
	v_cndmask_b32_e32 v44, v44, v45, vcc
	v_rsq_f32_e32 v44, v44
	s_nop 0
	v_mul_f32_e32 v45, 0x45800000, v44
	v_cndmask_b32_e32 v44, v44, v45, vcc
	ds_write_b32 v155, v44
	s_branch .LBB0_366

.Ltail392:
	s_add_i32 s0, s1, 2
	v_add_u32_e32 v111, v104, v105
	ds_read_b128 v[136:139], v111 offset:16384
	ds_read_b128 v[140:143], v111 offset:18432
	ds_read_b128 v[144:147], v111 offset:20480
	ds_read_b128 v[148:151], v111 offset:22528
	v_add_u32_e32 v110, v103, v105
	ds_read_b128 v[116:119], v110
	s_add_i32 s1, s1, 4
	ds_read_b128 v[120:123], v110 offset:2048
	s_min_u32 s1, s1, 15
	v_add_u32_e32 v113, v104, v114
	s_lshl_b32 s92, s1, 7
	ds_read_b128 v[124:127], v110 offset:4096
	v_add_u32_e32 v112, v103, v114
	ds_read_b128 v[194:197], v113 offset:16384
	ds_read_b128 v[198:201], v113 offset:18432
	ds_read_b128 v[202:205], v113 offset:20480
	ds_read_b128 v[206:209], v113 offset:22528
	v_lshl_add_u64 v[164:165], v[98:99], 0, s[92:93]
	ds_read_b128 v[132:135], v110 offset:6144
	ds_read_b128 v[152:155], v112
	ds_read_b128 v[156:159], v112 offset:2048
	ds_read_b128 v[160:163], v112 offset:4096
	ds_read_b128 v[190:193], v112 offset:6144
	s_waitcnt lgkmcnt(11)
	v_mfma_f32_16x16x32_bf16 v[92:95], v[136:139], v[116:119], v[92:95]
	v_mfma_f32_16x16x32_bf16 v[88:91], v[140:143], v[116:119], v[88:91]
	v_mfma_f32_16x16x32_bf16 v[52:55], v[144:147], v[116:119], v[52:55]
	v_mfma_f32_16x16x32_bf16 v[48:51], v[148:151], v[116:119], v[48:51]
	s_waitcnt vmcnt(7)
	ds_write_b128 v109, v[56:59] offset:32768
	v_add_co_u32_e32 v56, vcc, s11, v164
	s_waitcnt lgkmcnt(11)
	v_mfma_f32_16x16x32_bf16 v[44:47], v[136:139], v[120:123], v[44:47]
	v_addc_co_u32_e32 v57, vcc, 0, v165, vcc
	v_mfma_f32_16x16x32_bf16 v[40:43], v[140:143], v[120:123], v[40:43]
	v_mfma_f32_16x16x32_bf16 v[36:39], v[144:147], v[120:123], v[36:39]
	v_mfma_f32_16x16x32_bf16 v[32:35], v[148:151], v[120:123], v[32:35]
	v_add_co_u32_e32 v56, vcc, s33, v164
	s_waitcnt vmcnt(6)
	ds_write_b128 v109, v[60:63] offset:36864
	s_nop 0
	v_addc_co_u32_e32 v57, vcc, 0, v165, vcc
	s_waitcnt lgkmcnt(11)
	v_mfma_f32_16x16x32_bf16 v[28:31], v[136:139], v[124:127], v[28:31]
	v_mfma_f32_16x16x32_bf16 v[24:27], v[140:143], v[124:127], v[24:27]
	v_mfma_f32_16x16x32_bf16 v[20:23], v[144:147], v[124:127], v[20:23]
	v_mfma_f32_16x16x32_bf16 v[16:19], v[148:151], v[124:127], v[16:19]
	v_add_co_u32_e32 v56, vcc, s59, v164
	s_waitcnt vmcnt(5)
	ds_write_b128 v109, v[64:67] offset:40960
	s_nop 0
	v_addc_co_u32_e32 v57, vcc, 0, v165, vcc
	v_lshl_add_u64 v[64:65], v[100:101], 0, s[92:93]
	v_add_co_u32_e32 v66, vcc, s11, v64
	s_waitcnt lgkmcnt(7)
	v_mfma_f32_16x16x32_bf16 v[12:15], v[136:139], v[132:135], v[12:15]
	v_addc_co_u32_e32 v67, vcc, 0, v65, vcc
	v_mfma_f32_16x16x32_bf16 v[8:11], v[140:143], v[132:135], v[8:11]
	v_mfma_f32_16x16x32_bf16 v[4:7], v[144:147], v[132:135], v[4:7]
	v_mfma_f32_16x16x32_bf16 v[0:3], v[148:151], v[132:135], v[0:3]
	s_waitcnt vmcnt(4)
	ds_write_b128 v109, v[72:75] offset:45056
	s_waitcnt lgkmcnt(7)
	v_mfma_f32_16x16x32_bf16 v[56:59], v[194:197], v[152:155], v[92:95]
	v_mfma_f32_16x16x32_bf16 v[60:63], v[198:201], v[152:155], v[88:91]
	v_mfma_f32_16x16x32_bf16 v[52:55], v[202:205], v[152:155], v[52:55]
	v_mfma_f32_16x16x32_bf16 v[48:51], v[206:209], v[152:155], v[48:51]
	s_waitcnt vmcnt(3)
	ds_write_b128 v109, v[68:71] offset:49152
	s_waitcnt lgkmcnt(7)
	v_mfma_f32_16x16x32_bf16 v[44:47], v[194:197], v[156:159], v[44:47]
	v_mfma_f32_16x16x32_bf16 v[40:43], v[198:201], v[156:159], v[40:43]
	v_mfma_f32_16x16x32_bf16 v[36:39], v[202:205], v[156:159], v[36:39]
	v_mfma_f32_16x16x32_bf16 v[32:35], v[206:209], v[156:159], v[32:35]
	v_add_co_u32_e32 v66, vcc, s33, v64
	s_waitcnt vmcnt(2)
	ds_write_b128 v109, v[76:79] offset:53248
	v_addc_co_u32_e32 v67, vcc, 0, v65, vcc
	v_add_co_u32_e32 v64, vcc, s59, v64
	s_waitcnt lgkmcnt(7)
	v_mfma_f32_16x16x32_bf16 v[28:31], v[194:197], v[160:163], v[28:31]
	v_addc_co_u32_e32 v65, vcc, 0, v65, vcc
	v_mfma_f32_16x16x32_bf16 v[24:27], v[198:201], v[160:163], v[24:27]
	v_mfma_f32_16x16x32_bf16 v[20:23], v[202:205], v[160:163], v[20:23]
	v_mfma_f32_16x16x32_bf16 v[16:19], v[206:209], v[160:163], v[16:19]
	s_waitcnt vmcnt(1)
	ds_write_b128 v109, v[80:83] offset:57344
	s_waitcnt lgkmcnt(7)
	v_mfma_f32_16x16x32_bf16 v[12:15], v[194:197], v[190:193], v[12:15]
	v_mfma_f32_16x16x32_bf16 v[8:11], v[198:201], v[190:193], v[8:11]
	v_mfma_f32_16x16x32_bf16 v[4:7], v[202:205], v[190:193], v[4:7]
	v_mfma_f32_16x16x32_bf16 v[0:3], v[206:209], v[190:193], v[0:3]
	s_waitcnt vmcnt(0)
	ds_write_b128 v109, v[84:87] offset:61440
	s_waitcnt lgkmcnt(0)
	s_barrier
	ds_read_b128 v[84:87], v111 offset:51200
	ds_read_b128 v[80:83], v111 offset:49152
	ds_read_b128 v[88:91], v111 offset:53248
	ds_read_b128 v[92:95], v111 offset:55296
	ds_read_b128 v[64:67], v110 offset:32768
	s_min_u32 s1, s0, 12
	s_lshl_b32 s92, s1, 7
	ds_read_b128 v[68:71], v110 offset:34816
	v_lshl_add_u64 v[164:165], v[98:99], 0, s[92:93]
	ds_read_b128 v[72:75], v110 offset:36864
	ds_read_b128 v[76:79], v110 offset:38912
	ds_read_b128 v[152:155], v112 offset:32768
	ds_read_b128 v[156:159], v112 offset:34816
	ds_read_b128 v[160:163], v112 offset:36864
	ds_read_b128 v[190:193], v112 offset:38912
	ds_read_b128 v[194:197], v113 offset:49152
	ds_read_b128 v[198:201], v113 offset:51200
	ds_read_b128 v[202:205], v113 offset:53248
	ds_read_b128 v[206:209], v113 offset:55296
	s_waitcnt lgkmcnt(11)
	v_mfma_f32_16x16x32_bf16 v[214:217], v[84:87], v[64:67], v[60:63]
	v_mfma_f32_16x16x32_bf16 v[210:213], v[80:83], v[64:67], v[56:59]
	s_nop 1
	v_add_co_u32_e32 v60, vcc, s11, v164
	s_nop 1
	v_addc_co_u32_e32 v61, vcc, 0, v165, vcc
	v_mfma_f32_16x16x32_bf16 v[52:55], v[88:91], v[64:67], v[52:55]
	v_mfma_f32_16x16x32_bf16 v[48:51], v[92:95], v[64:67], v[48:51]
	v_add_co_u32_e32 v64, vcc, s33, v164
	s_nop 0
	v_addc_co_u32_e32 v65, vcc, 0, v165, vcc
	s_waitcnt lgkmcnt(10)
	v_mfma_f32_16x16x32_bf16 v[44:47], v[80:83], v[68:71], v[44:47]
	v_mfma_f32_16x16x32_bf16 v[40:43], v[84:87], v[68:71], v[40:43]
	v_mfma_f32_16x16x32_bf16 v[36:39], v[88:91], v[68:71], v[36:39]
	v_mfma_f32_16x16x32_bf16 v[32:35], v[92:95], v[68:71], v[32:35]
	v_add_co_u32_e32 v68, vcc, s59, v164
	s_waitcnt lgkmcnt(9)
	v_mfma_f32_16x16x32_bf16 v[28:31], v[80:83], v[72:75], v[28:31]
	v_addc_co_u32_e32 v69, vcc, 0, v165, vcc
	v_mfma_f32_16x16x32_bf16 v[24:27], v[84:87], v[72:75], v[24:27]
	v_mfma_f32_16x16x32_bf16 v[20:23], v[88:91], v[72:75], v[20:23]
	v_mfma_f32_16x16x32_bf16 v[16:19], v[92:95], v[72:75], v[16:19]
	s_waitcnt lgkmcnt(8)
	v_mfma_f32_16x16x32_bf16 v[8:11], v[84:87], v[76:79], v[8:11]
	v_lshl_add_u64 v[84:85], v[100:101], 0, s[92:93]
	v_mfma_f32_16x16x32_bf16 v[12:15], v[80:83], v[76:79], v[12:15]
	v_mfma_f32_16x16x32_bf16 v[4:7], v[88:91], v[76:79], v[4:7]
	v_mfma_f32_16x16x32_bf16 v[0:3], v[92:95], v[76:79], v[0:3]
	v_add_co_u32_e32 v76, vcc, s11, v84
	s_nop 0
	v_addc_co_u32_e32 v77, vcc, 0, v85, vcc
	v_add_co_u32_e32 v80, vcc, s33, v84
	v_addc_co_u32_e32 v81, vcc, 0, v85, vcc
	s_waitcnt lgkmcnt(3)
	v_mfma_f32_16x16x32_bf16 v[92:95], v[194:197], v[152:155], v[210:213]
	s_waitcnt lgkmcnt(2)
	v_mfma_f32_16x16x32_bf16 v[88:91], v[198:201], v[152:155], v[214:217]
	s_waitcnt lgkmcnt(1)
	v_mfma_f32_16x16x32_bf16 v[52:55], v[202:205], v[152:155], v[52:55]
	s_waitcnt lgkmcnt(0)
	v_mfma_f32_16x16x32_bf16 v[48:51], v[206:209], v[152:155], v[48:51]
	v_add_co_u32_e32 v84, vcc, s59, v84
	v_addc_co_u32_e32 v85, vcc, 0, v85, vcc
	v_mfma_f32_16x16x32_bf16 v[44:47], v[194:197], v[156:159], v[44:47]
	v_mfma_f32_16x16x32_bf16 v[40:43], v[198:201], v[156:159], v[40:43]
	v_mfma_f32_16x16x32_bf16 v[36:39], v[202:205], v[156:159], v[36:39]
	v_mfma_f32_16x16x32_bf16 v[32:35], v[206:209], v[156:159], v[32:35]
	v_mfma_f32_16x16x32_bf16 v[28:31], v[194:197], v[160:163], v[28:31]
	v_mfma_f32_16x16x32_bf16 v[24:27], v[198:201], v[160:163], v[24:27]
	v_mfma_f32_16x16x32_bf16 v[20:23], v[202:205], v[160:163], v[20:23]
	v_mfma_f32_16x16x32_bf16 v[16:19], v[206:209], v[160:163], v[16:19]
	v_mfma_f32_16x16x32_bf16 v[12:15], v[194:197], v[190:193], v[12:15]
	v_mfma_f32_16x16x32_bf16 v[8:11], v[198:201], v[190:193], v[8:11]
	v_mfma_f32_16x16x32_bf16 v[4:7], v[202:205], v[190:193], v[4:7]
	v_mfma_f32_16x16x32_bf16 v[0:3], v[206:209], v[190:193], v[0:3]
	s_mov_b32 s1, s0
	s_waitcnt lgkmcnt(0)
	s_barrier
	s_mul_i32 s0, s69, 0x12000
	v_readlane_b32 s16, v250, 25
	s_add_u32 s24, s16, s0
	v_readlane_b32 s0, v251, 5
	v_lshlrev_b32_e32 v114, 6, v102
	v_readlane_b32 s17, v250, 26
	s_waitcnt vmcnt(5)
	v_add_u32_e32 v64, s0, v108
	v_readlane_b32 s0, v251, 6
	v_add_u32_e32 v56, 0xffffe000, v64
	v_or_b32_e32 v62, v64, v107
	v_or_b32_e32 v65, s0, v114
	v_lshrrev_b32_e32 v56, 10, v56
	s_movk_i32 s0, 0x1800
	v_mad_u32_u24 v56, v56, s0, s0
	v_cmp_lt_i32_e32 vcc, s13, v62
	s_addc_u32 s25, s17, 0
	v_lshlrev_b32_e32 v115, 2, v97
	v_cndmask_b32_e32 v56, 0, v56, vcc
	s_add_u32 s40, s24, 0x2000
	v_or_b32_e32 v58, v65, v115
	v_ashrrev_i32_e32 v57, 31, v56
	s_addc_u32 s41, s25, 0
	s_waitcnt vmcnt(4)
	v_lshlrev_b64 v[74:75], 2, v[56:57]
	v_ashrrev_i32_e32 v59, 31, v58
	v_ashrrev_i32_e32 v63, 31, v62
	v_lshl_add_u64 v[56:57], s[40:41], 0, v[74:75]
	v_lshlrev_b64 v[60:61], 2, v[58:59]
	v_readlane_b32 s0, v250, 15
	s_waitcnt vmcnt(1)
	v_lshl_add_u64 v[82:83], v[56:57], 0, v[60:61]
	v_lshlrev_b64 v[56:57], 12, v[62:63]
	v_readlane_b32 s1, v250, 16
	v_readlane_b32 s16, v250, 21
	v_lshlrev_b64 v[78:79], 11, v[62:63]
	v_lshl_add_u64 v[56:57], s[0:1], 0, v[56:57]
	s_waitcnt vmcnt(0)
	v_lshl_add_u64 v[84:85], v[56:57], 0, v[60:61]
	global_load_dwordx4 v[116:119], v[82:83], off
	global_load_dwordx4 v[120:123], v[82:83], off offset:64
	global_load_dwordx4 v[124:127], v[82:83], off offset:128
	global_load_dwordx4 v[132:135], v[82:83], off offset:192
	global_load_dwordx4 v[190:193], v[84:85], off
	global_load_dwordx4 v[194:197], v[84:85], off offset:64
	global_load_dwordx4 v[198:201], v[84:85], off offset:128
	global_load_dwordx4 v[202:205], v[84:85], off offset:192
	v_add_co_u32_e32 v164, vcc, 0x10000, v84
	s_nop 1
	v_addc_co_u32_e32 v165, vcc, 0, v85, vcc
	v_add_co_u32_e32 v222, vcc, 0x20000, v84
	s_nop 1
	v_addc_co_u32_e32 v223, vcc, 0, v85, vcc
	v_add_co_u32_e32 v224, vcc, 0x30000, v84
	s_nop 1
	v_addc_co_u32_e32 v225, vcc, 0, v85, vcc
	global_load_dwordx4 v[206:209], v[164:165], off
	global_load_dwordx4 v[210:213], v[164:165], off offset:64
	global_load_dwordx4 v[214:217], v[164:165], off offset:128
	global_load_dwordx4 v[218:221], v[164:165], off offset:192
	s_lshl_b32 s0, s69, 12
	v_readlane_b32 s68, v250, 41
	v_readlane_b32 s72, v250, 45
	v_readlane_b32 s73, v250, 46
	s_add_u32 s0, s72, s0
	s_addc_u32 s1, s73, 0
	s_add_u32 s42, s24, 0x4000
	s_addc_u32 s43, s25, 0
	v_lshl_add_u64 v[74:75], s[42:43], 0, v[74:75]
	v_lshl_add_u64 v[56:57], s[0:1], 0, v[60:61]
	v_lshl_add_u64 v[86:87], v[74:75], 0, v[60:61]
	v_readlane_b32 s17, v250, 22
	v_readlane_b32 s69, v250, 42
	v_readlane_b32 s69, v254, 49
	v_lshl_add_u64 v[78:79], s[16:17], 0, v[78:79]
	s_mul_i32 s24, s69, 0x140000
	s_add_u32 s24, s86, s24
	v_lshrrev_b32_e32 v65, 6, v65
	s_mov_b32 s16, 0xa000
	s_addc_u32 s25, s87, 0
	s_add_u32 s38, s24, 0xaf1a000
	s_addc_u32 s39, s25, 0
	v_cmp_eq_u32_e64 s[36:37], 0, v97
	v_readlane_b32 s70, v250, 43
	v_readlane_b32 s71, v250, 44
	v_readlane_b32 s74, v250, 47
	v_readlane_b32 s75, v250, 48
	v_readlane_b32 s76, v250, 49
	v_readlane_b32 s77, v250, 50
	v_readlane_b32 s78, v250, 51
	v_readlane_b32 s79, v250, 52
	v_readlane_b32 s80, v250, 53
	v_readlane_b32 s81, v250, 54
	v_readlane_b32 s82, v250, 55
	v_readlane_b32 s83, v250, 56
	s_waitcnt vmcnt(4)
	v_pk_fma_f32 v[68:69], v[94:95], v[118:119], v[192:193]
	v_pk_fma_f32 v[66:67], v[92:93], v[116:117], v[190:191]
	global_store_dwordx4 v[84:85], v[66:69], off
	global_load_dwordx4 v[136:139], v[56:57], off
	global_load_dwordx4 v[140:143], v[56:57], off offset:64
	global_load_dwordx4 v[144:147], v[56:57], off offset:128
	global_load_dwordx4 v[148:151], v[56:57], off offset:192
	global_load_dwordx4 v[152:155], v[86:87], off
	global_load_dwordx4 v[156:159], v[86:87], off offset:64
	global_load_dwordx4 v[160:163], v[86:87], off offset:128
	global_load_dwordx4 v[180:183], v[86:87], off offset:192
	v_lshl_add_u64 v[92:93], v[58:59], 1, v[78:79]
	s_waitcnt vmcnt(0)
	v_pk_mul_f32 v[72:73], v[68:69], v[138:139]
	v_pk_mul_f32 v[70:71], v[66:67], v[136:137]
	s_waitcnt vmcnt(0)
	v_pk_add_f32 v[76:77], v[154:155], 1.0 op_sel_hi:[1,0]
	v_pk_add_f32 v[74:75], v[152:153], 1.0 op_sel_hi:[1,0]
	v_pk_mul_f32 v[72:73], v[72:73], v[76:77]
	v_pk_mul_f32 v[70:71], v[70:71], v[74:75]
	v_and_b32_sdwa v76, v73, v170 dst_sel:DWORD dst_unused:UNUSED_PAD src0_sel:WORD_1 src1_sel:DWORD
	v_and_b32_sdwa v77, v71, v170 dst_sel:DWORD dst_unused:UNUSED_PAD src0_sel:WORD_1 src1_sel:DWORD
	v_and_b32_sdwa v74, v72, v170 dst_sel:DWORD dst_unused:UNUSED_PAD src0_sel:WORD_1 src1_sel:DWORD
	v_and_b32_sdwa v75, v70, v170 dst_sel:DWORD dst_unused:UNUSED_PAD src0_sel:WORD_1 src1_sel:DWORD
	v_add3_u32 v73, v73, v76, s56
	v_add3_u32 v71, v71, v77, s56
	v_add3_u32 v70, v70, v75, s56
	v_add3_u32 v72, v72, v74, s56
	v_and_b32_e32 v73, 0xffff0000, v73
	v_and_b32_e32 v74, 0xffff0000, v71
	v_or_b32_sdwa v71, v73, v72 dst_sel:DWORD dst_unused:UNUSED_PAD src0_sel:DWORD src1_sel:WORD_1
	v_or_b32_sdwa v70, v74, v70 dst_sel:DWORD dst_unused:UNUSED_PAD src0_sel:DWORD src1_sel:WORD_1
	global_store_dwordx2 v[92:93], v[70:71], off
	s_nop 0
	s_waitcnt vmcnt(0)
	v_pk_fma_f32 v[72:73], v[90:91], v[122:123], v[196:197]
	v_pk_fma_f32 v[70:71], v[88:89], v[120:121], v[194:195]
	global_store_dwordx4 v[84:85], v[70:73], off offset:64
	v_pk_mul_f32 v[76:77], v[72:73], v[142:143]
	v_pk_mul_f32 v[74:75], v[70:71], v[140:141]
	v_pk_add_f32 v[80:81], v[158:159], 1.0 op_sel_hi:[1,0]
	v_pk_add_f32 v[78:79], v[156:157], 1.0 op_sel_hi:[1,0]
	v_pk_mul_f32 v[76:77], v[76:77], v[80:81]
	v_pk_mul_f32 v[74:75], v[74:75], v[78:79]
	v_and_b32_sdwa v80, v77, v170 dst_sel:DWORD dst_unused:UNUSED_PAD src0_sel:WORD_1 src1_sel:DWORD
	v_and_b32_sdwa v81, v75, v170 dst_sel:DWORD dst_unused:UNUSED_PAD src0_sel:WORD_1 src1_sel:DWORD
	v_and_b32_sdwa v78, v76, v170 dst_sel:DWORD dst_unused:UNUSED_PAD src0_sel:WORD_1 src1_sel:DWORD
	v_and_b32_sdwa v79, v74, v170 dst_sel:DWORD dst_unused:UNUSED_PAD src0_sel:WORD_1 src1_sel:DWORD
	v_add3_u32 v77, v77, v80, s56
	v_add3_u32 v75, v75, v81, s56
	v_add3_u32 v74, v74, v79, s56
	v_add3_u32 v76, v76, v78, s56
	v_and_b32_e32 v77, 0xffff0000, v77
	v_and_b32_e32 v78, 0xffff0000, v75
	v_or_b32_sdwa v75, v77, v76 dst_sel:DWORD dst_unused:UNUSED_PAD src0_sel:DWORD src1_sel:WORD_1
	v_or_b32_sdwa v74, v78, v74 dst_sel:DWORD dst_unused:UNUSED_PAD src0_sel:DWORD src1_sel:WORD_1
	global_store_dwordx2 v[92:93], v[74:75], off offset:32
	s_nop 0
	v_pk_fma_f32 v[54:55], v[54:55], v[126:127], v[200:201]
	v_pk_fma_f32 v[52:53], v[52:53], v[124:125], v[198:199]
	global_store_dwordx4 v[84:85], v[52:55], off offset:128
	v_pk_mul_f32 v[76:77], v[54:55], v[146:147]
	v_pk_mul_f32 v[74:75], v[52:53], v[144:145]
	v_pk_add_f32 v[80:81], v[162:163], 1.0 op_sel_hi:[1,0]
	v_pk_add_f32 v[78:79], v[160:161], 1.0 op_sel_hi:[1,0]
	v_pk_mul_f32 v[76:77], v[76:77], v[80:81]
	v_pk_mul_f32 v[74:75], v[74:75], v[78:79]
	v_and_b32_sdwa v80, v77, v170 dst_sel:DWORD dst_unused:UNUSED_PAD src0_sel:WORD_1 src1_sel:DWORD
	v_and_b32_sdwa v81, v75, v170 dst_sel:DWORD dst_unused:UNUSED_PAD src0_sel:WORD_1 src1_sel:DWORD
	v_and_b32_sdwa v78, v76, v170 dst_sel:DWORD dst_unused:UNUSED_PAD src0_sel:WORD_1 src1_sel:DWORD
	v_and_b32_sdwa v79, v74, v170 dst_sel:DWORD dst_unused:UNUSED_PAD src0_sel:WORD_1 src1_sel:DWORD
	v_add3_u32 v77, v77, v80, s56
	v_add3_u32 v75, v75, v81, s56
	v_add3_u32 v74, v74, v79, s56
	v_add3_u32 v76, v76, v78, s56
	v_and_b32_e32 v77, 0xffff0000, v77
	v_and_b32_e32 v78, 0xffff0000, v75
	v_or_b32_sdwa v75, v77, v76 dst_sel:DWORD dst_unused:UNUSED_PAD src0_sel:DWORD src1_sel:WORD_1
	v_or_b32_sdwa v74, v78, v74 dst_sel:DWORD dst_unused:UNUSED_PAD src0_sel:DWORD src1_sel:WORD_1
	global_store_dwordx2 v[92:93], v[74:75], off offset:64
	s_nop 0
	v_pk_fma_f32 v[76:77], v[50:51], v[134:135], v[204:205]
	v_pk_fma_f32 v[74:75], v[48:49], v[132:133], v[202:203]
	global_store_dwordx4 v[84:85], v[74:77], off offset:192
	s_nop 0
	v_mbcnt_lo_u32_b32 v48, -1, 0
	v_mbcnt_hi_u32_b32 v48, -1, v48
	v_and_b32_e32 v50, 64, v48
	v_xor_b32_e32 v49, 16, v48
	v_add_u32_e32 v50, 64, v50
	v_xor_b32_e32 v51, 32, v48
	v_cmp_lt_i32_e32 vcc, v49, v50
	s_nop 1
	v_cndmask_b32_e32 v49, v48, v49, vcc
	v_cmp_lt_i32_e32 vcc, v51, v50
	v_lshlrev_b32_e32 v105, 2, v49
	s_nop 0
	v_cndmask_b32_e32 v50, v48, v51, vcc
	v_lshlrev_b32_e32 v104, 2, v50
	v_mul_f32_e32 v50, v67, v67
	v_mul_f32_e32 v51, v71, v71
	v_fmac_f32_e32 v50, v66, v66
	v_fmac_f32_e32 v51, v70, v70
	v_fmac_f32_e32 v50, v68, v68
	v_fmac_f32_e32 v51, v72, v72
	v_fmac_f32_e32 v50, v69, v69
	v_fmac_f32_e32 v51, v73, v73
	v_add_f32_e32 v50, v50, v51
	v_mul_f32_e32 v51, v53, v53
	v_fmac_f32_e32 v51, v52, v52
	v_fmac_f32_e32 v51, v54, v54
	v_fmac_f32_e32 v51, v55, v55
	v_add_f32_e32 v50, v50, v51
	v_mul_f32_e32 v51, v75, v75
	v_fmac_f32_e32 v51, v74, v74
	v_fmac_f32_e32 v51, v76, v76
	v_fmac_f32_e32 v51, v77, v77
	v_add_f32_e32 v50, v50, v51
	ds_bpermute_b32 v51, v105, v50
	v_mul_lo_u32 v48, v65, s16
	v_ashrrev_i32_e32 v49, 31, v48
	v_lshl_add_u64 v[48:49], s[38:39], 0, v[48:49]
	v_lshl_add_u64 v[48:49], v[62:63], 2, v[48:49]
	s_waitcnt lgkmcnt(0)
	v_add_f32_e32 v50, v50, v51
	ds_bpermute_b32 v51, v104, v50
	v_pk_mul_f32 v[52:53], v[76:77], v[150:151]
	v_pk_mul_f32 v[54:55], v[74:75], v[148:149]
	v_pk_add_f32 v[66:67], v[182:183], 1.0 op_sel_hi:[1,0]
	v_pk_add_f32 v[68:69], v[180:181], 1.0 op_sel_hi:[1,0]
	v_pk_mul_f32 v[52:53], v[52:53], v[66:67]
	v_pk_mul_f32 v[54:55], v[54:55], v[68:69]
	v_and_b32_sdwa v67, v53, v170 dst_sel:DWORD dst_unused:UNUSED_PAD src0_sel:WORD_1 src1_sel:DWORD
	v_and_b32_sdwa v68, v55, v170 dst_sel:DWORD dst_unused:UNUSED_PAD src0_sel:WORD_1 src1_sel:DWORD
	v_and_b32_sdwa v65, v52, v170 dst_sel:DWORD dst_unused:UNUSED_PAD src0_sel:WORD_1 src1_sel:DWORD
	v_and_b32_sdwa v66, v54, v170 dst_sel:DWORD dst_unused:UNUSED_PAD src0_sel:WORD_1 src1_sel:DWORD
	v_add3_u32 v53, v53, v67, s56
	v_add3_u32 v55, v55, v68, s56
	v_add3_u32 v54, v54, v66, s56
	v_add3_u32 v52, v52, v65, s56
	v_and_b32_e32 v53, 0xffff0000, v53
	v_and_b32_e32 v55, 0xffff0000, v55
	v_or_b32_sdwa v53, v53, v52 dst_sel:DWORD dst_unused:UNUSED_PAD src0_sel:DWORD src1_sel:WORD_1
	v_or_b32_sdwa v52, v55, v54 dst_sel:DWORD dst_unused:UNUSED_PAD src0_sel:DWORD src1_sel:WORD_1
	global_store_dwordx2 v[92:93], v[52:53], off offset:96
	s_and_saveexec_b64 s[24:25], s[36:37]
	s_cbranch_execz .LBB0_395
	s_waitcnt lgkmcnt(0)
	v_add_f32_e32 v50, v50, v51
	global_store_dword v[48:49], v50, off

.Ltail406:
	s_add_i32 s29, s44, 2
	ds_read_b128 v[136:139], v111 offset:16384
	ds_read_b128 v[140:143], v111 offset:18432
	ds_read_b128 v[144:147], v111 offset:20480
	ds_read_b128 v[148:151], v111 offset:22528
	ds_read_b128 v[116:119], v110
	s_add_i32 s44, s44, 4
	ds_read_b128 v[120:123], v110 offset:2048
	s_min_u32 s44, s44, 15
	s_lshl_b32 s92, s44, 7
	ds_read_b128 v[124:127], v110 offset:4096
	ds_read_b128 v[194:197], v113 offset:16384
	ds_read_b128 v[198:201], v113 offset:18432
	ds_read_b128 v[202:205], v113 offset:20480
	ds_read_b128 v[206:209], v113 offset:22528
	v_lshl_add_u64 v[164:165], v[100:101], 0, s[92:93]
	ds_read_b128 v[132:135], v110 offset:6144
	ds_read_b128 v[152:155], v112
	ds_read_b128 v[156:159], v112 offset:2048
	ds_read_b128 v[160:163], v112 offset:4096
	ds_read_b128 v[190:193], v112 offset:6144
	s_waitcnt lgkmcnt(11)
	v_mfma_f32_16x16x32_bf16 v[92:95], v[136:139], v[116:119], v[92:95]
	v_mfma_f32_16x16x32_bf16 v[88:91], v[140:143], v[116:119], v[88:91]
	v_mfma_f32_16x16x32_bf16 v[56:59], v[144:147], v[116:119], v[56:59]
	v_mfma_f32_16x16x32_bf16 v[48:51], v[148:151], v[116:119], v[48:51]
	s_waitcnt vmcnt(7)
	ds_write_b128 v109, v[52:55] offset:32768
	v_add_co_u32_e32 v52, vcc, s11, v164
	s_waitcnt lgkmcnt(11)
	v_mfma_f32_16x16x32_bf16 v[44:47], v[136:139], v[120:123], v[44:47]
	v_addc_co_u32_e32 v53, vcc, 0, v165, vcc
	v_mfma_f32_16x16x32_bf16 v[40:43], v[140:143], v[120:123], v[40:43]
	v_mfma_f32_16x16x32_bf16 v[36:39], v[144:147], v[120:123], v[36:39]
	v_mfma_f32_16x16x32_bf16 v[32:35], v[148:151], v[120:123], v[32:35]
	v_add_co_u32_e32 v52, vcc, s33, v164
	s_waitcnt vmcnt(6)
	ds_write_b128 v109, v[60:63] offset:36864
	s_nop 0
	v_addc_co_u32_e32 v53, vcc, 0, v165, vcc
	s_waitcnt lgkmcnt(11)
	v_mfma_f32_16x16x32_bf16 v[28:31], v[136:139], v[124:127], v[28:31]
	v_mfma_f32_16x16x32_bf16 v[24:27], v[140:143], v[124:127], v[24:27]
	v_mfma_f32_16x16x32_bf16 v[20:23], v[144:147], v[124:127], v[20:23]
	v_mfma_f32_16x16x32_bf16 v[16:19], v[148:151], v[124:127], v[16:19]
	v_add_co_u32_e32 v52, vcc, s59, v164
	s_waitcnt vmcnt(5)
	ds_write_b128 v109, v[64:67] offset:40960
	s_nop 0
	v_addc_co_u32_e32 v53, vcc, 0, v165, vcc
	v_lshl_add_u64 v[64:65], v[102:103], 0, s[92:93]
	v_add_co_u32_e32 v66, vcc, s11, v64
	s_waitcnt lgkmcnt(7)
	v_mfma_f32_16x16x32_bf16 v[12:15], v[136:139], v[132:135], v[12:15]
	v_addc_co_u32_e32 v67, vcc, 0, v65, vcc
	v_mfma_f32_16x16x32_bf16 v[8:11], v[140:143], v[132:135], v[8:11]
	v_mfma_f32_16x16x32_bf16 v[4:7], v[144:147], v[132:135], v[4:7]
	v_mfma_f32_16x16x32_bf16 v[0:3], v[148:151], v[132:135], v[0:3]
	s_waitcnt vmcnt(4)
	ds_write_b128 v109, v[72:75] offset:45056
	s_waitcnt lgkmcnt(7)
	v_mfma_f32_16x16x32_bf16 v[52:55], v[194:197], v[152:155], v[92:95]
	v_mfma_f32_16x16x32_bf16 v[60:63], v[198:201], v[152:155], v[88:91]
	v_mfma_f32_16x16x32_bf16 v[56:59], v[202:205], v[152:155], v[56:59]
	v_mfma_f32_16x16x32_bf16 v[48:51], v[206:209], v[152:155], v[48:51]
	s_waitcnt vmcnt(3)
	ds_write_b128 v109, v[68:71] offset:49152
	s_waitcnt lgkmcnt(7)
	v_mfma_f32_16x16x32_bf16 v[44:47], v[194:197], v[156:159], v[44:47]
	v_mfma_f32_16x16x32_bf16 v[40:43], v[198:201], v[156:159], v[40:43]
	v_mfma_f32_16x16x32_bf16 v[36:39], v[202:205], v[156:159], v[36:39]
	v_mfma_f32_16x16x32_bf16 v[32:35], v[206:209], v[156:159], v[32:35]
	v_add_co_u32_e32 v66, vcc, s33, v64
	s_waitcnt vmcnt(2)
	ds_write_b128 v109, v[76:79] offset:53248
	v_addc_co_u32_e32 v67, vcc, 0, v65, vcc
	v_add_co_u32_e32 v64, vcc, s59, v64
	s_waitcnt lgkmcnt(7)
	v_mfma_f32_16x16x32_bf16 v[28:31], v[194:197], v[160:163], v[28:31]
	v_addc_co_u32_e32 v65, vcc, 0, v65, vcc
	v_mfma_f32_16x16x32_bf16 v[24:27], v[198:201], v[160:163], v[24:27]
	v_mfma_f32_16x16x32_bf16 v[20:23], v[202:205], v[160:163], v[20:23]
	v_mfma_f32_16x16x32_bf16 v[16:19], v[206:209], v[160:163], v[16:19]
	s_waitcnt vmcnt(1)
	ds_write_b128 v109, v[80:83] offset:57344
	s_waitcnt lgkmcnt(7)
	v_mfma_f32_16x16x32_bf16 v[12:15], v[194:197], v[190:193], v[12:15]
	v_mfma_f32_16x16x32_bf16 v[8:11], v[198:201], v[190:193], v[8:11]
	v_mfma_f32_16x16x32_bf16 v[4:7], v[202:205], v[190:193], v[4:7]
	v_mfma_f32_16x16x32_bf16 v[0:3], v[206:209], v[190:193], v[0:3]
	s_waitcnt vmcnt(0)
	ds_write_b128 v109, v[84:87] offset:61440
	s_waitcnt lgkmcnt(0)
	s_barrier
	ds_read_b128 v[84:87], v111 offset:51200
	ds_read_b128 v[80:83], v111 offset:49152
	ds_read_b128 v[88:91], v111 offset:53248
	ds_read_b128 v[92:95], v111 offset:55296
	ds_read_b128 v[64:67], v110 offset:32768
	s_min_u32 s44, s29, 12
	s_lshl_b32 s92, s44, 7
	ds_read_b128 v[68:71], v110 offset:34816
	v_lshl_add_u64 v[164:165], v[100:101], 0, s[92:93]
	ds_read_b128 v[72:75], v110 offset:36864
	ds_read_b128 v[76:79], v110 offset:38912
	ds_read_b128 v[152:155], v112 offset:32768
	ds_read_b128 v[156:159], v112 offset:34816
	ds_read_b128 v[160:163], v112 offset:36864
	ds_read_b128 v[190:193], v112 offset:38912
	ds_read_b128 v[194:197], v113 offset:49152
	ds_read_b128 v[198:201], v113 offset:51200
	ds_read_b128 v[202:205], v113 offset:53248
	ds_read_b128 v[206:209], v113 offset:55296
	s_waitcnt lgkmcnt(11)
	v_mfma_f32_16x16x32_bf16 v[214:217], v[84:87], v[64:67], v[60:63]
	v_mfma_f32_16x16x32_bf16 v[210:213], v[80:83], v[64:67], v[52:55]
	s_nop 1
	v_add_co_u32_e32 v60, vcc, s11, v164
	s_nop 1
	v_addc_co_u32_e32 v61, vcc, 0, v165, vcc
	v_mfma_f32_16x16x32_bf16 v[56:59], v[88:91], v[64:67], v[56:59]
	v_mfma_f32_16x16x32_bf16 v[48:51], v[92:95], v[64:67], v[48:51]
	v_add_co_u32_e32 v64, vcc, s33, v164
	s_nop 0
	v_addc_co_u32_e32 v65, vcc, 0, v165, vcc
	s_waitcnt lgkmcnt(10)
	v_mfma_f32_16x16x32_bf16 v[44:47], v[80:83], v[68:71], v[44:47]
	v_mfma_f32_16x16x32_bf16 v[40:43], v[84:87], v[68:71], v[40:43]
	v_mfma_f32_16x16x32_bf16 v[36:39], v[88:91], v[68:71], v[36:39]
	v_mfma_f32_16x16x32_bf16 v[32:35], v[92:95], v[68:71], v[32:35]
	v_add_co_u32_e32 v68, vcc, s59, v164
	s_waitcnt lgkmcnt(9)
	v_mfma_f32_16x16x32_bf16 v[28:31], v[80:83], v[72:75], v[28:31]
	v_addc_co_u32_e32 v69, vcc, 0, v165, vcc
	v_mfma_f32_16x16x32_bf16 v[24:27], v[84:87], v[72:75], v[24:27]
	v_mfma_f32_16x16x32_bf16 v[20:23], v[88:91], v[72:75], v[20:23]
	v_mfma_f32_16x16x32_bf16 v[16:19], v[92:95], v[72:75], v[16:19]
	s_waitcnt lgkmcnt(8)
	v_mfma_f32_16x16x32_bf16 v[8:11], v[84:87], v[76:79], v[8:11]
	v_lshl_add_u64 v[84:85], v[102:103], 0, s[92:93]
	v_mfma_f32_16x16x32_bf16 v[12:15], v[80:83], v[76:79], v[12:15]
	v_mfma_f32_16x16x32_bf16 v[4:7], v[88:91], v[76:79], v[4:7]
	v_mfma_f32_16x16x32_bf16 v[0:3], v[92:95], v[76:79], v[0:3]
	v_add_co_u32_e32 v76, vcc, s11, v84
	s_nop 0
	v_addc_co_u32_e32 v77, vcc, 0, v85, vcc
	v_add_co_u32_e32 v80, vcc, s33, v84
	v_addc_co_u32_e32 v81, vcc, 0, v85, vcc
	s_waitcnt lgkmcnt(3)
	v_mfma_f32_16x16x32_bf16 v[92:95], v[194:197], v[152:155], v[210:213]
	s_waitcnt lgkmcnt(2)
	v_mfma_f32_16x16x32_bf16 v[88:91], v[198:201], v[152:155], v[214:217]
	s_waitcnt lgkmcnt(1)
	v_mfma_f32_16x16x32_bf16 v[56:59], v[202:205], v[152:155], v[56:59]
	s_waitcnt lgkmcnt(0)
	v_mfma_f32_16x16x32_bf16 v[48:51], v[206:209], v[152:155], v[48:51]
	v_add_co_u32_e32 v84, vcc, s59, v84
	v_addc_co_u32_e32 v85, vcc, 0, v85, vcc
	v_mfma_f32_16x16x32_bf16 v[44:47], v[194:197], v[156:159], v[44:47]
	v_mfma_f32_16x16x32_bf16 v[40:43], v[198:201], v[156:159], v[40:43]
	v_mfma_f32_16x16x32_bf16 v[36:39], v[202:205], v[156:159], v[36:39]
	v_mfma_f32_16x16x32_bf16 v[32:35], v[206:209], v[156:159], v[32:35]
	v_mfma_f32_16x16x32_bf16 v[28:31], v[194:197], v[160:163], v[28:31]
	v_mfma_f32_16x16x32_bf16 v[24:27], v[198:201], v[160:163], v[24:27]
	v_mfma_f32_16x16x32_bf16 v[20:23], v[202:205], v[160:163], v[20:23]
	v_mfma_f32_16x16x32_bf16 v[16:19], v[206:209], v[160:163], v[16:19]
	v_mfma_f32_16x16x32_bf16 v[12:15], v[194:197], v[190:193], v[12:15]
	v_mfma_f32_16x16x32_bf16 v[8:11], v[198:201], v[190:193], v[8:11]
	v_mfma_f32_16x16x32_bf16 v[4:7], v[202:205], v[190:193], v[4:7]
	v_mfma_f32_16x16x32_bf16 v[0:3], v[206:209], v[190:193], v[0:3]
	s_mov_b32 s44, s29
	s_waitcnt lgkmcnt(0)
	s_barrier
	s_waitcnt vmcnt(5)
	v_add_u32_e32 v64, s24, v108
	v_add_u32_e32 v52, 0xffffe000, v64
	v_or_b32_e32 v62, v64, v107
	v_lshrrev_b32_e32 v52, 10, v52
	s_movk_i32 s16, 0x1800
	v_mad_u32_u24 v52, v52, s16, s16
	v_cmp_lt_i32_e32 vcc, s13, v62
	v_or_b32_e32 v65, s25, v114
	v_or_b32_e32 v54, v65, v115
	v_cndmask_b32_e32 v52, 0, v52, vcc
	v_ashrrev_i32_e32 v53, 31, v52
	s_waitcnt vmcnt(4)
	v_lshlrev_b64 v[74:75], 2, v[52:53]
	v_ashrrev_i32_e32 v55, 31, v54
	v_ashrrev_i32_e32 v63, 31, v62
	v_lshl_add_u64 v[52:53], s[40:41], 0, v[74:75]
	v_lshlrev_b64 v[60:61], 2, v[54:55]
	v_readlane_b32 s16, v250, 15
	s_waitcnt vmcnt(1)
	v_lshl_add_u64 v[82:83], v[52:53], 0, v[60:61]
	v_lshlrev_b64 v[52:53], 12, v[62:63]
	v_readlane_b32 s17, v250, 16
	v_lshl_add_u64 v[74:75], s[42:43], 0, v[74:75]
	s_waitcnt vmcnt(0)
	v_lshl_add_u64 v[86:87], v[74:75], 0, v[60:61]
	v_lshl_add_u64 v[52:53], s[16:17], 0, v[52:53]
	v_lshl_add_u64 v[84:85], v[52:53], 0, v[60:61]
	global_load_dwordx4 v[66:69], v[82:83], off
	global_load_dwordx4 v[70:73], v[84:85], off
	v_lshl_add_u64 v[52:53], s[0:1], 0, v[60:61]
	v_readlane_b32 s16, v250, 21
	v_lshlrev_b64 v[78:79], 11, v[62:63]
	v_readlane_b32 s17, v250, 22
	s_waitcnt vmcnt(0)
	v_pk_fma_f32 v[68:69], v[94:95], v[68:69], v[72:73]
	v_pk_fma_f32 v[66:67], v[92:93], v[66:67], v[70:71]
	global_store_dwordx4 v[84:85], v[66:69], off
	global_load_dwordx4 v[70:73], v[52:53], off
	global_load_dwordx4 v[74:77], v[86:87], off
	v_lshl_add_u64 v[78:79], s[16:17], 0, v[78:79]
	v_lshl_add_u64 v[92:93], v[54:55], 1, v[78:79]
	s_mov_b32 s16, 0xa000
	s_waitcnt vmcnt(1)
	v_pk_mul_f32 v[72:73], v[68:69], v[72:73]
	v_pk_mul_f32 v[70:71], v[66:67], v[70:71]
	s_waitcnt vmcnt(0)
	v_pk_add_f32 v[76:77], v[76:77], 1.0 op_sel_hi:[1,0]
	v_pk_add_f32 v[74:75], v[74:75], 1.0 op_sel_hi:[1,0]
	v_pk_mul_f32 v[72:73], v[72:73], v[76:77]
	v_pk_mul_f32 v[70:71], v[70:71], v[74:75]
	v_and_b32_sdwa v76, v73, v170 dst_sel:DWORD dst_unused:UNUSED_PAD src0_sel:WORD_1 src1_sel:DWORD
	v_and_b32_sdwa v77, v71, v170 dst_sel:DWORD dst_unused:UNUSED_PAD src0_sel:WORD_1 src1_sel:DWORD
	v_and_b32_sdwa v74, v72, v170 dst_sel:DWORD dst_unused:UNUSED_PAD src0_sel:WORD_1 src1_sel:DWORD
	v_and_b32_sdwa v75, v70, v170 dst_sel:DWORD dst_unused:UNUSED_PAD src0_sel:WORD_1 src1_sel:DWORD
	v_add3_u32 v73, v73, v76, s56
	v_add3_u32 v71, v71, v77, s56
	v_add3_u32 v70, v70, v75, s56
	v_add3_u32 v72, v72, v74, s56
	v_and_b32_e32 v73, 0xffff0000, v73
	v_and_b32_e32 v74, 0xffff0000, v71
	v_or_b32_sdwa v71, v73, v72 dst_sel:DWORD dst_unused:UNUSED_PAD src0_sel:DWORD src1_sel:WORD_1
	v_or_b32_sdwa v70, v74, v70 dst_sel:DWORD dst_unused:UNUSED_PAD src0_sel:DWORD src1_sel:WORD_1
	global_store_dwordx2 v[92:93], v[70:71], off
	global_load_dwordx4 v[70:73], v[82:83], off offset:64
	s_nop 0
	global_load_dwordx4 v[74:77], v[84:85], off offset:64
	s_waitcnt vmcnt(0)
	v_pk_fma_f32 v[72:73], v[90:91], v[72:73], v[76:77]
	v_pk_fma_f32 v[70:71], v[88:89], v[70:71], v[74:75]
	global_store_dwordx4 v[84:85], v[70:73], off offset:64
	global_load_dwordx4 v[74:77], v[52:53], off offset:64
	global_load_dwordx4 v[78:81], v[86:87], off offset:64
	s_waitcnt vmcnt(1)
	v_pk_mul_f32 v[76:77], v[72:73], v[76:77]
	v_pk_mul_f32 v[74:75], v[70:71], v[74:75]
	s_waitcnt vmcnt(0)
	v_pk_add_f32 v[80:81], v[80:81], 1.0 op_sel_hi:[1,0]
	v_pk_add_f32 v[78:79], v[78:79], 1.0 op_sel_hi:[1,0]
	v_pk_mul_f32 v[76:77], v[76:77], v[80:81]
	v_pk_mul_f32 v[74:75], v[74:75], v[78:79]
	v_and_b32_sdwa v80, v77, v170 dst_sel:DWORD dst_unused:UNUSED_PAD src0_sel:WORD_1 src1_sel:DWORD
	v_and_b32_sdwa v81, v75, v170 dst_sel:DWORD dst_unused:UNUSED_PAD src0_sel:WORD_1 src1_sel:DWORD
	v_and_b32_sdwa v78, v76, v170 dst_sel:DWORD dst_unused:UNUSED_PAD src0_sel:WORD_1 src1_sel:DWORD
	v_and_b32_sdwa v79, v74, v170 dst_sel:DWORD dst_unused:UNUSED_PAD src0_sel:WORD_1 src1_sel:DWORD
	v_add3_u32 v77, v77, v80, s56
	v_add3_u32 v75, v75, v81, s56
	v_add3_u32 v74, v74, v79, s56
	v_add3_u32 v76, v76, v78, s56
	v_and_b32_e32 v77, 0xffff0000, v77
	v_and_b32_e32 v78, 0xffff0000, v75
	v_or_b32_sdwa v75, v77, v76 dst_sel:DWORD dst_unused:UNUSED_PAD src0_sel:DWORD src1_sel:WORD_1
	v_or_b32_sdwa v74, v78, v74 dst_sel:DWORD dst_unused:UNUSED_PAD src0_sel:DWORD src1_sel:WORD_1
	global_store_dwordx2 v[92:93], v[74:75], off offset:32
	global_load_dwordx4 v[74:77], v[82:83], off offset:128
	s_nop 0
	global_load_dwordx4 v[78:81], v[84:85], off offset:128
	s_waitcnt vmcnt(0)
	v_pk_fma_f32 v[58:59], v[58:59], v[76:77], v[80:81]
	v_pk_fma_f32 v[56:57], v[56:57], v[74:75], v[78:79]
	global_store_dwordx4 v[84:85], v[56:59], off offset:128
	global_load_dwordx4 v[74:77], v[52:53], off offset:128
	global_load_dwordx4 v[78:81], v[86:87], off offset:128
	s_waitcnt vmcnt(1)
	v_pk_mul_f32 v[76:77], v[58:59], v[76:77]
	v_pk_mul_f32 v[74:75], v[56:57], v[74:75]
	s_waitcnt vmcnt(0)
	v_pk_add_f32 v[80:81], v[80:81], 1.0 op_sel_hi:[1,0]
	v_pk_add_f32 v[78:79], v[78:79], 1.0 op_sel_hi:[1,0]
	v_pk_mul_f32 v[76:77], v[76:77], v[80:81]
	v_pk_mul_f32 v[74:75], v[74:75], v[78:79]
	v_and_b32_sdwa v80, v77, v170 dst_sel:DWORD dst_unused:UNUSED_PAD src0_sel:WORD_1 src1_sel:DWORD
	v_and_b32_sdwa v81, v75, v170 dst_sel:DWORD dst_unused:UNUSED_PAD src0_sel:WORD_1 src1_sel:DWORD
	v_and_b32_sdwa v78, v76, v170 dst_sel:DWORD dst_unused:UNUSED_PAD src0_sel:WORD_1 src1_sel:DWORD
	v_and_b32_sdwa v79, v74, v170 dst_sel:DWORD dst_unused:UNUSED_PAD src0_sel:WORD_1 src1_sel:DWORD
	v_add3_u32 v77, v77, v80, s56
	v_add3_u32 v75, v75, v81, s56
	v_add3_u32 v74, v74, v79, s56
	v_add3_u32 v76, v76, v78, s56
	v_and_b32_e32 v77, 0xffff0000, v77
	v_and_b32_e32 v78, 0xffff0000, v75
	v_or_b32_sdwa v75, v77, v76 dst_sel:DWORD dst_unused:UNUSED_PAD src0_sel:DWORD src1_sel:WORD_1
	v_or_b32_sdwa v74, v78, v74 dst_sel:DWORD dst_unused:UNUSED_PAD src0_sel:DWORD src1_sel:WORD_1
	global_store_dwordx2 v[92:93], v[74:75], off offset:64
	global_load_dwordx4 v[74:77], v[82:83], off offset:192
	s_nop 0
	global_load_dwordx4 v[78:81], v[84:85], off offset:192
	s_waitcnt vmcnt(0)
	v_pk_fma_f32 v[76:77], v[50:51], v[76:77], v[80:81]
	v_pk_fma_f32 v[74:75], v[48:49], v[74:75], v[78:79]
	global_store_dwordx4 v[84:85], v[74:77], off offset:192
	global_load_dwordx4 v[78:81], v[52:53], off offset:192
	s_nop 0
	global_load_dwordx4 v[82:85], v[86:87], off offset:192
	v_mul_f32_e32 v48, v67, v67
	v_mul_f32_e32 v49, v71, v71
	v_fmac_f32_e32 v48, v66, v66
	v_fmac_f32_e32 v49, v70, v70
	v_fmac_f32_e32 v48, v68, v68
	v_fmac_f32_e32 v49, v72, v72
	v_fmac_f32_e32 v48, v69, v69
	v_fmac_f32_e32 v49, v73, v73
	v_add_f32_e32 v48, v48, v49
	v_mul_f32_e32 v49, v57, v57
	v_fmac_f32_e32 v49, v56, v56
	v_fmac_f32_e32 v49, v58, v58
	v_fmac_f32_e32 v49, v59, v59
	v_add_f32_e32 v48, v48, v49
	v_mul_f32_e32 v49, v75, v75
	v_fmac_f32_e32 v49, v74, v74
	v_fmac_f32_e32 v49, v76, v76
	v_fmac_f32_e32 v49, v77, v77
	v_add_f32_e32 v50, v48, v49
	ds_bpermute_b32 v51, v105, v50
	v_lshrrev_b32_e32 v48, 6, v65
	v_mul_lo_u32 v48, v48, s16
	v_ashrrev_i32_e32 v49, 31, v48
	v_lshl_add_u64 v[48:49], s[38:39], 0, v[48:49]
	s_waitcnt lgkmcnt(0)
	v_add_f32_e32 v50, v50, v51
	ds_bpermute_b32 v51, v104, v50
	v_lshl_add_u64 v[48:49], v[62:63], 2, v[48:49]
	s_waitcnt vmcnt(1)
	v_pk_mul_f32 v[56:57], v[76:77], v[80:81]
	v_pk_mul_f32 v[58:59], v[74:75], v[78:79]
	s_waitcnt vmcnt(0)
	v_pk_add_f32 v[66:67], v[84:85], 1.0 op_sel_hi:[1,0]
	v_pk_add_f32 v[68:69], v[82:83], 1.0 op_sel_hi:[1,0]
	v_pk_mul_f32 v[56:57], v[56:57], v[66:67]
	v_pk_mul_f32 v[58:59], v[58:59], v[68:69]
	v_and_b32_sdwa v67, v57, v170 dst_sel:DWORD dst_unused:UNUSED_PAD src0_sel:WORD_1 src1_sel:DWORD
	v_and_b32_sdwa v68, v59, v170 dst_sel:DWORD dst_unused:UNUSED_PAD src0_sel:WORD_1 src1_sel:DWORD
	v_and_b32_sdwa v65, v56, v170 dst_sel:DWORD dst_unused:UNUSED_PAD src0_sel:WORD_1 src1_sel:DWORD
	v_and_b32_sdwa v66, v58, v170 dst_sel:DWORD dst_unused:UNUSED_PAD src0_sel:WORD_1 src1_sel:DWORD
	v_add3_u32 v57, v57, v67, s56
	v_add3_u32 v59, v59, v68, s56
	v_add3_u32 v58, v58, v66, s56
	v_add3_u32 v56, v56, v65, s56
	v_and_b32_e32 v57, 0xffff0000, v57
	v_and_b32_e32 v59, 0xffff0000, v59
	v_or_b32_sdwa v57, v57, v56 dst_sel:DWORD dst_unused:UNUSED_PAD src0_sel:DWORD src1_sel:WORD_1
	v_or_b32_sdwa v56, v59, v58 dst_sel:DWORD dst_unused:UNUSED_PAD src0_sel:DWORD src1_sel:WORD_1
	global_store_dwordx2 v[92:93], v[56:57], off offset:96
	s_and_saveexec_b64 s[24:25], s[36:37]
	s_cbranch_execz .LBB0_409
	s_waitcnt lgkmcnt(0)
	v_add_f32_e32 v50, v50, v51
	global_store_dword v[48:49], v50, off

.Ltail419:
	s_add_i32 s2, s3, 2
	v_add_u32_e32 v127, v89, v90
	ds_read_b128 v[100:103], v127 offset:16384
	ds_read_b128 v[106:109], v127 offset:18432
	ds_read_b128 v[110:113], v127 offset:20480
	ds_read_b128 v[114:117], v127 offset:22528
	v_add_u32_e32 v126, v88, v90
	ds_read_b128 v[92:95], v126
	ds_read_b128 v[96:99], v126 offset:2048
	s_add_i32 s3, s3, 4
	s_min_u32 s3, s3, 15
	v_add_u32_e32 v128, v88, v91
	v_add_u32_e32 v130, v89, v91
	s_lshl_b32 s92, s3, 7
	ds_read_b128 v[118:121], v130 offset:18432
	ds_read_b128 v[122:125], v130 offset:20480
	ds_read_b128 v[132:135], v130 offset:22528
	s_waitcnt lgkmcnt(4)
	v_mfma_f32_16x16x32_bf16 v[76:79], v[100:103], v[92:95], v[76:79]
	v_lshl_add_u64 v[44:45], v[80:81], 0, s[92:93]
	v_add_co_u32_e32 v46, vcc, s11, v44
	v_mfma_f32_16x16x32_bf16 v[68:71], v[106:109], v[92:95], v[68:71]
	s_nop 0
	v_addc_co_u32_e32 v47, vcc, 0, v45, vcc
	v_mfma_f32_16x16x32_bf16 v[52:55], v[110:113], v[92:95], v[52:55]
	v_mfma_f32_16x16x32_bf16 v[40:43], v[114:117], v[92:95], v[40:43]
	s_waitcnt lgkmcnt(3)
	v_mfma_f32_16x16x32_bf16 v[92:95], v[100:103], v[96:99], v[36:39]
	s_nop 2
	ds_read_b128 v[36:39], v128
	v_mfma_f32_16x16x32_bf16 v[100:103], v[106:109], v[96:99], v[8:11]
	v_mfma_f32_16x16x32_bf16 v[106:109], v[110:113], v[96:99], v[4:7]
	ds_read_b128 v[110:113], v128 offset:2048
	v_mfma_f32_16x16x32_bf16 v[96:99], v[114:117], v[96:99], v[0:3]
	ds_read_b128 v[114:117], v130 offset:16384
	s_waitcnt vmcnt(0)
	ds_write_b128 v87, v[12:15] offset:53248
	v_add_co_u32_e32 v46, vcc, s33, v44
	s_waitcnt vmcnt(1)
	ds_write_b128 v87, v[16:19] offset:49152
	s_nop 0
	v_addc_co_u32_e32 v47, vcc, 0, v45, vcc
	v_add_co_u32_e32 v44, vcc, s59, v44
	s_nop 0
	v_addc_co_u32_e32 v45, vcc, 0, v45, vcc
	s_waitcnt vmcnt(2)
	ds_write_b128 v87, v[20:23] offset:45056
	v_lshl_add_u64 v[44:45], v[82:83], 0, s[92:93]
	s_waitcnt vmcnt(5)
	ds_write_b128 v87, v[28:31] offset:32768
	s_waitcnt lgkmcnt(4)
	v_mfma_f32_16x16x32_bf16 v[0:3], v[114:117], v[36:39], v[76:79]
	v_mfma_f32_16x16x32_bf16 v[4:7], v[118:121], v[36:39], v[68:71]
	v_add_co_u32_e32 v44, vcc, s11, v44
	s_waitcnt vmcnt(4)
	ds_write_b128 v87, v[32:35] offset:36864
	s_nop 0
	v_addc_co_u32_e32 v45, vcc, 0, v45, vcc
	v_mfma_f32_16x16x32_bf16 v[8:11], v[122:125], v[36:39], v[52:55]
	v_mfma_f32_16x16x32_bf16 v[36:39], v[132:135], v[36:39], v[40:43]
	s_waitcnt vmcnt(3)
	ds_write_b128 v87, v[24:27] offset:40960
	v_mfma_f32_16x16x32_bf16 v[40:43], v[114:117], v[110:113], v[92:95]
	v_mfma_f32_16x16x32_bf16 v[52:55], v[118:121], v[110:113], v[100:103]
	v_mfma_f32_16x16x32_bf16 v[68:71], v[122:125], v[110:113], v[106:109]
	v_mfma_f32_16x16x32_bf16 v[76:79], v[132:135], v[110:113], v[96:99]
	s_waitcnt lgkmcnt(0)
	s_barrier
	ds_read_b128 v[100:103], v127 offset:49152
	ds_read_b128 v[106:109], v127 offset:51200
	ds_read_b128 v[110:113], v127 offset:53248
	ds_read_b128 v[114:117], v127 offset:55296
	ds_read_b128 v[92:95], v126 offset:32768
	ds_read_b128 v[96:99], v126 offset:34816
	s_min_u32 s3, s2, 12
	s_lshl_b32 s92, s3, 7
	ds_read_b128 v[118:121], v130 offset:51200
	ds_read_b128 v[122:125], v130 offset:53248
	ds_read_b128 v[132:135], v130 offset:55296
	s_waitcnt lgkmcnt(4)
	v_mfma_f32_16x16x32_bf16 v[0:3], v[100:103], v[92:95], v[0:3]
	v_lshl_add_u64 v[12:13], v[80:81], 0, s[92:93]
	v_add_co_u32_e32 v14, vcc, s11, v12
	v_mfma_f32_16x16x32_bf16 v[4:7], v[106:109], v[92:95], v[4:7]
	s_nop 0
	v_addc_co_u32_e32 v15, vcc, 0, v13, vcc
	v_mfma_f32_16x16x32_bf16 v[8:11], v[110:113], v[92:95], v[8:11]
	v_mfma_f32_16x16x32_bf16 v[36:39], v[114:117], v[92:95], v[36:39]
	s_waitcnt lgkmcnt(3)
	v_mfma_f32_16x16x32_bf16 v[92:95], v[100:103], v[96:99], v[40:43]
	s_nop 2
	ds_read_b128 v[40:43], v128 offset:32768
	v_mfma_f32_16x16x32_bf16 v[100:103], v[106:109], v[96:99], v[52:55]
	v_mfma_f32_16x16x32_bf16 v[106:109], v[110:113], v[96:99], v[68:71]
	ds_read_b128 v[110:113], v128 offset:34816
	v_mfma_f32_16x16x32_bf16 v[96:99], v[114:117], v[96:99], v[76:79]
	ds_read_b128 v[114:117], v130 offset:49152
	v_add_co_u32_e32 v14, vcc, s33, v12
	s_nop 0
	v_addc_co_u32_e32 v15, vcc, 0, v13, vcc
	v_add_co_u32_e32 v12, vcc, s59, v12
	s_nop 0
	v_addc_co_u32_e32 v13, vcc, 0, v13, vcc
	v_lshl_add_u64 v[12:13], v[82:83], 0, s[92:93]
	s_waitcnt lgkmcnt(0)
	v_mfma_f32_16x16x32_bf16 v[76:79], v[114:117], v[40:43], v[0:3]
	v_mfma_f32_16x16x32_bf16 v[68:71], v[118:121], v[40:43], v[4:7]
	v_add_co_u32_e32 v12, vcc, s11, v12
	s_nop 0
	v_addc_co_u32_e32 v13, vcc, 0, v13, vcc
	v_mfma_f32_16x16x32_bf16 v[52:55], v[122:125], v[40:43], v[8:11]
	v_mfma_f32_16x16x32_bf16 v[40:43], v[132:135], v[40:43], v[36:39]
	v_mfma_f32_16x16x32_bf16 v[36:39], v[114:117], v[110:113], v[92:95]
	v_mfma_f32_16x16x32_bf16 v[8:11], v[118:121], v[110:113], v[100:103]
	v_mfma_f32_16x16x32_bf16 v[4:7], v[122:125], v[110:113], v[106:109]
	v_mfma_f32_16x16x32_bf16 v[0:3], v[132:135], v[110:113], v[96:99]
	s_mov_b32 s3, s2
	s_waitcnt lgkmcnt(0)
	s_barrier
	v_readlane_b32 s2, v251, 18
	s_waitcnt vmcnt(1)
	s_nop 0
	v_add_u32_e32 v18, s2, v86
	v_readlane_b32 s2, v251, 19
	s_waitcnt vmcnt(0)
	v_add_u32_e32 v13, 0xffffe000, v18
	v_or_b32_e32 v12, v18, v85
	v_lshl_or_b32 v19, v84, 2, s2
	v_lshrrev_b32_e32 v13, 10, v13
	s_movk_i32 s2, 0x1800
	v_mad_u32_u24 v13, v13, s2, s2
	v_cmp_lt_i32_e32 vcc, s13, v12
	v_lshlrev_b32_e32 v128, 2, v19
	v_readlane_b32 s2, v250, 15
	v_cndmask_b32_e32 v14, 0, v13, vcc
	v_ashrrev_i32_e32 v15, 31, v14
	v_lshlrev_b64 v[24:25], 2, v[14:15]
	v_ashrrev_i32_e32 v13, 31, v12
	v_lshl_add_u64 v[14:15], s[40:41], 0, v[24:25]
	v_lshl_add_u64 v[48:49], v[14:15], 0, v[128:129]
	v_lshlrev_b64 v[14:15], 12, v[12:13]
	v_readlane_b32 s3, v250, 16
	v_lshl_add_u64 v[28:29], s[42:43], 0, v[24:25]
	v_lshlrev_b64 v[32:33], 11, v[12:13]
	v_lshl_add_u64 v[14:15], s[2:3], 0, v[14:15]
	v_lshl_add_u64 v[50:51], v[14:15], 0, v[128:129]
	global_load_dwordx4 v[72:75], v[48:49], off
	global_load_dwordx4 v[80:83], v[48:49], off offset:64
	global_load_dwordx4 v[88:91], v[48:49], off offset:128
	global_load_dwordx4 v[136:139], v[48:49], off offset:192
	global_load_dwordx4 v[194:197], v[50:51], off
	global_load_dwordx4 v[198:201], v[50:51], off offset:64
	global_load_dwordx4 v[202:205], v[50:51], off offset:128
	global_load_dwordx4 v[206:209], v[50:51], off offset:192
	v_add_co_u32_e32 v58, vcc, 0x10000, v50
	s_nop 1
	v_addc_co_u32_e32 v59, vcc, 0, v51, vcc
	global_load_dwordx4 v[210:213], v[58:59], off
	global_load_dwordx4 v[214:217], v[58:59], off offset:64
	global_load_dwordx4 v[218:221], v[58:59], off offset:128
	global_load_dwordx4 v[222:225], v[58:59], off offset:192
	v_readlane_b32 s2, v250, 21
	v_readlane_b32 s3, v250, 22
	v_cmp_eq_u32_e32 vcc, 0, v84
	s_waitcnt vmcnt(4)
	v_pk_fma_f32 v[22:23], v[78:79], v[74:75], v[196:197]
	v_pk_fma_f32 v[20:21], v[76:77], v[72:73], v[194:195]
	global_store_dwordx4 v[50:51], v[20:23], off
	v_lshl_add_u64 v[14:15], v[28:29], 0, v[128:129]
	global_load_dwordx4 v[140:143], v128, s[0:1]
	global_load_dwordx4 v[144:147], v128, s[0:1] offset:64
	global_load_dwordx4 v[148:151], v128, s[0:1] offset:128
	global_load_dwordx4 v[152:155], v128, s[0:1] offset:192
	global_load_dwordx4 v[156:159], v[14:15], off
	global_load_dwordx4 v[160:163], v[14:15], off offset:64
	global_load_dwordx4 v[180:183], v[14:15], off offset:128
	global_load_dwordx4 v[190:193], v[14:15], off offset:192
	v_lshlrev_b32_e32 v16, 1, v19
	v_mov_b32_e32 v17, v129
	v_lshl_add_u64 v[32:33], s[2:3], 0, v[32:33]
	v_lshl_add_u64 v[56:57], v[32:33], 0, v[16:17]
	s_waitcnt vmcnt(0)
	v_pk_mul_f32 v[26:27], v[22:23], v[142:143]
	v_pk_mul_f32 v[24:25], v[20:21], v[140:141]
	s_waitcnt vmcnt(0)
	v_pk_add_f32 v[30:31], v[158:159], 1.0 op_sel_hi:[1,0]
	v_pk_add_f32 v[28:29], v[156:157], 1.0 op_sel_hi:[1,0]
	v_pk_mul_f32 v[26:27], v[26:27], v[30:31]
	v_pk_mul_f32 v[24:25], v[24:25], v[28:29]
	v_and_b32_sdwa v19, v26, v170 dst_sel:DWORD dst_unused:UNUSED_PAD src0_sel:WORD_1 src1_sel:DWORD
	v_and_b32_sdwa v29, v27, v170 dst_sel:DWORD dst_unused:UNUSED_PAD src0_sel:WORD_1 src1_sel:DWORD
	v_and_b32_sdwa v30, v25, v170 dst_sel:DWORD dst_unused:UNUSED_PAD src0_sel:WORD_1 src1_sel:DWORD
	v_and_b32_sdwa v28, v24, v170 dst_sel:DWORD dst_unused:UNUSED_PAD src0_sel:WORD_1 src1_sel:DWORD
	v_add3_u32 v19, v26, v19, s56
	v_add3_u32 v26, v27, v29, s56
	v_add3_u32 v25, v25, v30, s56
	v_add3_u32 v24, v24, v28, s56
	v_and_b32_e32 v26, 0xffff0000, v26
	v_and_b32_e32 v27, 0xffff0000, v25
	v_or_b32_sdwa v25, v26, v19 dst_sel:DWORD dst_unused:UNUSED_PAD src0_sel:DWORD src1_sel:WORD_1
	v_or_b32_sdwa v24, v27, v24 dst_sel:DWORD dst_unused:UNUSED_PAD src0_sel:DWORD src1_sel:WORD_1
	global_store_dwordx2 v[56:57], v[24:25], off
	s_nop 0
	s_waitcnt vmcnt(0)
	v_pk_fma_f32 v[26:27], v[70:71], v[82:83], v[200:201]
	v_pk_fma_f32 v[24:25], v[68:69], v[80:81], v[198:199]
	global_store_dwordx4 v[50:51], v[24:27], off offset:64
	v_pk_mul_f32 v[30:31], v[26:27], v[146:147]
	v_pk_mul_f32 v[28:29], v[24:25], v[144:145]
	v_pk_add_f32 v[34:35], v[162:163], 1.0 op_sel_hi:[1,0]
	v_pk_add_f32 v[32:33], v[160:161], 1.0 op_sel_hi:[1,0]
	v_pk_mul_f32 v[30:31], v[30:31], v[34:35]
	v_pk_mul_f32 v[28:29], v[28:29], v[32:33]
	v_and_b32_sdwa v19, v30, v170 dst_sel:DWORD dst_unused:UNUSED_PAD src0_sel:WORD_1 src1_sel:DWORD
	v_and_b32_sdwa v33, v31, v170 dst_sel:DWORD dst_unused:UNUSED_PAD src0_sel:WORD_1 src1_sel:DWORD
	v_and_b32_sdwa v34, v29, v170 dst_sel:DWORD dst_unused:UNUSED_PAD src0_sel:WORD_1 src1_sel:DWORD
	v_and_b32_sdwa v32, v28, v170 dst_sel:DWORD dst_unused:UNUSED_PAD src0_sel:WORD_1 src1_sel:DWORD
	v_add3_u32 v19, v30, v19, s56
	v_add3_u32 v30, v31, v33, s56
	v_add3_u32 v29, v29, v34, s56
	v_add3_u32 v28, v28, v32, s56
	v_and_b32_e32 v30, 0xffff0000, v30
	v_and_b32_e32 v31, 0xffff0000, v29
	v_or_b32_sdwa v29, v30, v19 dst_sel:DWORD dst_unused:UNUSED_PAD src0_sel:DWORD src1_sel:WORD_1
	v_or_b32_sdwa v28, v31, v28 dst_sel:DWORD dst_unused:UNUSED_PAD src0_sel:DWORD src1_sel:WORD_1
	global_store_dwordx2 v[56:57], v[28:29], off offset:32
	s_nop 0
	v_pk_fma_f32 v[30:31], v[54:55], v[90:91], v[204:205]
	v_pk_fma_f32 v[28:29], v[52:53], v[88:89], v[202:203]
	global_store_dwordx4 v[50:51], v[28:31], off offset:128
	v_pk_mul_f32 v[34:35], v[30:31], v[150:151]
	v_pk_mul_f32 v[32:33], v[28:29], v[148:149]
	v_pk_add_f32 v[46:47], v[182:183], 1.0 op_sel_hi:[1,0]
	v_pk_add_f32 v[44:45], v[180:181], 1.0 op_sel_hi:[1,0]
	v_pk_mul_f32 v[34:35], v[34:35], v[46:47]
	v_pk_mul_f32 v[32:33], v[32:33], v[44:45]
	v_and_b32_sdwa v19, v34, v170 dst_sel:DWORD dst_unused:UNUSED_PAD src0_sel:WORD_1 src1_sel:DWORD
	v_and_b32_sdwa v45, v35, v170 dst_sel:DWORD dst_unused:UNUSED_PAD src0_sel:WORD_1 src1_sel:DWORD
	v_and_b32_sdwa v46, v33, v170 dst_sel:DWORD dst_unused:UNUSED_PAD src0_sel:WORD_1 src1_sel:DWORD
	v_and_b32_sdwa v44, v32, v170 dst_sel:DWORD dst_unused:UNUSED_PAD src0_sel:WORD_1 src1_sel:DWORD
	v_add3_u32 v19, v34, v19, s56
	v_add3_u32 v34, v35, v45, s56
	v_add3_u32 v33, v33, v46, s56
	v_add3_u32 v32, v32, v44, s56
	v_and_b32_e32 v34, 0xffff0000, v34
	v_and_b32_e32 v35, 0xffff0000, v33
	v_or_b32_sdwa v33, v34, v19 dst_sel:DWORD dst_unused:UNUSED_PAD src0_sel:DWORD src1_sel:WORD_1
	v_or_b32_sdwa v32, v35, v32 dst_sel:DWORD dst_unused:UNUSED_PAD src0_sel:DWORD src1_sel:WORD_1
	global_store_dwordx2 v[56:57], v[32:33], off offset:64
	s_nop 0
	v_pk_fma_f32 v[34:35], v[42:43], v[138:139], v[208:209]
	v_pk_fma_f32 v[32:33], v[40:41], v[136:137], v[206:207]
	global_store_dwordx4 v[50:51], v[32:35], off offset:192
	v_mul_f32_e32 v14, v21, v21
	v_mul_f32_e32 v15, v25, v25
	v_fmac_f32_e32 v14, v20, v20
	v_fmac_f32_e32 v15, v24, v24
	v_fmac_f32_e32 v14, v22, v22
	v_fmac_f32_e32 v15, v26, v26
	v_fmac_f32_e32 v14, v23, v23
	v_fmac_f32_e32 v15, v27, v27
	v_add_f32_e32 v14, v14, v15
	v_mul_f32_e32 v15, v29, v29
	v_fmac_f32_e32 v15, v28, v28
	v_fmac_f32_e32 v15, v30, v30
	v_fmac_f32_e32 v15, v31, v31
	v_add_f32_e32 v14, v14, v15
	v_mul_f32_e32 v15, v33, v33
	v_fmac_f32_e32 v15, v32, v32
	v_fmac_f32_e32 v15, v34, v34
	v_fmac_f32_e32 v15, v35, v35
	v_add_f32_e32 v14, v14, v15
	ds_bpermute_b32 v15, v105, v14
	s_waitcnt lgkmcnt(0)
	v_add_f32_e32 v14, v14, v15
	ds_bpermute_b32 v15, v104, v14
	v_pk_mul_f32 v[20:21], v[34:35], v[154:155]
	v_pk_mul_f32 v[22:23], v[32:33], v[152:153]
	v_pk_add_f32 v[24:25], v[192:193], 1.0 op_sel_hi:[1,0]
	v_pk_add_f32 v[26:27], v[190:191], 1.0 op_sel_hi:[1,0]
	v_pk_mul_f32 v[20:21], v[20:21], v[24:25]
	v_pk_mul_f32 v[22:23], v[22:23], v[26:27]
	v_and_b32_sdwa v19, v20, v170 dst_sel:DWORD dst_unused:UNUSED_PAD src0_sel:WORD_1 src1_sel:DWORD
	v_and_b32_sdwa v25, v21, v170 dst_sel:DWORD dst_unused:UNUSED_PAD src0_sel:WORD_1 src1_sel:DWORD
	v_and_b32_sdwa v26, v23, v170 dst_sel:DWORD dst_unused:UNUSED_PAD src0_sel:WORD_1 src1_sel:DWORD
	v_and_b32_sdwa v24, v22, v170 dst_sel:DWORD dst_unused:UNUSED_PAD src0_sel:WORD_1 src1_sel:DWORD
	v_add3_u32 v19, v20, v19, s56
	v_add3_u32 v20, v21, v25, s56
	v_add3_u32 v21, v23, v26, s56
	v_add3_u32 v22, v22, v24, s56
	v_and_b32_e32 v20, 0xffff0000, v20
	v_and_b32_e32 v23, 0xffff0000, v21
	v_or_b32_sdwa v21, v20, v19 dst_sel:DWORD dst_unused:UNUSED_PAD src0_sel:DWORD src1_sel:WORD_1
	v_or_b32_sdwa v20, v23, v22 dst_sel:DWORD dst_unused:UNUSED_PAD src0_sel:DWORD src1_sel:WORD_1
	global_store_dwordx2 v[56:57], v[20:21], off offset:96
	s_and_saveexec_b64 s[2:3], vcc
	s_cbranch_execz .LBB0_422
	v_readlane_b32 s16, v253, 20
	s_add_u32 s24, s38, s16
	s_addc_u32 s25, s39, 0
	v_lshl_add_u64 v[20:21], v[12:13], 2, s[24:25]
	s_waitcnt lgkmcnt(0)
	v_add_f32_e32 v13, v14, v15
	global_store_dword v[20:21], v13, off

.LBB0_582:
	s_add_i32 s0, s1, 2
	v_add_u32_e32 v111, v104, v105
	ds_read_b128 v[136:139], v111 offset:16384
	ds_read_b128 v[140:143], v111 offset:18432
	ds_read_b128 v[144:147], v111 offset:20480
	ds_read_b128 v[148:151], v111 offset:22528
	v_add_u32_e32 v110, v103, v105
	ds_read_b128 v[116:119], v110
	s_add_i32 s1, s1, 4
	ds_read_b128 v[120:123], v110 offset:2048
	s_min_u32 s1, s1, 63
	v_add_u32_e32 v113, v104, v114
	s_lshl_b32 s92, s1, 7
	ds_read_b128 v[124:127], v110 offset:4096
	v_add_u32_e32 v112, v103, v114
	ds_read_b128 v[194:197], v113 offset:16384
	ds_read_b128 v[198:201], v113 offset:18432
	ds_read_b128 v[202:205], v113 offset:20480
	ds_read_b128 v[206:209], v113 offset:22528
	v_lshl_add_u64 v[164:165], v[98:99], 0, s[92:93]
	ds_read_b128 v[132:135], v110 offset:6144
	ds_read_b128 v[152:155], v112
	ds_read_b128 v[156:159], v112 offset:2048
	ds_read_b128 v[160:163], v112 offset:4096
	ds_read_b128 v[190:193], v112 offset:6144
	s_waitcnt lgkmcnt(11)
	v_mfma_f32_16x16x32_bf16 v[92:95], v[136:139], v[116:119], v[92:95]
	v_mfma_f32_16x16x32_bf16 v[88:91], v[140:143], v[116:119], v[88:91]
	v_mfma_f32_16x16x32_bf16 v[52:55], v[144:147], v[116:119], v[52:55]
	v_mfma_f32_16x16x32_bf16 v[48:51], v[148:151], v[116:119], v[48:51]
	global_load_dwordx4 v[116:119], v[164:165], off
	s_waitcnt vmcnt(6)
	ds_write_b128 v109, v[56:59] offset:32768
	v_add_co_u32_e32 v56, vcc, s7, v164
	s_waitcnt lgkmcnt(11)
	v_mfma_f32_16x16x32_bf16 v[44:47], v[136:139], v[120:123], v[44:47]
	v_addc_co_u32_e32 v57, vcc, 0, v165, vcc
	v_mfma_f32_16x16x32_bf16 v[40:43], v[140:143], v[120:123], v[40:43]
	v_mfma_f32_16x16x32_bf16 v[36:39], v[144:147], v[120:123], v[36:39]
	v_mfma_f32_16x16x32_bf16 v[32:35], v[148:151], v[120:123], v[32:35]
	global_load_dwordx4 v[120:123], v[56:57], off
	v_add_co_u32_e32 v56, vcc, s52, v164
	ds_write_b128 v109, v[60:63] offset:36864
	s_nop 0
	v_addc_co_u32_e32 v57, vcc, 0, v165, vcc
	s_waitcnt lgkmcnt(11)
	v_mfma_f32_16x16x32_bf16 v[28:31], v[136:139], v[124:127], v[28:31]
	v_mfma_f32_16x16x32_bf16 v[24:27], v[140:143], v[124:127], v[24:27]
	v_mfma_f32_16x16x32_bf16 v[20:23], v[144:147], v[124:127], v[20:23]
	v_mfma_f32_16x16x32_bf16 v[16:19], v[148:151], v[124:127], v[16:19]
	global_load_dwordx4 v[124:127], v[56:57], off
	v_add_co_u32_e32 v56, vcc, s34, v164
	ds_write_b128 v109, v[64:67] offset:40960
	s_nop 0
	v_addc_co_u32_e32 v57, vcc, 0, v165, vcc
	v_lshl_add_u64 v[64:65], v[100:101], 0, s[92:93]
	v_add_co_u32_e32 v66, vcc, s7, v64
	s_waitcnt lgkmcnt(7)
	v_mfma_f32_16x16x32_bf16 v[12:15], v[136:139], v[132:135], v[12:15]
	v_addc_co_u32_e32 v67, vcc, 0, v65, vcc
	v_mfma_f32_16x16x32_bf16 v[8:11], v[140:143], v[132:135], v[8:11]
	v_mfma_f32_16x16x32_bf16 v[4:7], v[144:147], v[132:135], v[4:7]
	v_mfma_f32_16x16x32_bf16 v[0:3], v[148:151], v[132:135], v[0:3]
	global_load_dwordx4 v[132:135], v[56:57], off
	s_waitcnt vmcnt(7)
	ds_write_b128 v109, v[72:75] offset:45056
	s_waitcnt lgkmcnt(7)
	v_mfma_f32_16x16x32_bf16 v[56:59], v[194:197], v[152:155], v[92:95]
	v_mfma_f32_16x16x32_bf16 v[60:63], v[198:201], v[152:155], v[88:91]
	v_mfma_f32_16x16x32_bf16 v[52:55], v[202:205], v[152:155], v[52:55]
	v_mfma_f32_16x16x32_bf16 v[48:51], v[206:209], v[152:155], v[48:51]
	global_load_dwordx4 v[136:139], v[64:65], off
	ds_write_b128 v109, v[68:71] offset:49152
	s_waitcnt lgkmcnt(7)
	v_mfma_f32_16x16x32_bf16 v[44:47], v[194:197], v[156:159], v[44:47]
	v_mfma_f32_16x16x32_bf16 v[40:43], v[198:201], v[156:159], v[40:43]
	v_mfma_f32_16x16x32_bf16 v[36:39], v[202:205], v[156:159], v[36:39]
	v_mfma_f32_16x16x32_bf16 v[32:35], v[206:209], v[156:159], v[32:35]
	global_load_dwordx4 v[140:143], v[66:67], off
	v_add_co_u32_e32 v66, vcc, s52, v64
	s_waitcnt vmcnt(8)
	ds_write_b128 v109, v[76:79] offset:53248
	v_addc_co_u32_e32 v67, vcc, 0, v65, vcc
	v_add_co_u32_e32 v64, vcc, s34, v64
	s_waitcnt lgkmcnt(7)
	v_mfma_f32_16x16x32_bf16 v[28:31], v[194:197], v[160:163], v[28:31]
	v_addc_co_u32_e32 v65, vcc, 0, v65, vcc
	v_mfma_f32_16x16x32_bf16 v[24:27], v[198:201], v[160:163], v[24:27]
	v_mfma_f32_16x16x32_bf16 v[20:23], v[202:205], v[160:163], v[20:23]
	v_mfma_f32_16x16x32_bf16 v[16:19], v[206:209], v[160:163], v[16:19]
	global_load_dwordx4 v[144:147], v[66:67], off
	s_waitcnt vmcnt(8)
	ds_write_b128 v109, v[80:83] offset:57344
	s_waitcnt lgkmcnt(7)
	v_mfma_f32_16x16x32_bf16 v[12:15], v[194:197], v[190:193], v[12:15]
	v_mfma_f32_16x16x32_bf16 v[8:11], v[198:201], v[190:193], v[8:11]
	v_mfma_f32_16x16x32_bf16 v[4:7], v[202:205], v[190:193], v[4:7]
	v_mfma_f32_16x16x32_bf16 v[0:3], v[206:209], v[190:193], v[0:3]
	global_load_dwordx4 v[148:151], v[64:65], off
	s_waitcnt vmcnt(8)
	ds_write_b128 v109, v[84:87] offset:61440
	s_waitcnt lgkmcnt(0)
	s_barrier
	ds_read_b128 v[84:87], v111 offset:51200
	ds_read_b128 v[80:83], v111 offset:49152
	ds_read_b128 v[88:91], v111 offset:53248
	ds_read_b128 v[92:95], v111 offset:55296
	ds_read_b128 v[64:67], v110 offset:32768
	s_min_u32 s1, s0, 60
	s_lshl_b32 s92, s1, 7
	ds_read_b128 v[68:71], v110 offset:34816
	v_lshl_add_u64 v[164:165], v[98:99], 0, s[92:93]
	ds_read_b128 v[72:75], v110 offset:36864
	ds_read_b128 v[76:79], v110 offset:38912
	ds_read_b128 v[152:155], v112 offset:32768
	ds_read_b128 v[156:159], v112 offset:34816
	ds_read_b128 v[160:163], v112 offset:36864
	ds_read_b128 v[190:193], v112 offset:38912
	ds_read_b128 v[194:197], v113 offset:49152
	ds_read_b128 v[198:201], v113 offset:51200
	ds_read_b128 v[202:205], v113 offset:53248
	ds_read_b128 v[206:209], v113 offset:55296
	s_waitcnt lgkmcnt(11)
	v_mfma_f32_16x16x32_bf16 v[214:217], v[84:87], v[64:67], v[60:63]
	v_mfma_f32_16x16x32_bf16 v[210:213], v[80:83], v[64:67], v[56:59]
	s_nop 1
	v_add_co_u32_e32 v60, vcc, s7, v164
	s_nop 1
	v_addc_co_u32_e32 v61, vcc, 0, v165, vcc
	v_mfma_f32_16x16x32_bf16 v[52:55], v[88:91], v[64:67], v[52:55]
	v_mfma_f32_16x16x32_bf16 v[48:51], v[92:95], v[64:67], v[48:51]
	v_add_co_u32_e32 v64, vcc, s52, v164
	global_load_dwordx4 v[56:59], v[164:165], off offset:384
	s_nop 0
	v_addc_co_u32_e32 v65, vcc, 0, v165, vcc
	s_waitcnt vmcnt(8)
	ds_write_b128 v109, v[116:119]
	s_waitcnt lgkmcnt(11)
	v_mfma_f32_16x16x32_bf16 v[44:47], v[80:83], v[68:71], v[44:47]
	v_mfma_f32_16x16x32_bf16 v[40:43], v[84:87], v[68:71], v[40:43]
	v_mfma_f32_16x16x32_bf16 v[36:39], v[88:91], v[68:71], v[36:39]
	v_mfma_f32_16x16x32_bf16 v[32:35], v[92:95], v[68:71], v[32:35]
	v_add_co_u32_e32 v68, vcc, s34, v164
	global_load_dwordx4 v[60:63], v[60:61], off offset:384
	s_waitcnt vmcnt(8)
	ds_write_b128 v109, v[120:123] offset:4096
	s_waitcnt lgkmcnt(11)
	v_mfma_f32_16x16x32_bf16 v[28:31], v[80:83], v[72:75], v[28:31]
	v_addc_co_u32_e32 v69, vcc, 0, v165, vcc
	v_mfma_f32_16x16x32_bf16 v[24:27], v[84:87], v[72:75], v[24:27]
	v_mfma_f32_16x16x32_bf16 v[20:23], v[88:91], v[72:75], v[20:23]
	v_mfma_f32_16x16x32_bf16 v[16:19], v[92:95], v[72:75], v[16:19]
	global_load_dwordx4 v[64:67], v[64:65], off offset:384
	s_waitcnt vmcnt(8)
	ds_write_b128 v109, v[124:127] offset:8192
	s_waitcnt lgkmcnt(11)
	v_mfma_f32_16x16x32_bf16 v[8:11], v[84:87], v[76:79], v[8:11]
	v_lshl_add_u64 v[84:85], v[100:101], 0, s[92:93]
	v_mfma_f32_16x16x32_bf16 v[12:15], v[80:83], v[76:79], v[12:15]
	v_mfma_f32_16x16x32_bf16 v[4:7], v[88:91], v[76:79], v[4:7]
	v_mfma_f32_16x16x32_bf16 v[0:3], v[92:95], v[76:79], v[0:3]
	v_add_co_u32_e32 v76, vcc, s7, v84
	global_load_dwordx4 v[72:75], v[68:69], off offset:384
	s_nop 0
	v_addc_co_u32_e32 v77, vcc, 0, v85, vcc
	v_add_co_u32_e32 v80, vcc, s52, v84
	s_waitcnt vmcnt(8)
	ds_write_b128 v109, v[132:135] offset:12288
	v_addc_co_u32_e32 v81, vcc, 0, v85, vcc
	s_waitcnt lgkmcnt(7)
	v_mfma_f32_16x16x32_bf16 v[92:95], v[194:197], v[152:155], v[210:213]
	s_waitcnt lgkmcnt(6)
	v_mfma_f32_16x16x32_bf16 v[88:91], v[198:201], v[152:155], v[214:217]
	s_waitcnt lgkmcnt(5)
	v_mfma_f32_16x16x32_bf16 v[52:55], v[202:205], v[152:155], v[52:55]
	s_waitcnt lgkmcnt(4)
	v_mfma_f32_16x16x32_bf16 v[48:51], v[206:209], v[152:155], v[48:51]
	global_load_dwordx4 v[68:71], v[84:85], off offset:384
	v_add_co_u32_e32 v84, vcc, s34, v84
	s_waitcnt vmcnt(8)
	ds_write_b128 v109, v[136:139] offset:16384
	v_addc_co_u32_e32 v85, vcc, 0, v85, vcc
	v_mfma_f32_16x16x32_bf16 v[44:47], v[194:197], v[156:159], v[44:47]
	v_mfma_f32_16x16x32_bf16 v[40:43], v[198:201], v[156:159], v[40:43]
	v_mfma_f32_16x16x32_bf16 v[36:39], v[202:205], v[156:159], v[36:39]
	v_mfma_f32_16x16x32_bf16 v[32:35], v[206:209], v[156:159], v[32:35]
	global_load_dwordx4 v[76:79], v[76:77], off offset:384
	s_waitcnt vmcnt(8)
	ds_write_b128 v109, v[140:143] offset:20480
	v_mfma_f32_16x16x32_bf16 v[28:31], v[194:197], v[160:163], v[28:31]
	v_mfma_f32_16x16x32_bf16 v[24:27], v[198:201], v[160:163], v[24:27]
	v_mfma_f32_16x16x32_bf16 v[20:23], v[202:205], v[160:163], v[20:23]
	v_mfma_f32_16x16x32_bf16 v[16:19], v[206:209], v[160:163], v[16:19]
	global_load_dwordx4 v[80:83], v[80:81], off offset:384
	s_waitcnt vmcnt(8)
	ds_write_b128 v109, v[144:147] offset:24576
	v_mfma_f32_16x16x32_bf16 v[12:15], v[194:197], v[190:193], v[12:15]
	v_mfma_f32_16x16x32_bf16 v[8:11], v[198:201], v[190:193], v[8:11]
	v_mfma_f32_16x16x32_bf16 v[4:7], v[202:205], v[190:193], v[4:7]
	v_mfma_f32_16x16x32_bf16 v[0:3], v[206:209], v[190:193], v[0:3]
	global_load_dwordx4 v[84:87], v[84:85], off offset:384
	s_waitcnt vmcnt(8)
	ds_write_b128 v109, v[148:151] offset:28672
	s_cmp_lt_u32 s0, 60
	s_mov_b32 s1, s0
	s_waitcnt lgkmcnt(0)
	s_barrier
	s_cbranch_scc1 .LBB0_582
.Ltail582:
	s_add_i32 s0, s1, 2
	v_add_u32_e32 v111, v104, v105
	ds_read_b128 v[136:139], v111 offset:16384
	ds_read_b128 v[140:143], v111 offset:18432
	ds_read_b128 v[144:147], v111 offset:20480
	ds_read_b128 v[148:151], v111 offset:22528
	v_add_u32_e32 v110, v103, v105
	ds_read_b128 v[116:119], v110
	s_add_i32 s1, s1, 4
	ds_read_b128 v[120:123], v110 offset:2048
	s_min_u32 s1, s1, 63
	v_add_u32_e32 v113, v104, v114
	s_lshl_b32 s92, s1, 7
	ds_read_b128 v[124:127], v110 offset:4096
	v_add_u32_e32 v112, v103, v114
	ds_read_b128 v[194:197], v113 offset:16384
	ds_read_b128 v[198:201], v113 offset:18432
	ds_read_b128 v[202:205], v113 offset:20480
	ds_read_b128 v[206:209], v113 offset:22528
	v_lshl_add_u64 v[164:165], v[98:99], 0, s[92:93]
	ds_read_b128 v[132:135], v110 offset:6144
	ds_read_b128 v[152:155], v112
	ds_read_b128 v[156:159], v112 offset:2048
	ds_read_b128 v[160:163], v112 offset:4096
	ds_read_b128 v[190:193], v112 offset:6144
	s_waitcnt lgkmcnt(11)
	v_mfma_f32_16x16x32_bf16 v[92:95], v[136:139], v[116:119], v[92:95]
	v_mfma_f32_16x16x32_bf16 v[88:91], v[140:143], v[116:119], v[88:91]
	v_mfma_f32_16x16x32_bf16 v[52:55], v[144:147], v[116:119], v[52:55]
	v_mfma_f32_16x16x32_bf16 v[48:51], v[148:151], v[116:119], v[48:51]
	s_waitcnt vmcnt(7)
	ds_write_b128 v109, v[56:59] offset:32768
	v_add_co_u32_e32 v56, vcc, s7, v164
	s_waitcnt lgkmcnt(11)
	v_mfma_f32_16x16x32_bf16 v[44:47], v[136:139], v[120:123], v[44:47]
	v_addc_co_u32_e32 v57, vcc, 0, v165, vcc
	v_mfma_f32_16x16x32_bf16 v[40:43], v[140:143], v[120:123], v[40:43]
	v_mfma_f32_16x16x32_bf16 v[36:39], v[144:147], v[120:123], v[36:39]
	v_mfma_f32_16x16x32_bf16 v[32:35], v[148:151], v[120:123], v[32:35]
	v_add_co_u32_e32 v56, vcc, s52, v164
	s_waitcnt vmcnt(6)
	ds_write_b128 v109, v[60:63] offset:36864
	s_nop 0
	v_addc_co_u32_e32 v57, vcc, 0, v165, vcc
	s_waitcnt lgkmcnt(11)
	v_mfma_f32_16x16x32_bf16 v[28:31], v[136:139], v[124:127], v[28:31]
	v_mfma_f32_16x16x32_bf16 v[24:27], v[140:143], v[124:127], v[24:27]
	v_mfma_f32_16x16x32_bf16 v[20:23], v[144:147], v[124:127], v[20:23]
	v_mfma_f32_16x16x32_bf16 v[16:19], v[148:151], v[124:127], v[16:19]
	v_add_co_u32_e32 v56, vcc, s34, v164
	s_waitcnt vmcnt(5)
	ds_write_b128 v109, v[64:67] offset:40960
	s_nop 0
	v_addc_co_u32_e32 v57, vcc, 0, v165, vcc
	v_lshl_add_u64 v[64:65], v[100:101], 0, s[92:93]
	v_add_co_u32_e32 v66, vcc, s7, v64
	s_waitcnt lgkmcnt(7)
	v_mfma_f32_16x16x32_bf16 v[12:15], v[136:139], v[132:135], v[12:15]
	v_addc_co_u32_e32 v67, vcc, 0, v65, vcc
	v_mfma_f32_16x16x32_bf16 v[8:11], v[140:143], v[132:135], v[8:11]
	v_mfma_f32_16x16x32_bf16 v[4:7], v[144:147], v[132:135], v[4:7]
	v_mfma_f32_16x16x32_bf16 v[0:3], v[148:151], v[132:135], v[0:3]
	s_waitcnt vmcnt(4)
	ds_write_b128 v109, v[72:75] offset:45056
	s_waitcnt lgkmcnt(7)
	v_mfma_f32_16x16x32_bf16 v[56:59], v[194:197], v[152:155], v[92:95]
	v_mfma_f32_16x16x32_bf16 v[60:63], v[198:201], v[152:155], v[88:91]
	v_mfma_f32_16x16x32_bf16 v[52:55], v[202:205], v[152:155], v[52:55]
	v_mfma_f32_16x16x32_bf16 v[48:51], v[206:209], v[152:155], v[48:51]
	s_waitcnt vmcnt(3)
	ds_write_b128 v109, v[68:71] offset:49152
	s_waitcnt lgkmcnt(7)
	v_mfma_f32_16x16x32_bf16 v[44:47], v[194:197], v[156:159], v[44:47]
	v_mfma_f32_16x16x32_bf16 v[40:43], v[198:201], v[156:159], v[40:43]
	v_mfma_f32_16x16x32_bf16 v[36:39], v[202:205], v[156:159], v[36:39]
	v_mfma_f32_16x16x32_bf16 v[32:35], v[206:209], v[156:159], v[32:35]
	v_add_co_u32_e32 v66, vcc, s52, v64
	s_waitcnt vmcnt(2)
	ds_write_b128 v109, v[76:79] offset:53248
	v_addc_co_u32_e32 v67, vcc, 0, v65, vcc
	v_add_co_u32_e32 v64, vcc, s34, v64
	s_waitcnt lgkmcnt(7)
	v_mfma_f32_16x16x32_bf16 v[28:31], v[194:197], v[160:163], v[28:31]
	v_addc_co_u32_e32 v65, vcc, 0, v65, vcc
	v_mfma_f32_16x16x32_bf16 v[24:27], v[198:201], v[160:163], v[24:27]
	v_mfma_f32_16x16x32_bf16 v[20:23], v[202:205], v[160:163], v[20:23]
	v_mfma_f32_16x16x32_bf16 v[16:19], v[206:209], v[160:163], v[16:19]
	s_waitcnt vmcnt(1)
	ds_write_b128 v109, v[80:83] offset:57344
	s_waitcnt lgkmcnt(7)
	v_mfma_f32_16x16x32_bf16 v[12:15], v[194:197], v[190:193], v[12:15]
	v_mfma_f32_16x16x32_bf16 v[8:11], v[198:201], v[190:193], v[8:11]
	v_mfma_f32_16x16x32_bf16 v[4:7], v[202:205], v[190:193], v[4:7]
	v_mfma_f32_16x16x32_bf16 v[0:3], v[206:209], v[190:193], v[0:3]
	s_waitcnt vmcnt(0)
	ds_write_b128 v109, v[84:87] offset:61440
	s_waitcnt lgkmcnt(0)
	s_barrier
	ds_read_b128 v[84:87], v111 offset:51200
	ds_read_b128 v[80:83], v111 offset:49152
	ds_read_b128 v[88:91], v111 offset:53248
	ds_read_b128 v[92:95], v111 offset:55296
	ds_read_b128 v[64:67], v110 offset:32768
	s_min_u32 s1, s0, 60
	s_lshl_b32 s92, s1, 7
	ds_read_b128 v[68:71], v110 offset:34816
	v_lshl_add_u64 v[164:165], v[98:99], 0, s[92:93]
	ds_read_b128 v[72:75], v110 offset:36864
	ds_read_b128 v[76:79], v110 offset:38912
	ds_read_b128 v[152:155], v112 offset:32768
	ds_read_b128 v[156:159], v112 offset:34816
	ds_read_b128 v[160:163], v112 offset:36864
	ds_read_b128 v[190:193], v112 offset:38912
	ds_read_b128 v[194:197], v113 offset:49152
	ds_read_b128 v[198:201], v113 offset:51200
	ds_read_b128 v[202:205], v113 offset:53248
	ds_read_b128 v[206:209], v113 offset:55296
	s_waitcnt lgkmcnt(11)
	v_mfma_f32_16x16x32_bf16 v[214:217], v[84:87], v[64:67], v[60:63]
	v_mfma_f32_16x16x32_bf16 v[210:213], v[80:83], v[64:67], v[56:59]
	s_nop 1
	v_add_co_u32_e32 v60, vcc, s7, v164
	s_nop 1
	v_addc_co_u32_e32 v61, vcc, 0, v165, vcc
	v_mfma_f32_16x16x32_bf16 v[52:55], v[88:91], v[64:67], v[52:55]
	v_mfma_f32_16x16x32_bf16 v[48:51], v[92:95], v[64:67], v[48:51]
	v_add_co_u32_e32 v64, vcc, s52, v164
	s_nop 0
	v_addc_co_u32_e32 v65, vcc, 0, v165, vcc
	s_waitcnt lgkmcnt(10)
	v_mfma_f32_16x16x32_bf16 v[44:47], v[80:83], v[68:71], v[44:47]
	v_mfma_f32_16x16x32_bf16 v[40:43], v[84:87], v[68:71], v[40:43]
	v_mfma_f32_16x16x32_bf16 v[36:39], v[88:91], v[68:71], v[36:39]
	v_mfma_f32_16x16x32_bf16 v[32:35], v[92:95], v[68:71], v[32:35]
	v_add_co_u32_e32 v68, vcc, s34, v164
	s_waitcnt lgkmcnt(9)
	v_mfma_f32_16x16x32_bf16 v[28:31], v[80:83], v[72:75], v[28:31]
	v_addc_co_u32_e32 v69, vcc, 0, v165, vcc
	v_mfma_f32_16x16x32_bf16 v[24:27], v[84:87], v[72:75], v[24:27]
	v_mfma_f32_16x16x32_bf16 v[20:23], v[88:91], v[72:75], v[20:23]
	v_mfma_f32_16x16x32_bf16 v[16:19], v[92:95], v[72:75], v[16:19]
	s_waitcnt lgkmcnt(8)
	v_mfma_f32_16x16x32_bf16 v[8:11], v[84:87], v[76:79], v[8:11]
	v_lshl_add_u64 v[84:85], v[100:101], 0, s[92:93]
	v_mfma_f32_16x16x32_bf16 v[12:15], v[80:83], v[76:79], v[12:15]
	v_mfma_f32_16x16x32_bf16 v[4:7], v[88:91], v[76:79], v[4:7]
	v_mfma_f32_16x16x32_bf16 v[0:3], v[92:95], v[76:79], v[0:3]
	v_add_co_u32_e32 v76, vcc, s7, v84
	s_nop 0
	v_addc_co_u32_e32 v77, vcc, 0, v85, vcc
	v_add_co_u32_e32 v80, vcc, s52, v84
	v_addc_co_u32_e32 v81, vcc, 0, v85, vcc
	s_waitcnt lgkmcnt(3)
	v_mfma_f32_16x16x32_bf16 v[92:95], v[194:197], v[152:155], v[210:213]
	s_waitcnt lgkmcnt(2)
	v_mfma_f32_16x16x32_bf16 v[88:91], v[198:201], v[152:155], v[214:217]
	s_waitcnt lgkmcnt(1)
	v_mfma_f32_16x16x32_bf16 v[52:55], v[202:205], v[152:155], v[52:55]
	s_waitcnt lgkmcnt(0)
	v_mfma_f32_16x16x32_bf16 v[48:51], v[206:209], v[152:155], v[48:51]
	v_add_co_u32_e32 v84, vcc, s34, v84
	v_addc_co_u32_e32 v85, vcc, 0, v85, vcc
	v_mfma_f32_16x16x32_bf16 v[44:47], v[194:197], v[156:159], v[44:47]
	v_mfma_f32_16x16x32_bf16 v[40:43], v[198:201], v[156:159], v[40:43]
	v_mfma_f32_16x16x32_bf16 v[36:39], v[202:205], v[156:159], v[36:39]
	v_mfma_f32_16x16x32_bf16 v[32:35], v[206:209], v[156:159], v[32:35]
	v_mfma_f32_16x16x32_bf16 v[28:31], v[194:197], v[160:163], v[28:31]
	v_mfma_f32_16x16x32_bf16 v[24:27], v[198:201], v[160:163], v[24:27]
	v_mfma_f32_16x16x32_bf16 v[20:23], v[202:205], v[160:163], v[20:23]
	v_mfma_f32_16x16x32_bf16 v[16:19], v[206:209], v[160:163], v[16:19]
	v_mfma_f32_16x16x32_bf16 v[12:15], v[194:197], v[190:193], v[12:15]
	v_mfma_f32_16x16x32_bf16 v[8:11], v[198:201], v[190:193], v[8:11]
	v_mfma_f32_16x16x32_bf16 v[4:7], v[202:205], v[190:193], v[4:7]
	v_mfma_f32_16x16x32_bf16 v[0:3], v[206:209], v[190:193], v[0:3]
	s_mov_b32 s1, s0
	s_waitcnt lgkmcnt(0)
	s_barrier
	s_or_b32 s0, s69, 1
	s_mul_i32 s1, s69, 0x12000
	v_readlane_b32 s26, v250, 25
	v_readlane_b32 s27, v250, 26
	s_add_u32 s1, s26, s1
	s_addc_u32 s24, s27, 0
	s_add_u32 s38, s1, 0x5000
	v_readlane_b32 s1, v251, 5
	v_lshlrev_b32_e32 v114, 6, v102
	v_lshlrev_b32_e32 v115, 2, v97
	s_waitcnt vmcnt(5)
	v_add_u32_e32 v64, s1, v108
	v_readlane_b32 s1, v251, 6
	v_add_u32_e32 v56, 0xffffe000, v64
	v_or_b32_e32 v62, v64, v107
	v_or_b32_e32 v65, s1, v114
	v_lshrrev_b32_e32 v56, 10, v56
	s_movk_i32 s1, 0x1800
	v_mad_u32_u24 v56, v56, s1, s1
	v_cmp_lt_i32_e32 vcc, s13, v62
	v_or_b32_e32 v58, v65, v115
	s_addc_u32 s39, s24, 0
	v_cndmask_b32_e32 v56, 0, v56, vcc
	v_ashrrev_i32_e32 v57, 31, v56
	s_waitcnt vmcnt(4)
	v_lshlrev_b64 v[74:75], 2, v[56:57]
	v_ashrrev_i32_e32 v59, 31, v58
	v_ashrrev_i32_e32 v63, 31, v62
	v_lshl_add_u64 v[56:57], s[38:39], 0, v[74:75]
	v_lshlrev_b64 v[60:61], 2, v[58:59]
	v_readlane_b32 s16, v250, 15
	s_waitcnt vmcnt(1)
	v_lshl_add_u64 v[82:83], v[56:57], 0, v[60:61]
	v_lshlrev_b64 v[56:57], 12, v[62:63]
	v_readlane_b32 s17, v250, 16
	v_readlane_b32 s68, v250, 41
	s_mul_i32 s24, s0, 0x12000
	v_lshl_add_u64 v[56:57], s[16:17], 0, v[56:57]
	s_waitcnt vmcnt(0)
	v_lshl_add_u64 v[84:85], v[56:57], 0, v[60:61]
	global_load_dwordx4 v[116:119], v[82:83], off
	global_load_dwordx4 v[120:123], v[82:83], off offset:64
	global_load_dwordx4 v[124:127], v[82:83], off offset:128
	global_load_dwordx4 v[132:135], v[82:83], off offset:192
	global_load_dwordx4 v[190:193], v[84:85], off
	global_load_dwordx4 v[194:197], v[84:85], off offset:64
	global_load_dwordx4 v[198:201], v[84:85], off offset:128
	global_load_dwordx4 v[202:205], v[84:85], off offset:192
	v_add_co_u32_e32 v164, vcc, 0x10000, v84
	s_nop 1
	v_addc_co_u32_e32 v165, vcc, 0, v85, vcc
	v_add_co_u32_e32 v222, vcc, 0x20000, v84
	s_nop 1
	v_addc_co_u32_e32 v223, vcc, 0, v85, vcc
	v_add_co_u32_e32 v224, vcc, 0x30000, v84
	s_nop 1
	v_addc_co_u32_e32 v225, vcc, 0, v85, vcc
	global_load_dwordx4 v[206:209], v[164:165], off
	global_load_dwordx4 v[210:213], v[164:165], off offset:64
	global_load_dwordx4 v[214:217], v[164:165], off offset:128
	global_load_dwordx4 v[218:221], v[164:165], off offset:192
	s_lshl_b32 s0, s0, 12
	v_readlane_b32 s70, v250, 43
	v_readlane_b32 s71, v250, 44
	s_add_u32 s0, s70, s0
	s_addc_u32 s1, s71, 0
	s_add_u32 s24, s26, s24
	s_addc_u32 s25, s27, 0
	s_add_u32 s40, s24, 0x1000
	s_addc_u32 s41, s25, 0
	v_lshl_add_u64 v[74:75], s[40:41], 0, v[74:75]
	v_lshl_add_u64 v[56:57], s[0:1], 0, v[60:61]
	v_lshl_add_u64 v[86:87], v[74:75], 0, v[60:61]
	v_readlane_b32 s16, v250, 21
	v_lshlrev_b64 v[78:79], 11, v[62:63]
	v_readlane_b32 s17, v250, 22
	v_readlane_b32 s69, v250, 42
	v_readlane_b32 s69, v254, 49
	v_lshl_add_u64 v[78:79], s[16:17], 0, v[78:79]
	s_mul_i32 s24, s69, 0x140000
	s_add_u32 s24, s86, s24
	s_mov_b32 s16, 0xa000
	s_addc_u32 s25, s87, 0
	s_add_u32 s26, s24, 0xafba000
	s_addc_u32 s27, s25, 0
	v_cmp_eq_u32_e64 s[36:37], 0, v97
	v_readlane_b32 s72, v250, 45
	v_readlane_b32 s73, v250, 46
	v_readlane_b32 s74, v250, 47
	v_readlane_b32 s75, v250, 48
	v_readlane_b32 s76, v250, 49
	v_readlane_b32 s77, v250, 50
	v_readlane_b32 s78, v250, 51
	v_readlane_b32 s79, v250, 52
	v_readlane_b32 s80, v250, 53
	v_readlane_b32 s81, v250, 54
	v_readlane_b32 s82, v250, 55
	v_readlane_b32 s83, v250, 56
	s_waitcnt vmcnt(4)
	v_pk_fma_f32 v[68:69], v[94:95], v[118:119], v[192:193]
	v_pk_fma_f32 v[66:67], v[92:93], v[116:117], v[190:191]
	global_store_dwordx4 v[84:85], v[66:69], off
	global_load_dwordx4 v[136:139], v[56:57], off
	global_load_dwordx4 v[140:143], v[56:57], off offset:64
	global_load_dwordx4 v[144:147], v[56:57], off offset:128
	global_load_dwordx4 v[148:151], v[56:57], off offset:192
	global_load_dwordx4 v[152:155], v[86:87], off
	global_load_dwordx4 v[156:159], v[86:87], off offset:64
	global_load_dwordx4 v[160:163], v[86:87], off offset:128
	global_load_dwordx4 v[180:183], v[86:87], off offset:192
	v_lshl_add_u64 v[92:93], v[58:59], 1, v[78:79]
	s_waitcnt vmcnt(0)
	v_pk_mul_f32 v[72:73], v[68:69], v[138:139]
	v_pk_mul_f32 v[70:71], v[66:67], v[136:137]
	s_waitcnt vmcnt(0)
	v_pk_add_f32 v[76:77], v[154:155], 1.0 op_sel_hi:[1,0]
	v_pk_add_f32 v[74:75], v[152:153], 1.0 op_sel_hi:[1,0]
	v_pk_mul_f32 v[72:73], v[72:73], v[76:77]
	v_pk_mul_f32 v[70:71], v[70:71], v[74:75]
	v_and_b32_sdwa v76, v73, v170 dst_sel:DWORD dst_unused:UNUSED_PAD src0_sel:WORD_1 src1_sel:DWORD
	v_and_b32_sdwa v77, v71, v170 dst_sel:DWORD dst_unused:UNUSED_PAD src0_sel:WORD_1 src1_sel:DWORD
	v_and_b32_sdwa v74, v72, v170 dst_sel:DWORD dst_unused:UNUSED_PAD src0_sel:WORD_1 src1_sel:DWORD
	v_and_b32_sdwa v75, v70, v170 dst_sel:DWORD dst_unused:UNUSED_PAD src0_sel:WORD_1 src1_sel:DWORD
	v_add3_u32 v73, v73, v76, s56
	v_add3_u32 v71, v71, v77, s56
	v_add3_u32 v70, v70, v75, s56
	v_add3_u32 v72, v72, v74, s56
	v_and_b32_e32 v73, 0xffff0000, v73
	v_and_b32_e32 v74, 0xffff0000, v71
	v_or_b32_sdwa v71, v73, v72 dst_sel:DWORD dst_unused:UNUSED_PAD src0_sel:DWORD src1_sel:WORD_1
	v_or_b32_sdwa v70, v74, v70 dst_sel:DWORD dst_unused:UNUSED_PAD src0_sel:DWORD src1_sel:WORD_1
	global_store_dwordx2 v[92:93], v[70:71], off
	s_nop 0
	s_waitcnt vmcnt(0)
	v_pk_fma_f32 v[72:73], v[90:91], v[122:123], v[196:197]
	v_pk_fma_f32 v[70:71], v[88:89], v[120:121], v[194:195]
	global_store_dwordx4 v[84:85], v[70:73], off offset:64
	v_pk_mul_f32 v[76:77], v[72:73], v[142:143]
	v_pk_mul_f32 v[74:75], v[70:71], v[140:141]
	v_pk_add_f32 v[80:81], v[158:159], 1.0 op_sel_hi:[1,0]
	v_pk_add_f32 v[78:79], v[156:157], 1.0 op_sel_hi:[1,0]
	v_pk_mul_f32 v[76:77], v[76:77], v[80:81]
	v_pk_mul_f32 v[74:75], v[74:75], v[78:79]
	v_and_b32_sdwa v80, v77, v170 dst_sel:DWORD dst_unused:UNUSED_PAD src0_sel:WORD_1 src1_sel:DWORD
	v_and_b32_sdwa v81, v75, v170 dst_sel:DWORD dst_unused:UNUSED_PAD src0_sel:WORD_1 src1_sel:DWORD
	v_and_b32_sdwa v78, v76, v170 dst_sel:DWORD dst_unused:UNUSED_PAD src0_sel:WORD_1 src1_sel:DWORD
	v_and_b32_sdwa v79, v74, v170 dst_sel:DWORD dst_unused:UNUSED_PAD src0_sel:WORD_1 src1_sel:DWORD
	v_add3_u32 v77, v77, v80, s56
	v_add3_u32 v75, v75, v81, s56
	v_add3_u32 v74, v74, v79, s56
	v_add3_u32 v76, v76, v78, s56
	v_and_b32_e32 v77, 0xffff0000, v77
	v_and_b32_e32 v78, 0xffff0000, v75
	v_or_b32_sdwa v75, v77, v76 dst_sel:DWORD dst_unused:UNUSED_PAD src0_sel:DWORD src1_sel:WORD_1
	v_or_b32_sdwa v74, v78, v74 dst_sel:DWORD dst_unused:UNUSED_PAD src0_sel:DWORD src1_sel:WORD_1
	global_store_dwordx2 v[92:93], v[74:75], off offset:32
	s_nop 0
	v_pk_fma_f32 v[54:55], v[54:55], v[126:127], v[200:201]
	v_pk_fma_f32 v[52:53], v[52:53], v[124:125], v[198:199]
	global_store_dwordx4 v[84:85], v[52:55], off offset:128
	v_pk_mul_f32 v[76:77], v[54:55], v[146:147]
	v_pk_mul_f32 v[74:75], v[52:53], v[144:145]
	v_pk_add_f32 v[80:81], v[162:163], 1.0 op_sel_hi:[1,0]
	v_pk_add_f32 v[78:79], v[160:161], 1.0 op_sel_hi:[1,0]
	v_pk_mul_f32 v[76:77], v[76:77], v[80:81]
	v_pk_mul_f32 v[74:75], v[74:75], v[78:79]
	v_and_b32_sdwa v80, v77, v170 dst_sel:DWORD dst_unused:UNUSED_PAD src0_sel:WORD_1 src1_sel:DWORD
	v_and_b32_sdwa v81, v75, v170 dst_sel:DWORD dst_unused:UNUSED_PAD src0_sel:WORD_1 src1_sel:DWORD
	v_and_b32_sdwa v78, v76, v170 dst_sel:DWORD dst_unused:UNUSED_PAD src0_sel:WORD_1 src1_sel:DWORD
	v_and_b32_sdwa v79, v74, v170 dst_sel:DWORD dst_unused:UNUSED_PAD src0_sel:WORD_1 src1_sel:DWORD
	v_add3_u32 v77, v77, v80, s56
	v_add3_u32 v75, v75, v81, s56
	v_add3_u32 v74, v74, v79, s56
	v_add3_u32 v76, v76, v78, s56
	v_and_b32_e32 v77, 0xffff0000, v77
	v_and_b32_e32 v78, 0xffff0000, v75
	v_or_b32_sdwa v75, v77, v76 dst_sel:DWORD dst_unused:UNUSED_PAD src0_sel:DWORD src1_sel:WORD_1
	v_or_b32_sdwa v74, v78, v74 dst_sel:DWORD dst_unused:UNUSED_PAD src0_sel:DWORD src1_sel:WORD_1
	global_store_dwordx2 v[92:93], v[74:75], off offset:64
	s_nop 0
	v_pk_fma_f32 v[76:77], v[50:51], v[134:135], v[204:205]
	v_pk_fma_f32 v[74:75], v[48:49], v[132:133], v[202:203]
	global_store_dwordx4 v[84:85], v[74:77], off offset:192
	s_nop 0
	v_mul_f32_e32 v50, v67, v67
	v_mul_f32_e32 v51, v71, v71
	v_fmac_f32_e32 v50, v66, v66
	v_fmac_f32_e32 v51, v70, v70
	v_fmac_f32_e32 v50, v68, v68
	v_fmac_f32_e32 v51, v72, v72
	v_fmac_f32_e32 v50, v69, v69
	v_fmac_f32_e32 v51, v73, v73
	v_add_f32_e32 v50, v50, v51
	v_mul_f32_e32 v51, v53, v53
	v_fmac_f32_e32 v51, v52, v52
	v_fmac_f32_e32 v51, v54, v54
	v_fmac_f32_e32 v51, v55, v55
	v_add_f32_e32 v50, v50, v51
	v_mul_f32_e32 v51, v75, v75
	v_xor_b32_e32 v48, 16, v176
	v_fmac_f32_e32 v51, v74, v74
	v_cmp_lt_i32_e32 vcc, v48, v177
	v_fmac_f32_e32 v51, v76, v76
	v_fmac_f32_e32 v51, v77, v77
	v_cndmask_b32_e32 v48, v176, v48, vcc
	v_lshlrev_b32_e32 v105, 2, v48
	v_add_f32_e32 v50, v50, v51
	ds_bpermute_b32 v51, v105, v50
	v_xor_b32_e32 v49, 32, v176
	v_cmp_lt_i32_e32 vcc, v49, v177
	v_lshrrev_b32_e32 v48, 6, v65
	v_mul_lo_u32 v48, v48, s16
	v_cndmask_b32_e32 v49, v176, v49, vcc
	v_lshlrev_b32_e32 v104, 2, v49
	s_waitcnt lgkmcnt(0)
	v_add_f32_e32 v50, v50, v51
	ds_bpermute_b32 v51, v104, v50
	v_ashrrev_i32_e32 v49, 31, v48
	v_lshl_add_u64 v[48:49], s[26:27], 0, v[48:49]
	v_lshl_add_u64 v[48:49], v[62:63], 2, v[48:49]
	v_pk_mul_f32 v[52:53], v[76:77], v[150:151]
	v_pk_mul_f32 v[54:55], v[74:75], v[148:149]
	v_pk_add_f32 v[66:67], v[182:183], 1.0 op_sel_hi:[1,0]
	v_pk_add_f32 v[68:69], v[180:181], 1.0 op_sel_hi:[1,0]
	v_pk_mul_f32 v[52:53], v[52:53], v[66:67]
	v_pk_mul_f32 v[54:55], v[54:55], v[68:69]
	v_and_b32_sdwa v67, v53, v170 dst_sel:DWORD dst_unused:UNUSED_PAD src0_sel:WORD_1 src1_sel:DWORD
	v_and_b32_sdwa v68, v55, v170 dst_sel:DWORD dst_unused:UNUSED_PAD src0_sel:WORD_1 src1_sel:DWORD
	v_and_b32_sdwa v65, v52, v170 dst_sel:DWORD dst_unused:UNUSED_PAD src0_sel:WORD_1 src1_sel:DWORD
	v_and_b32_sdwa v66, v54, v170 dst_sel:DWORD dst_unused:UNUSED_PAD src0_sel:WORD_1 src1_sel:DWORD
	v_add3_u32 v53, v53, v67, s56
	v_add3_u32 v55, v55, v68, s56
	v_add3_u32 v54, v54, v66, s56
	v_add3_u32 v52, v52, v65, s56
	v_and_b32_e32 v53, 0xffff0000, v53
	v_and_b32_e32 v55, 0xffff0000, v55
	v_or_b32_sdwa v53, v53, v52 dst_sel:DWORD dst_unused:UNUSED_PAD src0_sel:DWORD src1_sel:WORD_1
	v_or_b32_sdwa v52, v55, v54 dst_sel:DWORD dst_unused:UNUSED_PAD src0_sel:DWORD src1_sel:WORD_1
	global_store_dwordx2 v[92:93], v[52:53], off offset:96
	s_and_saveexec_b64 s[24:25], s[36:37]
	s_cbranch_execz .LBB0_585
	s_waitcnt lgkmcnt(0)
	v_add_f32_e32 v50, v50, v51
	global_store_dword v[48:49], v50, off

.LBB0_596:
	s_add_i32 s29, s42, 2
	ds_read_b128 v[136:139], v111 offset:16384
	ds_read_b128 v[140:143], v111 offset:18432
	ds_read_b128 v[144:147], v111 offset:20480
	ds_read_b128 v[148:151], v111 offset:22528
	ds_read_b128 v[116:119], v110
	s_add_i32 s42, s42, 4
	ds_read_b128 v[120:123], v110 offset:2048
	s_min_u32 s42, s42, 63
	s_lshl_b32 s92, s42, 7
	ds_read_b128 v[124:127], v110 offset:4096
	ds_read_b128 v[194:197], v113 offset:16384
	ds_read_b128 v[198:201], v113 offset:18432
	ds_read_b128 v[202:205], v113 offset:20480
	ds_read_b128 v[206:209], v113 offset:22528
	v_lshl_add_u64 v[164:165], v[100:101], 0, s[92:93]
	ds_read_b128 v[132:135], v110 offset:6144
	ds_read_b128 v[152:155], v112
	ds_read_b128 v[156:159], v112 offset:2048
	ds_read_b128 v[160:163], v112 offset:4096
	ds_read_b128 v[190:193], v112 offset:6144
	s_waitcnt lgkmcnt(11)
	v_mfma_f32_16x16x32_bf16 v[92:95], v[136:139], v[116:119], v[92:95]
	v_mfma_f32_16x16x32_bf16 v[88:91], v[140:143], v[116:119], v[88:91]
	v_mfma_f32_16x16x32_bf16 v[56:59], v[144:147], v[116:119], v[56:59]
	v_mfma_f32_16x16x32_bf16 v[48:51], v[148:151], v[116:119], v[48:51]
	global_load_dwordx4 v[116:119], v[164:165], off
	s_waitcnt vmcnt(6)
	ds_write_b128 v109, v[52:55] offset:32768
	v_add_co_u32_e32 v52, vcc, s7, v164
	s_waitcnt lgkmcnt(11)
	v_mfma_f32_16x16x32_bf16 v[44:47], v[136:139], v[120:123], v[44:47]
	v_addc_co_u32_e32 v53, vcc, 0, v165, vcc
	v_mfma_f32_16x16x32_bf16 v[40:43], v[140:143], v[120:123], v[40:43]
	v_mfma_f32_16x16x32_bf16 v[36:39], v[144:147], v[120:123], v[36:39]
	v_mfma_f32_16x16x32_bf16 v[32:35], v[148:151], v[120:123], v[32:35]
	global_load_dwordx4 v[120:123], v[52:53], off
	v_add_co_u32_e32 v52, vcc, s52, v164
	ds_write_b128 v109, v[60:63] offset:36864
	s_nop 0
	v_addc_co_u32_e32 v53, vcc, 0, v165, vcc
	s_waitcnt lgkmcnt(11)
	v_mfma_f32_16x16x32_bf16 v[28:31], v[136:139], v[124:127], v[28:31]
	v_mfma_f32_16x16x32_bf16 v[24:27], v[140:143], v[124:127], v[24:27]
	v_mfma_f32_16x16x32_bf16 v[20:23], v[144:147], v[124:127], v[20:23]
	v_mfma_f32_16x16x32_bf16 v[16:19], v[148:151], v[124:127], v[16:19]
	global_load_dwordx4 v[124:127], v[52:53], off
	v_add_co_u32_e32 v52, vcc, s34, v164
	ds_write_b128 v109, v[64:67] offset:40960
	s_nop 0
	v_addc_co_u32_e32 v53, vcc, 0, v165, vcc
	v_lshl_add_u64 v[64:65], v[102:103], 0, s[92:93]
	v_add_co_u32_e32 v66, vcc, s7, v64
	s_waitcnt lgkmcnt(7)
	v_mfma_f32_16x16x32_bf16 v[12:15], v[136:139], v[132:135], v[12:15]
	v_addc_co_u32_e32 v67, vcc, 0, v65, vcc
	v_mfma_f32_16x16x32_bf16 v[8:11], v[140:143], v[132:135], v[8:11]
	v_mfma_f32_16x16x32_bf16 v[4:7], v[144:147], v[132:135], v[4:7]
	v_mfma_f32_16x16x32_bf16 v[0:3], v[148:151], v[132:135], v[0:3]
	global_load_dwordx4 v[132:135], v[52:53], off
	s_waitcnt vmcnt(7)
	ds_write_b128 v109, v[72:75] offset:45056
	s_waitcnt lgkmcnt(7)
	v_mfma_f32_16x16x32_bf16 v[52:55], v[194:197], v[152:155], v[92:95]
	v_mfma_f32_16x16x32_bf16 v[60:63], v[198:201], v[152:155], v[88:91]
	v_mfma_f32_16x16x32_bf16 v[56:59], v[202:205], v[152:155], v[56:59]
	v_mfma_f32_16x16x32_bf16 v[48:51], v[206:209], v[152:155], v[48:51]
	global_load_dwordx4 v[136:139], v[64:65], off
	ds_write_b128 v109, v[68:71] offset:49152
	s_waitcnt lgkmcnt(7)
	v_mfma_f32_16x16x32_bf16 v[44:47], v[194:197], v[156:159], v[44:47]
	v_mfma_f32_16x16x32_bf16 v[40:43], v[198:201], v[156:159], v[40:43]
	v_mfma_f32_16x16x32_bf16 v[36:39], v[202:205], v[156:159], v[36:39]
	v_mfma_f32_16x16x32_bf16 v[32:35], v[206:209], v[156:159], v[32:35]
	global_load_dwordx4 v[140:143], v[66:67], off
	v_add_co_u32_e32 v66, vcc, s52, v64
	s_waitcnt vmcnt(8)
	ds_write_b128 v109, v[76:79] offset:53248
	v_addc_co_u32_e32 v67, vcc, 0, v65, vcc
	v_add_co_u32_e32 v64, vcc, s34, v64
	s_waitcnt lgkmcnt(7)
	v_mfma_f32_16x16x32_bf16 v[28:31], v[194:197], v[160:163], v[28:31]
	v_addc_co_u32_e32 v65, vcc, 0, v65, vcc
	v_mfma_f32_16x16x32_bf16 v[24:27], v[198:201], v[160:163], v[24:27]
	v_mfma_f32_16x16x32_bf16 v[20:23], v[202:205], v[160:163], v[20:23]
	v_mfma_f32_16x16x32_bf16 v[16:19], v[206:209], v[160:163], v[16:19]
	global_load_dwordx4 v[144:147], v[66:67], off
	s_waitcnt vmcnt(8)
	ds_write_b128 v109, v[80:83] offset:57344
	s_waitcnt lgkmcnt(7)
	v_mfma_f32_16x16x32_bf16 v[12:15], v[194:197], v[190:193], v[12:15]
	v_mfma_f32_16x16x32_bf16 v[8:11], v[198:201], v[190:193], v[8:11]
	v_mfma_f32_16x16x32_bf16 v[4:7], v[202:205], v[190:193], v[4:7]
	v_mfma_f32_16x16x32_bf16 v[0:3], v[206:209], v[190:193], v[0:3]
	global_load_dwordx4 v[148:151], v[64:65], off
	s_waitcnt vmcnt(8)
	ds_write_b128 v109, v[84:87] offset:61440
	s_waitcnt lgkmcnt(0)
	s_barrier
	ds_read_b128 v[84:87], v111 offset:51200
	ds_read_b128 v[80:83], v111 offset:49152
	ds_read_b128 v[88:91], v111 offset:53248
	ds_read_b128 v[92:95], v111 offset:55296
	ds_read_b128 v[64:67], v110 offset:32768
	s_min_u32 s42, s29, 60
	s_lshl_b32 s92, s42, 7
	ds_read_b128 v[68:71], v110 offset:34816
	v_lshl_add_u64 v[164:165], v[100:101], 0, s[92:93]
	ds_read_b128 v[72:75], v110 offset:36864
	ds_read_b128 v[76:79], v110 offset:38912
	ds_read_b128 v[152:155], v112 offset:32768
	ds_read_b128 v[156:159], v112 offset:34816
	ds_read_b128 v[160:163], v112 offset:36864
	ds_read_b128 v[190:193], v112 offset:38912
	ds_read_b128 v[194:197], v113 offset:49152
	ds_read_b128 v[198:201], v113 offset:51200
	ds_read_b128 v[202:205], v113 offset:53248
	ds_read_b128 v[206:209], v113 offset:55296
	s_waitcnt lgkmcnt(11)
	v_mfma_f32_16x16x32_bf16 v[214:217], v[84:87], v[64:67], v[60:63]
	v_mfma_f32_16x16x32_bf16 v[210:213], v[80:83], v[64:67], v[52:55]
	s_nop 1
	v_add_co_u32_e32 v60, vcc, s7, v164
	s_nop 1
	v_addc_co_u32_e32 v61, vcc, 0, v165, vcc
	v_mfma_f32_16x16x32_bf16 v[56:59], v[88:91], v[64:67], v[56:59]
	v_mfma_f32_16x16x32_bf16 v[48:51], v[92:95], v[64:67], v[48:51]
	v_add_co_u32_e32 v64, vcc, s52, v164
	global_load_dwordx4 v[52:55], v[164:165], off offset:384
	s_nop 0
	v_addc_co_u32_e32 v65, vcc, 0, v165, vcc
	s_waitcnt vmcnt(8)
	ds_write_b128 v109, v[116:119]
	s_waitcnt lgkmcnt(11)
	v_mfma_f32_16x16x32_bf16 v[44:47], v[80:83], v[68:71], v[44:47]
	v_mfma_f32_16x16x32_bf16 v[40:43], v[84:87], v[68:71], v[40:43]
	v_mfma_f32_16x16x32_bf16 v[36:39], v[88:91], v[68:71], v[36:39]
	v_mfma_f32_16x16x32_bf16 v[32:35], v[92:95], v[68:71], v[32:35]
	v_add_co_u32_e32 v68, vcc, s34, v164
	global_load_dwordx4 v[60:63], v[60:61], off offset:384
	s_waitcnt vmcnt(8)
	ds_write_b128 v109, v[120:123] offset:4096
	s_waitcnt lgkmcnt(11)
	v_mfma_f32_16x16x32_bf16 v[28:31], v[80:83], v[72:75], v[28:31]
	v_addc_co_u32_e32 v69, vcc, 0, v165, vcc
	v_mfma_f32_16x16x32_bf16 v[24:27], v[84:87], v[72:75], v[24:27]
	v_mfma_f32_16x16x32_bf16 v[20:23], v[88:91], v[72:75], v[20:23]
	v_mfma_f32_16x16x32_bf16 v[16:19], v[92:95], v[72:75], v[16:19]
	global_load_dwordx4 v[64:67], v[64:65], off offset:384
	s_waitcnt vmcnt(8)
	ds_write_b128 v109, v[124:127] offset:8192
	s_waitcnt lgkmcnt(11)
	v_mfma_f32_16x16x32_bf16 v[8:11], v[84:87], v[76:79], v[8:11]
	v_lshl_add_u64 v[84:85], v[102:103], 0, s[92:93]
	v_mfma_f32_16x16x32_bf16 v[12:15], v[80:83], v[76:79], v[12:15]
	v_mfma_f32_16x16x32_bf16 v[4:7], v[88:91], v[76:79], v[4:7]
	v_mfma_f32_16x16x32_bf16 v[0:3], v[92:95], v[76:79], v[0:3]
	v_add_co_u32_e32 v76, vcc, s7, v84
	global_load_dwordx4 v[72:75], v[68:69], off offset:384
	s_nop 0
	v_addc_co_u32_e32 v77, vcc, 0, v85, vcc
	v_add_co_u32_e32 v80, vcc, s52, v84
	s_waitcnt vmcnt(8)
	ds_write_b128 v109, v[132:135] offset:12288
	v_addc_co_u32_e32 v81, vcc, 0, v85, vcc
	s_waitcnt lgkmcnt(7)
	v_mfma_f32_16x16x32_bf16 v[92:95], v[194:197], v[152:155], v[210:213]
	s_waitcnt lgkmcnt(6)
	v_mfma_f32_16x16x32_bf16 v[88:91], v[198:201], v[152:155], v[214:217]
	s_waitcnt lgkmcnt(5)
	v_mfma_f32_16x16x32_bf16 v[56:59], v[202:205], v[152:155], v[56:59]
	s_waitcnt lgkmcnt(4)
	v_mfma_f32_16x16x32_bf16 v[48:51], v[206:209], v[152:155], v[48:51]
	global_load_dwordx4 v[68:71], v[84:85], off offset:384
	v_add_co_u32_e32 v84, vcc, s34, v84
	s_waitcnt vmcnt(8)
	ds_write_b128 v109, v[136:139] offset:16384
	v_addc_co_u32_e32 v85, vcc, 0, v85, vcc
	v_mfma_f32_16x16x32_bf16 v[44:47], v[194:197], v[156:159], v[44:47]
	v_mfma_f32_16x16x32_bf16 v[40:43], v[198:201], v[156:159], v[40:43]
	v_mfma_f32_16x16x32_bf16 v[36:39], v[202:205], v[156:159], v[36:39]
	v_mfma_f32_16x16x32_bf16 v[32:35], v[206:209], v[156:159], v[32:35]
	global_load_dwordx4 v[76:79], v[76:77], off offset:384
	s_waitcnt vmcnt(8)
	ds_write_b128 v109, v[140:143] offset:20480
	v_mfma_f32_16x16x32_bf16 v[28:31], v[194:197], v[160:163], v[28:31]
	v_mfma_f32_16x16x32_bf16 v[24:27], v[198:201], v[160:163], v[24:27]
	v_mfma_f32_16x16x32_bf16 v[20:23], v[202:205], v[160:163], v[20:23]
	v_mfma_f32_16x16x32_bf16 v[16:19], v[206:209], v[160:163], v[16:19]
	global_load_dwordx4 v[80:83], v[80:81], off offset:384
	s_waitcnt vmcnt(8)
	ds_write_b128 v109, v[144:147] offset:24576
	v_mfma_f32_16x16x32_bf16 v[12:15], v[194:197], v[190:193], v[12:15]
	v_mfma_f32_16x16x32_bf16 v[8:11], v[198:201], v[190:193], v[8:11]
	v_mfma_f32_16x16x32_bf16 v[4:7], v[202:205], v[190:193], v[4:7]
	v_mfma_f32_16x16x32_bf16 v[0:3], v[206:209], v[190:193], v[0:3]
	global_load_dwordx4 v[84:87], v[84:85], off offset:384
	s_waitcnt vmcnt(8)
	ds_write_b128 v109, v[148:151] offset:28672
	s_cmp_lt_u32 s29, 60
	s_mov_b32 s42, s29
	s_waitcnt lgkmcnt(0)
	s_barrier
	s_cbranch_scc1 .LBB0_596
.Ltail596:
	s_add_i32 s29, s42, 2
	ds_read_b128 v[136:139], v111 offset:16384
	ds_read_b128 v[140:143], v111 offset:18432
	ds_read_b128 v[144:147], v111 offset:20480
	ds_read_b128 v[148:151], v111 offset:22528
	ds_read_b128 v[116:119], v110
	s_add_i32 s42, s42, 4
	ds_read_b128 v[120:123], v110 offset:2048
	s_min_u32 s42, s42, 63
	s_lshl_b32 s92, s42, 7
	ds_read_b128 v[124:127], v110 offset:4096
	ds_read_b128 v[194:197], v113 offset:16384
	ds_read_b128 v[198:201], v113 offset:18432
	ds_read_b128 v[202:205], v113 offset:20480
	ds_read_b128 v[206:209], v113 offset:22528
	v_lshl_add_u64 v[164:165], v[100:101], 0, s[92:93]
	ds_read_b128 v[132:135], v110 offset:6144
	ds_read_b128 v[152:155], v112
	ds_read_b128 v[156:159], v112 offset:2048
	ds_read_b128 v[160:163], v112 offset:4096
	ds_read_b128 v[190:193], v112 offset:6144
	s_waitcnt lgkmcnt(11)
	v_mfma_f32_16x16x32_bf16 v[92:95], v[136:139], v[116:119], v[92:95]
	v_mfma_f32_16x16x32_bf16 v[88:91], v[140:143], v[116:119], v[88:91]
	v_mfma_f32_16x16x32_bf16 v[56:59], v[144:147], v[116:119], v[56:59]
	v_mfma_f32_16x16x32_bf16 v[48:51], v[148:151], v[116:119], v[48:51]
	s_waitcnt vmcnt(7)
	ds_write_b128 v109, v[52:55] offset:32768
	v_add_co_u32_e32 v52, vcc, s7, v164
	s_waitcnt lgkmcnt(11)
	v_mfma_f32_16x16x32_bf16 v[44:47], v[136:139], v[120:123], v[44:47]
	v_addc_co_u32_e32 v53, vcc, 0, v165, vcc
	v_mfma_f32_16x16x32_bf16 v[40:43], v[140:143], v[120:123], v[40:43]
	v_mfma_f32_16x16x32_bf16 v[36:39], v[144:147], v[120:123], v[36:39]
	v_mfma_f32_16x16x32_bf16 v[32:35], v[148:151], v[120:123], v[32:35]
	v_add_co_u32_e32 v52, vcc, s52, v164
	s_waitcnt vmcnt(6)
	ds_write_b128 v109, v[60:63] offset:36864
	s_nop 0
	v_addc_co_u32_e32 v53, vcc, 0, v165, vcc
	s_waitcnt lgkmcnt(11)
	v_mfma_f32_16x16x32_bf16 v[28:31], v[136:139], v[124:127], v[28:31]
	v_mfma_f32_16x16x32_bf16 v[24:27], v[140:143], v[124:127], v[24:27]
	v_mfma_f32_16x16x32_bf16 v[20:23], v[144:147], v[124:127], v[20:23]
	v_mfma_f32_16x16x32_bf16 v[16:19], v[148:151], v[124:127], v[16:19]
	v_add_co_u32_e32 v52, vcc, s34, v164
	s_waitcnt vmcnt(5)
	ds_write_b128 v109, v[64:67] offset:40960
	s_nop 0
	v_addc_co_u32_e32 v53, vcc, 0, v165, vcc
	v_lshl_add_u64 v[64:65], v[102:103], 0, s[92:93]
	v_add_co_u32_e32 v66, vcc, s7, v64
	s_waitcnt lgkmcnt(7)
	v_mfma_f32_16x16x32_bf16 v[12:15], v[136:139], v[132:135], v[12:15]
	v_addc_co_u32_e32 v67, vcc, 0, v65, vcc
	v_mfma_f32_16x16x32_bf16 v[8:11], v[140:143], v[132:135], v[8:11]
	v_mfma_f32_16x16x32_bf16 v[4:7], v[144:147], v[132:135], v[4:7]
	v_mfma_f32_16x16x32_bf16 v[0:3], v[148:151], v[132:135], v[0:3]
	s_waitcnt vmcnt(4)
	ds_write_b128 v109, v[72:75] offset:45056
	s_waitcnt lgkmcnt(7)
	v_mfma_f32_16x16x32_bf16 v[52:55], v[194:197], v[152:155], v[92:95]
	v_mfma_f32_16x16x32_bf16 v[60:63], v[198:201], v[152:155], v[88:91]
	v_mfma_f32_16x16x32_bf16 v[56:59], v[202:205], v[152:155], v[56:59]
	v_mfma_f32_16x16x32_bf16 v[48:51], v[206:209], v[152:155], v[48:51]
	s_waitcnt vmcnt(3)
	ds_write_b128 v109, v[68:71] offset:49152
	s_waitcnt lgkmcnt(7)
	v_mfma_f32_16x16x32_bf16 v[44:47], v[194:197], v[156:159], v[44:47]
	v_mfma_f32_16x16x32_bf16 v[40:43], v[198:201], v[156:159], v[40:43]
	v_mfma_f32_16x16x32_bf16 v[36:39], v[202:205], v[156:159], v[36:39]
	v_mfma_f32_16x16x32_bf16 v[32:35], v[206:209], v[156:159], v[32:35]
	v_add_co_u32_e32 v66, vcc, s52, v64
	s_waitcnt vmcnt(2)
	ds_write_b128 v109, v[76:79] offset:53248
	v_addc_co_u32_e32 v67, vcc, 0, v65, vcc
	v_add_co_u32_e32 v64, vcc, s34, v64
	s_waitcnt lgkmcnt(7)
	v_mfma_f32_16x16x32_bf16 v[28:31], v[194:197], v[160:163], v[28:31]
	v_addc_co_u32_e32 v65, vcc, 0, v65, vcc
	v_mfma_f32_16x16x32_bf16 v[24:27], v[198:201], v[160:163], v[24:27]
	v_mfma_f32_16x16x32_bf16 v[20:23], v[202:205], v[160:163], v[20:23]
	v_mfma_f32_16x16x32_bf16 v[16:19], v[206:209], v[160:163], v[16:19]
	s_waitcnt vmcnt(1)
	ds_write_b128 v109, v[80:83] offset:57344
	s_waitcnt lgkmcnt(7)
	v_mfma_f32_16x16x32_bf16 v[12:15], v[194:197], v[190:193], v[12:15]
	v_mfma_f32_16x16x32_bf16 v[8:11], v[198:201], v[190:193], v[8:11]
	v_mfma_f32_16x16x32_bf16 v[4:7], v[202:205], v[190:193], v[4:7]
	v_mfma_f32_16x16x32_bf16 v[0:3], v[206:209], v[190:193], v[0:3]
	s_waitcnt vmcnt(0)
	ds_write_b128 v109, v[84:87] offset:61440
	s_waitcnt lgkmcnt(0)
	s_barrier
	ds_read_b128 v[84:87], v111 offset:51200
	ds_read_b128 v[80:83], v111 offset:49152
	ds_read_b128 v[88:91], v111 offset:53248
	ds_read_b128 v[92:95], v111 offset:55296
	ds_read_b128 v[64:67], v110 offset:32768
	s_min_u32 s42, s29, 60
	s_lshl_b32 s92, s42, 7
	ds_read_b128 v[68:71], v110 offset:34816
	v_lshl_add_u64 v[164:165], v[100:101], 0, s[92:93]
	ds_read_b128 v[72:75], v110 offset:36864
	ds_read_b128 v[76:79], v110 offset:38912
	ds_read_b128 v[152:155], v112 offset:32768
	ds_read_b128 v[156:159], v112 offset:34816
	ds_read_b128 v[160:163], v112 offset:36864
	ds_read_b128 v[190:193], v112 offset:38912
	ds_read_b128 v[194:197], v113 offset:49152
	ds_read_b128 v[198:201], v113 offset:51200
	ds_read_b128 v[202:205], v113 offset:53248
	ds_read_b128 v[206:209], v113 offset:55296
	s_waitcnt lgkmcnt(11)
	v_mfma_f32_16x16x32_bf16 v[214:217], v[84:87], v[64:67], v[60:63]
	v_mfma_f32_16x16x32_bf16 v[210:213], v[80:83], v[64:67], v[52:55]
	s_nop 1
	v_add_co_u32_e32 v60, vcc, s7, v164
	s_nop 1
	v_addc_co_u32_e32 v61, vcc, 0, v165, vcc
	v_mfma_f32_16x16x32_bf16 v[56:59], v[88:91], v[64:67], v[56:59]
	v_mfma_f32_16x16x32_bf16 v[48:51], v[92:95], v[64:67], v[48:51]
	v_add_co_u32_e32 v64, vcc, s52, v164
	s_nop 0
	v_addc_co_u32_e32 v65, vcc, 0, v165, vcc
	s_waitcnt lgkmcnt(10)
	v_mfma_f32_16x16x32_bf16 v[44:47], v[80:83], v[68:71], v[44:47]
	v_mfma_f32_16x16x32_bf16 v[40:43], v[84:87], v[68:71], v[40:43]
	v_mfma_f32_16x16x32_bf16 v[36:39], v[88:91], v[68:71], v[36:39]
	v_mfma_f32_16x16x32_bf16 v[32:35], v[92:95], v[68:71], v[32:35]
	v_add_co_u32_e32 v68, vcc, s34, v164
	s_waitcnt lgkmcnt(9)
	v_mfma_f32_16x16x32_bf16 v[28:31], v[80:83], v[72:75], v[28:31]
	v_addc_co_u32_e32 v69, vcc, 0, v165, vcc
	v_mfma_f32_16x16x32_bf16 v[24:27], v[84:87], v[72:75], v[24:27]
	v_mfma_f32_16x16x32_bf16 v[20:23], v[88:91], v[72:75], v[20:23]
	v_mfma_f32_16x16x32_bf16 v[16:19], v[92:95], v[72:75], v[16:19]
	s_waitcnt lgkmcnt(8)
	v_mfma_f32_16x16x32_bf16 v[8:11], v[84:87], v[76:79], v[8:11]
	v_lshl_add_u64 v[84:85], v[102:103], 0, s[92:93]
	v_mfma_f32_16x16x32_bf16 v[12:15], v[80:83], v[76:79], v[12:15]
	v_mfma_f32_16x16x32_bf16 v[4:7], v[88:91], v[76:79], v[4:7]
	v_mfma_f32_16x16x32_bf16 v[0:3], v[92:95], v[76:79], v[0:3]
	v_add_co_u32_e32 v76, vcc, s7, v84
	s_nop 0
	v_addc_co_u32_e32 v77, vcc, 0, v85, vcc
	v_add_co_u32_e32 v80, vcc, s52, v84
	v_addc_co_u32_e32 v81, vcc, 0, v85, vcc
	s_waitcnt lgkmcnt(3)
	v_mfma_f32_16x16x32_bf16 v[92:95], v[194:197], v[152:155], v[210:213]
	s_waitcnt lgkmcnt(2)
	v_mfma_f32_16x16x32_bf16 v[88:91], v[198:201], v[152:155], v[214:217]
	s_waitcnt lgkmcnt(1)
	v_mfma_f32_16x16x32_bf16 v[56:59], v[202:205], v[152:155], v[56:59]
	s_waitcnt lgkmcnt(0)
	v_mfma_f32_16x16x32_bf16 v[48:51], v[206:209], v[152:155], v[48:51]
	v_add_co_u32_e32 v84, vcc, s34, v84
	v_addc_co_u32_e32 v85, vcc, 0, v85, vcc
	v_mfma_f32_16x16x32_bf16 v[44:47], v[194:197], v[156:159], v[44:47]
	v_mfma_f32_16x16x32_bf16 v[40:43], v[198:201], v[156:159], v[40:43]
	v_mfma_f32_16x16x32_bf16 v[36:39], v[202:205], v[156:159], v[36:39]
	v_mfma_f32_16x16x32_bf16 v[32:35], v[206:209], v[156:159], v[32:35]
	v_mfma_f32_16x16x32_bf16 v[28:31], v[194:197], v[160:163], v[28:31]
	v_mfma_f32_16x16x32_bf16 v[24:27], v[198:201], v[160:163], v[24:27]
	v_mfma_f32_16x16x32_bf16 v[20:23], v[202:205], v[160:163], v[20:23]
	v_mfma_f32_16x16x32_bf16 v[16:19], v[206:209], v[160:163], v[16:19]
	v_mfma_f32_16x16x32_bf16 v[12:15], v[194:197], v[190:193], v[12:15]
	v_mfma_f32_16x16x32_bf16 v[8:11], v[198:201], v[190:193], v[8:11]
	v_mfma_f32_16x16x32_bf16 v[4:7], v[202:205], v[190:193], v[4:7]
	v_mfma_f32_16x16x32_bf16 v[0:3], v[206:209], v[190:193], v[0:3]
	s_mov_b32 s42, s29
	s_waitcnt lgkmcnt(0)
	s_barrier
	s_waitcnt vmcnt(5)
	v_add_u32_e32 v64, s24, v108
	v_add_u32_e32 v52, 0xffffe000, v64
	v_or_b32_e32 v62, v64, v107
	v_lshrrev_b32_e32 v52, 10, v52
	s_movk_i32 s16, 0x1800
	v_mad_u32_u24 v52, v52, s16, s16
	v_cmp_lt_i32_e32 vcc, s13, v62
	v_or_b32_e32 v65, s25, v114
	v_or_b32_e32 v54, v65, v115
	v_cndmask_b32_e32 v52, 0, v52, vcc
	v_ashrrev_i32_e32 v53, 31, v52
	s_waitcnt vmcnt(4)
	v_lshlrev_b64 v[74:75], 2, v[52:53]
	v_ashrrev_i32_e32 v55, 31, v54
	v_ashrrev_i32_e32 v63, 31, v62
	v_lshl_add_u64 v[52:53], s[38:39], 0, v[74:75]
	v_lshlrev_b64 v[60:61], 2, v[54:55]
	v_readlane_b32 s16, v250, 15
	s_waitcnt vmcnt(1)
	v_lshl_add_u64 v[82:83], v[52:53], 0, v[60:61]
	v_lshlrev_b64 v[52:53], 12, v[62:63]
	v_readlane_b32 s17, v250, 16
	v_lshl_add_u64 v[74:75], s[40:41], 0, v[74:75]
	s_waitcnt vmcnt(0)
	v_lshl_add_u64 v[86:87], v[74:75], 0, v[60:61]
	v_lshl_add_u64 v[52:53], s[16:17], 0, v[52:53]
	v_lshl_add_u64 v[84:85], v[52:53], 0, v[60:61]
	global_load_dwordx4 v[66:69], v[82:83], off
	global_load_dwordx4 v[70:73], v[84:85], off
	v_lshl_add_u64 v[52:53], s[0:1], 0, v[60:61]
	v_readlane_b32 s16, v250, 21
	v_lshlrev_b64 v[78:79], 11, v[62:63]
	v_readlane_b32 s17, v250, 22
	s_waitcnt vmcnt(0)
	v_pk_fma_f32 v[68:69], v[94:95], v[68:69], v[72:73]
	v_pk_fma_f32 v[66:67], v[92:93], v[66:67], v[70:71]
	global_store_dwordx4 v[84:85], v[66:69], off
	global_load_dwordx4 v[70:73], v[52:53], off
	global_load_dwordx4 v[74:77], v[86:87], off
	v_lshl_add_u64 v[78:79], s[16:17], 0, v[78:79]
	v_lshl_add_u64 v[92:93], v[54:55], 1, v[78:79]
	s_mov_b32 s16, 0xa000
	s_waitcnt vmcnt(1)
	v_pk_mul_f32 v[72:73], v[68:69], v[72:73]
	v_pk_mul_f32 v[70:71], v[66:67], v[70:71]
	s_waitcnt vmcnt(0)
	v_pk_add_f32 v[76:77], v[76:77], 1.0 op_sel_hi:[1,0]
	v_pk_add_f32 v[74:75], v[74:75], 1.0 op_sel_hi:[1,0]
	v_pk_mul_f32 v[72:73], v[72:73], v[76:77]
	v_pk_mul_f32 v[70:71], v[70:71], v[74:75]
	v_and_b32_sdwa v76, v73, v170 dst_sel:DWORD dst_unused:UNUSED_PAD src0_sel:WORD_1 src1_sel:DWORD
	v_and_b32_sdwa v77, v71, v170 dst_sel:DWORD dst_unused:UNUSED_PAD src0_sel:WORD_1 src1_sel:DWORD
	v_and_b32_sdwa v74, v72, v170 dst_sel:DWORD dst_unused:UNUSED_PAD src0_sel:WORD_1 src1_sel:DWORD
	v_and_b32_sdwa v75, v70, v170 dst_sel:DWORD dst_unused:UNUSED_PAD src0_sel:WORD_1 src1_sel:DWORD
	v_add3_u32 v73, v73, v76, s56
	v_add3_u32 v71, v71, v77, s56
	v_add3_u32 v70, v70, v75, s56
	v_add3_u32 v72, v72, v74, s56
	v_and_b32_e32 v73, 0xffff0000, v73
	v_and_b32_e32 v74, 0xffff0000, v71
	v_or_b32_sdwa v71, v73, v72 dst_sel:DWORD dst_unused:UNUSED_PAD src0_sel:DWORD src1_sel:WORD_1
	v_or_b32_sdwa v70, v74, v70 dst_sel:DWORD dst_unused:UNUSED_PAD src0_sel:DWORD src1_sel:WORD_1
	global_store_dwordx2 v[92:93], v[70:71], off
	global_load_dwordx4 v[70:73], v[82:83], off offset:64
	s_nop 0
	global_load_dwordx4 v[74:77], v[84:85], off offset:64
	s_waitcnt vmcnt(0)
	v_pk_fma_f32 v[72:73], v[90:91], v[72:73], v[76:77]
	v_pk_fma_f32 v[70:71], v[88:89], v[70:71], v[74:75]
	global_store_dwordx4 v[84:85], v[70:73], off offset:64
	global_load_dwordx4 v[74:77], v[52:53], off offset:64
	global_load_dwordx4 v[78:81], v[86:87], off offset:64
	s_waitcnt vmcnt(1)
	v_pk_mul_f32 v[76:77], v[72:73], v[76:77]
	v_pk_mul_f32 v[74:75], v[70:71], v[74:75]
	s_waitcnt vmcnt(0)
	v_pk_add_f32 v[80:81], v[80:81], 1.0 op_sel_hi:[1,0]
	v_pk_add_f32 v[78:79], v[78:79], 1.0 op_sel_hi:[1,0]
	v_pk_mul_f32 v[76:77], v[76:77], v[80:81]
	v_pk_mul_f32 v[74:75], v[74:75], v[78:79]
	v_and_b32_sdwa v80, v77, v170 dst_sel:DWORD dst_unused:UNUSED_PAD src0_sel:WORD_1 src1_sel:DWORD
	v_and_b32_sdwa v81, v75, v170 dst_sel:DWORD dst_unused:UNUSED_PAD src0_sel:WORD_1 src1_sel:DWORD
	v_and_b32_sdwa v78, v76, v170 dst_sel:DWORD dst_unused:UNUSED_PAD src0_sel:WORD_1 src1_sel:DWORD
	v_and_b32_sdwa v79, v74, v170 dst_sel:DWORD dst_unused:UNUSED_PAD src0_sel:WORD_1 src1_sel:DWORD
	v_add3_u32 v77, v77, v80, s56
	v_add3_u32 v75, v75, v81, s56
	v_add3_u32 v74, v74, v79, s56
	v_add3_u32 v76, v76, v78, s56
	v_and_b32_e32 v77, 0xffff0000, v77
	v_and_b32_e32 v78, 0xffff0000, v75
	v_or_b32_sdwa v75, v77, v76 dst_sel:DWORD dst_unused:UNUSED_PAD src0_sel:DWORD src1_sel:WORD_1
	v_or_b32_sdwa v74, v78, v74 dst_sel:DWORD dst_unused:UNUSED_PAD src0_sel:DWORD src1_sel:WORD_1
	global_store_dwordx2 v[92:93], v[74:75], off offset:32
	global_load_dwordx4 v[74:77], v[82:83], off offset:128
	s_nop 0
	global_load_dwordx4 v[78:81], v[84:85], off offset:128
	s_waitcnt vmcnt(0)
	v_pk_fma_f32 v[58:59], v[58:59], v[76:77], v[80:81]
	v_pk_fma_f32 v[56:57], v[56:57], v[74:75], v[78:79]
	global_store_dwordx4 v[84:85], v[56:59], off offset:128
	global_load_dwordx4 v[74:77], v[52:53], off offset:128
	global_load_dwordx4 v[78:81], v[86:87], off offset:128
	s_waitcnt vmcnt(1)
	v_pk_mul_f32 v[76:77], v[58:59], v[76:77]
	v_pk_mul_f32 v[74:75], v[56:57], v[74:75]
	s_waitcnt vmcnt(0)
	v_pk_add_f32 v[80:81], v[80:81], 1.0 op_sel_hi:[1,0]
	v_pk_add_f32 v[78:79], v[78:79], 1.0 op_sel_hi:[1,0]
	v_pk_mul_f32 v[76:77], v[76:77], v[80:81]
	v_pk_mul_f32 v[74:75], v[74:75], v[78:79]
	v_and_b32_sdwa v80, v77, v170 dst_sel:DWORD dst_unused:UNUSED_PAD src0_sel:WORD_1 src1_sel:DWORD
	v_and_b32_sdwa v81, v75, v170 dst_sel:DWORD dst_unused:UNUSED_PAD src0_sel:WORD_1 src1_sel:DWORD
	v_and_b32_sdwa v78, v76, v170 dst_sel:DWORD dst_unused:UNUSED_PAD src0_sel:WORD_1 src1_sel:DWORD
	v_and_b32_sdwa v79, v74, v170 dst_sel:DWORD dst_unused:UNUSED_PAD src0_sel:WORD_1 src1_sel:DWORD
	v_add3_u32 v77, v77, v80, s56
	v_add3_u32 v75, v75, v81, s56
	v_add3_u32 v74, v74, v79, s56
	v_add3_u32 v76, v76, v78, s56
	v_and_b32_e32 v77, 0xffff0000, v77
	v_and_b32_e32 v78, 0xffff0000, v75
	v_or_b32_sdwa v75, v77, v76 dst_sel:DWORD dst_unused:UNUSED_PAD src0_sel:DWORD src1_sel:WORD_1
	v_or_b32_sdwa v74, v78, v74 dst_sel:DWORD dst_unused:UNUSED_PAD src0_sel:DWORD src1_sel:WORD_1
	global_store_dwordx2 v[92:93], v[74:75], off offset:64
	global_load_dwordx4 v[74:77], v[82:83], off offset:192
	s_nop 0
	global_load_dwordx4 v[78:81], v[84:85], off offset:192
	s_waitcnt vmcnt(0)
	v_pk_fma_f32 v[76:77], v[50:51], v[76:77], v[80:81]
	v_pk_fma_f32 v[74:75], v[48:49], v[74:75], v[78:79]
	global_store_dwordx4 v[84:85], v[74:77], off offset:192
	global_load_dwordx4 v[78:81], v[52:53], off offset:192
	s_nop 0
	global_load_dwordx4 v[82:85], v[86:87], off offset:192
	v_mul_f32_e32 v48, v67, v67
	v_mul_f32_e32 v49, v71, v71
	v_fmac_f32_e32 v48, v66, v66
	v_fmac_f32_e32 v49, v70, v70
	v_fmac_f32_e32 v48, v68, v68
	v_fmac_f32_e32 v49, v72, v72
	v_fmac_f32_e32 v48, v69, v69
	v_fmac_f32_e32 v49, v73, v73
	v_add_f32_e32 v48, v48, v49
	v_mul_f32_e32 v49, v57, v57
	v_fmac_f32_e32 v49, v56, v56
	v_fmac_f32_e32 v49, v58, v58
	v_fmac_f32_e32 v49, v59, v59
	v_add_f32_e32 v48, v48, v49
	v_mul_f32_e32 v49, v75, v75
	v_fmac_f32_e32 v49, v74, v74
	v_fmac_f32_e32 v49, v76, v76
	v_fmac_f32_e32 v49, v77, v77
	v_add_f32_e32 v50, v48, v49
	ds_bpermute_b32 v51, v105, v50
	v_lshrrev_b32_e32 v48, 6, v65
	v_mul_lo_u32 v48, v48, s16
	v_ashrrev_i32_e32 v49, 31, v48
	v_lshl_add_u64 v[48:49], s[26:27], 0, v[48:49]
	s_waitcnt lgkmcnt(0)
	v_add_f32_e32 v50, v50, v51
	ds_bpermute_b32 v51, v104, v50
	v_lshl_add_u64 v[48:49], v[62:63], 2, v[48:49]
	s_waitcnt vmcnt(1)
	v_pk_mul_f32 v[56:57], v[76:77], v[80:81]
	v_pk_mul_f32 v[58:59], v[74:75], v[78:79]
	s_waitcnt vmcnt(0)
	v_pk_add_f32 v[66:67], v[84:85], 1.0 op_sel_hi:[1,0]
	v_pk_add_f32 v[68:69], v[82:83], 1.0 op_sel_hi:[1,0]
	v_pk_mul_f32 v[56:57], v[56:57], v[66:67]
	v_pk_mul_f32 v[58:59], v[58:59], v[68:69]
	v_and_b32_sdwa v67, v57, v170 dst_sel:DWORD dst_unused:UNUSED_PAD src0_sel:WORD_1 src1_sel:DWORD
	v_and_b32_sdwa v68, v59, v170 dst_sel:DWORD dst_unused:UNUSED_PAD src0_sel:WORD_1 src1_sel:DWORD
	v_and_b32_sdwa v65, v56, v170 dst_sel:DWORD dst_unused:UNUSED_PAD src0_sel:WORD_1 src1_sel:DWORD
	v_and_b32_sdwa v66, v58, v170 dst_sel:DWORD dst_unused:UNUSED_PAD src0_sel:WORD_1 src1_sel:DWORD
	v_add3_u32 v57, v57, v67, s56
	v_add3_u32 v59, v59, v68, s56
	v_add3_u32 v58, v58, v66, s56
	v_add3_u32 v56, v56, v65, s56
	v_and_b32_e32 v57, 0xffff0000, v57
	v_and_b32_e32 v59, 0xffff0000, v59
	v_or_b32_sdwa v57, v57, v56 dst_sel:DWORD dst_unused:UNUSED_PAD src0_sel:DWORD src1_sel:WORD_1
	v_or_b32_sdwa v56, v59, v58 dst_sel:DWORD dst_unused:UNUSED_PAD src0_sel:DWORD src1_sel:WORD_1
	global_store_dwordx2 v[92:93], v[56:57], off offset:96
	s_and_saveexec_b64 s[24:25], s[36:37]
	s_cbranch_execz .LBB0_599
	s_waitcnt lgkmcnt(0)
	v_add_f32_e32 v50, v50, v51
	global_store_dword v[48:49], v50, off

.LBB0_609:
	s_add_i32 s2, s3, 2
	v_add_u32_e32 v127, v89, v90
	ds_read_b128 v[100:103], v127 offset:16384
	ds_read_b128 v[106:109], v127 offset:18432
	ds_read_b128 v[110:113], v127 offset:20480
	ds_read_b128 v[114:117], v127 offset:22528
	v_add_u32_e32 v126, v88, v90
	ds_read_b128 v[92:95], v126
	ds_read_b128 v[96:99], v126 offset:2048
	s_add_i32 s3, s3, 4
	s_min_u32 s3, s3, 63
	v_add_u32_e32 v128, v88, v91
	v_add_u32_e32 v130, v89, v91
	s_lshl_b32 s92, s3, 7
	ds_read_b128 v[118:121], v130 offset:18432
	ds_read_b128 v[122:125], v130 offset:20480
	ds_read_b128 v[132:135], v130 offset:22528
	s_waitcnt lgkmcnt(4)
	v_mfma_f32_16x16x32_bf16 v[76:79], v[100:103], v[92:95], v[76:79]
	v_lshl_add_u64 v[44:45], v[80:81], 0, s[92:93]
	v_add_co_u32_e32 v46, vcc, s7, v44
	v_mfma_f32_16x16x32_bf16 v[68:71], v[106:109], v[92:95], v[68:71]
	s_nop 0
	v_addc_co_u32_e32 v47, vcc, 0, v45, vcc
	v_mfma_f32_16x16x32_bf16 v[52:55], v[110:113], v[92:95], v[52:55]
	v_mfma_f32_16x16x32_bf16 v[40:43], v[114:117], v[92:95], v[40:43]
	s_waitcnt lgkmcnt(3)
	v_mfma_f32_16x16x32_bf16 v[92:95], v[100:103], v[96:99], v[36:39]
	s_nop 2
	ds_read_b128 v[36:39], v128
	v_mfma_f32_16x16x32_bf16 v[100:103], v[106:109], v[96:99], v[8:11]
	v_mfma_f32_16x16x32_bf16 v[106:109], v[110:113], v[96:99], v[4:7]
	ds_read_b128 v[110:113], v128 offset:2048
	v_mfma_f32_16x16x32_bf16 v[96:99], v[114:117], v[96:99], v[0:3]
	ds_read_b128 v[114:117], v130 offset:16384
	global_load_dwordx4 v[72:75], v[44:45], off
	s_waitcnt vmcnt(1)
	ds_write_b128 v87, v[12:15] offset:53248
	global_load_dwordx4 v[64:67], v[46:47], off
	v_add_co_u32_e32 v46, vcc, s52, v44
	ds_write_b128 v87, v[16:19] offset:49152
	s_nop 0
	v_addc_co_u32_e32 v47, vcc, 0, v45, vcc
	v_add_co_u32_e32 v44, vcc, s34, v44
	global_load_dwordx4 v[60:63], v[46:47], off
	s_nop 0
	v_addc_co_u32_e32 v45, vcc, 0, v45, vcc
	ds_write_b128 v87, v[20:23] offset:45056
	global_load_dwordx4 v[56:59], v[44:45], off
	v_lshl_add_u64 v[44:45], v[82:83], 0, s[92:93]
	ds_write_b128 v87, v[28:31] offset:32768
	s_waitcnt lgkmcnt(4)
	v_mfma_f32_16x16x32_bf16 v[0:3], v[114:117], v[36:39], v[76:79]
	v_mfma_f32_16x16x32_bf16 v[4:7], v[118:121], v[36:39], v[68:71]
	global_load_dwordx4 v[48:51], v[44:45], off
	v_add_co_u32_e32 v44, vcc, s7, v44
	ds_write_b128 v87, v[32:35] offset:36864
	s_nop 0
	v_addc_co_u32_e32 v45, vcc, 0, v45, vcc
	v_mfma_f32_16x16x32_bf16 v[8:11], v[122:125], v[36:39], v[52:55]
	v_mfma_f32_16x16x32_bf16 v[36:39], v[132:135], v[36:39], v[40:43]
	global_load_dwordx4 v[44:47], v[44:45], off
	ds_write_b128 v87, v[24:27] offset:40960
	v_mfma_f32_16x16x32_bf16 v[40:43], v[114:117], v[110:113], v[92:95]
	v_mfma_f32_16x16x32_bf16 v[52:55], v[118:121], v[110:113], v[100:103]
	v_mfma_f32_16x16x32_bf16 v[68:71], v[122:125], v[110:113], v[106:109]
	v_mfma_f32_16x16x32_bf16 v[76:79], v[132:135], v[110:113], v[96:99]
	s_waitcnt lgkmcnt(0)
	s_barrier
	ds_read_b128 v[100:103], v127 offset:49152
	ds_read_b128 v[106:109], v127 offset:51200
	ds_read_b128 v[110:113], v127 offset:53248
	ds_read_b128 v[114:117], v127 offset:55296
	ds_read_b128 v[92:95], v126 offset:32768
	ds_read_b128 v[96:99], v126 offset:34816
	s_min_u32 s3, s2, 60
	s_lshl_b32 s92, s3, 7
	ds_read_b128 v[118:121], v130 offset:51200
	ds_read_b128 v[122:125], v130 offset:53248
	ds_read_b128 v[132:135], v130 offset:55296
	s_waitcnt lgkmcnt(4)
	v_mfma_f32_16x16x32_bf16 v[0:3], v[100:103], v[92:95], v[0:3]
	v_lshl_add_u64 v[12:13], v[80:81], 0, s[92:93]
	v_add_co_u32_e32 v14, vcc, s7, v12
	v_mfma_f32_16x16x32_bf16 v[4:7], v[106:109], v[92:95], v[4:7]
	s_nop 0
	v_addc_co_u32_e32 v15, vcc, 0, v13, vcc
	v_mfma_f32_16x16x32_bf16 v[8:11], v[110:113], v[92:95], v[8:11]
	v_mfma_f32_16x16x32_bf16 v[36:39], v[114:117], v[92:95], v[36:39]
	s_waitcnt lgkmcnt(3)
	v_mfma_f32_16x16x32_bf16 v[92:95], v[100:103], v[96:99], v[40:43]
	s_nop 2
	ds_read_b128 v[40:43], v128 offset:32768
	v_mfma_f32_16x16x32_bf16 v[100:103], v[106:109], v[96:99], v[52:55]
	v_mfma_f32_16x16x32_bf16 v[106:109], v[110:113], v[96:99], v[68:71]
	ds_read_b128 v[110:113], v128 offset:34816
	v_mfma_f32_16x16x32_bf16 v[96:99], v[114:117], v[96:99], v[76:79]
	ds_read_b128 v[114:117], v130 offset:49152
	global_load_dwordx4 v[28:31], v[12:13], off offset:384
	s_waitcnt vmcnt(1)
	ds_write_b128 v87, v[44:47] offset:20480
	global_load_dwordx4 v[32:35], v[14:15], off offset:384
	v_add_co_u32_e32 v14, vcc, s52, v12
	ds_write_b128 v87, v[48:51] offset:16384
	s_nop 0
	v_addc_co_u32_e32 v15, vcc, 0, v13, vcc
	v_add_co_u32_e32 v12, vcc, s34, v12
	global_load_dwordx4 v[24:27], v[14:15], off offset:384
	s_nop 0
	v_addc_co_u32_e32 v13, vcc, 0, v13, vcc
	ds_write_b128 v87, v[56:59] offset:12288
	global_load_dwordx4 v[20:23], v[12:13], off offset:384
	v_lshl_add_u64 v[12:13], v[82:83], 0, s[92:93]
	ds_write_b128 v87, v[72:75]
	s_waitcnt lgkmcnt(4)
	v_mfma_f32_16x16x32_bf16 v[76:79], v[114:117], v[40:43], v[0:3]
	v_mfma_f32_16x16x32_bf16 v[68:71], v[118:121], v[40:43], v[4:7]
	global_load_dwordx4 v[16:19], v[12:13], off offset:384
	v_add_co_u32_e32 v12, vcc, s7, v12
	ds_write_b128 v87, v[64:67] offset:4096
	s_nop 0
	v_addc_co_u32_e32 v13, vcc, 0, v13, vcc
	v_mfma_f32_16x16x32_bf16 v[52:55], v[122:125], v[40:43], v[8:11]
	v_mfma_f32_16x16x32_bf16 v[40:43], v[132:135], v[40:43], v[36:39]
	global_load_dwordx4 v[12:15], v[12:13], off offset:384
	ds_write_b128 v87, v[60:63] offset:8192
	v_mfma_f32_16x16x32_bf16 v[36:39], v[114:117], v[110:113], v[92:95]
	v_mfma_f32_16x16x32_bf16 v[8:11], v[118:121], v[110:113], v[100:103]
	v_mfma_f32_16x16x32_bf16 v[4:7], v[122:125], v[110:113], v[106:109]
	v_mfma_f32_16x16x32_bf16 v[0:3], v[132:135], v[110:113], v[96:99]
	s_cmp_lt_u32 s2, 60
	s_mov_b32 s3, s2
	s_waitcnt lgkmcnt(0)
	s_barrier
	s_cbranch_scc1 .LBB0_609
.Ltail609:
	s_add_i32 s2, s3, 2
	v_add_u32_e32 v127, v89, v90
	ds_read_b128 v[100:103], v127 offset:16384
	ds_read_b128 v[106:109], v127 offset:18432
	ds_read_b128 v[110:113], v127 offset:20480
	ds_read_b128 v[114:117], v127 offset:22528
	v_add_u32_e32 v126, v88, v90
	ds_read_b128 v[92:95], v126
	ds_read_b128 v[96:99], v126 offset:2048
	s_add_i32 s3, s3, 4
	s_min_u32 s3, s3, 63
	v_add_u32_e32 v128, v88, v91
	v_add_u32_e32 v130, v89, v91
	s_lshl_b32 s92, s3, 7
	ds_read_b128 v[118:121], v130 offset:18432
	ds_read_b128 v[122:125], v130 offset:20480
	ds_read_b128 v[132:135], v130 offset:22528
	s_waitcnt lgkmcnt(4)
	v_mfma_f32_16x16x32_bf16 v[76:79], v[100:103], v[92:95], v[76:79]
	v_lshl_add_u64 v[44:45], v[80:81], 0, s[92:93]
	v_add_co_u32_e32 v46, vcc, s7, v44
	v_mfma_f32_16x16x32_bf16 v[68:71], v[106:109], v[92:95], v[68:71]
	s_nop 0
	v_addc_co_u32_e32 v47, vcc, 0, v45, vcc
	v_mfma_f32_16x16x32_bf16 v[52:55], v[110:113], v[92:95], v[52:55]
	v_mfma_f32_16x16x32_bf16 v[40:43], v[114:117], v[92:95], v[40:43]
	s_waitcnt lgkmcnt(3)
	v_mfma_f32_16x16x32_bf16 v[92:95], v[100:103], v[96:99], v[36:39]
	s_nop 2
	ds_read_b128 v[36:39], v128
	v_mfma_f32_16x16x32_bf16 v[100:103], v[106:109], v[96:99], v[8:11]
	v_mfma_f32_16x16x32_bf16 v[106:109], v[110:113], v[96:99], v[4:7]
	ds_read_b128 v[110:113], v128 offset:2048
	v_mfma_f32_16x16x32_bf16 v[96:99], v[114:117], v[96:99], v[0:3]
	ds_read_b128 v[114:117], v130 offset:16384
	s_waitcnt vmcnt(0)
	ds_write_b128 v87, v[12:15] offset:53248
	v_add_co_u32_e32 v46, vcc, s52, v44
	s_waitcnt vmcnt(1)
	ds_write_b128 v87, v[16:19] offset:49152
	s_nop 0
	v_addc_co_u32_e32 v47, vcc, 0, v45, vcc
	v_add_co_u32_e32 v44, vcc, s34, v44
	s_nop 0
	v_addc_co_u32_e32 v45, vcc, 0, v45, vcc
	s_waitcnt vmcnt(2)
	ds_write_b128 v87, v[20:23] offset:45056
	v_lshl_add_u64 v[44:45], v[82:83], 0, s[92:93]
	s_waitcnt vmcnt(5)
	ds_write_b128 v87, v[28:31] offset:32768
	s_waitcnt lgkmcnt(4)
	v_mfma_f32_16x16x32_bf16 v[0:3], v[114:117], v[36:39], v[76:79]
	v_mfma_f32_16x16x32_bf16 v[4:7], v[118:121], v[36:39], v[68:71]
	v_add_co_u32_e32 v44, vcc, s7, v44
	s_waitcnt vmcnt(4)
	ds_write_b128 v87, v[32:35] offset:36864
	s_nop 0
	v_addc_co_u32_e32 v45, vcc, 0, v45, vcc
	v_mfma_f32_16x16x32_bf16 v[8:11], v[122:125], v[36:39], v[52:55]
	v_mfma_f32_16x16x32_bf16 v[36:39], v[132:135], v[36:39], v[40:43]
	s_waitcnt vmcnt(3)
	ds_write_b128 v87, v[24:27] offset:40960
	v_mfma_f32_16x16x32_bf16 v[40:43], v[114:117], v[110:113], v[92:95]
	v_mfma_f32_16x16x32_bf16 v[52:55], v[118:121], v[110:113], v[100:103]
	v_mfma_f32_16x16x32_bf16 v[68:71], v[122:125], v[110:113], v[106:109]
	v_mfma_f32_16x16x32_bf16 v[76:79], v[132:135], v[110:113], v[96:99]
	s_waitcnt lgkmcnt(0)
	s_barrier
	ds_read_b128 v[100:103], v127 offset:49152
	ds_read_b128 v[106:109], v127 offset:51200
	ds_read_b128 v[110:113], v127 offset:53248
	ds_read_b128 v[114:117], v127 offset:55296
	ds_read_b128 v[92:95], v126 offset:32768
	ds_read_b128 v[96:99], v126 offset:34816
	s_min_u32 s3, s2, 60
	s_lshl_b32 s92, s3, 7
	ds_read_b128 v[118:121], v130 offset:51200
	ds_read_b128 v[122:125], v130 offset:53248
	ds_read_b128 v[132:135], v130 offset:55296
	s_waitcnt lgkmcnt(4)
	v_mfma_f32_16x16x32_bf16 v[0:3], v[100:103], v[92:95], v[0:3]
	v_lshl_add_u64 v[12:13], v[80:81], 0, s[92:93]
	v_add_co_u32_e32 v14, vcc, s7, v12
	v_mfma_f32_16x16x32_bf16 v[4:7], v[106:109], v[92:95], v[4:7]
	s_nop 0
	v_addc_co_u32_e32 v15, vcc, 0, v13, vcc
	v_mfma_f32_16x16x32_bf16 v[8:11], v[110:113], v[92:95], v[8:11]
	v_mfma_f32_16x16x32_bf16 v[36:39], v[114:117], v[92:95], v[36:39]
	s_waitcnt lgkmcnt(3)
	v_mfma_f32_16x16x32_bf16 v[92:95], v[100:103], v[96:99], v[40:43]
	s_nop 2
	ds_read_b128 v[40:43], v128 offset:32768
	v_mfma_f32_16x16x32_bf16 v[100:103], v[106:109], v[96:99], v[52:55]
	v_mfma_f32_16x16x32_bf16 v[106:109], v[110:113], v[96:99], v[68:71]
	ds_read_b128 v[110:113], v128 offset:34816
	v_mfma_f32_16x16x32_bf16 v[96:99], v[114:117], v[96:99], v[76:79]
	ds_read_b128 v[114:117], v130 offset:49152
	v_add_co_u32_e32 v14, vcc, s52, v12
	s_nop 0
	v_addc_co_u32_e32 v15, vcc, 0, v13, vcc
	v_add_co_u32_e32 v12, vcc, s34, v12
	s_nop 0
	v_addc_co_u32_e32 v13, vcc, 0, v13, vcc
	v_lshl_add_u64 v[12:13], v[82:83], 0, s[92:93]
	s_waitcnt lgkmcnt(0)
	v_mfma_f32_16x16x32_bf16 v[76:79], v[114:117], v[40:43], v[0:3]
	v_mfma_f32_16x16x32_bf16 v[68:71], v[118:121], v[40:43], v[4:7]
	v_add_co_u32_e32 v12, vcc, s7, v12
	s_nop 0
	v_addc_co_u32_e32 v13, vcc, 0, v13, vcc
	v_mfma_f32_16x16x32_bf16 v[52:55], v[122:125], v[40:43], v[8:11]
	v_mfma_f32_16x16x32_bf16 v[40:43], v[132:135], v[40:43], v[36:39]
	v_mfma_f32_16x16x32_bf16 v[36:39], v[114:117], v[110:113], v[92:95]
	v_mfma_f32_16x16x32_bf16 v[8:11], v[118:121], v[110:113], v[100:103]
	v_mfma_f32_16x16x32_bf16 v[4:7], v[122:125], v[110:113], v[106:109]
	v_mfma_f32_16x16x32_bf16 v[0:3], v[132:135], v[110:113], v[96:99]
	s_mov_b32 s3, s2
	s_waitcnt lgkmcnt(0)
	s_barrier
	v_readlane_b32 s2, v251, 18
	s_waitcnt vmcnt(1)
	s_nop 0
	v_add_u32_e32 v18, s2, v86
	v_readlane_b32 s2, v251, 19
	s_waitcnt vmcnt(0)
	v_add_u32_e32 v13, 0xffffe000, v18
	v_or_b32_e32 v12, v18, v85
	v_lshl_or_b32 v19, v84, 2, s2
	v_lshrrev_b32_e32 v13, 10, v13
	s_movk_i32 s2, 0x1800
	v_mad_u32_u24 v13, v13, s2, s2
	v_cmp_lt_i32_e32 vcc, s13, v12
	v_lshlrev_b32_e32 v128, 2, v19
	v_readlane_b32 s2, v250, 15
	v_cndmask_b32_e32 v14, 0, v13, vcc
	v_ashrrev_i32_e32 v15, 31, v14
	v_lshlrev_b64 v[24:25], 2, v[14:15]
	v_ashrrev_i32_e32 v13, 31, v12
	v_lshl_add_u64 v[14:15], s[38:39], 0, v[24:25]
	v_lshl_add_u64 v[48:49], v[14:15], 0, v[128:129]
	v_lshlrev_b64 v[14:15], 12, v[12:13]
	v_readlane_b32 s3, v250, 16
	v_lshl_add_u64 v[28:29], s[40:41], 0, v[24:25]
	v_lshlrev_b64 v[32:33], 11, v[12:13]
	v_lshl_add_u64 v[14:15], s[2:3], 0, v[14:15]
	v_lshl_add_u64 v[50:51], v[14:15], 0, v[128:129]
	global_load_dwordx4 v[72:75], v[48:49], off
	global_load_dwordx4 v[80:83], v[48:49], off offset:64
	global_load_dwordx4 v[88:91], v[48:49], off offset:128
	global_load_dwordx4 v[136:139], v[48:49], off offset:192
	global_load_dwordx4 v[194:197], v[50:51], off
	global_load_dwordx4 v[198:201], v[50:51], off offset:64
	global_load_dwordx4 v[202:205], v[50:51], off offset:128
	global_load_dwordx4 v[206:209], v[50:51], off offset:192
	v_add_co_u32_e32 v58, vcc, 0x10000, v50
	s_nop 1
	v_addc_co_u32_e32 v59, vcc, 0, v51, vcc
	global_load_dwordx4 v[210:213], v[58:59], off
	global_load_dwordx4 v[214:217], v[58:59], off offset:64
	global_load_dwordx4 v[218:221], v[58:59], off offset:128
	global_load_dwordx4 v[222:225], v[58:59], off offset:192
	v_readlane_b32 s2, v250, 21
	v_readlane_b32 s3, v250, 22
	v_cmp_eq_u32_e32 vcc, 0, v84
	s_waitcnt vmcnt(4)
	v_pk_fma_f32 v[22:23], v[78:79], v[74:75], v[196:197]
	v_pk_fma_f32 v[20:21], v[76:77], v[72:73], v[194:195]
	global_store_dwordx4 v[50:51], v[20:23], off
	v_lshl_add_u64 v[14:15], v[28:29], 0, v[128:129]
	global_load_dwordx4 v[140:143], v128, s[0:1]
	global_load_dwordx4 v[144:147], v128, s[0:1] offset:64
	global_load_dwordx4 v[148:151], v128, s[0:1] offset:128
	global_load_dwordx4 v[152:155], v128, s[0:1] offset:192
	global_load_dwordx4 v[156:159], v[14:15], off
	global_load_dwordx4 v[160:163], v[14:15], off offset:64
	global_load_dwordx4 v[180:183], v[14:15], off offset:128
	global_load_dwordx4 v[190:193], v[14:15], off offset:192
	v_lshlrev_b32_e32 v16, 1, v19
	v_mov_b32_e32 v17, v129
	v_lshl_add_u64 v[32:33], s[2:3], 0, v[32:33]
	v_lshl_add_u64 v[56:57], v[32:33], 0, v[16:17]
	s_waitcnt vmcnt(0)
	v_pk_mul_f32 v[26:27], v[22:23], v[142:143]
	v_pk_mul_f32 v[24:25], v[20:21], v[140:141]
	s_waitcnt vmcnt(0)
	v_pk_add_f32 v[30:31], v[158:159], 1.0 op_sel_hi:[1,0]
	v_pk_add_f32 v[28:29], v[156:157], 1.0 op_sel_hi:[1,0]
	v_pk_mul_f32 v[26:27], v[26:27], v[30:31]
	v_pk_mul_f32 v[24:25], v[24:25], v[28:29]
	v_and_b32_sdwa v19, v26, v170 dst_sel:DWORD dst_unused:UNUSED_PAD src0_sel:WORD_1 src1_sel:DWORD
	v_and_b32_sdwa v29, v27, v170 dst_sel:DWORD dst_unused:UNUSED_PAD src0_sel:WORD_1 src1_sel:DWORD
	v_and_b32_sdwa v30, v25, v170 dst_sel:DWORD dst_unused:UNUSED_PAD src0_sel:WORD_1 src1_sel:DWORD
	v_and_b32_sdwa v28, v24, v170 dst_sel:DWORD dst_unused:UNUSED_PAD src0_sel:WORD_1 src1_sel:DWORD
	v_add3_u32 v19, v26, v19, s56
	v_add3_u32 v26, v27, v29, s56
	v_add3_u32 v25, v25, v30, s56
	v_add3_u32 v24, v24, v28, s56
	v_and_b32_e32 v26, 0xffff0000, v26
	v_and_b32_e32 v27, 0xffff0000, v25
	v_or_b32_sdwa v25, v26, v19 dst_sel:DWORD dst_unused:UNUSED_PAD src0_sel:DWORD src1_sel:WORD_1
	v_or_b32_sdwa v24, v27, v24 dst_sel:DWORD dst_unused:UNUSED_PAD src0_sel:DWORD src1_sel:WORD_1
	global_store_dwordx2 v[56:57], v[24:25], off
	s_nop 0
	s_waitcnt vmcnt(0)
	v_pk_fma_f32 v[26:27], v[70:71], v[82:83], v[200:201]
	v_pk_fma_f32 v[24:25], v[68:69], v[80:81], v[198:199]
	global_store_dwordx4 v[50:51], v[24:27], off offset:64
	v_pk_mul_f32 v[30:31], v[26:27], v[146:147]
	v_pk_mul_f32 v[28:29], v[24:25], v[144:145]
	v_pk_add_f32 v[34:35], v[162:163], 1.0 op_sel_hi:[1,0]
	v_pk_add_f32 v[32:33], v[160:161], 1.0 op_sel_hi:[1,0]
	v_pk_mul_f32 v[30:31], v[30:31], v[34:35]
	v_pk_mul_f32 v[28:29], v[28:29], v[32:33]
	v_and_b32_sdwa v19, v30, v170 dst_sel:DWORD dst_unused:UNUSED_PAD src0_sel:WORD_1 src1_sel:DWORD
	v_and_b32_sdwa v33, v31, v170 dst_sel:DWORD dst_unused:UNUSED_PAD src0_sel:WORD_1 src1_sel:DWORD
	v_and_b32_sdwa v34, v29, v170 dst_sel:DWORD dst_unused:UNUSED_PAD src0_sel:WORD_1 src1_sel:DWORD
	v_and_b32_sdwa v32, v28, v170 dst_sel:DWORD dst_unused:UNUSED_PAD src0_sel:WORD_1 src1_sel:DWORD
	v_add3_u32 v19, v30, v19, s56
	v_add3_u32 v30, v31, v33, s56
	v_add3_u32 v29, v29, v34, s56
	v_add3_u32 v28, v28, v32, s56
	v_and_b32_e32 v30, 0xffff0000, v30
	v_and_b32_e32 v31, 0xffff0000, v29
	v_or_b32_sdwa v29, v30, v19 dst_sel:DWORD dst_unused:UNUSED_PAD src0_sel:DWORD src1_sel:WORD_1
	v_or_b32_sdwa v28, v31, v28 dst_sel:DWORD dst_unused:UNUSED_PAD src0_sel:DWORD src1_sel:WORD_1
	global_store_dwordx2 v[56:57], v[28:29], off offset:32
	s_nop 0
	v_pk_fma_f32 v[30:31], v[54:55], v[90:91], v[204:205]
	v_pk_fma_f32 v[28:29], v[52:53], v[88:89], v[202:203]
	global_store_dwordx4 v[50:51], v[28:31], off offset:128
	v_pk_mul_f32 v[34:35], v[30:31], v[150:151]
	v_pk_mul_f32 v[32:33], v[28:29], v[148:149]
	v_pk_add_f32 v[46:47], v[182:183], 1.0 op_sel_hi:[1,0]
	v_pk_add_f32 v[44:45], v[180:181], 1.0 op_sel_hi:[1,0]
	v_pk_mul_f32 v[34:35], v[34:35], v[46:47]
	v_pk_mul_f32 v[32:33], v[32:33], v[44:45]
	v_and_b32_sdwa v19, v34, v170 dst_sel:DWORD dst_unused:UNUSED_PAD src0_sel:WORD_1 src1_sel:DWORD
	v_and_b32_sdwa v45, v35, v170 dst_sel:DWORD dst_unused:UNUSED_PAD src0_sel:WORD_1 src1_sel:DWORD
	v_and_b32_sdwa v46, v33, v170 dst_sel:DWORD dst_unused:UNUSED_PAD src0_sel:WORD_1 src1_sel:DWORD
	v_and_b32_sdwa v44, v32, v170 dst_sel:DWORD dst_unused:UNUSED_PAD src0_sel:WORD_1 src1_sel:DWORD
	v_add3_u32 v19, v34, v19, s56
	v_add3_u32 v34, v35, v45, s56
	v_add3_u32 v33, v33, v46, s56
	v_add3_u32 v32, v32, v44, s56
	v_and_b32_e32 v34, 0xffff0000, v34
	v_and_b32_e32 v35, 0xffff0000, v33
	v_or_b32_sdwa v33, v34, v19 dst_sel:DWORD dst_unused:UNUSED_PAD src0_sel:DWORD src1_sel:WORD_1
	v_or_b32_sdwa v32, v35, v32 dst_sel:DWORD dst_unused:UNUSED_PAD src0_sel:DWORD src1_sel:WORD_1
	global_store_dwordx2 v[56:57], v[32:33], off offset:64
	s_nop 0
	v_pk_fma_f32 v[34:35], v[42:43], v[138:139], v[208:209]
	v_pk_fma_f32 v[32:33], v[40:41], v[136:137], v[206:207]
	global_store_dwordx4 v[50:51], v[32:35], off offset:192
	v_mul_f32_e32 v14, v21, v21
	v_mul_f32_e32 v15, v25, v25
	v_fmac_f32_e32 v14, v20, v20
	v_fmac_f32_e32 v15, v24, v24
	v_fmac_f32_e32 v14, v22, v22
	v_fmac_f32_e32 v15, v26, v26
	v_fmac_f32_e32 v14, v23, v23
	v_fmac_f32_e32 v15, v27, v27
	v_add_f32_e32 v14, v14, v15
	v_mul_f32_e32 v15, v29, v29
	v_fmac_f32_e32 v15, v28, v28
	v_fmac_f32_e32 v15, v30, v30
	v_fmac_f32_e32 v15, v31, v31
	v_add_f32_e32 v14, v14, v15
	v_mul_f32_e32 v15, v33, v33
	v_fmac_f32_e32 v15, v32, v32
	v_fmac_f32_e32 v15, v34, v34
	v_fmac_f32_e32 v15, v35, v35
	v_add_f32_e32 v14, v14, v15
	ds_bpermute_b32 v15, v105, v14
	s_waitcnt lgkmcnt(0)
	v_add_f32_e32 v14, v14, v15
	ds_bpermute_b32 v15, v104, v14
	v_pk_mul_f32 v[20:21], v[34:35], v[154:155]
	v_pk_mul_f32 v[22:23], v[32:33], v[152:153]
	v_pk_add_f32 v[24:25], v[192:193], 1.0 op_sel_hi:[1,0]
	v_pk_add_f32 v[26:27], v[190:191], 1.0 op_sel_hi:[1,0]
	v_pk_mul_f32 v[20:21], v[20:21], v[24:25]
	v_pk_mul_f32 v[22:23], v[22:23], v[26:27]
	v_and_b32_sdwa v19, v20, v170 dst_sel:DWORD dst_unused:UNUSED_PAD src0_sel:WORD_1 src1_sel:DWORD
	v_and_b32_sdwa v25, v21, v170 dst_sel:DWORD dst_unused:UNUSED_PAD src0_sel:WORD_1 src1_sel:DWORD
	v_and_b32_sdwa v26, v23, v170 dst_sel:DWORD dst_unused:UNUSED_PAD src0_sel:WORD_1 src1_sel:DWORD
	v_and_b32_sdwa v24, v22, v170 dst_sel:DWORD dst_unused:UNUSED_PAD src0_sel:WORD_1 src1_sel:DWORD
	v_add3_u32 v19, v20, v19, s56
	v_add3_u32 v20, v21, v25, s56
	v_add3_u32 v21, v23, v26, s56
	v_add3_u32 v22, v22, v24, s56
	v_and_b32_e32 v20, 0xffff0000, v20
	v_and_b32_e32 v23, 0xffff0000, v21
	v_or_b32_sdwa v21, v20, v19 dst_sel:DWORD dst_unused:UNUSED_PAD src0_sel:DWORD src1_sel:WORD_1
	v_or_b32_sdwa v20, v23, v22 dst_sel:DWORD dst_unused:UNUSED_PAD src0_sel:DWORD src1_sel:WORD_1
	global_store_dwordx2 v[56:57], v[20:21], off offset:96
	s_and_saveexec_b64 s[2:3], vcc
	s_cbranch_execz .LBB0_612
	v_readlane_b32 s16, v253, 20
	s_add_u32 s24, s26, s16
	s_addc_u32 s25, s27, 0
	v_lshl_add_u64 v[20:21], v[12:13], 2, s[24:25]
	s_waitcnt lgkmcnt(0)
	v_add_f32_e32 v13, v14, v15
	global_store_dword v[20:21], v13, off

.LBB0_628:
	s_add_i32 s3, s24, 2
	v_add_u32_e32 v227, v144, v145
	ds_read_b128 v[36:39], v227 offset:16384
	ds_read_b128 v[40:43], v227 offset:18432
	ds_read_b128 v[44:47], v227 offset:20480
	ds_read_b128 v[48:51], v227 offset:22528
	v_add_u32_e32 v226, v143, v145
	ds_read_b128 v[16:19], v226
	v_add_u32_e32 v232, v144, v146
	s_add_i32 s24, s24, 4
	ds_read_b128 v[20:23], v226 offset:2048
	ds_read_b128 v[216:219], v232 offset:20480
	s_min_u32 s24, s24, 15
	s_lshl_b32 s92, s24, 7
	ds_read_b128 v[28:31], v226 offset:4096
	ds_read_b128 v[32:35], v226 offset:6144
	v_add_u32_e32 v228, v143, v146
	v_lshl_add_u64 v[224:225], v[138:139], 0, s[92:93]
	ds_read_b128 v[192:195], v228
	ds_read_b128 v[196:199], v228 offset:2048
	ds_read_b128 v[200:203], v228 offset:4096
	ds_read_b128 v[204:207], v228 offset:6144
	ds_read_b128 v[208:211], v232 offset:16384
	ds_read_b128 v[212:215], v232 offset:18432
	ds_read_b128 v[220:223], v232 offset:22528
	s_waitcnt lgkmcnt(11)
	v_mfma_f32_16x16x32_bf16 v[92:95], v[36:39], v[16:19], v[92:95]
	v_mfma_f32_16x16x32_bf16 v[88:91], v[40:43], v[16:19], v[88:91]
	v_mfma_f32_16x16x32_bf16 v[84:87], v[44:47], v[16:19], v[84:87]
	v_mfma_f32_16x16x32_bf16 v[16:19], v[48:51], v[16:19], v[80:83]
	s_nop 2
	global_load_dwordx4 v[80:83], v[224:225], off
	s_waitcnt vmcnt(6)
	ds_write_b128 v156, v[96:99] offset:32768
	v_add_co_u32_e32 v96, vcc, s11, v224
	s_waitcnt lgkmcnt(11)
	v_mfma_f32_16x16x32_bf16 v[76:79], v[36:39], v[20:23], v[76:79]
	v_addc_co_u32_e32 v97, vcc, 0, v225, vcc
	v_mfma_f32_16x16x32_bf16 v[72:75], v[40:43], v[20:23], v[72:75]
	v_mfma_f32_16x16x32_bf16 v[68:71], v[44:47], v[20:23], v[68:71]
	v_mfma_f32_16x16x32_bf16 v[20:23], v[48:51], v[20:23], v[64:67]
	s_nop 2
	global_load_dwordx4 v[64:67], v[96:97], off
	v_add_co_u32_e32 v96, vcc, s33, v224
	ds_write_b128 v156, v[100:103] offset:36864
	s_nop 0
	v_addc_co_u32_e32 v97, vcc, 0, v225, vcc
	s_waitcnt lgkmcnt(10)
	v_mfma_f32_16x16x32_bf16 v[60:63], v[36:39], v[28:31], v[60:63]
	v_mfma_f32_16x16x32_bf16 v[56:59], v[40:43], v[28:31], v[56:59]
	v_mfma_f32_16x16x32_bf16 v[52:55], v[44:47], v[28:31], v[52:55]
	v_mfma_f32_16x16x32_bf16 v[24:27], v[48:51], v[28:31], v[24:27]
	global_load_dwordx4 v[28:31], v[96:97], off
	ds_write_b128 v156, v[104:107] offset:40960
	s_waitcnt lgkmcnt(10)
	v_mfma_f32_16x16x32_bf16 v[12:15], v[36:39], v[32:35], v[12:15]
	v_add_co_u32_e32 v36, vcc, s59, v224
	s_nop 1
	v_addc_co_u32_e32 v37, vcc, 0, v225, vcc
	v_mfma_f32_16x16x32_bf16 v[8:11], v[40:43], v[32:35], v[8:11]
	v_mfma_f32_16x16x32_bf16 v[4:7], v[44:47], v[32:35], v[4:7]
	v_mfma_f32_16x16x32_bf16 v[0:3], v[48:51], v[32:35], v[0:3]
	global_load_dwordx4 v[32:35], v[36:37], off
	s_waitcnt vmcnt(7)
	ds_write_b128 v156, v[112:115] offset:45056
	s_waitcnt lgkmcnt(10)
	v_mfma_f32_16x16x32_bf16 v[44:47], v[216:219], v[192:195], v[84:87]
	s_nop 2
	v_lshl_add_u64 v[84:85], v[140:141], 0, s[92:93]
	v_add_co_u32_e32 v86, vcc, s11, v84
	s_waitcnt lgkmcnt(6)
	v_mfma_f32_16x16x32_bf16 v[36:39], v[208:211], v[192:195], v[92:95]
	v_addc_co_u32_e32 v87, vcc, 0, v85, vcc
	s_waitcnt lgkmcnt(5)
	v_mfma_f32_16x16x32_bf16 v[40:43], v[212:215], v[192:195], v[88:91]
	s_waitcnt lgkmcnt(4)
	v_mfma_f32_16x16x32_bf16 v[16:19], v[220:223], v[192:195], v[16:19]
	global_load_dwordx4 v[48:51], v[84:85], off
	ds_write_b128 v156, v[108:111] offset:49152
	v_mfma_f32_16x16x32_bf16 v[76:79], v[208:211], v[196:199], v[76:79]
	v_mfma_f32_16x16x32_bf16 v[72:75], v[212:215], v[196:199], v[72:75]
	v_mfma_f32_16x16x32_bf16 v[68:71], v[216:219], v[196:199], v[68:71]
	v_mfma_f32_16x16x32_bf16 v[20:23], v[220:223], v[196:199], v[20:23]
	global_load_dwordx4 v[192:195], v[86:87], off
	v_add_co_u32_e32 v86, vcc, s33, v84
	s_waitcnt vmcnt(8)
	ds_write_b128 v156, v[116:119] offset:53248
	v_addc_co_u32_e32 v87, vcc, 0, v85, vcc
	v_add_co_u32_e32 v84, vcc, s59, v84
	v_mfma_f32_16x16x32_bf16 v[60:63], v[208:211], v[200:203], v[60:63]
	s_nop 0
	v_addc_co_u32_e32 v85, vcc, 0, v85, vcc
	v_mfma_f32_16x16x32_bf16 v[56:59], v[212:215], v[200:203], v[56:59]
	v_mfma_f32_16x16x32_bf16 v[52:55], v[216:219], v[200:203], v[52:55]
	v_mfma_f32_16x16x32_bf16 v[24:27], v[220:223], v[200:203], v[24:27]
	global_load_dwordx4 v[196:199], v[86:87], off
	s_waitcnt vmcnt(8)
	ds_write_b128 v156, v[120:123] offset:57344
	v_mfma_f32_16x16x32_bf16 v[12:15], v[208:211], v[204:207], v[12:15]
	v_mfma_f32_16x16x32_bf16 v[8:11], v[212:215], v[204:207], v[8:11]
	v_mfma_f32_16x16x32_bf16 v[4:7], v[216:219], v[204:207], v[4:7]
	v_mfma_f32_16x16x32_bf16 v[0:3], v[220:223], v[204:207], v[0:3]
	global_load_dwordx4 v[200:203], v[84:85], off
	s_waitcnt vmcnt(8)
	ds_write_b128 v156, v[124:127] offset:61440
	s_waitcnt lgkmcnt(0)
	s_barrier
	ds_read_b128 v[112:115], v227 offset:49152
	ds_read_b128 v[116:119], v227 offset:51200
	ds_read_b128 v[120:123], v227 offset:53248
	ds_read_b128 v[124:127], v227 offset:55296
	ds_read_b128 v[84:87], v226 offset:32768
	ds_read_b128 v[88:91], v226 offset:34816
	ds_read_b128 v[92:95], v226 offset:36864
	ds_read_b128 v[108:111], v226 offset:38912
	ds_read_b128 v[204:207], v228 offset:32768
	ds_read_b128 v[208:211], v228 offset:34816
	ds_read_b128 v[212:215], v228 offset:36864
	ds_read_b128 v[216:219], v228 offset:38912
	ds_read_b128 v[220:223], v232 offset:49152
	ds_read_b128 v[224:227], v232 offset:51200
	ds_read_b128 v[228:231], v232 offset:53248
	ds_read_b128 v[232:235], v232 offset:55296
	s_min_u32 s24, s3, 12
	s_lshl_b32 s92, s24, 7
	s_waitcnt lgkmcnt(11)
	v_mfma_f32_16x16x32_bf16 v[36:39], v[112:115], v[84:87], v[36:39]
	v_mfma_f32_16x16x32_bf16 v[40:43], v[116:119], v[84:87], v[40:43]
	v_mfma_f32_16x16x32_bf16 v[44:47], v[120:123], v[84:87], v[44:47]
	v_mfma_f32_16x16x32_bf16 v[16:19], v[124:127], v[84:87], v[16:19]
	v_lshl_add_u64 v[84:85], v[138:139], 0, s[92:93]
	global_load_dwordx4 v[96:99], v[84:85], off offset:384
	s_waitcnt vmcnt(8)
	ds_write_b128 v156, v[80:83]
	v_add_co_u32_e32 v80, vcc, s11, v84
	s_waitcnt lgkmcnt(11)
	v_mfma_f32_16x16x32_bf16 v[76:79], v[112:115], v[88:91], v[76:79]
	v_addc_co_u32_e32 v81, vcc, 0, v85, vcc
	v_mfma_f32_16x16x32_bf16 v[72:75], v[116:119], v[88:91], v[72:75]
	v_mfma_f32_16x16x32_bf16 v[68:71], v[120:123], v[88:91], v[68:71]
	v_mfma_f32_16x16x32_bf16 v[20:23], v[124:127], v[88:91], v[20:23]
	global_load_dwordx4 v[100:103], v[80:81], off offset:384
	s_waitcnt vmcnt(8)
	ds_write_b128 v156, v[64:67] offset:4096
	v_add_co_u32_e32 v64, vcc, s33, v84
	s_waitcnt lgkmcnt(11)
	v_mfma_f32_16x16x32_bf16 v[60:63], v[112:115], v[92:95], v[60:63]
	v_addc_co_u32_e32 v65, vcc, 0, v85, vcc
	v_mfma_f32_16x16x32_bf16 v[56:59], v[116:119], v[92:95], v[56:59]
	v_mfma_f32_16x16x32_bf16 v[52:55], v[120:123], v[92:95], v[52:55]
	v_mfma_f32_16x16x32_bf16 v[24:27], v[124:127], v[92:95], v[24:27]
	global_load_dwordx4 v[104:107], v[64:65], off offset:384
	s_waitcnt vmcnt(8)
	ds_write_b128 v156, v[28:31] offset:8192
	v_add_co_u32_e32 v28, vcc, s59, v84
	s_waitcnt lgkmcnt(11)
	v_mfma_f32_16x16x32_bf16 v[12:15], v[112:115], v[108:111], v[12:15]
	v_addc_co_u32_e32 v29, vcc, 0, v85, vcc
	v_mfma_f32_16x16x32_bf16 v[8:11], v[116:119], v[108:111], v[8:11]
	v_mfma_f32_16x16x32_bf16 v[4:7], v[120:123], v[108:111], v[4:7]
	v_mfma_f32_16x16x32_bf16 v[0:3], v[124:127], v[108:111], v[0:3]
	global_load_dwordx4 v[112:115], v[28:29], off offset:384
	s_waitcnt vmcnt(8)
	ds_write_b128 v156, v[32:35] offset:12288
	s_waitcnt lgkmcnt(4)
	v_mfma_f32_16x16x32_bf16 v[80:83], v[232:235], v[204:207], v[16:19]
	s_nop 2
	v_lshl_add_u64 v[16:17], v[140:141], 0, s[92:93]
	v_add_co_u32_e32 v18, vcc, s11, v16
	v_mfma_f32_16x16x32_bf16 v[92:95], v[220:223], v[204:207], v[36:39]
	s_nop 0
	v_addc_co_u32_e32 v19, vcc, 0, v17, vcc
	v_mfma_f32_16x16x32_bf16 v[88:91], v[224:227], v[204:207], v[40:43]
	v_mfma_f32_16x16x32_bf16 v[84:87], v[228:231], v[204:207], v[44:47]
	global_load_dwordx4 v[108:111], v[16:17], off offset:384
	s_waitcnt vmcnt(8)
	ds_write_b128 v156, v[48:51] offset:16384
	v_mfma_f32_16x16x32_bf16 v[76:79], v[220:223], v[208:211], v[76:79]
	v_mfma_f32_16x16x32_bf16 v[72:75], v[224:227], v[208:211], v[72:75]
	v_mfma_f32_16x16x32_bf16 v[68:71], v[228:231], v[208:211], v[68:71]
	v_mfma_f32_16x16x32_bf16 v[64:67], v[232:235], v[208:211], v[20:23]
	global_load_dwordx4 v[116:119], v[18:19], off offset:384
	v_add_co_u32_e32 v18, vcc, s33, v16
	s_waitcnt vmcnt(8)
	ds_write_b128 v156, v[192:195] offset:20480
	v_addc_co_u32_e32 v19, vcc, 0, v17, vcc
	v_add_co_u32_e32 v16, vcc, s59, v16
	v_mfma_f32_16x16x32_bf16 v[60:63], v[220:223], v[212:215], v[60:63]
	s_nop 0
	v_addc_co_u32_e32 v17, vcc, 0, v17, vcc
	v_mfma_f32_16x16x32_bf16 v[56:59], v[224:227], v[212:215], v[56:59]
	v_mfma_f32_16x16x32_bf16 v[52:55], v[228:231], v[212:215], v[52:55]
	v_mfma_f32_16x16x32_bf16 v[24:27], v[232:235], v[212:215], v[24:27]
	global_load_dwordx4 v[120:123], v[18:19], off offset:384
	s_waitcnt vmcnt(8)
	ds_write_b128 v156, v[196:199] offset:24576
	v_mfma_f32_16x16x32_bf16 v[12:15], v[220:223], v[216:219], v[12:15]
	v_mfma_f32_16x16x32_bf16 v[8:11], v[224:227], v[216:219], v[8:11]
	v_mfma_f32_16x16x32_bf16 v[4:7], v[228:231], v[216:219], v[4:7]
	v_mfma_f32_16x16x32_bf16 v[0:3], v[232:235], v[216:219], v[0:3]
	global_load_dwordx4 v[124:127], v[16:17], off offset:384
	s_waitcnt vmcnt(8)
	ds_write_b128 v156, v[200:203] offset:28672
	s_cmp_gt_u32 s3, 11
	s_mov_b32 s24, s3
	s_waitcnt lgkmcnt(0)
	s_barrier
	s_cbranch_scc0 .LBB0_628
.Ltail628:
	s_add_i32 s3, s24, 2
	v_add_u32_e32 v227, v144, v145
	ds_read_b128 v[36:39], v227 offset:16384
	ds_read_b128 v[40:43], v227 offset:18432
	ds_read_b128 v[44:47], v227 offset:20480
	ds_read_b128 v[48:51], v227 offset:22528
	v_add_u32_e32 v226, v143, v145
	ds_read_b128 v[16:19], v226
	v_add_u32_e32 v232, v144, v146
	s_add_i32 s24, s24, 4
	ds_read_b128 v[20:23], v226 offset:2048
	ds_read_b128 v[216:219], v232 offset:20480
	s_min_u32 s24, s24, 15
	s_lshl_b32 s92, s24, 7
	ds_read_b128 v[28:31], v226 offset:4096
	ds_read_b128 v[32:35], v226 offset:6144
	v_add_u32_e32 v228, v143, v146
	v_lshl_add_u64 v[224:225], v[138:139], 0, s[92:93]
	ds_read_b128 v[192:195], v228
	ds_read_b128 v[196:199], v228 offset:2048
	ds_read_b128 v[200:203], v228 offset:4096
	ds_read_b128 v[204:207], v228 offset:6144
	ds_read_b128 v[208:211], v232 offset:16384
	ds_read_b128 v[212:215], v232 offset:18432
	ds_read_b128 v[220:223], v232 offset:22528
	s_waitcnt lgkmcnt(11)
	v_mfma_f32_16x16x32_bf16 v[92:95], v[36:39], v[16:19], v[92:95]
	v_mfma_f32_16x16x32_bf16 v[88:91], v[40:43], v[16:19], v[88:91]
	v_mfma_f32_16x16x32_bf16 v[84:87], v[44:47], v[16:19], v[84:87]
	v_mfma_f32_16x16x32_bf16 v[16:19], v[48:51], v[16:19], v[80:83]
	s_nop 2
	s_waitcnt vmcnt(7)
	ds_write_b128 v156, v[96:99] offset:32768
	v_add_co_u32_e32 v96, vcc, s11, v224
	s_waitcnt lgkmcnt(11)
	v_mfma_f32_16x16x32_bf16 v[76:79], v[36:39], v[20:23], v[76:79]
	v_addc_co_u32_e32 v97, vcc, 0, v225, vcc
	v_mfma_f32_16x16x32_bf16 v[72:75], v[40:43], v[20:23], v[72:75]
	v_mfma_f32_16x16x32_bf16 v[68:71], v[44:47], v[20:23], v[68:71]
	v_mfma_f32_16x16x32_bf16 v[20:23], v[48:51], v[20:23], v[64:67]
	s_nop 2
	v_add_co_u32_e32 v96, vcc, s33, v224
	s_waitcnt vmcnt(6)
	ds_write_b128 v156, v[100:103] offset:36864
	s_nop 0
	v_addc_co_u32_e32 v97, vcc, 0, v225, vcc
	s_waitcnt lgkmcnt(10)
	v_mfma_f32_16x16x32_bf16 v[60:63], v[36:39], v[28:31], v[60:63]
	v_mfma_f32_16x16x32_bf16 v[56:59], v[40:43], v[28:31], v[56:59]
	v_mfma_f32_16x16x32_bf16 v[52:55], v[44:47], v[28:31], v[52:55]
	v_mfma_f32_16x16x32_bf16 v[24:27], v[48:51], v[28:31], v[24:27]
	s_waitcnt vmcnt(5)
	ds_write_b128 v156, v[104:107] offset:40960
	s_waitcnt lgkmcnt(10)
	v_mfma_f32_16x16x32_bf16 v[12:15], v[36:39], v[32:35], v[12:15]
	v_add_co_u32_e32 v36, vcc, s59, v224
	s_nop 1
	v_addc_co_u32_e32 v37, vcc, 0, v225, vcc
	v_mfma_f32_16x16x32_bf16 v[8:11], v[40:43], v[32:35], v[8:11]
	v_mfma_f32_16x16x32_bf16 v[4:7], v[44:47], v[32:35], v[4:7]
	v_mfma_f32_16x16x32_bf16 v[0:3], v[48:51], v[32:35], v[0:3]
	s_waitcnt vmcnt(4)
	ds_write_b128 v156, v[112:115] offset:45056
	s_waitcnt lgkmcnt(10)
	v_mfma_f32_16x16x32_bf16 v[44:47], v[216:219], v[192:195], v[84:87]
	s_nop 2
	v_lshl_add_u64 v[84:85], v[140:141], 0, s[92:93]
	v_add_co_u32_e32 v86, vcc, s11, v84
	s_waitcnt lgkmcnt(6)
	v_mfma_f32_16x16x32_bf16 v[36:39], v[208:211], v[192:195], v[92:95]
	v_addc_co_u32_e32 v87, vcc, 0, v85, vcc
	s_waitcnt lgkmcnt(5)
	v_mfma_f32_16x16x32_bf16 v[40:43], v[212:215], v[192:195], v[88:91]
	s_waitcnt lgkmcnt(4)
	v_mfma_f32_16x16x32_bf16 v[16:19], v[220:223], v[192:195], v[16:19]
	s_waitcnt vmcnt(3)
	ds_write_b128 v156, v[108:111] offset:49152
	v_mfma_f32_16x16x32_bf16 v[76:79], v[208:211], v[196:199], v[76:79]
	v_mfma_f32_16x16x32_bf16 v[72:75], v[212:215], v[196:199], v[72:75]
	v_mfma_f32_16x16x32_bf16 v[68:71], v[216:219], v[196:199], v[68:71]
	v_mfma_f32_16x16x32_bf16 v[20:23], v[220:223], v[196:199], v[20:23]
	v_add_co_u32_e32 v86, vcc, s33, v84
	s_waitcnt vmcnt(2)
	ds_write_b128 v156, v[116:119] offset:53248
	v_addc_co_u32_e32 v87, vcc, 0, v85, vcc
	v_add_co_u32_e32 v84, vcc, s59, v84
	v_mfma_f32_16x16x32_bf16 v[60:63], v[208:211], v[200:203], v[60:63]
	s_nop 0
	v_addc_co_u32_e32 v85, vcc, 0, v85, vcc
	v_mfma_f32_16x16x32_bf16 v[56:59], v[212:215], v[200:203], v[56:59]
	v_mfma_f32_16x16x32_bf16 v[52:55], v[216:219], v[200:203], v[52:55]
	v_mfma_f32_16x16x32_bf16 v[24:27], v[220:223], v[200:203], v[24:27]
	s_waitcnt vmcnt(1)
	ds_write_b128 v156, v[120:123] offset:57344
	v_mfma_f32_16x16x32_bf16 v[12:15], v[208:211], v[204:207], v[12:15]
	v_mfma_f32_16x16x32_bf16 v[8:11], v[212:215], v[204:207], v[8:11]
	v_mfma_f32_16x16x32_bf16 v[4:7], v[216:219], v[204:207], v[4:7]
	v_mfma_f32_16x16x32_bf16 v[0:3], v[220:223], v[204:207], v[0:3]
	s_waitcnt vmcnt(0)
	ds_write_b128 v156, v[124:127] offset:61440
	s_waitcnt lgkmcnt(0)
	s_barrier
	ds_read_b128 v[112:115], v227 offset:49152
	ds_read_b128 v[116:119], v227 offset:51200
	ds_read_b128 v[120:123], v227 offset:53248
	ds_read_b128 v[124:127], v227 offset:55296
	ds_read_b128 v[84:87], v226 offset:32768
	ds_read_b128 v[88:91], v226 offset:34816
	ds_read_b128 v[92:95], v226 offset:36864
	ds_read_b128 v[108:111], v226 offset:38912
	ds_read_b128 v[204:207], v228 offset:32768
	ds_read_b128 v[208:211], v228 offset:34816
	ds_read_b128 v[212:215], v228 offset:36864
	ds_read_b128 v[216:219], v228 offset:38912
	ds_read_b128 v[220:223], v232 offset:49152
	ds_read_b128 v[224:227], v232 offset:51200
	ds_read_b128 v[228:231], v232 offset:53248
	ds_read_b128 v[232:235], v232 offset:55296
	s_min_u32 s24, s3, 12
	s_lshl_b32 s92, s24, 7
	s_waitcnt lgkmcnt(11)
	v_mfma_f32_16x16x32_bf16 v[36:39], v[112:115], v[84:87], v[36:39]
	v_mfma_f32_16x16x32_bf16 v[40:43], v[116:119], v[84:87], v[40:43]
	v_mfma_f32_16x16x32_bf16 v[44:47], v[120:123], v[84:87], v[44:47]
	v_mfma_f32_16x16x32_bf16 v[16:19], v[124:127], v[84:87], v[16:19]
	v_lshl_add_u64 v[84:85], v[138:139], 0, s[92:93]
	v_add_co_u32_e32 v80, vcc, s11, v84
	s_waitcnt lgkmcnt(10)
	v_mfma_f32_16x16x32_bf16 v[76:79], v[112:115], v[88:91], v[76:79]
	v_addc_co_u32_e32 v81, vcc, 0, v85, vcc
	v_mfma_f32_16x16x32_bf16 v[72:75], v[116:119], v[88:91], v[72:75]
	v_mfma_f32_16x16x32_bf16 v[68:71], v[120:123], v[88:91], v[68:71]
	v_mfma_f32_16x16x32_bf16 v[20:23], v[124:127], v[88:91], v[20:23]
	v_add_co_u32_e32 v64, vcc, s33, v84
	s_waitcnt lgkmcnt(9)
	v_mfma_f32_16x16x32_bf16 v[60:63], v[112:115], v[92:95], v[60:63]
	v_addc_co_u32_e32 v65, vcc, 0, v85, vcc
	v_mfma_f32_16x16x32_bf16 v[56:59], v[116:119], v[92:95], v[56:59]
	v_mfma_f32_16x16x32_bf16 v[52:55], v[120:123], v[92:95], v[52:55]
	v_mfma_f32_16x16x32_bf16 v[24:27], v[124:127], v[92:95], v[24:27]
	v_add_co_u32_e32 v28, vcc, s59, v84
	s_waitcnt lgkmcnt(8)
	v_mfma_f32_16x16x32_bf16 v[12:15], v[112:115], v[108:111], v[12:15]
	v_addc_co_u32_e32 v29, vcc, 0, v85, vcc
	v_mfma_f32_16x16x32_bf16 v[8:11], v[116:119], v[108:111], v[8:11]
	v_mfma_f32_16x16x32_bf16 v[4:7], v[120:123], v[108:111], v[4:7]
	v_mfma_f32_16x16x32_bf16 v[0:3], v[124:127], v[108:111], v[0:3]
	s_waitcnt lgkmcnt(0)
	v_mfma_f32_16x16x32_bf16 v[80:83], v[232:235], v[204:207], v[16:19]
	s_nop 2
	v_lshl_add_u64 v[16:17], v[140:141], 0, s[92:93]
	v_add_co_u32_e32 v18, vcc, s11, v16
	v_mfma_f32_16x16x32_bf16 v[92:95], v[220:223], v[204:207], v[36:39]
	s_nop 0
	v_addc_co_u32_e32 v19, vcc, 0, v17, vcc
	v_mfma_f32_16x16x32_bf16 v[88:91], v[224:227], v[204:207], v[40:43]
	v_mfma_f32_16x16x32_bf16 v[84:87], v[228:231], v[204:207], v[44:47]
	v_mfma_f32_16x16x32_bf16 v[76:79], v[220:223], v[208:211], v[76:79]
	v_mfma_f32_16x16x32_bf16 v[72:75], v[224:227], v[208:211], v[72:75]
	v_mfma_f32_16x16x32_bf16 v[68:71], v[228:231], v[208:211], v[68:71]
	v_mfma_f32_16x16x32_bf16 v[64:67], v[232:235], v[208:211], v[20:23]
	v_add_co_u32_e32 v18, vcc, s33, v16
	v_addc_co_u32_e32 v19, vcc, 0, v17, vcc
	v_add_co_u32_e32 v16, vcc, s59, v16
	v_mfma_f32_16x16x32_bf16 v[60:63], v[220:223], v[212:215], v[60:63]
	s_nop 0
	v_addc_co_u32_e32 v17, vcc, 0, v17, vcc
	v_mfma_f32_16x16x32_bf16 v[56:59], v[224:227], v[212:215], v[56:59]
	v_mfma_f32_16x16x32_bf16 v[52:55], v[228:231], v[212:215], v[52:55]
	v_mfma_f32_16x16x32_bf16 v[24:27], v[232:235], v[212:215], v[24:27]
	v_mfma_f32_16x16x32_bf16 v[12:15], v[220:223], v[216:219], v[12:15]
	v_mfma_f32_16x16x32_bf16 v[8:11], v[224:227], v[216:219], v[8:11]
	v_mfma_f32_16x16x32_bf16 v[4:7], v[228:231], v[216:219], v[4:7]
	v_mfma_f32_16x16x32_bf16 v[0:3], v[232:235], v[216:219], v[0:3]
	s_mov_b32 s24, s3
	s_waitcnt lgkmcnt(0)
	s_barrier
	s_and_saveexec_b64 s[24:25], s[36:37]
	s_cbranch_execz .LBB0_631
	v_add_f32_e32 v16, 0, v128
	v_add_f32_e32 v16, v16, v157
	v_add_f32_e32 v16, v16, v158
	v_add_f32_e32 v16, v16, v159
	v_add_f32_e32 v16, v16, v160
	v_add_f32_e32 v16, v16, v161
	v_add_f32_e32 v16, v16, v162
	v_add_f32_e32 v16, v16, v163
	v_add_f32_e32 v16, v16, v164
	v_add_f32_e32 v16, v16, v165
	v_add_f32_e32 v16, v16, v168
	v_add_f32_e32 v16, v16, v175
	v_add_f32_e32 v16, v16, v179
	v_add_f32_e32 v16, v16, v183
	v_add_f32_e32 v16, v16, v190
	v_add_f32_e32 v16, v16, v191
	v_fmamk_f32 v16, v16, 0x3a800000, v167
	s_mov_b32 s3, 0x800000
	v_mul_f32_e32 v17, 0x4b800000, v16
	v_cmp_gt_f32_e32 vcc, s3, v16
	s_nop 1
	v_cndmask_b32_e32 v16, v16, v17, vcc
	v_rsq_f32_e32 v16, v16
	s_nop 0
	v_mul_f32_e32 v17, 0x45800000, v16
	v_cndmask_b32_e32 v16, v16, v17, vcc
	ds_write_b32 v155, v16

.LBB0_666:
	s_add_i32 s2, s3, 2
	v_add_u32_e32 v123, v111, v126
	ds_read_b128 v[154:157], v123 offset:16384
	ds_read_b128 v[158:161], v123 offset:18432
	ds_read_b128 v[162:165], v123 offset:20480
	ds_read_b128 v[190:193], v123 offset:22528
	v_add_u32_e32 v122, v110, v126
	ds_read_b128 v[138:141], v122
	ds_read_b128 v[142:145], v122 offset:2048
	v_add_u32_e32 v125, v111, v137
	s_add_i32 s3, s3, 4
	ds_read_b128 v[146:149], v122 offset:4096
	ds_read_b128 v[214:217], v125 offset:18432
	s_min_u32 s3, s3, 15
	ds_read_b128 v[210:213], v125 offset:16384
	ds_read_b128 v[218:221], v125 offset:20480
	ds_read_b128 v[222:225], v125 offset:22528
	s_lshl_b32 s92, s3, 7
	v_add_u32_e32 v124, v110, v137
	v_lshl_add_u64 v[226:227], v[102:103], 0, s[92:93]
	ds_read_b128 v[150:153], v122 offset:6144
	ds_read_b128 v[194:197], v124
	ds_read_b128 v[198:201], v124 offset:2048
	ds_read_b128 v[202:205], v124 offset:4096
	ds_read_b128 v[206:209], v124 offset:6144
	s_waitcnt lgkmcnt(11)
	v_mfma_f32_16x16x32_bf16 v[92:95], v[154:157], v[138:141], v[92:95]
	v_mfma_f32_16x16x32_bf16 v[88:91], v[158:161], v[138:141], v[88:91]
	v_mfma_f32_16x16x32_bf16 v[84:87], v[162:165], v[138:141], v[84:87]
	v_mfma_f32_16x16x32_bf16 v[80:83], v[190:193], v[138:141], v[80:83]
	global_load_dwordx4 v[138:141], v[226:227], off
	s_waitcnt vmcnt(6)
	ds_write_b128 v121, v[28:31] offset:32768
	s_waitcnt lgkmcnt(11)
	v_mfma_f32_16x16x32_bf16 v[28:31], v[154:157], v[142:145], v[76:79]
	s_nop 2
	v_add_co_u32_e32 v76, vcc, s11, v226
	v_mfma_f32_16x16x32_bf16 v[72:75], v[158:161], v[142:145], v[72:75]
	s_nop 0
	v_addc_co_u32_e32 v77, vcc, 0, v227, vcc
	v_mfma_f32_16x16x32_bf16 v[68:71], v[162:165], v[142:145], v[68:71]
	v_mfma_f32_16x16x32_bf16 v[64:67], v[190:193], v[142:145], v[64:67]
	global_load_dwordx4 v[76:79], v[76:77], off
	ds_write_b128 v121, v[32:35] offset:36864
	s_waitcnt lgkmcnt(11)
	v_mfma_f32_16x16x32_bf16 v[32:35], v[154:157], v[146:149], v[48:51]
	s_nop 2
	v_add_co_u32_e32 v48, vcc, s33, v226
	v_mfma_f32_16x16x32_bf16 v[24:27], v[158:161], v[146:149], v[24:27]
	s_nop 0
	v_addc_co_u32_e32 v49, vcc, 0, v227, vcc
	v_mfma_f32_16x16x32_bf16 v[20:23], v[162:165], v[146:149], v[20:23]
	v_mfma_f32_16x16x32_bf16 v[16:19], v[190:193], v[146:149], v[16:19]
	global_load_dwordx4 v[48:51], v[48:49], off
	ds_write_b128 v121, v[36:39] offset:40960
	v_add_co_u32_e32 v36, vcc, s59, v226
	s_waitcnt lgkmcnt(7)
	v_mfma_f32_16x16x32_bf16 v[12:15], v[154:157], v[150:153], v[12:15]
	v_addc_co_u32_e32 v37, vcc, 0, v227, vcc
	v_mfma_f32_16x16x32_bf16 v[8:11], v[158:161], v[150:153], v[8:11]
	v_mfma_f32_16x16x32_bf16 v[4:7], v[162:165], v[150:153], v[4:7]
	v_mfma_f32_16x16x32_bf16 v[0:3], v[190:193], v[150:153], v[0:3]
	global_load_dwordx4 v[142:145], v[36:37], off
	s_waitcnt vmcnt(7)
	ds_write_b128 v121, v[44:47] offset:45056
	s_waitcnt lgkmcnt(7)
	v_mfma_f32_16x16x32_bf16 v[44:47], v[214:217], v[194:197], v[88:91]
	s_nop 2
	v_lshl_add_u64 v[88:89], v[104:105], 0, s[92:93]
	v_mfma_f32_16x16x32_bf16 v[36:39], v[210:213], v[194:197], v[92:95]
	v_mfma_f32_16x16x32_bf16 v[84:87], v[218:221], v[194:197], v[84:87]
	v_mfma_f32_16x16x32_bf16 v[80:83], v[222:225], v[194:197], v[80:83]
	global_load_dwordx4 v[146:149], v[88:89], off
	ds_write_b128 v121, v[40:43] offset:49152
	s_waitcnt lgkmcnt(7)
	v_mfma_f32_16x16x32_bf16 v[40:43], v[210:213], v[198:201], v[28:31]
	s_nop 2
	v_add_co_u32_e32 v28, vcc, s11, v88
	v_mfma_f32_16x16x32_bf16 v[72:75], v[214:217], v[198:201], v[72:75]
	s_nop 0
	v_addc_co_u32_e32 v29, vcc, 0, v89, vcc
	v_mfma_f32_16x16x32_bf16 v[68:71], v[218:221], v[198:201], v[68:71]
	v_mfma_f32_16x16x32_bf16 v[64:67], v[222:225], v[198:201], v[64:67]
	global_load_dwordx4 v[150:153], v[28:29], off
	v_add_co_u32_e32 v28, vcc, s33, v88
	s_waitcnt vmcnt(8)
	ds_write_b128 v121, v[52:55] offset:53248
	v_addc_co_u32_e32 v29, vcc, 0, v89, vcc
	s_waitcnt lgkmcnt(7)
	v_mfma_f32_16x16x32_bf16 v[52:55], v[210:213], v[202:205], v[32:35]
	v_mfma_f32_16x16x32_bf16 v[24:27], v[214:217], v[202:205], v[24:27]
	v_mfma_f32_16x16x32_bf16 v[20:23], v[218:221], v[202:205], v[20:23]
	v_mfma_f32_16x16x32_bf16 v[16:19], v[222:225], v[202:205], v[16:19]
	global_load_dwordx4 v[154:157], v[28:29], off
	v_add_co_u32_e32 v28, vcc, s59, v88
	s_waitcnt vmcnt(8)
	ds_write_b128 v121, v[56:59] offset:57344
	v_addc_co_u32_e32 v29, vcc, 0, v89, vcc
	s_waitcnt lgkmcnt(7)
	v_mfma_f32_16x16x32_bf16 v[12:15], v[210:213], v[206:209], v[12:15]
	v_mfma_f32_16x16x32_bf16 v[8:11], v[214:217], v[206:209], v[8:11]
	v_mfma_f32_16x16x32_bf16 v[4:7], v[218:221], v[206:209], v[4:7]
	v_mfma_f32_16x16x32_bf16 v[0:3], v[222:225], v[206:209], v[0:3]
	global_load_dwordx4 v[158:161], v[28:29], off
	s_waitcnt vmcnt(8)
	ds_write_b128 v121, v[60:63] offset:61440
	s_waitcnt lgkmcnt(0)
	s_barrier
	ds_read_b128 v[92:95], v123 offset:51200
	ds_read_b128 v[88:91], v123 offset:49152
	ds_read_b128 v[162:165], v123 offset:53248
	ds_read_b128 v[190:193], v123 offset:55296
	ds_read_b128 v[28:31], v122 offset:32768
	ds_read_b128 v[32:35], v122 offset:34816
	s_min_u32 s3, s2, 12
	s_lshl_b32 s92, s3, 7
	ds_read_b128 v[56:59], v122 offset:36864
	ds_read_b128 v[60:63], v122 offset:38912
	ds_read_b128 v[194:197], v124 offset:32768
	ds_read_b128 v[198:201], v124 offset:34816
	ds_read_b128 v[202:205], v124 offset:36864
	ds_read_b128 v[206:209], v124 offset:38912
	ds_read_b128 v[210:213], v125 offset:49152
	ds_read_b128 v[214:217], v125 offset:51200
	ds_read_b128 v[218:221], v125 offset:53248
	ds_read_b128 v[222:225], v125 offset:55296
	s_waitcnt lgkmcnt(11)
	v_mfma_f32_16x16x32_bf16 v[230:233], v[92:95], v[28:31], v[44:47]
	v_mfma_f32_16x16x32_bf16 v[226:229], v[88:91], v[28:31], v[36:39]
	s_nop 1
	v_lshl_add_u64 v[44:45], v[102:103], 0, s[92:93]
	v_add_co_u32_e32 v36, vcc, s11, v44
	v_mfma_f32_16x16x32_bf16 v[84:87], v[162:165], v[28:31], v[84:87]
	s_nop 0
	v_addc_co_u32_e32 v37, vcc, 0, v45, vcc
	v_mfma_f32_16x16x32_bf16 v[80:83], v[190:193], v[28:31], v[80:83]
	global_load_dwordx4 v[28:31], v[44:45], off offset:384
	s_waitcnt vmcnt(8)
	ds_write_b128 v121, v[138:141]
	s_waitcnt lgkmcnt(11)
	v_mfma_f32_16x16x32_bf16 v[138:141], v[88:91], v[32:35], v[40:43]
	v_mfma_f32_16x16x32_bf16 v[72:75], v[92:95], v[32:35], v[72:75]
	v_mfma_f32_16x16x32_bf16 v[68:71], v[162:165], v[32:35], v[68:71]
	v_mfma_f32_16x16x32_bf16 v[64:67], v[190:193], v[32:35], v[64:67]
	global_load_dwordx4 v[32:35], v[36:37], off offset:384
	v_add_co_u32_e32 v36, vcc, s33, v44
	s_waitcnt vmcnt(8)
	ds_write_b128 v121, v[76:79] offset:4096
	v_addc_co_u32_e32 v37, vcc, 0, v45, vcc
	v_add_co_u32_e32 v40, vcc, s59, v44
	s_waitcnt lgkmcnt(11)
	v_mfma_f32_16x16x32_bf16 v[234:237], v[88:91], v[56:59], v[52:55]
	v_addc_co_u32_e32 v41, vcc, 0, v45, vcc
	v_mfma_f32_16x16x32_bf16 v[24:27], v[92:95], v[56:59], v[24:27]
	v_mfma_f32_16x16x32_bf16 v[20:23], v[162:165], v[56:59], v[20:23]
	v_mfma_f32_16x16x32_bf16 v[16:19], v[190:193], v[56:59], v[16:19]
	global_load_dwordx4 v[36:39], v[36:37], off offset:384
	s_waitcnt vmcnt(8)
	ds_write_b128 v121, v[48:51] offset:8192
	s_waitcnt lgkmcnt(11)
	v_mfma_f32_16x16x32_bf16 v[12:15], v[88:91], v[60:63], v[12:15]
	v_mfma_f32_16x16x32_bf16 v[8:11], v[92:95], v[60:63], v[8:11]
	v_mfma_f32_16x16x32_bf16 v[4:7], v[162:165], v[60:63], v[4:7]
	v_mfma_f32_16x16x32_bf16 v[0:3], v[190:193], v[60:63], v[0:3]
	v_lshl_add_u64 v[60:61], v[104:105], 0, s[92:93]
	v_add_co_u32_e32 v48, vcc, s11, v60
	global_load_dwordx4 v[44:47], v[40:41], off offset:384
	s_nop 0
	v_addc_co_u32_e32 v49, vcc, 0, v61, vcc
	v_add_co_u32_e32 v56, vcc, s33, v60
	s_waitcnt vmcnt(8)
	ds_write_b128 v121, v[142:145] offset:12288
	v_addc_co_u32_e32 v57, vcc, 0, v61, vcc
	s_waitcnt lgkmcnt(7)
	v_mfma_f32_16x16x32_bf16 v[92:95], v[210:213], v[194:197], v[226:229]
	s_waitcnt lgkmcnt(6)
	v_mfma_f32_16x16x32_bf16 v[88:91], v[214:217], v[194:197], v[230:233]
	s_waitcnt lgkmcnt(5)
	v_mfma_f32_16x16x32_bf16 v[84:87], v[218:221], v[194:197], v[84:87]
	s_waitcnt lgkmcnt(4)
	v_mfma_f32_16x16x32_bf16 v[80:83], v[222:225], v[194:197], v[80:83]
	global_load_dwordx4 v[40:43], v[60:61], off offset:384
	v_add_co_u32_e32 v60, vcc, s59, v60
	s_waitcnt vmcnt(8)
	ds_write_b128 v121, v[146:149] offset:16384
	v_addc_co_u32_e32 v61, vcc, 0, v61, vcc
	v_mfma_f32_16x16x32_bf16 v[76:79], v[210:213], v[198:201], v[138:141]
	v_mfma_f32_16x16x32_bf16 v[72:75], v[214:217], v[198:201], v[72:75]
	v_mfma_f32_16x16x32_bf16 v[68:71], v[218:221], v[198:201], v[68:71]
	v_mfma_f32_16x16x32_bf16 v[64:67], v[222:225], v[198:201], v[64:67]
	global_load_dwordx4 v[52:55], v[48:49], off offset:384
	s_waitcnt vmcnt(8)
	ds_write_b128 v121, v[150:153] offset:20480
	v_mfma_f32_16x16x32_bf16 v[48:51], v[210:213], v[202:205], v[234:237]
	v_mfma_f32_16x16x32_bf16 v[24:27], v[214:217], v[202:205], v[24:27]
	v_mfma_f32_16x16x32_bf16 v[20:23], v[218:221], v[202:205], v[20:23]
	v_mfma_f32_16x16x32_bf16 v[16:19], v[222:225], v[202:205], v[16:19]
	global_load_dwordx4 v[56:59], v[56:57], off offset:384
	s_waitcnt vmcnt(8)
	ds_write_b128 v121, v[154:157] offset:24576
	v_mfma_f32_16x16x32_bf16 v[12:15], v[210:213], v[206:209], v[12:15]
	v_mfma_f32_16x16x32_bf16 v[8:11], v[214:217], v[206:209], v[8:11]
	v_mfma_f32_16x16x32_bf16 v[4:7], v[218:221], v[206:209], v[4:7]
	v_mfma_f32_16x16x32_bf16 v[0:3], v[222:225], v[206:209], v[0:3]
	global_load_dwordx4 v[60:63], v[60:61], off offset:384
	s_waitcnt vmcnt(8)
	ds_write_b128 v121, v[158:161] offset:28672
	s_cmp_gt_u32 s2, 11
	s_mov_b32 s3, s2
	s_waitcnt lgkmcnt(0)
	s_barrier
	s_cbranch_scc0 .LBB0_666
.Ltail666:
	s_add_i32 s2, s3, 2
	v_add_u32_e32 v123, v111, v126
	ds_read_b128 v[154:157], v123 offset:16384
	ds_read_b128 v[158:161], v123 offset:18432
	ds_read_b128 v[162:165], v123 offset:20480
	ds_read_b128 v[190:193], v123 offset:22528
	v_add_u32_e32 v122, v110, v126
	ds_read_b128 v[138:141], v122
	ds_read_b128 v[142:145], v122 offset:2048
	v_add_u32_e32 v125, v111, v137
	s_add_i32 s3, s3, 4
	ds_read_b128 v[146:149], v122 offset:4096
	ds_read_b128 v[214:217], v125 offset:18432
	s_min_u32 s3, s3, 15
	ds_read_b128 v[210:213], v125 offset:16384
	ds_read_b128 v[218:221], v125 offset:20480
	ds_read_b128 v[222:225], v125 offset:22528
	s_lshl_b32 s92, s3, 7
	v_add_u32_e32 v124, v110, v137
	v_lshl_add_u64 v[226:227], v[102:103], 0, s[92:93]
	ds_read_b128 v[150:153], v122 offset:6144
	ds_read_b128 v[194:197], v124
	ds_read_b128 v[198:201], v124 offset:2048
	ds_read_b128 v[202:205], v124 offset:4096
	ds_read_b128 v[206:209], v124 offset:6144
	s_waitcnt lgkmcnt(11)
	v_mfma_f32_16x16x32_bf16 v[92:95], v[154:157], v[138:141], v[92:95]
	v_mfma_f32_16x16x32_bf16 v[88:91], v[158:161], v[138:141], v[88:91]
	v_mfma_f32_16x16x32_bf16 v[84:87], v[162:165], v[138:141], v[84:87]
	v_mfma_f32_16x16x32_bf16 v[80:83], v[190:193], v[138:141], v[80:83]
	s_waitcnt vmcnt(7)
	ds_write_b128 v121, v[28:31] offset:32768
	s_waitcnt lgkmcnt(11)
	v_mfma_f32_16x16x32_bf16 v[28:31], v[154:157], v[142:145], v[76:79]
	s_nop 2
	v_add_co_u32_e32 v76, vcc, s11, v226
	v_mfma_f32_16x16x32_bf16 v[72:75], v[158:161], v[142:145], v[72:75]
	s_nop 0
	v_addc_co_u32_e32 v77, vcc, 0, v227, vcc
	v_mfma_f32_16x16x32_bf16 v[68:71], v[162:165], v[142:145], v[68:71]
	v_mfma_f32_16x16x32_bf16 v[64:67], v[190:193], v[142:145], v[64:67]
	s_waitcnt vmcnt(6)
	ds_write_b128 v121, v[32:35] offset:36864
	s_waitcnt lgkmcnt(11)
	v_mfma_f32_16x16x32_bf16 v[32:35], v[154:157], v[146:149], v[48:51]
	s_nop 2
	v_add_co_u32_e32 v48, vcc, s33, v226
	v_mfma_f32_16x16x32_bf16 v[24:27], v[158:161], v[146:149], v[24:27]
	s_nop 0
	v_addc_co_u32_e32 v49, vcc, 0, v227, vcc
	v_mfma_f32_16x16x32_bf16 v[20:23], v[162:165], v[146:149], v[20:23]
	v_mfma_f32_16x16x32_bf16 v[16:19], v[190:193], v[146:149], v[16:19]
	s_waitcnt vmcnt(5)
	ds_write_b128 v121, v[36:39] offset:40960
	v_add_co_u32_e32 v36, vcc, s59, v226
	s_waitcnt lgkmcnt(7)
	v_mfma_f32_16x16x32_bf16 v[12:15], v[154:157], v[150:153], v[12:15]
	v_addc_co_u32_e32 v37, vcc, 0, v227, vcc
	v_mfma_f32_16x16x32_bf16 v[8:11], v[158:161], v[150:153], v[8:11]
	v_mfma_f32_16x16x32_bf16 v[4:7], v[162:165], v[150:153], v[4:7]
	v_mfma_f32_16x16x32_bf16 v[0:3], v[190:193], v[150:153], v[0:3]
	s_waitcnt vmcnt(4)
	ds_write_b128 v121, v[44:47] offset:45056
	s_waitcnt lgkmcnt(7)
	v_mfma_f32_16x16x32_bf16 v[44:47], v[214:217], v[194:197], v[88:91]
	s_nop 2
	v_lshl_add_u64 v[88:89], v[104:105], 0, s[92:93]
	v_mfma_f32_16x16x32_bf16 v[36:39], v[210:213], v[194:197], v[92:95]
	v_mfma_f32_16x16x32_bf16 v[84:87], v[218:221], v[194:197], v[84:87]
	v_mfma_f32_16x16x32_bf16 v[80:83], v[222:225], v[194:197], v[80:83]
	s_waitcnt vmcnt(3)
	ds_write_b128 v121, v[40:43] offset:49152
	s_waitcnt lgkmcnt(7)
	v_mfma_f32_16x16x32_bf16 v[40:43], v[210:213], v[198:201], v[28:31]
	s_nop 2
	v_add_co_u32_e32 v28, vcc, s11, v88
	v_mfma_f32_16x16x32_bf16 v[72:75], v[214:217], v[198:201], v[72:75]
	s_nop 0
	v_addc_co_u32_e32 v29, vcc, 0, v89, vcc
	v_mfma_f32_16x16x32_bf16 v[68:71], v[218:221], v[198:201], v[68:71]
	v_mfma_f32_16x16x32_bf16 v[64:67], v[222:225], v[198:201], v[64:67]
	v_add_co_u32_e32 v28, vcc, s33, v88
	s_waitcnt vmcnt(2)
	ds_write_b128 v121, v[52:55] offset:53248
	v_addc_co_u32_e32 v29, vcc, 0, v89, vcc
	s_waitcnt lgkmcnt(7)
	v_mfma_f32_16x16x32_bf16 v[52:55], v[210:213], v[202:205], v[32:35]
	v_mfma_f32_16x16x32_bf16 v[24:27], v[214:217], v[202:205], v[24:27]
	v_mfma_f32_16x16x32_bf16 v[20:23], v[218:221], v[202:205], v[20:23]
	v_mfma_f32_16x16x32_bf16 v[16:19], v[222:225], v[202:205], v[16:19]
	v_add_co_u32_e32 v28, vcc, s59, v88
	s_waitcnt vmcnt(1)
	ds_write_b128 v121, v[56:59] offset:57344
	v_addc_co_u32_e32 v29, vcc, 0, v89, vcc
	s_waitcnt lgkmcnt(7)
	v_mfma_f32_16x16x32_bf16 v[12:15], v[210:213], v[206:209], v[12:15]
	v_mfma_f32_16x16x32_bf16 v[8:11], v[214:217], v[206:209], v[8:11]
	v_mfma_f32_16x16x32_bf16 v[4:7], v[218:221], v[206:209], v[4:7]
	v_mfma_f32_16x16x32_bf16 v[0:3], v[222:225], v[206:209], v[0:3]
	s_waitcnt vmcnt(0)
	ds_write_b128 v121, v[60:63] offset:61440
	s_waitcnt lgkmcnt(0)
	s_barrier
	ds_read_b128 v[92:95], v123 offset:51200
	ds_read_b128 v[88:91], v123 offset:49152
	ds_read_b128 v[162:165], v123 offset:53248
	ds_read_b128 v[190:193], v123 offset:55296
	ds_read_b128 v[28:31], v122 offset:32768
	ds_read_b128 v[32:35], v122 offset:34816
	s_min_u32 s3, s2, 12
	s_lshl_b32 s92, s3, 7
	ds_read_b128 v[56:59], v122 offset:36864
	ds_read_b128 v[60:63], v122 offset:38912
	ds_read_b128 v[194:197], v124 offset:32768
	ds_read_b128 v[198:201], v124 offset:34816
	ds_read_b128 v[202:205], v124 offset:36864
	ds_read_b128 v[206:209], v124 offset:38912
	ds_read_b128 v[210:213], v125 offset:49152
	ds_read_b128 v[214:217], v125 offset:51200
	ds_read_b128 v[218:221], v125 offset:53248
	ds_read_b128 v[222:225], v125 offset:55296
	s_waitcnt lgkmcnt(11)
	v_mfma_f32_16x16x32_bf16 v[230:233], v[92:95], v[28:31], v[44:47]
	v_mfma_f32_16x16x32_bf16 v[226:229], v[88:91], v[28:31], v[36:39]
	s_nop 1
	v_lshl_add_u64 v[44:45], v[102:103], 0, s[92:93]
	v_add_co_u32_e32 v36, vcc, s11, v44
	v_mfma_f32_16x16x32_bf16 v[84:87], v[162:165], v[28:31], v[84:87]
	s_nop 0
	v_addc_co_u32_e32 v37, vcc, 0, v45, vcc
	v_mfma_f32_16x16x32_bf16 v[80:83], v[190:193], v[28:31], v[80:83]
	s_waitcnt lgkmcnt(10)
	v_mfma_f32_16x16x32_bf16 v[138:141], v[88:91], v[32:35], v[40:43]
	v_mfma_f32_16x16x32_bf16 v[72:75], v[92:95], v[32:35], v[72:75]
	v_mfma_f32_16x16x32_bf16 v[68:71], v[162:165], v[32:35], v[68:71]
	v_mfma_f32_16x16x32_bf16 v[64:67], v[190:193], v[32:35], v[64:67]
	v_add_co_u32_e32 v36, vcc, s33, v44
	v_addc_co_u32_e32 v37, vcc, 0, v45, vcc
	v_add_co_u32_e32 v40, vcc, s59, v44
	s_waitcnt lgkmcnt(9)
	v_mfma_f32_16x16x32_bf16 v[234:237], v[88:91], v[56:59], v[52:55]
	v_addc_co_u32_e32 v41, vcc, 0, v45, vcc
	v_mfma_f32_16x16x32_bf16 v[24:27], v[92:95], v[56:59], v[24:27]
	v_mfma_f32_16x16x32_bf16 v[20:23], v[162:165], v[56:59], v[20:23]
	v_mfma_f32_16x16x32_bf16 v[16:19], v[190:193], v[56:59], v[16:19]
	s_waitcnt lgkmcnt(8)
	v_mfma_f32_16x16x32_bf16 v[12:15], v[88:91], v[60:63], v[12:15]
	v_mfma_f32_16x16x32_bf16 v[8:11], v[92:95], v[60:63], v[8:11]
	v_mfma_f32_16x16x32_bf16 v[4:7], v[162:165], v[60:63], v[4:7]
	v_mfma_f32_16x16x32_bf16 v[0:3], v[190:193], v[60:63], v[0:3]
	v_lshl_add_u64 v[60:61], v[104:105], 0, s[92:93]
	v_add_co_u32_e32 v48, vcc, s11, v60
	s_nop 0
	v_addc_co_u32_e32 v49, vcc, 0, v61, vcc
	v_add_co_u32_e32 v56, vcc, s33, v60
	v_addc_co_u32_e32 v57, vcc, 0, v61, vcc
	s_waitcnt lgkmcnt(3)
	v_mfma_f32_16x16x32_bf16 v[92:95], v[210:213], v[194:197], v[226:229]
	s_waitcnt lgkmcnt(2)
	v_mfma_f32_16x16x32_bf16 v[88:91], v[214:217], v[194:197], v[230:233]
	s_waitcnt lgkmcnt(1)
	v_mfma_f32_16x16x32_bf16 v[84:87], v[218:221], v[194:197], v[84:87]
	s_waitcnt lgkmcnt(0)
	v_mfma_f32_16x16x32_bf16 v[80:83], v[222:225], v[194:197], v[80:83]
	v_add_co_u32_e32 v60, vcc, s59, v60
	v_addc_co_u32_e32 v61, vcc, 0, v61, vcc
	v_mfma_f32_16x16x32_bf16 v[76:79], v[210:213], v[198:201], v[138:141]
	v_mfma_f32_16x16x32_bf16 v[72:75], v[214:217], v[198:201], v[72:75]
	v_mfma_f32_16x16x32_bf16 v[68:71], v[218:221], v[198:201], v[68:71]
	v_mfma_f32_16x16x32_bf16 v[64:67], v[222:225], v[198:201], v[64:67]
	v_mfma_f32_16x16x32_bf16 v[48:51], v[210:213], v[202:205], v[234:237]
	v_mfma_f32_16x16x32_bf16 v[24:27], v[214:217], v[202:205], v[24:27]
	v_mfma_f32_16x16x32_bf16 v[20:23], v[218:221], v[202:205], v[20:23]
	v_mfma_f32_16x16x32_bf16 v[16:19], v[222:225], v[202:205], v[16:19]
	v_mfma_f32_16x16x32_bf16 v[12:15], v[210:213], v[206:209], v[12:15]
	v_mfma_f32_16x16x32_bf16 v[8:11], v[214:217], v[206:209], v[8:11]
	v_mfma_f32_16x16x32_bf16 v[4:7], v[218:221], v[206:209], v[4:7]
	v_mfma_f32_16x16x32_bf16 v[0:3], v[222:225], v[206:209], v[0:3]
	s_mov_b32 s3, s2
	s_waitcnt lgkmcnt(0)
	s_barrier
	s_movk_i32 s2, 0x80
	v_cmp_gt_i32_e64 s[36:37], s2, v109
	s_add_i32 s2, 0, 0x10000
	v_lshl_add_u32 v126, v109, 2, s2
	s_and_saveexec_b64 s[2:3], s[36:37]
	v_readlane_b32 s16, v251, 44
	v_readlane_b32 s17, v251, 45
	s_cbranch_execz .LBB0_669
	s_waitcnt vmcnt(7)
	v_add_f32_e32 v28, 0, v112
	v_add_f32_e32 v28, v28, v113
	v_add_f32_e32 v28, v28, v114
	v_add_f32_e32 v28, v28, v115
	v_add_f32_e32 v28, v28, v116
	v_add_f32_e32 v28, v28, v117
	v_add_f32_e32 v28, v28, v118
	v_add_f32_e32 v28, v28, v119
	v_add_f32_e32 v28, v28, v127
	v_add_f32_e32 v28, v28, v128
	v_add_f32_e32 v28, v28, v130
	v_add_f32_e32 v28, v28, v132
	v_add_f32_e32 v28, v28, v133
	v_add_f32_e32 v28, v28, v134
	v_add_f32_e32 v28, v28, v135
	v_add_f32_e32 v28, v28, v136
	v_fmamk_f32 v28, v28, 0x3a800000, v167
	s_mov_b32 s21, 0x800000
	v_mul_f32_e32 v29, 0x4b800000, v28
	v_cmp_gt_f32_e32 vcc, s21, v28
	s_nop 1
	v_cndmask_b32_e32 v28, v28, v29, vcc
	v_rsq_f32_e32 v28, v28
	s_nop 0
	v_mul_f32_e32 v29, 0x45800000, v28
	v_cndmask_b32_e32 v28, v28, v29, vcc
	ds_write_b32 v126, v28

.LBB0_702:
	s_add_i32 s2, s3, 2
	ds_read_b128 v[152:155], v123 offset:16384
	ds_read_b128 v[156:159], v123 offset:18432
	ds_read_b128 v[160:163], v123 offset:20480
	ds_read_b128 v[190:193], v123 offset:22528
	ds_read_b128 v[102:105], v122
	s_add_i32 s3, s3, 4
	ds_read_b128 v[140:143], v122 offset:2048
	s_min_u32 s3, s3, 15
	s_lshl_b32 s92, s3, 7
	ds_read_b128 v[144:147], v122 offset:4096
	v_lshl_add_u64 v[106:107], v[98:99], 0, s[92:93]
	ds_read_b128 v[148:151], v122 offset:6144
	ds_read_b128 v[194:197], v124
	ds_read_b128 v[198:201], v124 offset:2048
	ds_read_b128 v[202:205], v124 offset:4096
	ds_read_b128 v[206:209], v124 offset:6144
	ds_read_b128 v[210:213], v125 offset:16384
	ds_read_b128 v[214:217], v125 offset:18432
	ds_read_b128 v[218:221], v125 offset:20480
	ds_read_b128 v[222:225], v125 offset:22528
	s_waitcnt lgkmcnt(11)
	v_mfma_f32_16x16x32_bf16 v[60:63], v[152:155], v[102:105], v[60:63]
	v_mfma_f32_16x16x32_bf16 v[56:59], v[156:159], v[102:105], v[56:59]
	v_mfma_f32_16x16x32_bf16 v[52:55], v[160:163], v[102:105], v[52:55]
	v_mfma_f32_16x16x32_bf16 v[48:51], v[190:193], v[102:105], v[48:51]
	global_load_dwordx4 v[102:105], v[106:107], off
	s_waitcnt vmcnt(6)
	ds_write_b128 v121, v[64:67] offset:32768
	v_add_co_u32_e32 v64, vcc, s11, v106
	s_waitcnt lgkmcnt(11)
	v_mfma_f32_16x16x32_bf16 v[44:47], v[152:155], v[140:143], v[44:47]
	v_addc_co_u32_e32 v65, vcc, 0, v107, vcc
	v_mfma_f32_16x16x32_bf16 v[40:43], v[156:159], v[140:143], v[40:43]
	v_mfma_f32_16x16x32_bf16 v[36:39], v[160:163], v[140:143], v[36:39]
	v_mfma_f32_16x16x32_bf16 v[32:35], v[190:193], v[140:143], v[32:35]
	global_load_dwordx4 v[140:143], v[64:65], off
	v_add_co_u32_e32 v64, vcc, s33, v106
	ds_write_b128 v121, v[68:71] offset:36864
	s_nop 0
	v_addc_co_u32_e32 v65, vcc, 0, v107, vcc
	s_waitcnt lgkmcnt(11)
	v_mfma_f32_16x16x32_bf16 v[28:31], v[152:155], v[144:147], v[28:31]
	v_mfma_f32_16x16x32_bf16 v[24:27], v[156:159], v[144:147], v[24:27]
	v_mfma_f32_16x16x32_bf16 v[20:23], v[160:163], v[144:147], v[20:23]
	v_mfma_f32_16x16x32_bf16 v[16:19], v[190:193], v[144:147], v[16:19]
	global_load_dwordx4 v[144:147], v[64:65], off
	v_add_co_u32_e32 v64, vcc, s59, v106
	ds_write_b128 v121, v[72:75] offset:40960
	s_nop 0
	v_addc_co_u32_e32 v65, vcc, 0, v107, vcc
	s_waitcnt lgkmcnt(11)
	v_mfma_f32_16x16x32_bf16 v[12:15], v[152:155], v[148:151], v[12:15]
	v_mfma_f32_16x16x32_bf16 v[8:11], v[156:159], v[148:151], v[8:11]
	v_mfma_f32_16x16x32_bf16 v[4:7], v[160:163], v[148:151], v[4:7]
	v_mfma_f32_16x16x32_bf16 v[0:3], v[190:193], v[148:151], v[0:3]
	global_load_dwordx4 v[148:151], v[64:65], off
	v_lshl_add_u64 v[64:65], v[100:101], 0, s[92:93]
	v_add_co_u32_e32 v66, vcc, s11, v64
	s_waitcnt vmcnt(7)
	ds_write_b128 v121, v[80:83] offset:45056
	v_addc_co_u32_e32 v67, vcc, 0, v65, vcc
	s_waitcnt lgkmcnt(7)
	v_mfma_f32_16x16x32_bf16 v[60:63], v[210:213], v[194:197], v[60:63]
	s_waitcnt lgkmcnt(6)
	v_mfma_f32_16x16x32_bf16 v[56:59], v[214:217], v[194:197], v[56:59]
	s_waitcnt lgkmcnt(5)
	v_mfma_f32_16x16x32_bf16 v[52:55], v[218:221], v[194:197], v[52:55]
	s_waitcnt lgkmcnt(4)
	v_mfma_f32_16x16x32_bf16 v[48:51], v[222:225], v[194:197], v[48:51]
	global_load_dwordx4 v[152:155], v[64:65], off
	ds_write_b128 v121, v[76:79] offset:49152
	v_mfma_f32_16x16x32_bf16 v[44:47], v[210:213], v[198:201], v[44:47]
	v_mfma_f32_16x16x32_bf16 v[40:43], v[214:217], v[198:201], v[40:43]
	v_mfma_f32_16x16x32_bf16 v[36:39], v[218:221], v[198:201], v[36:39]
	v_mfma_f32_16x16x32_bf16 v[32:35], v[222:225], v[198:201], v[32:35]
	global_load_dwordx4 v[156:159], v[66:67], off
	v_add_co_u32_e32 v66, vcc, s33, v64
	s_waitcnt vmcnt(8)
	ds_write_b128 v121, v[84:87] offset:53248
	v_addc_co_u32_e32 v67, vcc, 0, v65, vcc
	v_add_co_u32_e32 v64, vcc, s59, v64
	v_mfma_f32_16x16x32_bf16 v[28:31], v[210:213], v[202:205], v[28:31]
	s_nop 0
	v_addc_co_u32_e32 v65, vcc, 0, v65, vcc
	v_mfma_f32_16x16x32_bf16 v[24:27], v[214:217], v[202:205], v[24:27]
	v_mfma_f32_16x16x32_bf16 v[20:23], v[218:221], v[202:205], v[20:23]
	v_mfma_f32_16x16x32_bf16 v[16:19], v[222:225], v[202:205], v[16:19]
	global_load_dwordx4 v[160:163], v[66:67], off
	s_waitcnt vmcnt(8)
	ds_write_b128 v121, v[88:91] offset:57344
	v_mfma_f32_16x16x32_bf16 v[12:15], v[210:213], v[206:209], v[12:15]
	v_mfma_f32_16x16x32_bf16 v[8:11], v[214:217], v[206:209], v[8:11]
	v_mfma_f32_16x16x32_bf16 v[4:7], v[218:221], v[206:209], v[4:7]
	v_mfma_f32_16x16x32_bf16 v[0:3], v[222:225], v[206:209], v[0:3]
	global_load_dwordx4 v[190:193], v[64:65], off
	s_waitcnt vmcnt(8)
	ds_write_b128 v121, v[92:95] offset:61440
	s_waitcnt lgkmcnt(0)
	s_barrier
	ds_read_b128 v[80:83], v123 offset:49152
	ds_read_b128 v[84:87], v123 offset:51200
	ds_read_b128 v[88:91], v123 offset:53248
	ds_read_b128 v[92:95], v123 offset:55296
	ds_read_b128 v[64:67], v122 offset:32768
	ds_read_b128 v[68:71], v122 offset:34816
	s_min_u32 s3, s2, 12
	s_lshl_b32 s92, s3, 7
	ds_read_b128 v[72:75], v122 offset:36864
	ds_read_b128 v[76:79], v122 offset:38912
	v_lshl_add_u64 v[106:107], v[98:99], 0, s[92:93]
	ds_read_b128 v[194:197], v124 offset:32768
	ds_read_b128 v[198:201], v124 offset:34816
	ds_read_b128 v[202:205], v124 offset:36864
	ds_read_b128 v[206:209], v124 offset:38912
	ds_read_b128 v[210:213], v125 offset:49152
	ds_read_b128 v[214:217], v125 offset:51200
	ds_read_b128 v[218:221], v125 offset:53248
	ds_read_b128 v[222:225], v125 offset:55296
	s_waitcnt lgkmcnt(11)
	v_mfma_f32_16x16x32_bf16 v[60:63], v[80:83], v[64:67], v[60:63]
	v_mfma_f32_16x16x32_bf16 v[56:59], v[84:87], v[64:67], v[56:59]
	v_mfma_f32_16x16x32_bf16 v[52:55], v[88:91], v[64:67], v[52:55]
	v_mfma_f32_16x16x32_bf16 v[48:51], v[92:95], v[64:67], v[48:51]
	global_load_dwordx4 v[64:67], v[106:107], off offset:384
	s_waitcnt vmcnt(8)
	ds_write_b128 v121, v[102:105]
	v_add_co_u32_e32 v102, vcc, s11, v106
	s_waitcnt lgkmcnt(11)
	v_mfma_f32_16x16x32_bf16 v[44:47], v[80:83], v[68:71], v[44:47]
	v_addc_co_u32_e32 v103, vcc, 0, v107, vcc
	v_mfma_f32_16x16x32_bf16 v[40:43], v[84:87], v[68:71], v[40:43]
	v_mfma_f32_16x16x32_bf16 v[36:39], v[88:91], v[68:71], v[36:39]
	v_mfma_f32_16x16x32_bf16 v[32:35], v[92:95], v[68:71], v[32:35]
	global_load_dwordx4 v[68:71], v[102:103], off offset:384
	v_add_co_u32_e32 v102, vcc, s33, v106
	s_waitcnt vmcnt(8)
	ds_write_b128 v121, v[140:143] offset:4096
	v_addc_co_u32_e32 v103, vcc, 0, v107, vcc
	s_waitcnt lgkmcnt(11)
	v_mfma_f32_16x16x32_bf16 v[28:31], v[80:83], v[72:75], v[28:31]
	v_mfma_f32_16x16x32_bf16 v[24:27], v[84:87], v[72:75], v[24:27]
	v_mfma_f32_16x16x32_bf16 v[20:23], v[88:91], v[72:75], v[20:23]
	v_mfma_f32_16x16x32_bf16 v[16:19], v[92:95], v[72:75], v[16:19]
	global_load_dwordx4 v[72:75], v[102:103], off offset:384
	s_waitcnt vmcnt(8)
	ds_write_b128 v121, v[144:147] offset:8192
	s_waitcnt lgkmcnt(11)
	v_mfma_f32_16x16x32_bf16 v[12:15], v[80:83], v[76:79], v[12:15]
	v_add_co_u32_e32 v80, vcc, s59, v106
	v_mfma_f32_16x16x32_bf16 v[0:3], v[92:95], v[76:79], v[0:3]
	s_nop 0
	v_addc_co_u32_e32 v81, vcc, 0, v107, vcc
	v_lshl_add_u64 v[92:93], v[100:101], 0, s[92:93]
	v_mfma_f32_16x16x32_bf16 v[8:11], v[84:87], v[76:79], v[8:11]
	v_add_co_u32_e32 v84, vcc, s11, v92
	s_nop 1
	v_addc_co_u32_e32 v85, vcc, 0, v93, vcc
	v_mfma_f32_16x16x32_bf16 v[4:7], v[88:91], v[76:79], v[4:7]
	v_add_co_u32_e32 v88, vcc, s33, v92
	global_load_dwordx4 v[80:83], v[80:81], off offset:384
	s_nop 0
	v_addc_co_u32_e32 v89, vcc, 0, v93, vcc
	s_waitcnt vmcnt(8)
	ds_write_b128 v121, v[148:151] offset:12288
	s_waitcnt lgkmcnt(7)
	v_mfma_f32_16x16x32_bf16 v[60:63], v[210:213], v[194:197], v[60:63]
	s_waitcnt lgkmcnt(6)
	v_mfma_f32_16x16x32_bf16 v[56:59], v[214:217], v[194:197], v[56:59]
	s_waitcnt lgkmcnt(5)
	v_mfma_f32_16x16x32_bf16 v[52:55], v[218:221], v[194:197], v[52:55]
	s_waitcnt lgkmcnt(4)
	v_mfma_f32_16x16x32_bf16 v[48:51], v[222:225], v[194:197], v[48:51]
	global_load_dwordx4 v[76:79], v[92:93], off offset:384
	v_add_co_u32_e32 v92, vcc, s59, v92
	s_waitcnt vmcnt(8)
	ds_write_b128 v121, v[152:155] offset:16384
	v_addc_co_u32_e32 v93, vcc, 0, v93, vcc
	v_mfma_f32_16x16x32_bf16 v[44:47], v[210:213], v[198:201], v[44:47]
	v_mfma_f32_16x16x32_bf16 v[40:43], v[214:217], v[198:201], v[40:43]
	v_mfma_f32_16x16x32_bf16 v[36:39], v[218:221], v[198:201], v[36:39]
	v_mfma_f32_16x16x32_bf16 v[32:35], v[222:225], v[198:201], v[32:35]
	global_load_dwordx4 v[84:87], v[84:85], off offset:384
	s_waitcnt vmcnt(8)
	ds_write_b128 v121, v[156:159] offset:20480
	v_mfma_f32_16x16x32_bf16 v[28:31], v[210:213], v[202:205], v[28:31]
	v_mfma_f32_16x16x32_bf16 v[24:27], v[214:217], v[202:205], v[24:27]
	v_mfma_f32_16x16x32_bf16 v[20:23], v[218:221], v[202:205], v[20:23]
	v_mfma_f32_16x16x32_bf16 v[16:19], v[222:225], v[202:205], v[16:19]
	global_load_dwordx4 v[88:91], v[88:89], off offset:384
	s_waitcnt vmcnt(8)
	ds_write_b128 v121, v[160:163] offset:24576
	v_mfma_f32_16x16x32_bf16 v[12:15], v[210:213], v[206:209], v[12:15]
	v_mfma_f32_16x16x32_bf16 v[8:11], v[214:217], v[206:209], v[8:11]
	v_mfma_f32_16x16x32_bf16 v[4:7], v[218:221], v[206:209], v[4:7]
	v_mfma_f32_16x16x32_bf16 v[0:3], v[222:225], v[206:209], v[0:3]
	global_load_dwordx4 v[92:95], v[92:93], off offset:384
	s_waitcnt vmcnt(8)
	ds_write_b128 v121, v[190:193] offset:28672
	s_cmp_lt_u32 s2, 12
	s_mov_b32 s3, s2
	s_waitcnt lgkmcnt(0)
	s_barrier
	s_cbranch_scc1 .LBB0_702
.Ltail702:
	s_add_i32 s2, s3, 2
	ds_read_b128 v[152:155], v123 offset:16384
	ds_read_b128 v[156:159], v123 offset:18432
	ds_read_b128 v[160:163], v123 offset:20480
	ds_read_b128 v[190:193], v123 offset:22528
	ds_read_b128 v[102:105], v122
	s_add_i32 s3, s3, 4
	ds_read_b128 v[140:143], v122 offset:2048
	s_min_u32 s3, s3, 15
	s_lshl_b32 s92, s3, 7
	ds_read_b128 v[144:147], v122 offset:4096
	v_lshl_add_u64 v[106:107], v[98:99], 0, s[92:93]
	ds_read_b128 v[148:151], v122 offset:6144
	ds_read_b128 v[194:197], v124
	ds_read_b128 v[198:201], v124 offset:2048
	ds_read_b128 v[202:205], v124 offset:4096
	ds_read_b128 v[206:209], v124 offset:6144
	ds_read_b128 v[210:213], v125 offset:16384
	ds_read_b128 v[214:217], v125 offset:18432
	ds_read_b128 v[218:221], v125 offset:20480
	ds_read_b128 v[222:225], v125 offset:22528
	s_waitcnt lgkmcnt(11)
	v_mfma_f32_16x16x32_bf16 v[60:63], v[152:155], v[102:105], v[60:63]
	v_mfma_f32_16x16x32_bf16 v[56:59], v[156:159], v[102:105], v[56:59]
	v_mfma_f32_16x16x32_bf16 v[52:55], v[160:163], v[102:105], v[52:55]
	v_mfma_f32_16x16x32_bf16 v[48:51], v[190:193], v[102:105], v[48:51]
	s_waitcnt vmcnt(7)
	ds_write_b128 v121, v[64:67] offset:32768
	v_add_co_u32_e32 v64, vcc, s11, v106
	s_waitcnt lgkmcnt(11)
	v_mfma_f32_16x16x32_bf16 v[44:47], v[152:155], v[140:143], v[44:47]
	v_addc_co_u32_e32 v65, vcc, 0, v107, vcc
	v_mfma_f32_16x16x32_bf16 v[40:43], v[156:159], v[140:143], v[40:43]
	v_mfma_f32_16x16x32_bf16 v[36:39], v[160:163], v[140:143], v[36:39]
	v_mfma_f32_16x16x32_bf16 v[32:35], v[190:193], v[140:143], v[32:35]
	v_add_co_u32_e32 v64, vcc, s33, v106
	s_waitcnt vmcnt(6)
	ds_write_b128 v121, v[68:71] offset:36864
	s_nop 0
	v_addc_co_u32_e32 v65, vcc, 0, v107, vcc
	s_waitcnt lgkmcnt(11)
	v_mfma_f32_16x16x32_bf16 v[28:31], v[152:155], v[144:147], v[28:31]
	v_mfma_f32_16x16x32_bf16 v[24:27], v[156:159], v[144:147], v[24:27]
	v_mfma_f32_16x16x32_bf16 v[20:23], v[160:163], v[144:147], v[20:23]
	v_mfma_f32_16x16x32_bf16 v[16:19], v[190:193], v[144:147], v[16:19]
	v_add_co_u32_e32 v64, vcc, s59, v106
	s_waitcnt vmcnt(5)
	ds_write_b128 v121, v[72:75] offset:40960
	s_nop 0
	v_addc_co_u32_e32 v65, vcc, 0, v107, vcc
	s_waitcnt lgkmcnt(11)
	v_mfma_f32_16x16x32_bf16 v[12:15], v[152:155], v[148:151], v[12:15]
	v_mfma_f32_16x16x32_bf16 v[8:11], v[156:159], v[148:151], v[8:11]
	v_mfma_f32_16x16x32_bf16 v[4:7], v[160:163], v[148:151], v[4:7]
	v_mfma_f32_16x16x32_bf16 v[0:3], v[190:193], v[148:151], v[0:3]
	v_lshl_add_u64 v[64:65], v[100:101], 0, s[92:93]
	v_add_co_u32_e32 v66, vcc, s11, v64
	s_waitcnt vmcnt(4)
	ds_write_b128 v121, v[80:83] offset:45056
	v_addc_co_u32_e32 v67, vcc, 0, v65, vcc
	s_waitcnt lgkmcnt(7)
	v_mfma_f32_16x16x32_bf16 v[60:63], v[210:213], v[194:197], v[60:63]
	s_waitcnt lgkmcnt(6)
	v_mfma_f32_16x16x32_bf16 v[56:59], v[214:217], v[194:197], v[56:59]
	s_waitcnt lgkmcnt(5)
	v_mfma_f32_16x16x32_bf16 v[52:55], v[218:221], v[194:197], v[52:55]
	s_waitcnt lgkmcnt(4)
	v_mfma_f32_16x16x32_bf16 v[48:51], v[222:225], v[194:197], v[48:51]
	s_waitcnt vmcnt(3)
	ds_write_b128 v121, v[76:79] offset:49152
	v_mfma_f32_16x16x32_bf16 v[44:47], v[210:213], v[198:201], v[44:47]
	v_mfma_f32_16x16x32_bf16 v[40:43], v[214:217], v[198:201], v[40:43]
	v_mfma_f32_16x16x32_bf16 v[36:39], v[218:221], v[198:201], v[36:39]
	v_mfma_f32_16x16x32_bf16 v[32:35], v[222:225], v[198:201], v[32:35]
	v_add_co_u32_e32 v66, vcc, s33, v64
	s_waitcnt vmcnt(2)
	ds_write_b128 v121, v[84:87] offset:53248
	v_addc_co_u32_e32 v67, vcc, 0, v65, vcc
	v_add_co_u32_e32 v64, vcc, s59, v64
	v_mfma_f32_16x16x32_bf16 v[28:31], v[210:213], v[202:205], v[28:31]
	s_nop 0
	v_addc_co_u32_e32 v65, vcc, 0, v65, vcc
	v_mfma_f32_16x16x32_bf16 v[24:27], v[214:217], v[202:205], v[24:27]
	v_mfma_f32_16x16x32_bf16 v[20:23], v[218:221], v[202:205], v[20:23]
	v_mfma_f32_16x16x32_bf16 v[16:19], v[222:225], v[202:205], v[16:19]
	s_waitcnt vmcnt(1)
	ds_write_b128 v121, v[88:91] offset:57344
	v_mfma_f32_16x16x32_bf16 v[12:15], v[210:213], v[206:209], v[12:15]
	v_mfma_f32_16x16x32_bf16 v[8:11], v[214:217], v[206:209], v[8:11]
	v_mfma_f32_16x16x32_bf16 v[4:7], v[218:221], v[206:209], v[4:7]
	v_mfma_f32_16x16x32_bf16 v[0:3], v[222:225], v[206:209], v[0:3]
	s_waitcnt vmcnt(0)
	ds_write_b128 v121, v[92:95] offset:61440
	s_waitcnt lgkmcnt(0)
	s_barrier
	ds_read_b128 v[80:83], v123 offset:49152
	ds_read_b128 v[84:87], v123 offset:51200
	ds_read_b128 v[88:91], v123 offset:53248
	ds_read_b128 v[92:95], v123 offset:55296
	ds_read_b128 v[64:67], v122 offset:32768
	ds_read_b128 v[68:71], v122 offset:34816
	s_min_u32 s3, s2, 12
	s_lshl_b32 s92, s3, 7
	ds_read_b128 v[72:75], v122 offset:36864
	ds_read_b128 v[76:79], v122 offset:38912
	v_lshl_add_u64 v[106:107], v[98:99], 0, s[92:93]
	ds_read_b128 v[194:197], v124 offset:32768
	ds_read_b128 v[198:201], v124 offset:34816
	ds_read_b128 v[202:205], v124 offset:36864
	ds_read_b128 v[206:209], v124 offset:38912
	ds_read_b128 v[210:213], v125 offset:49152
	ds_read_b128 v[214:217], v125 offset:51200
	ds_read_b128 v[218:221], v125 offset:53248
	ds_read_b128 v[222:225], v125 offset:55296
	s_waitcnt lgkmcnt(11)
	v_mfma_f32_16x16x32_bf16 v[60:63], v[80:83], v[64:67], v[60:63]
	v_mfma_f32_16x16x32_bf16 v[56:59], v[84:87], v[64:67], v[56:59]
	v_mfma_f32_16x16x32_bf16 v[52:55], v[88:91], v[64:67], v[52:55]
	v_mfma_f32_16x16x32_bf16 v[48:51], v[92:95], v[64:67], v[48:51]
	v_add_co_u32_e32 v102, vcc, s11, v106
	s_waitcnt lgkmcnt(10)
	v_mfma_f32_16x16x32_bf16 v[44:47], v[80:83], v[68:71], v[44:47]
	v_addc_co_u32_e32 v103, vcc, 0, v107, vcc
	v_mfma_f32_16x16x32_bf16 v[40:43], v[84:87], v[68:71], v[40:43]
	v_mfma_f32_16x16x32_bf16 v[36:39], v[88:91], v[68:71], v[36:39]
	v_mfma_f32_16x16x32_bf16 v[32:35], v[92:95], v[68:71], v[32:35]
	v_add_co_u32_e32 v102, vcc, s33, v106
	v_addc_co_u32_e32 v103, vcc, 0, v107, vcc
	s_waitcnt lgkmcnt(9)
	v_mfma_f32_16x16x32_bf16 v[28:31], v[80:83], v[72:75], v[28:31]
	v_mfma_f32_16x16x32_bf16 v[24:27], v[84:87], v[72:75], v[24:27]
	v_mfma_f32_16x16x32_bf16 v[20:23], v[88:91], v[72:75], v[20:23]
	v_mfma_f32_16x16x32_bf16 v[16:19], v[92:95], v[72:75], v[16:19]
	s_waitcnt lgkmcnt(8)
	v_mfma_f32_16x16x32_bf16 v[12:15], v[80:83], v[76:79], v[12:15]
	v_add_co_u32_e32 v80, vcc, s59, v106
	v_mfma_f32_16x16x32_bf16 v[0:3], v[92:95], v[76:79], v[0:3]
	s_nop 0
	v_addc_co_u32_e32 v81, vcc, 0, v107, vcc
	v_lshl_add_u64 v[92:93], v[100:101], 0, s[92:93]
	v_mfma_f32_16x16x32_bf16 v[8:11], v[84:87], v[76:79], v[8:11]
	v_add_co_u32_e32 v84, vcc, s11, v92
	s_nop 1
	v_addc_co_u32_e32 v85, vcc, 0, v93, vcc
	v_mfma_f32_16x16x32_bf16 v[4:7], v[88:91], v[76:79], v[4:7]
	v_add_co_u32_e32 v88, vcc, s33, v92
	s_nop 0
	v_addc_co_u32_e32 v89, vcc, 0, v93, vcc
	s_waitcnt lgkmcnt(3)
	v_mfma_f32_16x16x32_bf16 v[60:63], v[210:213], v[194:197], v[60:63]
	s_waitcnt lgkmcnt(2)
	v_mfma_f32_16x16x32_bf16 v[56:59], v[214:217], v[194:197], v[56:59]
	s_waitcnt lgkmcnt(1)
	v_mfma_f32_16x16x32_bf16 v[52:55], v[218:221], v[194:197], v[52:55]
	s_waitcnt lgkmcnt(0)
	v_mfma_f32_16x16x32_bf16 v[48:51], v[222:225], v[194:197], v[48:51]
	v_add_co_u32_e32 v92, vcc, s59, v92
	v_addc_co_u32_e32 v93, vcc, 0, v93, vcc
	v_mfma_f32_16x16x32_bf16 v[44:47], v[210:213], v[198:201], v[44:47]
	v_mfma_f32_16x16x32_bf16 v[40:43], v[214:217], v[198:201], v[40:43]
	v_mfma_f32_16x16x32_bf16 v[36:39], v[218:221], v[198:201], v[36:39]
	v_mfma_f32_16x16x32_bf16 v[32:35], v[222:225], v[198:201], v[32:35]
	v_mfma_f32_16x16x32_bf16 v[28:31], v[210:213], v[202:205], v[28:31]
	v_mfma_f32_16x16x32_bf16 v[24:27], v[214:217], v[202:205], v[24:27]
	v_mfma_f32_16x16x32_bf16 v[20:23], v[218:221], v[202:205], v[20:23]
	v_mfma_f32_16x16x32_bf16 v[16:19], v[222:225], v[202:205], v[16:19]
	v_mfma_f32_16x16x32_bf16 v[12:15], v[210:213], v[206:209], v[12:15]
	v_mfma_f32_16x16x32_bf16 v[8:11], v[214:217], v[206:209], v[8:11]
	v_mfma_f32_16x16x32_bf16 v[4:7], v[218:221], v[206:209], v[4:7]
	v_mfma_f32_16x16x32_bf16 v[0:3], v[222:225], v[206:209], v[0:3]
	s_mov_b32 s3, s2
	s_waitcnt lgkmcnt(0)
	s_barrier
	s_and_saveexec_b64 s[2:3], s[36:37]
	s_cbranch_execz .LBB0_705
	s_waitcnt vmcnt(7)
	v_add_f32_e32 v64, 0, v96
	v_add_f32_e32 v64, v64, v97
	v_add_f32_e32 v64, v64, v108
	v_add_f32_e32 v64, v64, v109
	v_add_f32_e32 v64, v64, v110
	v_add_f32_e32 v64, v64, v111
	v_add_f32_e32 v64, v64, v118
	v_add_f32_e32 v64, v64, v119
	v_add_f32_e32 v64, v64, v128
	v_add_f32_e32 v64, v64, v132
	v_add_f32_e32 v64, v64, v133
	v_add_f32_e32 v64, v64, v134
	v_add_f32_e32 v64, v64, v135
	v_add_f32_e32 v64, v64, v136
	v_add_f32_e32 v64, v64, v137
	v_add_f32_e32 v64, v64, v138
	v_fmamk_f32 v64, v64, 0x3a800000, v167
	s_mov_b32 s17, 0x800000
	v_mul_f32_e32 v65, 0x4b800000, v64
	v_cmp_gt_f32_e32 vcc, s17, v64
	s_nop 1
	v_cndmask_b32_e32 v64, v64, v65, vcc
	v_rsq_f32_e32 v64, v64
	s_nop 0
	v_mul_f32_e32 v65, 0x45800000, v64
	v_cndmask_b32_e32 v64, v64, v65, vcc
	ds_write_b32 v126, v64

.LBB0_739:
	s_add_i32 s2, s3, 2
	v_add_u32_e32 v130, v105, v106
	ds_read_b128 v[116:119], v130 offset:16384
	ds_read_b128 v[120:123], v130 offset:18432
	ds_read_b128 v[124:127], v130 offset:20480
	ds_read_b128 v[132:135], v130 offset:22528
	v_add_u32_e32 v128, v104, v106
	ds_read_b128 v[108:111], v128
	ds_read_b128 v[112:115], v128 offset:2048
	s_add_i32 s3, s3, 4
	s_min_u32 s3, s3, 15
	v_add_u32_e32 v148, v104, v107
	v_add_u32_e32 v149, v105, v107
	s_lshl_b32 s92, s3, 7
	ds_read_b128 v[136:139], v149 offset:18432
	ds_read_b128 v[140:143], v149 offset:20480
	ds_read_b128 v[144:147], v149 offset:22528
	s_waitcnt lgkmcnt(4)
	v_mfma_f32_16x16x32_bf16 v[72:75], v[116:119], v[108:111], v[72:75]
	v_lshl_add_u64 v[52:53], v[80:81], 0, s[92:93]
	v_add_co_u32_e32 v54, vcc, s11, v52
	v_mfma_f32_16x16x32_bf16 v[48:51], v[120:123], v[108:111], v[48:51]
	s_nop 0
	v_addc_co_u32_e32 v55, vcc, 0, v53, vcc
	v_mfma_f32_16x16x32_bf16 v[44:47], v[124:127], v[108:111], v[44:47]
	v_mfma_f32_16x16x32_bf16 v[40:43], v[132:135], v[108:111], v[40:43]
	s_waitcnt lgkmcnt(3)
	v_mfma_f32_16x16x32_bf16 v[108:111], v[116:119], v[112:115], v[16:19]
	s_nop 2
	ds_read_b128 v[16:19], v148
	v_mfma_f32_16x16x32_bf16 v[116:119], v[120:123], v[112:115], v[8:11]
	v_mfma_f32_16x16x32_bf16 v[120:123], v[124:127], v[112:115], v[4:7]
	ds_read_b128 v[124:127], v148 offset:2048
	v_mfma_f32_16x16x32_bf16 v[112:115], v[132:135], v[112:115], v[0:3]
	ds_read_b128 v[132:135], v149 offset:16384
	global_load_dwordx4 v[76:79], v[52:53], off
	s_waitcnt vmcnt(1)
	ds_write_b128 v103, v[12:15] offset:53248
	global_load_dwordx4 v[68:71], v[54:55], off
	v_add_co_u32_e32 v54, vcc, s33, v52
	ds_write_b128 v103, v[20:23] offset:49152
	s_nop 0
	v_addc_co_u32_e32 v55, vcc, 0, v53, vcc
	v_add_co_u32_e32 v52, vcc, s59, v52
	global_load_dwordx4 v[64:67], v[54:55], off
	s_nop 0
	v_addc_co_u32_e32 v53, vcc, 0, v53, vcc
	ds_write_b128 v103, v[24:27] offset:45056
	global_load_dwordx4 v[60:63], v[52:53], off
	v_lshl_add_u64 v[52:53], v[82:83], 0, s[92:93]
	ds_write_b128 v103, v[36:39] offset:32768
	s_waitcnt lgkmcnt(4)
	v_mfma_f32_16x16x32_bf16 v[0:3], v[132:135], v[16:19], v[72:75]
	v_mfma_f32_16x16x32_bf16 v[4:7], v[136:139], v[16:19], v[48:51]
	global_load_dwordx4 v[56:59], v[52:53], off
	v_add_co_u32_e32 v52, vcc, s11, v52
	ds_write_b128 v103, v[32:35] offset:36864
	s_nop 0
	v_addc_co_u32_e32 v53, vcc, 0, v53, vcc
	v_mfma_f32_16x16x32_bf16 v[8:11], v[140:143], v[16:19], v[44:47]
	v_mfma_f32_16x16x32_bf16 v[16:19], v[144:147], v[16:19], v[40:43]
	global_load_dwordx4 v[52:55], v[52:53], off
	ds_write_b128 v103, v[28:31] offset:40960
	v_mfma_f32_16x16x32_bf16 v[40:43], v[132:135], v[124:127], v[108:111]
	v_mfma_f32_16x16x32_bf16 v[44:47], v[136:139], v[124:127], v[116:119]
	v_mfma_f32_16x16x32_bf16 v[48:51], v[140:143], v[124:127], v[120:123]
	v_mfma_f32_16x16x32_bf16 v[72:75], v[144:147], v[124:127], v[112:115]
	s_waitcnt lgkmcnt(0)
	s_barrier
	ds_read_b128 v[116:119], v130 offset:49152
	ds_read_b128 v[120:123], v130 offset:51200
	ds_read_b128 v[124:127], v130 offset:53248
	ds_read_b128 v[132:135], v130 offset:55296
	ds_read_b128 v[108:111], v128 offset:32768
	ds_read_b128 v[112:115], v128 offset:34816
	s_min_u32 s3, s2, 12
	s_lshl_b32 s92, s3, 7
	ds_read_b128 v[136:139], v149 offset:51200
	ds_read_b128 v[140:143], v149 offset:53248
	ds_read_b128 v[144:147], v149 offset:55296
	s_waitcnt lgkmcnt(4)
	v_mfma_f32_16x16x32_bf16 v[0:3], v[116:119], v[108:111], v[0:3]
	v_lshl_add_u64 v[12:13], v[80:81], 0, s[92:93]
	v_add_co_u32_e32 v14, vcc, s11, v12
	v_mfma_f32_16x16x32_bf16 v[4:7], v[120:123], v[108:111], v[4:7]
	s_nop 0
	v_addc_co_u32_e32 v15, vcc, 0, v13, vcc
	v_mfma_f32_16x16x32_bf16 v[8:11], v[124:127], v[108:111], v[8:11]
	v_mfma_f32_16x16x32_bf16 v[16:19], v[132:135], v[108:111], v[16:19]
	s_waitcnt lgkmcnt(3)
	v_mfma_f32_16x16x32_bf16 v[108:111], v[116:119], v[112:115], v[40:43]
	s_nop 2
	ds_read_b128 v[40:43], v148 offset:32768
	v_mfma_f32_16x16x32_bf16 v[116:119], v[120:123], v[112:115], v[44:47]
	v_mfma_f32_16x16x32_bf16 v[120:123], v[124:127], v[112:115], v[48:51]
	ds_read_b128 v[124:127], v148 offset:34816
	v_mfma_f32_16x16x32_bf16 v[112:115], v[132:135], v[112:115], v[72:75]
	ds_read_b128 v[132:135], v149 offset:49152
	global_load_dwordx4 v[36:39], v[12:13], off offset:384
	s_waitcnt vmcnt(1)
	ds_write_b128 v103, v[52:55] offset:20480
	global_load_dwordx4 v[32:35], v[14:15], off offset:384
	v_add_co_u32_e32 v14, vcc, s33, v12
	ds_write_b128 v103, v[56:59] offset:16384
	s_nop 0
	v_addc_co_u32_e32 v15, vcc, 0, v13, vcc
	v_add_co_u32_e32 v12, vcc, s59, v12
	global_load_dwordx4 v[28:31], v[14:15], off offset:384
	s_nop 0
	v_addc_co_u32_e32 v13, vcc, 0, v13, vcc
	ds_write_b128 v103, v[60:63] offset:12288
	global_load_dwordx4 v[24:27], v[12:13], off offset:384
	v_lshl_add_u64 v[12:13], v[82:83], 0, s[92:93]
	ds_write_b128 v103, v[76:79]
	s_waitcnt lgkmcnt(4)
	v_mfma_f32_16x16x32_bf16 v[72:75], v[132:135], v[40:43], v[0:3]
	v_mfma_f32_16x16x32_bf16 v[48:51], v[136:139], v[40:43], v[4:7]
	global_load_dwordx4 v[20:23], v[12:13], off offset:384
	v_add_co_u32_e32 v12, vcc, s11, v12
	ds_write_b128 v103, v[68:71] offset:4096
	s_nop 0
	v_addc_co_u32_e32 v13, vcc, 0, v13, vcc
	v_mfma_f32_16x16x32_bf16 v[44:47], v[140:143], v[40:43], v[8:11]
	v_mfma_f32_16x16x32_bf16 v[40:43], v[144:147], v[40:43], v[16:19]
	global_load_dwordx4 v[12:15], v[12:13], off offset:384
	ds_write_b128 v103, v[64:67] offset:8192
	v_mfma_f32_16x16x32_bf16 v[16:19], v[132:135], v[124:127], v[108:111]
	v_mfma_f32_16x16x32_bf16 v[8:11], v[136:139], v[124:127], v[116:119]
	v_mfma_f32_16x16x32_bf16 v[4:7], v[140:143], v[124:127], v[120:123]
	v_mfma_f32_16x16x32_bf16 v[0:3], v[144:147], v[124:127], v[112:115]
	s_cmp_lt_u32 s2, 12
	s_mov_b32 s3, s2
	s_waitcnt lgkmcnt(0)
	s_barrier
	s_cbranch_scc1 .LBB0_739
.Ltail739:
	s_add_i32 s2, s3, 2
	v_add_u32_e32 v130, v105, v106
	ds_read_b128 v[116:119], v130 offset:16384
	ds_read_b128 v[120:123], v130 offset:18432
	ds_read_b128 v[124:127], v130 offset:20480
	ds_read_b128 v[132:135], v130 offset:22528
	v_add_u32_e32 v128, v104, v106
	ds_read_b128 v[108:111], v128
	ds_read_b128 v[112:115], v128 offset:2048
	s_add_i32 s3, s3, 4
	s_min_u32 s3, s3, 15
	v_add_u32_e32 v148, v104, v107
	v_add_u32_e32 v149, v105, v107
	s_lshl_b32 s92, s3, 7
	ds_read_b128 v[136:139], v149 offset:18432
	ds_read_b128 v[140:143], v149 offset:20480
	ds_read_b128 v[144:147], v149 offset:22528
	s_waitcnt lgkmcnt(4)
	v_mfma_f32_16x16x32_bf16 v[72:75], v[116:119], v[108:111], v[72:75]
	v_lshl_add_u64 v[52:53], v[80:81], 0, s[92:93]
	v_add_co_u32_e32 v54, vcc, s11, v52
	v_mfma_f32_16x16x32_bf16 v[48:51], v[120:123], v[108:111], v[48:51]
	s_nop 0
	v_addc_co_u32_e32 v55, vcc, 0, v53, vcc
	v_mfma_f32_16x16x32_bf16 v[44:47], v[124:127], v[108:111], v[44:47]
	v_mfma_f32_16x16x32_bf16 v[40:43], v[132:135], v[108:111], v[40:43]
	s_waitcnt lgkmcnt(3)
	v_mfma_f32_16x16x32_bf16 v[108:111], v[116:119], v[112:115], v[16:19]
	s_nop 2
	ds_read_b128 v[16:19], v148
	v_mfma_f32_16x16x32_bf16 v[116:119], v[120:123], v[112:115], v[8:11]
	v_mfma_f32_16x16x32_bf16 v[120:123], v[124:127], v[112:115], v[4:7]
	ds_read_b128 v[124:127], v148 offset:2048
	v_mfma_f32_16x16x32_bf16 v[112:115], v[132:135], v[112:115], v[0:3]
	ds_read_b128 v[132:135], v149 offset:16384
	s_waitcnt vmcnt(0)
	ds_write_b128 v103, v[12:15] offset:53248
	v_add_co_u32_e32 v54, vcc, s33, v52
	s_waitcnt vmcnt(1)
	ds_write_b128 v103, v[20:23] offset:49152
	s_nop 0
	v_addc_co_u32_e32 v55, vcc, 0, v53, vcc
	v_add_co_u32_e32 v52, vcc, s59, v52
	s_nop 0
	v_addc_co_u32_e32 v53, vcc, 0, v53, vcc
	s_waitcnt vmcnt(2)
	ds_write_b128 v103, v[24:27] offset:45056
	v_lshl_add_u64 v[52:53], v[82:83], 0, s[92:93]
	s_waitcnt vmcnt(5)
	ds_write_b128 v103, v[36:39] offset:32768
	s_waitcnt lgkmcnt(4)
	v_mfma_f32_16x16x32_bf16 v[0:3], v[132:135], v[16:19], v[72:75]
	v_mfma_f32_16x16x32_bf16 v[4:7], v[136:139], v[16:19], v[48:51]
	v_add_co_u32_e32 v52, vcc, s11, v52
	s_waitcnt vmcnt(4)
	ds_write_b128 v103, v[32:35] offset:36864
	s_nop 0
	v_addc_co_u32_e32 v53, vcc, 0, v53, vcc
	v_mfma_f32_16x16x32_bf16 v[8:11], v[140:143], v[16:19], v[44:47]
	v_mfma_f32_16x16x32_bf16 v[16:19], v[144:147], v[16:19], v[40:43]
	s_waitcnt vmcnt(3)
	ds_write_b128 v103, v[28:31] offset:40960
	v_mfma_f32_16x16x32_bf16 v[40:43], v[132:135], v[124:127], v[108:111]
	v_mfma_f32_16x16x32_bf16 v[44:47], v[136:139], v[124:127], v[116:119]
	v_mfma_f32_16x16x32_bf16 v[48:51], v[140:143], v[124:127], v[120:123]
	v_mfma_f32_16x16x32_bf16 v[72:75], v[144:147], v[124:127], v[112:115]
	s_waitcnt lgkmcnt(0)
	s_barrier
	ds_read_b128 v[116:119], v130 offset:49152
	ds_read_b128 v[120:123], v130 offset:51200
	ds_read_b128 v[124:127], v130 offset:53248
	ds_read_b128 v[132:135], v130 offset:55296
	ds_read_b128 v[108:111], v128 offset:32768
	ds_read_b128 v[112:115], v128 offset:34816
	s_min_u32 s3, s2, 12
	s_lshl_b32 s92, s3, 7
	ds_read_b128 v[136:139], v149 offset:51200
	ds_read_b128 v[140:143], v149 offset:53248
	ds_read_b128 v[144:147], v149 offset:55296
	s_waitcnt lgkmcnt(4)
	v_mfma_f32_16x16x32_bf16 v[0:3], v[116:119], v[108:111], v[0:3]
	v_lshl_add_u64 v[12:13], v[80:81], 0, s[92:93]
	v_add_co_u32_e32 v14, vcc, s11, v12
	v_mfma_f32_16x16x32_bf16 v[4:7], v[120:123], v[108:111], v[4:7]
	s_nop 0
	v_addc_co_u32_e32 v15, vcc, 0, v13, vcc
	v_mfma_f32_16x16x32_bf16 v[8:11], v[124:127], v[108:111], v[8:11]
	v_mfma_f32_16x16x32_bf16 v[16:19], v[132:135], v[108:111], v[16:19]
	s_waitcnt lgkmcnt(3)
	v_mfma_f32_16x16x32_bf16 v[108:111], v[116:119], v[112:115], v[40:43]
	s_nop 2
	ds_read_b128 v[40:43], v148 offset:32768
	v_mfma_f32_16x16x32_bf16 v[116:119], v[120:123], v[112:115], v[44:47]
	v_mfma_f32_16x16x32_bf16 v[120:123], v[124:127], v[112:115], v[48:51]
	ds_read_b128 v[124:127], v148 offset:34816
	v_mfma_f32_16x16x32_bf16 v[112:115], v[132:135], v[112:115], v[72:75]
	ds_read_b128 v[132:135], v149 offset:49152
	v_add_co_u32_e32 v14, vcc, s33, v12
	s_nop 0
	v_addc_co_u32_e32 v15, vcc, 0, v13, vcc
	v_add_co_u32_e32 v12, vcc, s59, v12
	s_nop 0
	v_addc_co_u32_e32 v13, vcc, 0, v13, vcc
	v_lshl_add_u64 v[12:13], v[82:83], 0, s[92:93]
	s_waitcnt lgkmcnt(0)
	v_mfma_f32_16x16x32_bf16 v[72:75], v[132:135], v[40:43], v[0:3]
	v_mfma_f32_16x16x32_bf16 v[48:51], v[136:139], v[40:43], v[4:7]
	v_add_co_u32_e32 v12, vcc, s11, v12
	s_nop 0
	v_addc_co_u32_e32 v13, vcc, 0, v13, vcc
	v_mfma_f32_16x16x32_bf16 v[44:47], v[140:143], v[40:43], v[8:11]
	v_mfma_f32_16x16x32_bf16 v[40:43], v[144:147], v[40:43], v[16:19]
	v_mfma_f32_16x16x32_bf16 v[16:19], v[132:135], v[124:127], v[108:111]
	v_mfma_f32_16x16x32_bf16 v[8:11], v[136:139], v[124:127], v[116:119]
	v_mfma_f32_16x16x32_bf16 v[4:7], v[140:143], v[124:127], v[120:123]
	v_mfma_f32_16x16x32_bf16 v[0:3], v[144:147], v[124:127], v[112:115]
	s_mov_b32 s3, s2
	s_waitcnt lgkmcnt(0)
	s_barrier
	s_movk_i32 s2, 0x80
	v_cmp_gt_i32_e32 vcc, s2, v85
	s_and_saveexec_b64 s[2:3], vcc
	s_cbranch_execz .LBB0_742
	s_waitcnt vmcnt(0)
	v_add_f32_e32 v12, 0, v102
	v_add_f32_e32 v12, v12, v86
	v_add_f32_e32 v12, v12, v87
	v_add_f32_e32 v12, v12, v88
	v_add_f32_e32 v12, v12, v89
	v_add_f32_e32 v12, v12, v90
	v_add_f32_e32 v12, v12, v91
	v_add_f32_e32 v12, v12, v92
	v_add_f32_e32 v12, v12, v93
	v_add_f32_e32 v12, v12, v95
	v_add_f32_e32 v12, v12, v96
	v_add_f32_e32 v12, v12, v97
	v_add_f32_e32 v12, v12, v98
	v_add_f32_e32 v12, v12, v99
	v_add_f32_e32 v12, v12, v100
	v_add_f32_e32 v12, v12, v101
	v_fmamk_f32 v12, v12, 0x3a800000, v167
	s_mov_b32 s16, 0x800000
	v_mul_f32_e32 v13, 0x4b800000, v12
	v_cmp_gt_f32_e32 vcc, s16, v12
	s_nop 1
	v_cndmask_b32_e32 v12, v12, v13, vcc
	v_rsq_f32_e32 v12, v12
	v_lshl_add_u32 v13, v85, 2, 0
	v_add_u32_e32 v13, 0x10000, v13
	v_mul_f32_e32 v14, 0x45800000, v12
	v_cndmask_b32_e32 v12, v12, v14, vcc
	ds_write_b32 v13, v12
